# speedup vs baseline: 1.0081x; 1.0081x over previous
; #define RAW_BARRIER() do { asm volatile("s_waitcnt lgkmcnt(0)" ::: "memory"); __builtin_amdgcn_s_barrier(); } while (0)
; #define GLDS_TILE(kt, st) do { _Pragma("unroll") for (int _i = 0; _i < NP; ++_i) GLDS_PIECE(_i, kt, st); } while (0)
;     ...
;     constexpr int NH = NI >= 4 ? NI / 2 : NI;
;     constexpr int NP = 2 + NB, IVL = (4 * NI) / NP;
;     RAW_BARRIER();
;     GLDS_TILE(0, 0);
;     GLDS_TILE(1, 1);
;     int st = 0;
;     for (int kt = 0; kt < nk - 1; ++kt) {
;         if (NI == 8) asm volatile("s_waitcnt vmcnt(6)" ::: "memory"); else if (NI == 4) asm volatile("s_waitcnt vmcnt(4)" ::: "memory"); else asm volatile("s_waitcnt vmcnt(3)" ::: "memory");
;         RAW_BARRIER();
;         const int s2 = st >= 1 ? st - 1 : 2;
;         const bool ld = kt + 2 < nk;
;         STEP_TILE(st, ld, kt + 2, s2);
;         st = st == 2 ? 0 : st + 1;
;     }
.LBB0_21:
	s_mul_i32 s28, s23, 0x6000
	s_add_i32 s29, s28, 0
	s_waitcnt vmcnt(6)
	v_add_u32_e32 v148, s29, v134
	v_add_u32_e32 v155, s29, v135
	s_waitcnt lgkmcnt(0)
	s_barrier
	ds_read_b128 v[158:161], v155 offset:8192
	ds_read_b128 v[136:139], v148
	ds_read_b128 v[140:143], v148 offset:1024
	ds_read_b128 v[144:147], v148 offset:2048
	ds_read_b128 v[148:151], v148 offset:3072
	ds_read_b128 v[162:165], v155 offset:9216
	ds_read_b128 v[166:169], v155 offset:10240
	ds_read_b128 v[170:173], v155 offset:11264
	s_addk_i32 s28, 0xa000
	s_cmp_gt_i32 s23, 0
	s_setprio 1
	s_waitcnt lgkmcnt(6)
	v_mfma_f32_16x16x32_bf16 v[126:129], v[158:161], v[136:139], v[126:129]
	s_cselect_b32 s28, s28, 0xc000
	v_add_u32_e32 v157, s28, v32
	v_lshl_add_u64 v[152:153], v[132:133], 0, s[8:9]
	s_waitcnt lgkmcnt(5)
	v_mfma_f32_16x16x32_bf16 v[110:113], v[158:161], v[140:143], v[110:113]
	v_lshl_add_u64 v[208:209], v[130:131], 0, s[8:9]
	s_mov_b64 s[28:29], 0xb52c080
	v_lshl_add_u64 v[206:207], v[152:153], 0, s[30:31]
	s_waitcnt lgkmcnt(4)
	v_mfma_f32_16x16x32_bf16 v[82:85], v[158:161], v[144:147], v[82:85]
	v_add_u32_e32 v205, 0x2000, v157
	s_waitcnt lgkmcnt(3)
	v_mfma_f32_16x16x32_bf16 v[50:53], v[158:161], v[148:151], v[50:53]
	v_lshl_add_u64 v[158:159], v[208:209], 0, s[28:29]
	s_waitcnt lgkmcnt(2)
	v_mfma_f32_16x16x32_bf16 v[122:125], v[162:165], v[136:139], v[122:125]
	v_readfirstlane_b32 s28, v157
	s_mov_b32 m0, s28
	v_mfma_f32_16x16x32_bf16 v[102:105], v[162:165], v[140:143], v[102:105]
	global_load_lds_dwordx4 v[158:159], off
	ds_read_b128 v[158:161], v155 offset:12288
	ds_read_b128 v[174:177], v155 offset:13312
	ds_read_b128 v[178:181], v155 offset:14336
	ds_read_b128 v[182:185], v155 offset:15360
	v_mfma_f32_16x16x32_bf16 v[70:73], v[162:165], v[144:147], v[70:73]
	v_mfma_f32_16x16x32_bf16 v[38:41], v[162:165], v[148:151], v[38:41]
	s_waitcnt lgkmcnt(5)
	v_mfma_f32_16x16x32_bf16 v[118:121], v[166:169], v[136:139], v[118:121]
	v_mfma_f32_16x16x32_bf16 v[94:97], v[166:169], v[140:143], v[94:97]
	v_add_u32_e32 v155, 0x1000, v157
	s_mov_b64 s[28:29], 0xb584080
	v_lshl_add_u64 v[162:163], v[208:209], 0, s[28:29]
	v_readfirstlane_b32 s28, v155
	s_mov_b32 m0, s28
	v_mfma_f32_16x16x32_bf16 v[62:65], v[166:169], v[144:147], v[62:65]
	global_load_lds_dwordx4 v[162:163], off
	v_mfma_f32_16x16x32_bf16 v[28:31], v[166:169], v[148:151], v[28:31]
	s_waitcnt lgkmcnt(4)
	v_mfma_f32_16x16x32_bf16 v[114:117], v[170:173], v[136:139], v[114:117]
	v_mfma_f32_16x16x32_bf16 v[86:89], v[170:173], v[140:143], v[86:89]
	v_mfma_f32_16x16x32_bf16 v[54:57], v[170:173], v[144:147], v[54:57]
	v_readfirstlane_b32 s28, v205
	s_mov_b32 m0, s28
	v_mfma_f32_16x16x32_bf16 v[20:23], v[170:173], v[148:151], v[20:23]
	global_load_lds_dwordx4 v[206:207], off
	s_waitcnt lgkmcnt(0)
	v_mfma_f32_16x16x32_bf16 v[106:109], v[158:161], v[136:139], v[106:109]
	v_mfma_f32_16x16x32_bf16 v[74:77], v[158:161], v[140:143], v[74:77]
	v_mfma_f32_16x16x32_bf16 v[42:45], v[158:161], v[144:147], v[42:45]
	v_mfma_f32_16x16x32_bf16 v[12:15], v[158:161], v[148:151], v[12:15]
	v_add_u32_e32 v155, 0x3000, v157
	s_mov_b64 s[28:29], 0x3558080
	v_lshl_add_u64 v[158:159], v[152:153], 0, s[28:29]
	v_readfirstlane_b32 s28, v155
	s_mov_b32 m0, s28
	v_mfma_f32_16x16x32_bf16 v[98:101], v[174:177], v[136:139], v[98:101]
	global_load_lds_dwordx4 v[158:159], off
	v_mfma_f32_16x16x32_bf16 v[66:69], v[174:177], v[140:143], v[66:69]
	v_mfma_f32_16x16x32_bf16 v[34:37], v[174:177], v[144:147], v[34:37]
	v_mfma_f32_16x16x32_bf16 v[8:11], v[174:177], v[148:151], v[8:11]
	v_mfma_f32_16x16x32_bf16 v[90:93], v[178:181], v[136:139], v[90:93]
	v_add_u32_e32 v155, 0x4000, v157
	s_mov_b64 s[28:29], 0x35b0080
	v_lshl_add_u64 v[158:159], v[152:153], 0, s[28:29]
	v_readfirstlane_b32 s28, v155
	s_mov_b32 m0, s28
	v_mfma_f32_16x16x32_bf16 v[58:61], v[178:181], v[140:143], v[58:61]
	global_load_lds_dwordx4 v[158:159], off
	v_mfma_f32_16x16x32_bf16 v[24:27], v[178:181], v[144:147], v[24:27]
	v_mfma_f32_16x16x32_bf16 v[4:7], v[178:181], v[148:151], v[4:7]
	v_mfma_f32_16x16x32_bf16 v[78:81], v[182:185], v[136:139], v[78:81]
	v_mfma_f32_16x16x32_bf16 v[46:49], v[182:185], v[140:143], v[46:49]
	v_add_u32_e32 v138, 0x5000, v157
	s_mov_b64 s[28:29], 0x3608080
	v_lshl_add_u64 v[136:137], v[152:153], 0, s[28:29]
	v_readfirstlane_b32 s28, v138
	s_mov_b32 m0, s28
	v_mfma_f32_16x16x32_bf16 v[16:19], v[182:185], v[144:147], v[16:19]
	global_load_lds_dwordx4 v[136:137], off
	v_mfma_f32_16x16x32_bf16 v[0:3], v[182:185], v[148:151], v[0:3]
	s_setprio 0
	s_add_i32 s28, s23, 1
	s_cmp_lg_u32 s23, 2
	s_cselect_b32 s23, s28, 0
	s_add_u32 s8, s8, 0x80
	s_addc_u32 s9, s9, 0
	s_cmpk_lg_i32 s8, 0x2b00
	s_cbranch_scc1 .LBB0_21
	s_waitcnt vmcnt(6)
	v_add_u32_e32 v32, 0, v134
	v_add_u32_e32 v152, 0, v135
	s_waitcnt lgkmcnt(0)
	s_barrier
; #define RAW_BARRIER() do { asm volatile("s_waitcnt lgkmcnt(0)" ::: "memory"); __builtin_amdgcn_s_barrier(); } while (0)
;     ...
;     asm volatile("s_waitcnt vmcnt(0)" ::: "memory");
;     RAW_BARRIER();
;     STEP_TILE(st, false, 0, 0);
;     RAW_BARRIER();
	ds_read_b128 v[130:133], v32 offset:49152
	ds_read_b128 v[136:139], v32 offset:50176
	ds_read_b128 v[140:143], v32 offset:51200
	ds_read_b128 v[144:147], v32 offset:52224
	ds_read_b128 v[148:151], v152 offset:57344
	ds_read_b128 v[158:161], v152 offset:58368
	ds_read_b128 v[162:165], v152 offset:59392
	ds_read_b128 v[166:169], v152 offset:60416
	s_setprio 1
	s_waitcnt lgkmcnt(0)
	v_mfma_f32_16x16x32_bf16 v[126:129], v[148:151], v[130:133], v[126:129]
	v_mfma_f32_16x16x32_bf16 v[110:113], v[148:151], v[136:139], v[110:113]
	v_mfma_f32_16x16x32_bf16 v[82:85], v[148:151], v[140:143], v[82:85]
	v_mfma_f32_16x16x32_bf16 v[50:53], v[148:151], v[144:147], v[50:53]
	v_mfma_f32_16x16x32_bf16 v[122:125], v[158:161], v[130:133], v[122:125]
	ds_read_b128 v[148:151], v152 offset:61440
	ds_read_b128 v[170:173], v152 offset:62464
	ds_read_b128 v[174:177], v152 offset:63488
	ds_read_b128 v[178:181], v152 offset:64512
	v_mfma_f32_16x16x32_bf16 v[102:105], v[158:161], v[136:139], v[102:105]
	v_mfma_f32_16x16x32_bf16 v[70:73], v[158:161], v[140:143], v[70:73]
	v_mfma_f32_16x16x32_bf16 v[38:41], v[158:161], v[144:147], v[38:41]
	v_mfma_f32_16x16x32_bf16 v[118:121], v[162:165], v[130:133], v[118:121]
	v_mfma_f32_16x16x32_bf16 v[158:161], v[162:165], v[136:139], v[94:97]
	v_mfma_f32_16x16x32_bf16 v[182:185], v[162:165], v[140:143], v[62:65]
	v_mfma_f32_16x16x32_bf16 v[162:165], v[162:165], v[144:147], v[28:31]
	v_mfma_f32_16x16x32_bf16 v[114:117], v[166:169], v[130:133], v[114:117]
	v_mfma_f32_16x16x32_bf16 v[206:209], v[166:169], v[136:139], v[86:89]
	v_mfma_f32_16x16x32_bf16 v[210:213], v[166:169], v[140:143], v[54:57]
	v_mfma_f32_16x16x32_bf16 v[166:169], v[166:169], v[144:147], v[20:23]
	s_waitcnt lgkmcnt(0)
	v_mfma_f32_16x16x32_bf16 v[106:109], v[148:151], v[130:133], v[106:109]
	v_mfma_f32_16x16x32_bf16 v[74:77], v[148:151], v[136:139], v[74:77]
	v_mfma_f32_16x16x32_bf16 v[42:45], v[148:151], v[140:143], v[42:45]
	v_mfma_f32_16x16x32_bf16 v[12:15], v[148:151], v[144:147], v[12:15]
	v_mfma_f32_16x16x32_bf16 v[98:101], v[170:173], v[130:133], v[98:101]
	v_mfma_f32_16x16x32_bf16 v[66:69], v[170:173], v[136:139], v[66:69]
	v_mfma_f32_16x16x32_bf16 v[34:37], v[170:173], v[140:143], v[34:37]
	v_mfma_f32_16x16x32_bf16 v[8:11], v[170:173], v[144:147], v[8:11]
	v_mfma_f32_16x16x32_bf16 v[148:151], v[174:177], v[130:133], v[90:93]
	v_mfma_f32_16x16x32_bf16 v[170:173], v[174:177], v[136:139], v[58:61]
	v_mfma_f32_16x16x32_bf16 v[214:217], v[174:177], v[140:143], v[24:27]
	v_mfma_f32_16x16x32_bf16 v[4:7], v[174:177], v[144:147], v[4:7]
	v_mfma_f32_16x16x32_bf16 v[130:133], v[178:181], v[130:133], v[78:81]
	v_mfma_f32_16x16x32_bf16 v[134:137], v[178:181], v[136:139], v[46:49]
	v_mfma_f32_16x16x32_bf16 v[138:141], v[178:181], v[140:143], v[16:19]
	v_mfma_f32_16x16x32_bf16 v[0:3], v[178:181], v[144:147], v[0:3]
	s_setprio 0
	s_waitcnt vmcnt(0)
	s_waitcnt lgkmcnt(0)
	s_barrier
	ds_read_b128 v[142:145], v32
	ds_read_b128 v[174:177], v32 offset:1024
	ds_read_b128 v[178:181], v32 offset:2048
	ds_read_b128 v[218:221], v32 offset:3072
	ds_read_b128 v[16:19], v152 offset:8192
	ds_read_b128 v[20:23], v152 offset:9216
	ds_read_b128 v[46:49], v152 offset:10240
	ds_read_b128 v[78:81], v152 offset:11264
	s_setprio 1
	s_waitcnt lgkmcnt(0)
	v_mfma_f32_16x16x32_bf16 v[126:129], v[16:19], v[142:145], v[126:129]
	v_mfma_f32_16x16x32_bf16 v[94:97], v[16:19], v[174:177], v[110:113]
	v_mfma_f32_16x16x32_bf16 v[62:65], v[16:19], v[178:181], v[82:85]
	v_mfma_f32_16x16x32_bf16 v[28:31], v[16:19], v[218:221], v[50:53]
	v_mfma_f32_16x16x32_bf16 v[122:125], v[20:23], v[142:145], v[122:125]
	ds_read_b128 v[110:113], v152 offset:12288
	ds_read_b128 v[222:225], v152 offset:13312
	ds_read_b128 v[226:229], v152 offset:14336
	ds_read_b128 v[230:233], v152 offset:15360
	v_mfma_f32_16x16x32_bf16 v[90:93], v[20:23], v[174:177], v[102:105]
	v_mfma_f32_16x16x32_bf16 v[58:61], v[20:23], v[178:181], v[70:73]
	v_mfma_f32_16x16x32_bf16 v[24:27], v[20:23], v[218:221], v[38:41]
	v_mfma_f32_16x16x32_bf16 v[118:121], v[46:49], v[142:145], v[118:121]
	v_mfma_f32_16x16x32_bf16 v[86:89], v[46:49], v[174:177], v[158:161]
	v_mfma_f32_16x16x32_bf16 v[54:57], v[46:49], v[178:181], v[182:185]
	v_mfma_f32_16x16x32_bf16 v[20:23], v[46:49], v[218:221], v[162:165]
	v_mfma_f32_16x16x32_bf16 v[114:117], v[78:81], v[142:145], v[114:117]
	v_mfma_f32_16x16x32_bf16 v[82:85], v[78:81], v[174:177], v[206:209]
	v_mfma_f32_16x16x32_bf16 v[50:53], v[78:81], v[178:181], v[210:213]
	v_mfma_f32_16x16x32_bf16 v[16:19], v[78:81], v[218:221], v[166:169]
	s_waitcnt lgkmcnt(0)
	v_mfma_f32_16x16x32_bf16 v[158:161], v[110:113], v[142:145], v[106:109]
	v_mfma_f32_16x16x32_bf16 v[78:81], v[110:113], v[174:177], v[74:77]
	v_mfma_f32_16x16x32_bf16 v[46:49], v[110:113], v[178:181], v[42:45]
	v_mfma_f32_16x16x32_bf16 v[12:15], v[110:113], v[218:221], v[12:15]
	v_mfma_f32_16x16x32_bf16 v[162:165], v[222:225], v[142:145], v[98:101]
	v_mfma_f32_16x16x32_bf16 v[74:77], v[222:225], v[174:177], v[66:69]
	v_mfma_f32_16x16x32_bf16 v[42:45], v[222:225], v[178:181], v[34:37]
	v_mfma_f32_16x16x32_bf16 v[8:11], v[222:225], v[218:221], v[8:11]
	v_mfma_f32_16x16x32_bf16 v[102:105], v[226:229], v[142:145], v[148:151]
	v_mfma_f32_16x16x32_bf16 v[70:73], v[226:229], v[174:177], v[170:173]
	v_mfma_f32_16x16x32_bf16 v[38:41], v[226:229], v[178:181], v[214:217]
	v_mfma_f32_16x16x32_bf16 v[4:7], v[226:229], v[218:221], v[4:7]
	v_mfma_f32_16x16x32_bf16 v[98:101], v[230:233], v[142:145], v[130:133]
	v_mfma_f32_16x16x32_bf16 v[66:69], v[230:233], v[174:177], v[134:137]
	v_mfma_f32_16x16x32_bf16 v[34:37], v[230:233], v[178:181], v[138:141]
	v_mfma_f32_16x16x32_bf16 v[0:3], v[230:233], v[218:221], v[0:3]
	s_setprio 0
	v_mov_b32_e32 v32, v186
	s_waitcnt lgkmcnt(0)
	s_barrier
;     __device__ __forceinline__ float* mod() const { return (float*)(ws + OFF_mod); }
; DEV void resid_big(const Params& p, int l, int mt, int nt, const bf16_t* A, int K, const bf16_t* W, int gate_off, bool res_from_input, char* smem) {
;     ...
;     for (int mi = 0; mi < 4; ++mi) {
;         const int row = rbase + mi * 16;
;         const float* gt = p.mod() + (size_t)(l * 9 + mod_index(row)) * 6144 + gate_off + c0;
;         const float* res = res_from_input ? xrow(p, l, row) : p.out + (size_t)row * 1024;
;         float* dst = p.out + (size_t)row * 1024;
; #pragma unroll
;         for (int ni = 0; ni < 8; ++ni) {
;             const f32x4 g4 = *(const f32x4*)(gt + ni * 16), r4 = *(const f32x4*)(res + c0 + ni * 16);
;             *(f32x4*)(dst + c0 + ni * 16) = r4 + g4 * acc[mi][ni];
;         }
;     }
	s_mov_b64 s[28:29], 0x5000
	v_ashrrev_i32_e32 v106, 1, v32
	v_and_b32_e32 v106, 0xffffffc0, v106
	v_lshl_add_u32 v112, s21, 7, v106
	v_and_or_b32 v108, v32, 15, v112
	v_lshlrev_b32_e32 v106, 1, v32
	v_lshrrev_b32_e32 v32, 2, v32
	v_and_b32_e32 v106, 0x80, v106
	v_and_b32_e32 v32, 12, v32
	v_or3_b32 v32, v106, v32, s22
	v_add_u32_e32 v106, 0xffffc000, v112
	v_lshrrev_b32_e32 v106, 4, v106
	s_movk_i32 s22, 0x3fff
	v_or_b32_e32 v106, 1, v106
	v_cmp_lt_i32_e32 vcc, s22, v108
	v_lshlrev_b32_e32 v32, 2, v32
	s_movk_i32 s21, 0x5000
	v_cndmask_b32_e32 v106, 0, v106, vcc
	v_add_u32_e32 v109, s16, v106
	v_mov_b64_e32 v[106:107], s[6:7]
	v_mad_i64_i32 v[110:111], s[8:9], v109, s33, v[106:107]
	v_lshl_add_u64 v[130:131], v[110:111], 0, v[32:33]
	v_ashrrev_i32_e32 v109, 31, v108
	v_lshl_add_u64 v[138:139], v[130:131], 0, s[28:29]
	v_lshlrev_b64 v[110:111], 12, v[108:109]
	v_add_co_u32_e32 v130, vcc, s21, v130
	v_lshl_add_u64 v[110:111], s[92:93], 0, v[110:111]
	s_nop 0
	v_addc_co_u32_e32 v131, vcc, 0, v131, vcc
	v_lshl_add_u64 v[110:111], v[110:111], 0, v[32:33]
	flat_load_dwordx4 v[206:209], v[130:131]
	flat_load_dwordx4 v[210:213], v[138:139] offset:64
	flat_load_dwordx4 v[214:217], v[138:139] offset:128
	flat_load_dwordx4 v[218:221], v[138:139] offset:192
	flat_load_dwordx4 v[222:225], v[138:139] offset:256
	flat_load_dwordx4 v[226:229], v[138:139] offset:320
	flat_load_dwordx4 v[230:233], v[138:139] offset:384
	flat_load_dwordx4 v[234:237], v[138:139] offset:448
	flat_load_dwordx4 v[238:241], v[110:111]
	flat_load_dwordx4 v[242:245], v[110:111] offset:64
	flat_load_dwordx4 v[246:249], v[110:111] offset:128
	flat_load_dwordx4 v[166:169], v[110:111] offset:192
	flat_load_dwordx4 v[170:173], v[110:111] offset:256
	flat_load_dwordx4 v[174:177], v[110:111] offset:320
	flat_load_dwordx4 v[178:181], v[110:111] offset:384
	flat_load_dwordx4 v[182:185], v[110:111] offset:448
	s_waitcnt vmcnt(0) lgkmcnt(0)
	v_pk_fma_f32 v[238:239], v[126:127], v[206:207], v[238:239]
	v_pk_fma_f32 v[240:241], v[128:129], v[208:209], v[240:241]
	v_pk_fma_f32 v[242:243], v[122:123], v[210:211], v[242:243]
	v_pk_fma_f32 v[244:245], v[124:125], v[212:213], v[244:245]
	v_pk_fma_f32 v[246:247], v[118:119], v[214:215], v[246:247]
	v_pk_fma_f32 v[248:249], v[120:121], v[216:217], v[248:249]
	v_pk_fma_f32 v[166:167], v[114:115], v[218:219], v[166:167]
	v_pk_fma_f32 v[168:169], v[116:117], v[220:221], v[168:169]
	v_pk_fma_f32 v[170:171], v[158:159], v[222:223], v[170:171]
	v_pk_fma_f32 v[172:173], v[160:161], v[224:225], v[172:173]
	v_pk_fma_f32 v[174:175], v[162:163], v[226:227], v[174:175]
	v_pk_fma_f32 v[176:177], v[164:165], v[228:229], v[176:177]
	v_pk_fma_f32 v[178:179], v[102:103], v[230:231], v[178:179]
	v_pk_fma_f32 v[180:181], v[104:105], v[232:233], v[180:181]
	v_pk_fma_f32 v[182:183], v[98:99], v[234:235], v[182:183]
	v_pk_fma_f32 v[184:185], v[100:101], v[236:237], v[184:185]
	flat_store_dwordx4 v[110:111], v[238:241]
	flat_store_dwordx4 v[110:111], v[242:245] offset:64
	flat_store_dwordx4 v[110:111], v[246:249] offset:128
	flat_store_dwordx4 v[110:111], v[166:169] offset:192
	flat_store_dwordx4 v[110:111], v[170:173] offset:256
	flat_store_dwordx4 v[110:111], v[174:177] offset:320
	flat_store_dwordx4 v[110:111], v[178:181] offset:384
	flat_store_dwordx4 v[110:111], v[182:185] offset:448
	s_nop 1
	s_add_i32 s17, s17, s18
	s_nop 1
	v_add_u32_e32 v98, 0xffffc010, v112
	v_or_b32_e32 v100, 16, v108
	v_lshrrev_b32_e32 v98, 4, v98
	v_add_u32_e32 v98, 1, v98
	v_cmp_lt_i32_e32 vcc, s22, v100
	v_ashrrev_i32_e32 v101, 31, v100
	v_lshlrev_b64 v[100:101], 12, v[100:101]
	v_cndmask_b32_e32 v98, 0, v98, vcc
	v_add_u32_e32 v98, s16, v98
	v_mad_i64_i32 v[98:99], s[8:9], v98, s33, v[106:107]
	v_lshl_add_u64 v[102:103], v[98:99], 0, v[32:33]
	v_lshl_add_u64 v[98:99], v[102:103], 0, s[28:29]
	v_add_co_u32_e32 v102, vcc, s21, v102
	v_lshl_add_u64 v[100:101], s[92:93], 0, v[100:101]
	s_nop 0
	v_addc_co_u32_e32 v103, vcc, 0, v103, vcc
	v_lshl_add_u64 v[100:101], v[100:101], 0, v[32:33]
	flat_load_dwordx4 v[206:209], v[102:103]
	flat_load_dwordx4 v[210:213], v[98:99] offset:64
	flat_load_dwordx4 v[214:217], v[98:99] offset:128
	flat_load_dwordx4 v[218:221], v[98:99] offset:192
	flat_load_dwordx4 v[222:225], v[98:99] offset:256
	flat_load_dwordx4 v[226:229], v[98:99] offset:320
	flat_load_dwordx4 v[230:233], v[98:99] offset:384
	flat_load_dwordx4 v[234:237], v[98:99] offset:448
	flat_load_dwordx4 v[238:241], v[100:101]
	flat_load_dwordx4 v[242:245], v[100:101] offset:64
	flat_load_dwordx4 v[246:249], v[100:101] offset:128
	flat_load_dwordx4 v[166:169], v[100:101] offset:192
	flat_load_dwordx4 v[170:173], v[100:101] offset:256
	flat_load_dwordx4 v[174:177], v[100:101] offset:320
	flat_load_dwordx4 v[178:181], v[100:101] offset:384
	flat_load_dwordx4 v[182:185], v[100:101] offset:448
	s_waitcnt vmcnt(0) lgkmcnt(0)
;     __device__ __forceinline__ float* mod() const { return (float*)(ws + OFF_mod); }
; DEV void resid_big(const Params& p, int l, int mt, int nt, const bf16_t* A, int K, const bf16_t* W, int gate_off, bool res_from_input, char* smem) {
;     ...
;     for (int mi = 0; mi < 4; ++mi) {
;         const int row = rbase + mi * 16;
;         const float* gt = p.mod() + (size_t)(l * 9 + mod_index(row)) * 6144 + gate_off + c0;
;         const float* res = res_from_input ? xrow(p, l, row) : p.out + (size_t)row * 1024;
;         float* dst = p.out + (size_t)row * 1024;
; #pragma unroll
;         for (int ni = 0; ni < 8; ++ni) {
;             const f32x4 g4 = *(const f32x4*)(gt + ni * 16), r4 = *(const f32x4*)(res + c0 + ni * 16);
;             *(f32x4*)(dst + c0 + ni * 16) = r4 + g4 * acc[mi][ni];
;         }
;     }
	v_pk_fma_f32 v[238:239], v[94:95], v[206:207], v[238:239]
	v_pk_fma_f32 v[240:241], v[96:97], v[208:209], v[240:241]
	v_pk_fma_f32 v[242:243], v[90:91], v[210:211], v[242:243]
	v_pk_fma_f32 v[244:245], v[92:93], v[212:213], v[244:245]
	v_pk_fma_f32 v[246:247], v[86:87], v[214:215], v[246:247]
	v_pk_fma_f32 v[248:249], v[88:89], v[216:217], v[248:249]
	v_pk_fma_f32 v[166:167], v[82:83], v[218:219], v[166:167]
	v_pk_fma_f32 v[168:169], v[84:85], v[220:221], v[168:169]
	v_pk_fma_f32 v[170:171], v[78:79], v[222:223], v[170:171]
	v_pk_fma_f32 v[172:173], v[80:81], v[224:225], v[172:173]
	v_pk_fma_f32 v[174:175], v[74:75], v[226:227], v[174:175]
	v_pk_fma_f32 v[176:177], v[76:77], v[228:229], v[176:177]
	v_pk_fma_f32 v[178:179], v[70:71], v[230:231], v[178:179]
	v_pk_fma_f32 v[180:181], v[72:73], v[232:233], v[180:181]
	v_pk_fma_f32 v[182:183], v[66:67], v[234:235], v[182:183]
	v_pk_fma_f32 v[184:185], v[68:69], v[236:237], v[184:185]
	flat_store_dwordx4 v[100:101], v[238:241]
	flat_store_dwordx4 v[100:101], v[242:245] offset:64
	flat_store_dwordx4 v[100:101], v[246:249] offset:128
	flat_store_dwordx4 v[100:101], v[166:169] offset:192
	flat_store_dwordx4 v[100:101], v[170:173] offset:256
	flat_store_dwordx4 v[100:101], v[174:177] offset:320
	flat_store_dwordx4 v[100:101], v[178:181] offset:384
	flat_store_dwordx4 v[100:101], v[182:185] offset:448
	s_nop 1
	s_nop 1
	v_add_u32_e32 v66, 0xffffc020, v112
	v_or_b32_e32 v68, 32, v108
	v_lshrrev_b32_e32 v66, 4, v66
	v_or_b32_e32 v66, 1, v66
	v_cmp_lt_i32_e32 vcc, s22, v68
	v_ashrrev_i32_e32 v69, 31, v68
	v_lshlrev_b64 v[68:69], 12, v[68:69]
	v_cndmask_b32_e32 v66, 0, v66, vcc
	v_add_u32_e32 v66, s16, v66
	v_mad_i64_i32 v[66:67], s[8:9], v66, s33, v[106:107]
	v_lshl_add_u64 v[70:71], v[66:67], 0, v[32:33]
	v_lshl_add_u64 v[66:67], v[70:71], 0, s[28:29]
	v_add_co_u32_e32 v70, vcc, s21, v70
	v_lshl_add_u64 v[68:69], s[92:93], 0, v[68:69]
	s_nop 0
	v_addc_co_u32_e32 v71, vcc, 0, v71, vcc
	v_lshl_add_u64 v[68:69], v[68:69], 0, v[32:33]
	flat_load_dwordx4 v[206:209], v[70:71]
	flat_load_dwordx4 v[210:213], v[66:67] offset:64
	flat_load_dwordx4 v[214:217], v[66:67] offset:128
	flat_load_dwordx4 v[218:221], v[66:67] offset:192
	flat_load_dwordx4 v[222:225], v[66:67] offset:256
	flat_load_dwordx4 v[226:229], v[66:67] offset:320
	flat_load_dwordx4 v[230:233], v[66:67] offset:384
	flat_load_dwordx4 v[234:237], v[66:67] offset:448
	flat_load_dwordx4 v[238:241], v[68:69]
	flat_load_dwordx4 v[242:245], v[68:69] offset:64
	flat_load_dwordx4 v[246:249], v[68:69] offset:128
	flat_load_dwordx4 v[166:169], v[68:69] offset:192
	flat_load_dwordx4 v[170:173], v[68:69] offset:256
	flat_load_dwordx4 v[174:177], v[68:69] offset:320
	flat_load_dwordx4 v[178:181], v[68:69] offset:384
	flat_load_dwordx4 v[182:185], v[68:69] offset:448
	s_waitcnt vmcnt(0) lgkmcnt(0)
;     __device__ __forceinline__ bf16_t* Wf2() const { return (bf16_t*)(ws + OFF_Wf2); }
;     __device__ __forceinline__ float* mod() const { return (float*)(ws + OFF_mod); }
;     __device__ __forceinline__ bf16_t* Act() const { return (bf16_t*)(ws + OFF_Act); }
; DEV void resid_big(const Params& p, int l, int mt, int nt, const bf16_t* A, int K, const bf16_t* W, int gate_off, bool res_from_input, char* smem) {
;     ...
;     for (int mi = 0; mi < 4; ++mi) {
;         const int row = rbase + mi * 16;
;         const float* gt = p.mod() + (size_t)(l * 9 + mod_index(row)) * 6144 + gate_off + c0;
;         const float* res = res_from_input ? xrow(p, l, row) : p.out + (size_t)row * 1024;
;         float* dst = p.out + (size_t)row * 1024;
; #pragma unroll
;         for (int ni = 0; ni < 8; ++ni) {
;             const f32x4 g4 = *(const f32x4*)(gt + ni * 16), r4 = *(const f32x4*)(res + c0 + ni * 16);
;             *(f32x4*)(dst + c0 + ni * 16) = r4 + g4 * acc[mi][ni];
;         }
;     }
; __global__ void __launch_bounds__(256, 2) fwd_kernel(Params p) {
;     ...
;                 for (int tile = bid; tile < 128 * 4; tile += nb) { const int x = tile & 7, q = tile >> 3; resid_big(pq, l, (q >> 2) * 8 + x, q & 3, pq.Act(), DFF, pq.Wf2() + (size_t)l * 1024 * DFF, 5120, false, smem); }
	v_pk_fma_f32 v[238:239], v[62:63], v[206:207], v[238:239]
	v_pk_fma_f32 v[240:241], v[64:65], v[208:209], v[240:241]
	v_pk_fma_f32 v[242:243], v[58:59], v[210:211], v[242:243]
	v_pk_fma_f32 v[244:245], v[60:61], v[212:213], v[244:245]
	v_pk_fma_f32 v[246:247], v[54:55], v[214:215], v[246:247]
	v_pk_fma_f32 v[248:249], v[56:57], v[216:217], v[248:249]
	v_pk_fma_f32 v[166:167], v[50:51], v[218:219], v[166:167]
	v_pk_fma_f32 v[168:169], v[52:53], v[220:221], v[168:169]
	v_pk_fma_f32 v[170:171], v[46:47], v[222:223], v[170:171]
	v_pk_fma_f32 v[172:173], v[48:49], v[224:225], v[172:173]
	v_pk_fma_f32 v[174:175], v[42:43], v[226:227], v[174:175]
	v_pk_fma_f32 v[176:177], v[44:45], v[228:229], v[176:177]
	v_pk_fma_f32 v[178:179], v[38:39], v[230:231], v[178:179]
	v_pk_fma_f32 v[180:181], v[40:41], v[232:233], v[180:181]
	v_pk_fma_f32 v[182:183], v[34:35], v[234:235], v[182:183]
	v_pk_fma_f32 v[184:185], v[36:37], v[236:237], v[184:185]
	flat_store_dwordx4 v[68:69], v[238:241]
	flat_store_dwordx4 v[68:69], v[242:245] offset:64
	flat_store_dwordx4 v[68:69], v[246:249] offset:128
	flat_store_dwordx4 v[68:69], v[166:169] offset:192
	flat_store_dwordx4 v[68:69], v[170:173] offset:256
	flat_store_dwordx4 v[68:69], v[174:177] offset:320
	flat_store_dwordx4 v[68:69], v[178:181] offset:384
	flat_store_dwordx4 v[68:69], v[182:185] offset:448
	s_nop 1
	v_add_u32_e32 v40, 0xffffc030, v112
	s_nop 0
	v_or_b32_e32 v34, 48, v108
	v_ashrrev_i32_e32 v35, 31, v34
	v_lshlrev_b64 v[36:37], 12, v[34:35]
	v_lshrrev_b32_e32 v35, 4, v40
	v_add_u32_e32 v35, 1, v35
	v_cmp_lt_i32_e32 vcc, s22, v34
	v_lshl_add_u64 v[38:39], s[92:93], 0, v[36:37]
	s_nop 0
	v_cndmask_b32_e32 v34, 0, v35, vcc
	v_add_u32_e32 v34, s16, v34
	v_mad_i64_i32 v[34:35], s[8:9], v34, s33, v[106:107]
	v_lshl_add_u64 v[40:41], v[34:35], 0, v[32:33]
	v_lshl_add_u64 v[34:35], v[38:39], 0, v[32:33]
	v_add_co_u32_e32 v38, vcc, s21, v40
	v_lshl_add_u64 v[36:37], v[40:41], 0, s[28:29]
	s_nop 0
	v_addc_co_u32_e32 v39, vcc, 0, v41, vcc
	flat_load_dwordx4 v[206:209], v[38:39]
	flat_load_dwordx4 v[210:213], v[36:37] offset:64
	flat_load_dwordx4 v[214:217], v[36:37] offset:128
	flat_load_dwordx4 v[218:221], v[36:37] offset:192
	flat_load_dwordx4 v[222:225], v[36:37] offset:256
	flat_load_dwordx4 v[226:229], v[36:37] offset:320
	flat_load_dwordx4 v[230:233], v[36:37] offset:384
	flat_load_dwordx4 v[234:237], v[36:37] offset:448
	flat_load_dwordx4 v[238:241], v[34:35]
	flat_load_dwordx4 v[242:245], v[34:35] offset:64
	flat_load_dwordx4 v[246:249], v[34:35] offset:128
	flat_load_dwordx4 v[166:169], v[34:35] offset:192
	flat_load_dwordx4 v[170:173], v[34:35] offset:256
	flat_load_dwordx4 v[174:177], v[34:35] offset:320
	flat_load_dwordx4 v[178:181], v[34:35] offset:384
	flat_load_dwordx4 v[182:185], v[34:35] offset:448
	s_waitcnt vmcnt(0) lgkmcnt(0)
	v_pk_fma_f32 v[238:239], v[28:29], v[206:207], v[238:239]
	v_pk_fma_f32 v[240:241], v[30:31], v[208:209], v[240:241]
	v_pk_fma_f32 v[242:243], v[24:25], v[210:211], v[242:243]
	v_pk_fma_f32 v[244:245], v[26:27], v[212:213], v[244:245]
	v_pk_fma_f32 v[246:247], v[20:21], v[214:215], v[246:247]
	v_pk_fma_f32 v[248:249], v[22:23], v[216:217], v[248:249]
	v_pk_fma_f32 v[166:167], v[16:17], v[218:219], v[166:167]
	v_pk_fma_f32 v[168:169], v[18:19], v[220:221], v[168:169]
	v_pk_fma_f32 v[170:171], v[12:13], v[222:223], v[170:171]
	v_pk_fma_f32 v[172:173], v[14:15], v[224:225], v[172:173]
	v_pk_fma_f32 v[174:175], v[8:9], v[226:227], v[174:175]
	v_pk_fma_f32 v[176:177], v[10:11], v[228:229], v[176:177]
	v_pk_fma_f32 v[178:179], v[4:5], v[230:231], v[178:179]
	v_pk_fma_f32 v[180:181], v[6:7], v[232:233], v[180:181]
	v_pk_fma_f32 v[182:183], v[0:1], v[234:235], v[182:183]
	v_pk_fma_f32 v[184:185], v[2:3], v[236:237], v[184:185]
	flat_store_dwordx4 v[34:35], v[238:241]
	flat_store_dwordx4 v[34:35], v[242:245] offset:64
	flat_store_dwordx4 v[34:35], v[246:249] offset:128
	flat_store_dwordx4 v[34:35], v[166:169] offset:192
	flat_store_dwordx4 v[34:35], v[170:173] offset:256
	flat_store_dwordx4 v[34:35], v[174:177] offset:320
	flat_store_dwordx4 v[34:35], v[178:181] offset:384
	flat_store_dwordx4 v[34:35], v[182:185] offset:448
	s_nop 1
	v_readlane_b32 s8, v254, 4
	s_add_i32 s20, s20, s8
	s_add_i32 s19, s19, s8
	s_cmpk_gt_i32 s20, 0x1ff
	v_readlane_b32 s9, v254, 5
	s_cbranch_scc0 .LBB0_20

; #define RAW_BARRIER() do { asm volatile("s_waitcnt lgkmcnt(0)" ::: "memory"); __builtin_amdgcn_s_barrier(); } while (0)
; #define GLDS_TILE(kt, st) do { _Pragma("unroll") for (int _i = 0; _i < NP; ++_i) GLDS_PIECE(_i, kt, st); } while (0)
;     ...
;     constexpr int NH = NI >= 4 ? NI / 2 : NI;
;     constexpr int NP = 2 + NB, IVL = (4 * NI) / NP;
;     RAW_BARRIER();
;     GLDS_TILE(0, 0);
;     GLDS_TILE(1, 1);
;     int st = 0;
;     for (int kt = 0; kt < nk - 1; ++kt) {
;         if (NI == 8) asm volatile("s_waitcnt vmcnt(6)" ::: "memory"); else if (NI == 4) asm volatile("s_waitcnt vmcnt(4)" ::: "memory"); else asm volatile("s_waitcnt vmcnt(3)" ::: "memory");
;         RAW_BARRIER();
;         const int s2 = st >= 1 ? st - 1 : 2;
;         const bool ld = kt + 2 < nk;
;         STEP_TILE(st, ld, kt + 2, s2);
;         st = st == 2 ? 0 : st + 1;
;     }
;     asm volatile("s_waitcnt vmcnt(0)" ::: "memory");
;     RAW_BARRIER();
;     STEP_TILE(st, false, 0, 0);
;     RAW_BARRIER();
;     ...
; }
.LBB0_26:
	s_mul_i32 s22, s21, 0x3000
	s_add_i32 s23, s22, 0
	s_waitcnt vmcnt(3)
	v_add_u32_e32 v32, s23, v39
	s_waitcnt lgkmcnt(0)
	s_barrier
	ds_read_b128 v[42:45], v32
	ds_read_b128 v[46:49], v32 offset:1024
	ds_read_b128 v[50:53], v32 offset:2048
	ds_read_b128 v[54:57], v32 offset:3072
	v_add_u32_e32 v32, s23, v40
	ds_read_b128 v[58:61], v32 offset:8192
	s_waitcnt vmcnt(0)
	ds_read_b128 v[62:65], v32 offset:9216
	s_addk_i32 s22, 0xd000
	s_cmp_gt_i32 s21, 0
	s_setprio 1
	s_waitcnt lgkmcnt(0)
	v_mfma_f32_16x16x32_bf16 v[28:31], v[58:61], v[42:45], v[28:31]
	s_cselect_b32 s22, s22, 0x6000
	v_add_u32_e32 v32, s22, v38
	v_lshl_add_u64 v[66:67], v[36:37], 0, s[10:11]
	v_mfma_f32_16x16x32_bf16 v[24:27], v[58:61], v[46:49], v[24:27]
	v_lshl_add_u64 v[70:71], v[34:35], 0, s[10:11]
	s_mov_b64 s[22:23], 0x10d2c080
	v_lshl_add_u64 v[68:69], v[66:67], 0, s[28:29]
	v_add_u32_e32 v41, 0x2000, v32
	v_lshl_add_u64 v[72:73], v[70:71], 0, s[22:23]
	v_readfirstlane_b32 s22, v32
	s_mov_b32 m0, s22
	v_mfma_f32_16x16x32_bf16 v[16:19], v[58:61], v[50:53], v[16:19]
	global_load_lds_dwordx4 v[72:73], off
	v_mfma_f32_16x16x32_bf16 v[8:11], v[58:61], v[54:57], v[8:11]
	s_mov_b64 s[22:23], 0x10d84080
	v_add_u32_e32 v32, 0x1000, v32
	v_lshl_add_u64 v[58:59], v[70:71], 0, s[22:23]
	v_readfirstlane_b32 s22, v32
	s_mov_b32 m0, s22
	v_mfma_f32_16x16x32_bf16 v[20:23], v[62:65], v[42:45], v[20:23]
	global_load_lds_dwordx4 v[58:59], off
	v_mfma_f32_16x16x32_bf16 v[12:15], v[62:65], v[46:49], v[12:15]
	v_readfirstlane_b32 s22, v41
	s_mov_b32 m0, s22
	v_mfma_f32_16x16x32_bf16 v[4:7], v[62:65], v[50:53], v[4:7]
	global_load_lds_dwordx4 v[68:69], off
	v_mfma_f32_16x16x32_bf16 v[0:3], v[62:65], v[54:57], v[0:3]
	s_setprio 0
	s_add_i32 s22, s21, 1
	s_cmp_lg_u32 s21, 2
	s_cselect_b32 s21, s22, 0
	s_mul_i32 s22, s21, 0x3000
	s_add_i32 s23, s22, 0
	s_waitcnt vmcnt(3)
	v_add_u32_e32 v32, s23, v39
	s_waitcnt lgkmcnt(0)
	s_barrier
	ds_read_b128 v[42:45], v32
	ds_read_b128 v[46:49], v32 offset:1024
	ds_read_b128 v[50:53], v32 offset:2048
	ds_read_b128 v[54:57], v32 offset:3072
	v_add_u32_e32 v32, s23, v40
	ds_read_b128 v[58:61], v32 offset:8192
	ds_read_b128 v[62:65], v32 offset:9216
	s_addk_i32 s22, 0xd000
	s_cmp_gt_i32 s21, 0
	s_setprio 1
	s_waitcnt lgkmcnt(0)
	v_mfma_f32_16x16x32_bf16 v[28:31], v[58:61], v[42:45], v[28:31]
	s_cselect_b32 s22, s22, 0x6000
	v_add_u32_e32 v32, s22, v38
	s_mov_b64 s[22:23], 0x3500100
	v_mfma_f32_16x16x32_bf16 v[24:27], v[58:61], v[46:49], v[24:27]
	v_lshl_add_u64 v[66:67], v[66:67], 0, s[22:23]
	s_mov_b64 s[22:23], 0x10d2c100
	v_add_u32_e32 v41, 0x2000, v32
	v_lshl_add_u64 v[68:69], v[70:71], 0, s[22:23]
	v_readfirstlane_b32 s22, v32
	s_mov_b32 m0, s22
	v_mfma_f32_16x16x32_bf16 v[16:19], v[58:61], v[50:53], v[16:19]
	global_load_lds_dwordx4 v[68:69], off
	v_mfma_f32_16x16x32_bf16 v[8:11], v[58:61], v[54:57], v[8:11]
	s_mov_b64 s[22:23], 0x10d84100
	v_add_u32_e32 v32, 0x1000, v32
	v_lshl_add_u64 v[58:59], v[70:71], 0, s[22:23]
	v_readfirstlane_b32 s22, v32
	s_mov_b32 m0, s22
	v_mfma_f32_16x16x32_bf16 v[20:23], v[62:65], v[42:45], v[20:23]
	global_load_lds_dwordx4 v[58:59], off
	v_mfma_f32_16x16x32_bf16 v[12:15], v[62:65], v[46:49], v[12:15]
	v_readfirstlane_b32 s22, v41
	s_mov_b32 m0, s22
	v_mfma_f32_16x16x32_bf16 v[4:7], v[62:65], v[50:53], v[4:7]
	global_load_lds_dwordx4 v[66:67], off
	v_mfma_f32_16x16x32_bf16 v[0:3], v[62:65], v[54:57], v[0:3]
	s_setprio 0
	s_add_i32 s22, s21, 1
	s_cmp_lg_u32 s21, 2
	s_cselect_b32 s21, s22, 0
	s_add_u32 s10, s10, 0x100
	s_addc_u32 s11, s11, 0
	s_cmpk_lg_i32 s10, 0xa00
	s_cbranch_scc1 .LBB0_26
	s_waitcnt vmcnt(3)
	v_add_u32_e32 v32, 0, v39
	s_waitcnt lgkmcnt(0)
	s_barrier
	ds_read_b128 v[34:37], v32 offset:24576
	ds_read_b128 v[42:45], v32 offset:25600
	ds_read_b128 v[46:49], v32 offset:26624
	ds_read_b128 v[50:53], v32 offset:27648
	v_add_u32_e32 v58, 0, v40
	ds_read_b128 v[38:41], v58 offset:32768
	ds_read_b128 v[54:57], v58 offset:33792
	s_setprio 1
	s_waitcnt lgkmcnt(0)
	v_mfma_f32_16x16x32_bf16 v[28:31], v[38:41], v[34:37], v[28:31]
	v_mfma_f32_16x16x32_bf16 v[24:27], v[38:41], v[42:45], v[24:27]
	v_mfma_f32_16x16x32_bf16 v[16:19], v[38:41], v[46:49], v[16:19]
	v_mfma_f32_16x16x32_bf16 v[8:11], v[38:41], v[50:53], v[8:11]
	v_mfma_f32_16x16x32_bf16 v[20:23], v[54:57], v[34:37], v[20:23]
	v_mfma_f32_16x16x32_bf16 v[34:37], v[54:57], v[42:45], v[12:15]
	v_mfma_f32_16x16x32_bf16 v[38:41], v[54:57], v[46:49], v[4:7]
	v_mfma_f32_16x16x32_bf16 v[0:3], v[54:57], v[50:53], v[0:3]
	s_setprio 0
	s_waitcnt vmcnt(0)
	s_waitcnt lgkmcnt(0)
	s_barrier
	ds_read_b128 v[42:45], v32
	ds_read_b128 v[46:49], v32 offset:1024
	ds_read_b128 v[50:53], v32 offset:2048
	ds_read_b128 v[54:57], v32 offset:3072
	ds_read_b128 v[4:7], v58 offset:8192
	ds_read_b128 v[58:61], v58 offset:9216
	s_setprio 1
	s_waitcnt lgkmcnt(0)
	v_mfma_f32_16x16x32_bf16 v[28:31], v[4:7], v[42:45], v[28:31]
	v_mfma_f32_16x16x32_bf16 v[24:27], v[4:7], v[46:49], v[24:27]
	v_mfma_f32_16x16x32_bf16 v[12:15], v[4:7], v[50:53], v[16:19]
	v_mfma_f32_16x16x32_bf16 v[4:7], v[4:7], v[54:57], v[8:11]
	v_mfma_f32_16x16x32_bf16 v[42:45], v[58:61], v[42:45], v[20:23]
	v_mfma_f32_16x16x32_bf16 v[34:37], v[58:61], v[46:49], v[34:37]
	v_mfma_f32_16x16x32_bf16 v[8:11], v[58:61], v[50:53], v[38:41]
	v_mfma_f32_16x16x32_bf16 v[0:3], v[58:61], v[54:57], v[0:3]
	s_setprio 0
	v_mov_b32_e32 v17, v186
	s_waitcnt lgkmcnt(0)
	s_barrier
;     __device__ __forceinline__ float* mod() const { return (float*)(ws + OFF_mod); }
; DEV int tid_opaque() { int t = threadIdx.x; asm volatile("" : "+v"(t)); return t; }
; DEV void resid_small(const Params& p, int l, int unit, const bf16_t* A, int K, const bf16_t* W, int gate_off, char* smem) {
;     ...
;     const int t = tid_opaque(), lane = t & 63, wid = t >> 6, wm = wid >> 1, wn = wid & 1, fr = lane & 15, fq = lane >> 4;
;     const int rbase = (MT - 1) * 128 + wm * 64 + fr, c0 = nt * 64 + wn * 32 + fq * 4;
; #pragma unroll
;     for (int mi = 0; mi < 4; ++mi) {
;         const int row = rbase + mi * 16;
;         const float* gt = p.mod() + (size_t)(l * 9 + mod_index(row)) * 6144 + gate_off + c0;
;         float* dst = (float*)(p.ws + OFF_part) + ((size_t)kq * 128 + (row - SEQ)) * 1024 + c0;
; #pragma unroll
;         for (int ni = 0; ni < 2; ++ni) {
;             const f32x4 g4 = *(const f32x4*)(gt + ni * 16);
;             *(f32x4*)(dst + ni * 16) = g4 * acc[mi][ni];
;         }
;     }
; }
	s_lshl_b32 s10, s20, 6
	v_ashrrev_i32_e32 v16, 1, v17
	v_and_b32_e32 v20, 0xffffffc0, v16
	v_and_or_b32 v16, v17, 15, v20
	v_lshrrev_b32_e32 v18, 1, v17
	v_lshrrev_b32_e32 v17, 2, v17
	v_and_b32_e32 v18, 32, v18
	v_and_b32_e32 v17, 12, v17
	v_add_u32_e32 v21, 0x4000, v16
	v_or3_b32 v18, v18, s10, v17
	v_lshrrev_b32_e32 v17, 4, v20
	s_movk_i32 s20, 0x3fff
	v_or_b32_e32 v17, 1, v17
	v_cmp_lt_i32_e32 vcc, s20, v21
	v_ashrrev_i32_e32 v19, 31, v18
	v_readlane_b32 s22, v252, 27
	v_cndmask_b32_e32 v17, 0, v17, vcc
	v_add_u32_e32 v17, s16, v17
	v_mov_b64_e32 v[20:21], s[6:7]
	v_readlane_b32 s23, v252, 28
	s_lshl_b32 s22, s19, 7
	v_mad_i64_i32 v[22:23], s[10:11], v17, s33, v[20:21]
	v_lshlrev_b64 v[18:19], 2, v[18:19]
	v_ashrrev_i32_e32 v17, 31, v16
	v_lshl_add_u64 v[22:23], v[22:23], 0, v[18:19]
	s_mov_b64 s[28:29], 0x5000
	v_lshl_add_u64 v[38:39], v[16:17], 0, s[22:23]
	s_movk_i32 s19, 0x5000
	v_lshl_add_u64 v[46:47], v[22:23], 0, s[28:29]
	v_lshlrev_b64 v[38:39], 12, v[38:39]
	v_add_co_u32_e32 v22, vcc, s19, v22
	v_lshl_add_u64 v[38:39], s[8:9], 0, v[38:39]
	s_nop 0
	v_addc_co_u32_e32 v23, vcc, 0, v23, vcc
	v_lshl_add_u64 v[48:49], v[38:39], 0, v[18:19]
	flat_load_dwordx4 v[38:41], v[22:23]
	v_or_b32_e32 v22, 16, v16
	v_add_u32_e32 v17, 0x4010, v16
	v_lshrrev_b32_e32 v23, 4, v22
	v_add_u32_e32 v23, 1, v23
	v_cmp_lt_i32_e32 vcc, s20, v17
	s_waitcnt vmcnt(0) lgkmcnt(0)
	v_pk_mul_f32 v[30:31], v[30:31], v[40:41]
	v_pk_mul_f32 v[28:29], v[28:29], v[38:39]
	flat_store_dwordx4 v[48:49], v[28:31]
	flat_load_dwordx4 v[28:31], v[46:47] offset:64
	v_cndmask_b32_e32 v17, 0, v23, vcc
	v_ashrrev_i32_e32 v23, 31, v22
	v_add_u32_e32 v17, s16, v17
	v_lshl_add_u64 v[22:23], v[22:23], 0, s[22:23]
	v_lshlrev_b64 v[22:23], 12, v[22:23]
	v_lshl_add_u64 v[22:23], s[8:9], 0, v[22:23]
	v_lshl_add_u64 v[40:41], v[22:23], 0, v[18:19]
	s_waitcnt vmcnt(0) lgkmcnt(0)
	v_pk_mul_f32 v[30:31], v[44:45], v[30:31]
	v_pk_mul_f32 v[28:29], v[42:43], v[28:29]
	flat_store_dwordx4 v[48:49], v[28:31] offset:64
	s_nop 1
	v_mad_i64_i32 v[28:29], s[10:11], v17, s33, v[20:21]
	v_lshl_add_u64 v[28:29], v[28:29], 0, v[18:19]
	v_add_co_u32_e32 v22, vcc, s19, v28
	v_lshl_add_u64 v[38:39], v[28:29], 0, s[28:29]
	s_nop 0
	v_addc_co_u32_e32 v23, vcc, 0, v29, vcc
	flat_load_dwordx4 v[28:31], v[22:23]
	v_add_u32_e32 v17, 0x4020, v16
	v_cmp_lt_i32_e32 vcc, s20, v17
	s_waitcnt vmcnt(0) lgkmcnt(0)
	v_pk_mul_f32 v[26:27], v[26:27], v[30:31]
	v_pk_mul_f32 v[24:25], v[24:25], v[28:29]
	flat_store_dwordx4 v[40:41], v[24:27]
	flat_load_dwordx4 v[22:25], v[38:39] offset:64
	s_waitcnt vmcnt(0) lgkmcnt(0)
	v_pk_mul_f32 v[22:23], v[34:35], v[22:23]
	v_pk_mul_f32 v[24:25], v[36:37], v[24:25]
	flat_store_dwordx4 v[40:41], v[22:25] offset:64
	s_nop 1
	v_or_b32_e32 v22, 32, v16
	v_lshrrev_b32_e32 v23, 4, v22
	v_or_b32_e32 v23, 1, v23
	v_cndmask_b32_e32 v17, 0, v23, vcc
	v_ashrrev_i32_e32 v23, 31, v22
	v_add_u32_e32 v17, s16, v17
	v_lshl_add_u64 v[22:23], v[22:23], 0, s[22:23]
	v_mad_i64_i32 v[24:25], s[10:11], v17, s33, v[20:21]
	v_lshlrev_b64 v[22:23], 12, v[22:23]
	v_lshl_add_u64 v[24:25], v[24:25], 0, v[18:19]
	v_lshl_add_u64 v[22:23], s[8:9], 0, v[22:23]
	v_lshl_add_u64 v[28:29], v[22:23], 0, v[18:19]
	v_add_co_u32_e32 v22, vcc, s19, v24
	v_lshl_add_u64 v[26:27], v[24:25], 0, s[28:29]
	s_nop 0
	v_addc_co_u32_e32 v23, vcc, 0, v25, vcc
	flat_load_dwordx4 v[22:25], v[22:23]
	s_waitcnt vmcnt(0) lgkmcnt(0)
	v_pk_mul_f32 v[14:15], v[14:15], v[24:25]
	v_pk_mul_f32 v[12:13], v[12:13], v[22:23]
	flat_store_dwordx4 v[28:29], v[12:15]
	flat_load_dwordx4 v[12:15], v[26:27] offset:64
	s_waitcnt vmcnt(0) lgkmcnt(0)
	v_pk_mul_f32 v[10:11], v[10:11], v[14:15]
	v_pk_mul_f32 v[8:9], v[8:9], v[12:13]
	flat_store_dwordx4 v[28:29], v[8:11] offset:64
	s_nop 1
	v_or_b32_e32 v8, 48, v16
	v_add_u32_e32 v9, 0x4030, v16
	v_lshrrev_b32_e32 v10, 4, v8
	v_add_u32_e32 v10, 1, v10
	v_cmp_lt_i32_e32 vcc, s20, v9
	s_nop 1
	v_cndmask_b32_e32 v9, 0, v10, vcc
	v_add_u32_e32 v9, s16, v9
	v_mad_i64_i32 v[10:11], s[10:11], v9, s33, v[20:21]
	v_ashrrev_i32_e32 v9, 31, v8
	v_lshl_add_u64 v[8:9], v[8:9], 0, s[22:23]
	v_lshlrev_b64 v[8:9], 12, v[8:9]
	v_lshl_add_u64 v[10:11], v[10:11], 0, v[18:19]
	v_lshl_add_u64 v[8:9], s[8:9], 0, v[8:9]
	v_lshl_add_u64 v[14:15], v[8:9], 0, v[18:19]
	v_add_co_u32_e32 v8, vcc, s19, v10
	v_lshl_add_u64 v[12:13], v[10:11], 0, s[28:29]
	s_nop 0
	v_addc_co_u32_e32 v9, vcc, 0, v11, vcc
	flat_load_dwordx4 v[8:11], v[8:9]
	s_mov_b32 s11, s23
	v_writelane_b32 v252, s10, 27
	s_waitcnt vmcnt(0) lgkmcnt(0)
	v_pk_mul_f32 v[6:7], v[6:7], v[10:11]
	v_pk_mul_f32 v[4:5], v[4:5], v[8:9]
	flat_store_dwordx4 v[14:15], v[4:7]
	flat_load_dwordx4 v[4:7], v[12:13] offset:64
	v_writelane_b32 v252, s11, 28
	v_readlane_b32 s10, v254, 4
	s_add_i32 s18, s18, s10
	s_add_i32 s17, s17, s10
	s_cmp_lt_i32 s18, 64
	v_readlane_b32 s11, v254, 5
	s_waitcnt vmcnt(0) lgkmcnt(0)
	v_pk_mul_f32 v[2:3], v[2:3], v[6:7]
	v_pk_mul_f32 v[0:1], v[0:1], v[4:5]
	flat_store_dwordx4 v[14:15], v[0:3] offset:64
	s_cbranch_scc1 .LBB0_25

; #define RAW_BARRIER() do { asm volatile("s_waitcnt lgkmcnt(0)" ::: "memory"); __builtin_amdgcn_s_barrier(); } while (0)
; #define GLDS_TILE(kt, st) do { _Pragma("unroll") for (int _i = 0; _i < NP; ++_i) GLDS_PIECE(_i, kt, st); } while (0)
;     ...
;     constexpr int NH = NI >= 4 ? NI / 2 : NI;
;     constexpr int NP = 2 + NB, IVL = (4 * NI) / NP;
;     RAW_BARRIER();
;     GLDS_TILE(0, 0);
;     GLDS_TILE(1, 1);
;     int st = 0;
;     for (int kt = 0; kt < nk - 1; ++kt) {
;         if (NI == 8) asm volatile("s_waitcnt vmcnt(6)" ::: "memory"); else if (NI == 4) asm volatile("s_waitcnt vmcnt(4)" ::: "memory"); else asm volatile("s_waitcnt vmcnt(3)" ::: "memory");
;         RAW_BARRIER();
;         const int s2 = st >= 1 ? st - 1 : 2;
;         const bool ld = kt + 2 < nk;
;         STEP_TILE(st, ld, kt + 2, s2);
;         st = st == 2 ? 0 : st + 1;
;     }
.LBB0_37:
	s_mul_i32 s18, s9, 0x6000
	s_add_i32 s19, s18, 0
	s_waitcnt vmcnt(6)
	v_add_u32_e32 v148, s19, v134
	v_add_u32_e32 v155, s19, v135
	s_waitcnt lgkmcnt(0)
	s_barrier
	ds_read_b128 v[158:161], v155 offset:8192
	ds_read_b128 v[136:139], v148
	ds_read_b128 v[140:143], v148 offset:1024
	ds_read_b128 v[144:147], v148 offset:2048
	ds_read_b128 v[148:151], v148 offset:3072
	ds_read_b128 v[162:165], v155 offset:9216
	ds_read_b128 v[166:169], v155 offset:10240
	ds_read_b128 v[170:173], v155 offset:11264
	s_addk_i32 s18, 0xa000
	s_cmp_gt_i32 s9, 0
	s_setprio 1
	s_waitcnt lgkmcnt(6)
	v_mfma_f32_16x16x32_bf16 v[126:129], v[158:161], v[136:139], v[126:129]
	s_cselect_b32 s18, s18, 0xc000
	v_add_u32_e32 v157, s18, v32
	v_lshl_add_u64 v[152:153], v[132:133], 0, s[10:11]
	s_waitcnt lgkmcnt(5)
	v_mfma_f32_16x16x32_bf16 v[110:113], v[158:161], v[140:143], v[110:113]
	s_mov_b64 s[18:19], 0x1f00080
	v_lshl_add_u64 v[208:209], v[130:131], 0, s[10:11]
	v_lshl_add_u64 v[206:207], v[152:153], 0, s[18:19]
	s_waitcnt lgkmcnt(4)
	v_mfma_f32_16x16x32_bf16 v[82:85], v[158:161], v[144:147], v[82:85]
	v_add_u32_e32 v205, 0x2000, v157
	s_waitcnt lgkmcnt(3)
	v_mfma_f32_16x16x32_bf16 v[50:53], v[158:161], v[148:151], v[50:53]
	v_lshl_add_u64 v[158:159], v[208:209], 0, s[20:21]
	s_waitcnt lgkmcnt(2)
	v_mfma_f32_16x16x32_bf16 v[122:125], v[162:165], v[136:139], v[122:125]
	v_readfirstlane_b32 s18, v157
	s_mov_b32 m0, s18
	v_mfma_f32_16x16x32_bf16 v[102:105], v[162:165], v[140:143], v[102:105]
	global_load_lds_dwordx4 v[158:159], off
	ds_read_b128 v[158:161], v155 offset:12288
	ds_read_b128 v[174:177], v155 offset:13312
	ds_read_b128 v[178:181], v155 offset:14336
	ds_read_b128 v[182:185], v155 offset:15360
	v_mfma_f32_16x16x32_bf16 v[70:73], v[162:165], v[144:147], v[70:73]
	v_mfma_f32_16x16x32_bf16 v[38:41], v[162:165], v[148:151], v[38:41]
	s_waitcnt lgkmcnt(5)
	v_mfma_f32_16x16x32_bf16 v[118:121], v[166:169], v[136:139], v[118:121]
	v_mfma_f32_16x16x32_bf16 v[94:97], v[166:169], v[140:143], v[94:97]
	v_add_u32_e32 v155, 0x1000, v157
	v_lshl_add_u64 v[162:163], v[208:209], 0, s[22:23]
	v_readfirstlane_b32 s18, v155
	s_mov_b32 m0, s18
	v_mfma_f32_16x16x32_bf16 v[62:65], v[166:169], v[144:147], v[62:65]
	global_load_lds_dwordx4 v[162:163], off
	v_mfma_f32_16x16x32_bf16 v[28:31], v[166:169], v[148:151], v[28:31]
	s_waitcnt lgkmcnt(4)
	v_mfma_f32_16x16x32_bf16 v[114:117], v[170:173], v[136:139], v[114:117]
	v_mfma_f32_16x16x32_bf16 v[86:89], v[170:173], v[140:143], v[86:89]
	v_mfma_f32_16x16x32_bf16 v[54:57], v[170:173], v[144:147], v[54:57]
	v_readfirstlane_b32 s18, v205
	s_mov_b32 m0, s18
	v_mfma_f32_16x16x32_bf16 v[20:23], v[170:173], v[148:151], v[20:23]
	global_load_lds_dwordx4 v[206:207], off
	s_waitcnt lgkmcnt(0)
	v_mfma_f32_16x16x32_bf16 v[106:109], v[158:161], v[136:139], v[106:109]
	v_mfma_f32_16x16x32_bf16 v[74:77], v[158:161], v[140:143], v[74:77]
	v_mfma_f32_16x16x32_bf16 v[42:45], v[158:161], v[144:147], v[42:45]
	v_mfma_f32_16x16x32_bf16 v[12:15], v[158:161], v[148:151], v[12:15]
	v_add_u32_e32 v155, 0x3000, v157
	s_mov_b64 s[18:19], 0x1f20080
	v_lshl_add_u64 v[158:159], v[152:153], 0, s[18:19]
	v_readfirstlane_b32 s18, v155
	s_mov_b32 m0, s18
	v_mfma_f32_16x16x32_bf16 v[98:101], v[174:177], v[136:139], v[98:101]
	global_load_lds_dwordx4 v[158:159], off
	v_mfma_f32_16x16x32_bf16 v[66:69], v[174:177], v[140:143], v[66:69]
	v_mfma_f32_16x16x32_bf16 v[34:37], v[174:177], v[144:147], v[34:37]
	v_mfma_f32_16x16x32_bf16 v[8:11], v[174:177], v[148:151], v[8:11]
	v_mfma_f32_16x16x32_bf16 v[90:93], v[178:181], v[136:139], v[90:93]
	v_add_u32_e32 v155, 0x4000, v157
	s_mov_b64 s[18:19], 0x1f40080
	v_lshl_add_u64 v[158:159], v[152:153], 0, s[18:19]
	v_readfirstlane_b32 s18, v155
	s_mov_b32 m0, s18
	v_mfma_f32_16x16x32_bf16 v[58:61], v[178:181], v[140:143], v[58:61]
	global_load_lds_dwordx4 v[158:159], off
	v_mfma_f32_16x16x32_bf16 v[24:27], v[178:181], v[144:147], v[24:27]
	v_mfma_f32_16x16x32_bf16 v[4:7], v[178:181], v[148:151], v[4:7]
	v_mfma_f32_16x16x32_bf16 v[78:81], v[182:185], v[136:139], v[78:81]
	v_mfma_f32_16x16x32_bf16 v[46:49], v[182:185], v[140:143], v[46:49]
	v_add_u32_e32 v138, 0x5000, v157
	s_mov_b64 s[18:19], 0x1f60080
	v_lshl_add_u64 v[136:137], v[152:153], 0, s[18:19]
	v_readfirstlane_b32 s18, v138
	s_mov_b32 m0, s18
	v_mfma_f32_16x16x32_bf16 v[16:19], v[182:185], v[144:147], v[16:19]
	global_load_lds_dwordx4 v[136:137], off
	v_mfma_f32_16x16x32_bf16 v[0:3], v[182:185], v[148:151], v[0:3]
	s_setprio 0
	s_add_i32 s18, s9, 1
	s_cmp_lg_u32 s9, 2
	s_cselect_b32 s9, s18, 0
	s_add_u32 s10, s10, 0x80
	s_addc_u32 s11, s11, 0
	s_cmpk_lg_i32 s10, 0xf00
	s_cbranch_scc1 .LBB0_37
	s_waitcnt vmcnt(6)
	v_add_u32_e32 v32, 0, v134
	v_add_u32_e32 v152, 0, v135
	s_waitcnt lgkmcnt(0)
	s_barrier
; #define RAW_BARRIER() do { asm volatile("s_waitcnt lgkmcnt(0)" ::: "memory"); __builtin_amdgcn_s_barrier(); } while (0)
;     ...
;     asm volatile("s_waitcnt vmcnt(0)" ::: "memory");
;     RAW_BARRIER();
;     STEP_TILE(st, false, 0, 0);
;     RAW_BARRIER();
;     ...
;                 for (int j = 0; j < 4; ++j) { const float a = acc[mi][h * 4 + nn][j]; o[j] = a * __builtin_amdgcn_rcpf(1.f + __expf(-a)) * acc[mi][h * 4 + 2 + nn][j]; }
	ds_read_b128 v[130:133], v32
	ds_read_b128 v[136:139], v32 offset:1024
	ds_read_b128 v[140:143], v32 offset:2048
	ds_read_b128 v[144:147], v32 offset:3072
	ds_read_b128 v[148:151], v152 offset:8192
	ds_read_b128 v[158:161], v152 offset:9216
	ds_read_b128 v[162:165], v152 offset:10240
	ds_read_b128 v[166:169], v152 offset:11264
	s_setprio 1
	s_waitcnt lgkmcnt(0)
	v_mfma_f32_16x16x32_bf16 v[126:129], v[148:151], v[130:133], v[126:129]
	v_mfma_f32_16x16x32_bf16 v[110:113], v[148:151], v[136:139], v[110:113]
	v_mfma_f32_16x16x32_bf16 v[82:85], v[148:151], v[140:143], v[82:85]
	v_mfma_f32_16x16x32_bf16 v[50:53], v[148:151], v[144:147], v[50:53]
	v_mfma_f32_16x16x32_bf16 v[122:125], v[158:161], v[130:133], v[122:125]
	ds_read_b128 v[148:151], v152 offset:12288
	ds_read_b128 v[170:173], v152 offset:13312
	ds_read_b128 v[174:177], v152 offset:14336
	ds_read_b128 v[178:181], v152 offset:15360
	v_mfma_f32_16x16x32_bf16 v[102:105], v[158:161], v[136:139], v[102:105]
	v_mfma_f32_16x16x32_bf16 v[70:73], v[158:161], v[140:143], v[70:73]
	v_mfma_f32_16x16x32_bf16 v[38:41], v[158:161], v[144:147], v[38:41]
	v_mfma_f32_16x16x32_bf16 v[118:121], v[162:165], v[130:133], v[118:121]
	v_mfma_f32_16x16x32_bf16 v[94:97], v[162:165], v[136:139], v[94:97]
	v_mfma_f32_16x16x32_bf16 v[62:65], v[162:165], v[140:143], v[62:65]
	v_mfma_f32_16x16x32_bf16 v[28:31], v[162:165], v[144:147], v[28:31]
	v_mfma_f32_16x16x32_bf16 v[158:161], v[166:169], v[130:133], v[114:117]
	v_mfma_f32_16x16x32_bf16 v[86:89], v[166:169], v[136:139], v[86:89]
	v_mfma_f32_16x16x32_bf16 v[54:57], v[166:169], v[140:143], v[54:57]
	v_mfma_f32_16x16x32_bf16 v[20:23], v[166:169], v[144:147], v[20:23]
	s_waitcnt lgkmcnt(0)
	v_mfma_f32_16x16x32_bf16 v[162:165], v[148:151], v[130:133], v[106:109]
	v_mfma_f32_16x16x32_bf16 v[166:169], v[148:151], v[136:139], v[74:77]
	v_mfma_f32_16x16x32_bf16 v[182:185], v[148:151], v[140:143], v[42:45]
	v_mfma_f32_16x16x32_bf16 v[12:15], v[148:151], v[144:147], v[12:15]
	v_mfma_f32_16x16x32_bf16 v[148:151], v[170:173], v[130:133], v[98:101]
	v_mfma_f32_16x16x32_bf16 v[206:209], v[170:173], v[136:139], v[66:69]
	v_mfma_f32_16x16x32_bf16 v[210:213], v[170:173], v[140:143], v[34:37]
	v_mfma_f32_16x16x32_bf16 v[170:173], v[170:173], v[144:147], v[8:11]
	v_mfma_f32_16x16x32_bf16 v[214:217], v[174:177], v[130:133], v[90:93]
	v_mfma_f32_16x16x32_bf16 v[218:221], v[174:177], v[136:139], v[58:61]
	v_mfma_f32_16x16x32_bf16 v[222:225], v[174:177], v[140:143], v[24:27]
	v_mfma_f32_16x16x32_bf16 v[4:7], v[174:177], v[144:147], v[4:7]
	v_mfma_f32_16x16x32_bf16 v[130:133], v[178:181], v[130:133], v[78:81]
	v_mfma_f32_16x16x32_bf16 v[134:137], v[178:181], v[136:139], v[46:49]
	v_mfma_f32_16x16x32_bf16 v[138:141], v[178:181], v[140:143], v[16:19]
	v_mfma_f32_16x16x32_bf16 v[142:145], v[178:181], v[144:147], v[0:3]
	s_setprio 0
	s_waitcnt vmcnt(0)
	s_waitcnt lgkmcnt(0)
	s_barrier
	ds_read_b128 v[174:177], v32 offset:24576
	ds_read_b128 v[178:181], v32 offset:25600
	ds_read_b128 v[226:229], v32 offset:26624
	ds_read_b128 v[230:233], v32 offset:27648
	ds_read_b128 v[0:3], v152 offset:32768
	ds_read_b128 v[8:11], v152 offset:33792
	ds_read_b128 v[16:19], v152 offset:34816
	ds_read_b128 v[24:27], v152 offset:35840
	s_setprio 1
	s_waitcnt lgkmcnt(0)
	v_mfma_f32_16x16x32_bf16 v[126:129], v[0:3], v[174:177], v[126:129]
	v_mfma_f32_16x16x32_bf16 v[106:109], v[0:3], v[178:181], v[110:113]
	v_mfma_f32_16x16x32_bf16 v[90:93], v[0:3], v[226:229], v[82:85]
	v_mfma_f32_16x16x32_bf16 v[74:77], v[0:3], v[230:233], v[50:53]
	v_mfma_f32_16x16x32_bf16 v[114:117], v[8:11], v[174:177], v[122:125]
	ds_read_b128 v[0:3], v152 offset:36864
	ds_read_b128 v[46:49], v152 offset:37888
	s_nop 0
	ds_read_b128 v[122:125], v152 offset:38912
	ds_read_b128 v[234:237], v152 offset:39936
	v_mfma_f32_16x16x32_bf16 v[98:101], v[8:11], v[178:181], v[102:105]
	v_mfma_f32_16x16x32_bf16 v[82:85], v[8:11], v[226:229], v[70:73]
	v_mfma_f32_16x16x32_bf16 v[66:69], v[8:11], v[230:233], v[38:41]
	v_mfma_f32_16x16x32_bf16 v[238:241], v[16:19], v[174:177], v[118:121]
	v_mfma_f32_16x16x32_bf16 v[110:113], v[16:19], v[178:181], v[94:97]
	v_mfma_f32_16x16x32_bf16 v[94:97], v[16:19], v[226:229], v[62:65]
	v_mfma_f32_16x16x32_bf16 v[78:81], v[16:19], v[230:233], v[28:31]
	v_mfma_f32_16x16x32_bf16 v[158:161], v[24:27], v[174:177], v[158:161]
	v_mfma_f32_16x16x32_bf16 v[102:105], v[24:27], v[178:181], v[86:89]
	v_mfma_f32_16x16x32_bf16 v[86:89], v[24:27], v[226:229], v[54:57]
	v_mfma_f32_16x16x32_bf16 v[70:73], v[24:27], v[230:233], v[20:23]
	s_waitcnt lgkmcnt(0)
	v_mfma_f32_16x16x32_bf16 v[58:61], v[0:3], v[174:177], v[162:165]
	v_mfma_f32_16x16x32_bf16 v[42:45], v[0:3], v[178:181], v[166:169]
	v_mfma_f32_16x16x32_bf16 v[24:27], v[0:3], v[226:229], v[182:185]
	v_mfma_f32_16x16x32_bf16 v[8:11], v[0:3], v[230:233], v[12:15]
	v_mfma_f32_16x16x32_bf16 v[50:53], v[46:49], v[174:177], v[148:151]
	v_mfma_f32_16x16x32_bf16 v[34:37], v[46:49], v[178:181], v[206:209]
	v_mfma_f32_16x16x32_bf16 v[16:19], v[46:49], v[226:229], v[210:213]
	v_mfma_f32_16x16x32_bf16 v[0:3], v[46:49], v[230:233], v[170:173]
	v_mfma_f32_16x16x32_bf16 v[62:65], v[122:125], v[174:177], v[214:217]
	v_mfma_f32_16x16x32_bf16 v[46:49], v[122:125], v[178:181], v[218:221]
	v_mfma_f32_16x16x32_bf16 v[28:31], v[122:125], v[226:229], v[222:225]
	v_mfma_f32_16x16x32_bf16 v[12:15], v[122:125], v[230:233], v[4:7]
	v_mfma_f32_16x16x32_bf16 v[54:57], v[234:237], v[174:177], v[130:133]
	v_mfma_f32_16x16x32_bf16 v[38:41], v[234:237], v[178:181], v[134:137]
	v_mfma_f32_16x16x32_bf16 v[20:23], v[234:237], v[226:229], v[138:141]
	v_mfma_f32_16x16x32_bf16 v[4:7], v[234:237], v[230:233], v[142:145]
	s_setprio 0
	v_mul_f32_e32 v120, 0xbfb8aa3b, v126
	v_mul_f32_e32 v121, 0xbfb8aa3b, v127
	v_mul_f32_e32 v122, 0xbfb8aa3b, v128
	v_mul_f32_e32 v123, 0xbfb8aa3b, v129
	v_exp_f32_e32 v120, v120
	v_exp_f32_e32 v121, v121
	v_exp_f32_e32 v122, v122
	v_exp_f32_e32 v123, v123
	v_add_f32_e32 v120, 1.0, v120
	v_add_f32_e32 v121, 1.0, v121
	v_add_f32_e32 v122, 1.0, v122
	v_add_f32_e32 v123, 1.0, v123
	v_rcp_f32_e32 v120, v120
	v_rcp_f32_e32 v121, v121
	v_rcp_f32_e32 v122, v122
	v_rcp_f32_e32 v123, v123
	v_mov_b32_e32 v32, v186
	v_pk_mul_f32 v[120:121], v[126:127], v[120:121]
	s_waitcnt lgkmcnt(0)
	v_pk_mul_f32 v[122:123], v[128:129], v[122:123]
	s_barrier
; DEV unsigned pk_bf16(float lo, float hi) { const f32x2_t f = {lo, hi}; const bf16x2_t b = __builtin_convertvector(f, bf16x2_t); return __builtin_bit_cast(unsigned, b); }
; DEV void wst_put4(char* wsm, int row, int col, float a, float b, float c, float d) { uint2 w; w.x = pk_bf16(a, b); w.y = pk_bf16(c, d); *(uint2*)(wsm + row * WST_ROW + col * 2) = w; }
;     ...
;     for (int h = 0; h < 2; ++h) {
;         const int ch0 = (nt * 4 + wn * 2 + h) * 32 + fq * 4;
; #pragma unroll
;         for (int mi = 0; mi < 4; ++mi)
; #pragma unroll
;             for (int nn = 0; nn < 2; ++nn) {
;                 float o[4];
; #pragma unroll
;                 for (int j = 0; j < 4; ++j) { const float a = acc[mi][h * 4 + nn][j]; o[j] = a * __builtin_amdgcn_rcpf(1.f + __expf(-a)) * acc[mi][h * 4 + 2 + nn][j]; }
;                 wst_put4(wsm, mi * 16 + fr, h * 32 + nn * 16 + fq * 4, o[0], o[1], o[2], o[3]);
;             }
;         (void)ch0;
	s_movk_i32 s9, 0x4400
	v_lshrrev_b32_e32 v118, 6, v32
	v_pk_mul_f32 v[120:121], v[120:121], v[238:239]
	v_pk_mul_f32 v[122:123], v[122:123], v[240:241]
	v_and_b32_e32 v119, 15, v32
	v_mul_lo_u32 v118, v118, s9
	v_cvt_pk_bf16_f32 v120, v120, v121
	v_cvt_pk_bf16_f32 v121, v122, v123
	v_lshrrev_b32_e32 v122, 1, v32
	v_add_u32_e32 v118, 0, v118
	v_mul_u32_u24_e32 v119, 0x110, v119
	v_and_b32_e32 v122, 24, v122
	v_add3_u32 v119, v118, v119, v122
	v_mul_f32_e32 v122, 0xbfb8aa3b, v114
	v_mul_f32_e32 v123, 0xbfb8aa3b, v115
	v_exp_f32_e32 v122, v122
	v_exp_f32_e32 v123, v123
	s_movk_i32 s9, 0x1600
	s_lshl_b32 s8, s8, 7
	v_add_f32_e32 v122, 1.0, v122
	v_add_f32_e32 v123, 1.0, v123
	v_rcp_f32_e32 v122, v122
	v_rcp_f32_e32 v123, v123
	s_nop 0
	v_pk_mul_f32 v[114:115], v[114:115], v[122:123]
	v_mul_f32_e32 v122, 0xbfb8aa3b, v116
	v_mul_f32_e32 v123, 0xbfb8aa3b, v117
	v_exp_f32_e32 v122, v122
	v_exp_f32_e32 v123, v123
	v_pk_mul_f32 v[114:115], v[114:115], v[158:159]
	v_add_f32_e32 v122, 1.0, v122
	v_add_f32_e32 v123, 1.0, v123
	v_rcp_f32_e32 v122, v122
	v_rcp_f32_e32 v123, v123
	v_cvt_pk_bf16_f32 v114, v114, v115
	v_pk_mul_f32 v[116:117], v[116:117], v[122:123]
	s_nop 0
	v_pk_mul_f32 v[116:117], v[116:117], v[160:161]
	s_nop 0
	v_cvt_pk_bf16_f32 v115, v116, v117
	s_waitcnt vmcnt(0)
	ds_write2_b64 v119, v[120:121], v[114:115] offset1:4
	v_mul_f32_e32 v114, 0xbfb8aa3b, v106
	v_mul_f32_e32 v115, 0xbfb8aa3b, v107
	v_exp_f32_e32 v114, v114
	v_exp_f32_e32 v115, v115
	v_add_f32_e32 v114, 1.0, v114
	v_add_f32_e32 v115, 1.0, v115
	v_rcp_f32_e32 v114, v114
	v_rcp_f32_e32 v115, v115
	s_nop 0
	v_pk_mul_f32 v[106:107], v[106:107], v[114:115]
	s_nop 0
	v_pk_mul_f32 v[106:107], v[106:107], v[110:111]
	v_mul_f32_e32 v110, 0xbfb8aa3b, v108
	v_mul_f32_e32 v111, 0xbfb8aa3b, v109
	v_exp_f32_e32 v110, v110
	v_exp_f32_e32 v111, v111
	v_cvt_pk_bf16_f32 v106, v106, v107
	v_add_f32_e32 v110, 1.0, v110
	v_add_f32_e32 v111, 1.0, v111
	v_rcp_f32_e32 v110, v110
	v_rcp_f32_e32 v111, v111
	s_nop 0
	v_pk_mul_f32 v[108:109], v[108:109], v[110:111]
	s_nop 0
	v_pk_mul_f32 v[108:109], v[108:109], v[112:113]
	s_nop 0
	v_cvt_pk_bf16_f32 v107, v108, v109
	v_mul_f32_e32 v108, 0xbfb8aa3b, v98
	v_mul_f32_e32 v109, 0xbfb8aa3b, v99
	v_exp_f32_e32 v108, v108
	v_exp_f32_e32 v109, v109
	v_add_f32_e32 v108, 1.0, v108
	v_add_f32_e32 v109, 1.0, v109
	v_rcp_f32_e32 v108, v108
	v_rcp_f32_e32 v109, v109
	s_nop 0
	v_pk_mul_f32 v[98:99], v[98:99], v[108:109]
	s_nop 0
	v_pk_mul_f32 v[98:99], v[98:99], v[102:103]
	v_mul_f32_e32 v102, 0xbfb8aa3b, v100
	v_mul_f32_e32 v103, 0xbfb8aa3b, v101
	v_exp_f32_e32 v102, v102
	v_exp_f32_e32 v103, v103
	v_add_f32_e32 v102, 1.0, v102
	v_add_f32_e32 v103, 1.0, v103
	v_rcp_f32_e32 v102, v102
	v_rcp_f32_e32 v103, v103
	s_nop 0
	v_pk_mul_f32 v[100:101], v[100:101], v[102:103]
	v_cvt_pk_bf16_f32 v102, v98, v99
	v_mul_f32_e32 v99, 0xbfb8aa3b, v90
	v_exp_f32_e32 v99, v99
	v_pk_mul_f32 v[100:101], v[100:101], v[104:105]
	v_add_u32_e32 v98, 0x1000, v119
	v_cvt_pk_bf16_f32 v103, v100, v101
	v_add_f32_e32 v99, 1.0, v99
	v_rcp_f32_e32 v100, v99
	v_mul_f32_e32 v99, 0xbfb8aa3b, v91
	v_exp_f32_e32 v99, v99
	ds_write2_b64 v98, v[106:107], v[102:103] offset0:32 offset1:36
	v_add_f32_e32 v99, 1.0, v99
	v_rcp_f32_e32 v101, v99
	s_nop 0
	v_pk_mul_f32 v[90:91], v[90:91], v[100:101]
	s_nop 0
	v_pk_mul_f32 v[90:91], v[90:91], v[94:95]
	v_mul_f32_e32 v94, 0xbfb8aa3b, v92
	v_mul_f32_e32 v95, 0xbfb8aa3b, v93
	v_exp_f32_e32 v94, v94
	v_exp_f32_e32 v95, v95
	v_cvt_pk_bf16_f32 v90, v90, v91
	v_add_f32_e32 v94, 1.0, v94
	v_add_f32_e32 v95, 1.0, v95
	v_rcp_f32_e32 v94, v94
	v_rcp_f32_e32 v95, v95
	s_nop 0
	v_pk_mul_f32 v[92:93], v[92:93], v[94:95]
	s_nop 0
	v_pk_mul_f32 v[92:93], v[92:93], v[96:97]
	s_nop 0
	v_cvt_pk_bf16_f32 v91, v92, v93
	v_mul_f32_e32 v92, 0xbfb8aa3b, v82
	v_mul_f32_e32 v93, 0xbfb8aa3b, v83
	v_exp_f32_e32 v92, v92
	v_exp_f32_e32 v93, v93
	v_add_f32_e32 v92, 1.0, v92
	v_add_f32_e32 v93, 1.0, v93
	v_rcp_f32_e32 v92, v92
	v_rcp_f32_e32 v93, v93
	s_nop 0
	v_pk_mul_f32 v[82:83], v[82:83], v[92:93]
	s_nop 0
	v_pk_mul_f32 v[82:83], v[82:83], v[86:87]
	v_mul_f32_e32 v86, 0xbfb8aa3b, v84
	v_mul_f32_e32 v87, 0xbfb8aa3b, v85
	v_exp_f32_e32 v86, v86
	v_exp_f32_e32 v87, v87
	v_add_f32_e32 v86, 1.0, v86
	v_add_f32_e32 v87, 1.0, v87
	v_rcp_f32_e32 v86, v86
	v_rcp_f32_e32 v87, v87
	s_nop 0
	v_pk_mul_f32 v[84:85], v[84:85], v[86:87]
	v_cvt_pk_bf16_f32 v86, v82, v83
	v_mul_f32_e32 v83, 0xbfb8aa3b, v74
	v_exp_f32_e32 v83, v83
	v_pk_mul_f32 v[84:85], v[84:85], v[88:89]
	v_add_u32_e32 v82, 0x2000, v119
	v_cvt_pk_bf16_f32 v87, v84, v85
	v_add_f32_e32 v83, 1.0, v83
	v_rcp_f32_e32 v84, v83
	v_mul_f32_e32 v83, 0xbfb8aa3b, v75
	v_exp_f32_e32 v83, v83
	ds_write2_b64 v82, v[90:91], v[86:87] offset0:64 offset1:68
	v_add_f32_e32 v83, 1.0, v83
	v_rcp_f32_e32 v85, v83
	s_nop 0
	v_pk_mul_f32 v[74:75], v[74:75], v[84:85]
	s_nop 0
	v_pk_mul_f32 v[74:75], v[74:75], v[78:79]
	v_mul_f32_e32 v78, 0xbfb8aa3b, v76
	v_mul_f32_e32 v79, 0xbfb8aa3b, v77
	v_exp_f32_e32 v78, v78
	v_exp_f32_e32 v79, v79
	v_cvt_pk_bf16_f32 v74, v74, v75
	v_add_f32_e32 v78, 1.0, v78
	v_add_f32_e32 v79, 1.0, v79
	v_rcp_f32_e32 v78, v78
	v_rcp_f32_e32 v79, v79
	s_nop 0
	v_pk_mul_f32 v[76:77], v[76:77], v[78:79]
	s_nop 0
	v_pk_mul_f32 v[76:77], v[76:77], v[80:81]
	s_nop 0
	v_cvt_pk_bf16_f32 v75, v76, v77
	v_mul_f32_e32 v76, 0xbfb8aa3b, v66
	v_mul_f32_e32 v77, 0xbfb8aa3b, v67
	v_exp_f32_e32 v76, v76
	v_exp_f32_e32 v77, v77
	v_add_f32_e32 v76, 1.0, v76
	v_add_f32_e32 v77, 1.0, v77
	v_rcp_f32_e32 v76, v76
	v_rcp_f32_e32 v77, v77
	s_nop 0
	v_pk_mul_f32 v[66:67], v[66:67], v[76:77]
	s_nop 0
	v_pk_mul_f32 v[66:67], v[66:67], v[70:71]
	v_mul_f32_e32 v70, 0xbfb8aa3b, v68
;     __device__ __forceinline__ bf16_t* Act() const { return (bf16_t*)(ws + OFF_Act); }
; DEV void wst_put4(char* wsm, int row, int col, float a, float b, float c, float d) { uint2 w; w.x = pk_bf16(a, b); w.y = pk_bf16(c, d); *(uint2*)(wsm + row * WST_ROW + col * 2) = w; }
;     ...
;     for (int h = 0; h < 2; ++h) {
;         const int ch0 = (nt * 4 + wn * 2 + h) * 32 + fq * 4;
; #pragma unroll
;         for (int mi = 0; mi < 4; ++mi)
; #pragma unroll
;             for (int nn = 0; nn < 2; ++nn) {
;                 float o[4];
; #pragma unroll
;                 for (int j = 0; j < 4; ++j) { const float a = acc[mi][h * 4 + nn][j]; o[j] = a * __builtin_amdgcn_rcpf(1.f + __expf(-a)) * acc[mi][h * 4 + 2 + nn][j]; }
;                 wst_put4(wsm, mi * 16 + fr, h * 32 + nn * 16 + fq * 4, o[0], o[1], o[2], o[3]);
;             }
;         (void)ch0;
;     }
;     wst_flush<64>(wsm, p.Act() + (size_t)(mt * 128 + wm * 64) * DFF + (nt * 4 + wn * 2) * 32, DFF, lane);
	v_mul_f32_e32 v71, 0xbfb8aa3b, v69
	v_exp_f32_e32 v70, v70
	v_exp_f32_e32 v71, v71
	v_add_f32_e32 v70, 1.0, v70
	v_add_f32_e32 v71, 1.0, v71
	v_rcp_f32_e32 v70, v70
	v_rcp_f32_e32 v71, v71
	s_nop 0
	v_pk_mul_f32 v[68:69], v[68:69], v[70:71]
	v_cvt_pk_bf16_f32 v70, v66, v67
	v_mul_f32_e32 v67, 0xbfb8aa3b, v58
	v_exp_f32_e32 v67, v67
	v_pk_mul_f32 v[68:69], v[68:69], v[72:73]
	v_add_u32_e32 v66, 0x3000, v119
	v_cvt_pk_bf16_f32 v71, v68, v69
	v_add_f32_e32 v67, 1.0, v67
	v_rcp_f32_e32 v68, v67
	v_mul_f32_e32 v67, 0xbfb8aa3b, v59
	v_exp_f32_e32 v67, v67
	ds_write2_b64 v66, v[74:75], v[70:71] offset0:96 offset1:100
	v_add_f32_e32 v67, 1.0, v67
	v_rcp_f32_e32 v69, v67
	s_nop 0
	v_pk_mul_f32 v[58:59], v[58:59], v[68:69]
	s_nop 0
	v_pk_mul_f32 v[58:59], v[58:59], v[62:63]
	v_mul_f32_e32 v62, 0xbfb8aa3b, v60
	v_mul_f32_e32 v63, 0xbfb8aa3b, v61
	v_exp_f32_e32 v62, v62
	v_exp_f32_e32 v63, v63
	v_cvt_pk_bf16_f32 v58, v58, v59
	v_add_f32_e32 v62, 1.0, v62
	v_add_f32_e32 v63, 1.0, v63
	v_rcp_f32_e32 v62, v62
	v_rcp_f32_e32 v63, v63
	s_nop 0
	v_pk_mul_f32 v[60:61], v[60:61], v[62:63]
	s_nop 0
	v_pk_mul_f32 v[60:61], v[60:61], v[64:65]
	s_nop 0
	v_cvt_pk_bf16_f32 v59, v60, v61
	v_mul_f32_e32 v60, 0xbfb8aa3b, v50
	v_mul_f32_e32 v61, 0xbfb8aa3b, v51
	v_exp_f32_e32 v60, v60
	v_exp_f32_e32 v61, v61
	v_add_f32_e32 v60, 1.0, v60
	v_add_f32_e32 v61, 1.0, v61
	v_rcp_f32_e32 v60, v60
	v_rcp_f32_e32 v61, v61
	s_nop 0
	v_pk_mul_f32 v[50:51], v[50:51], v[60:61]
	s_nop 0
	v_pk_mul_f32 v[50:51], v[50:51], v[54:55]
	v_mul_f32_e32 v54, 0xbfb8aa3b, v52
	v_mul_f32_e32 v55, 0xbfb8aa3b, v53
	v_exp_f32_e32 v54, v54
	v_exp_f32_e32 v55, v55
	v_cvt_pk_bf16_f32 v50, v50, v51
	v_add_f32_e32 v54, 1.0, v54
	v_add_f32_e32 v55, 1.0, v55
	v_rcp_f32_e32 v54, v54
	v_rcp_f32_e32 v55, v55
	s_nop 0
	v_pk_mul_f32 v[52:53], v[52:53], v[54:55]
	s_nop 0
	v_pk_mul_f32 v[52:53], v[52:53], v[56:57]
	s_nop 0
	v_cvt_pk_bf16_f32 v51, v52, v53
	ds_write2_b64 v119, v[58:59], v[50:51] offset0:8 offset1:12
	v_mul_f32_e32 v50, 0xbfb8aa3b, v42
	v_mul_f32_e32 v51, 0xbfb8aa3b, v43
	v_exp_f32_e32 v50, v50
	v_exp_f32_e32 v51, v51
	v_add_f32_e32 v50, 1.0, v50
	v_add_f32_e32 v51, 1.0, v51
	v_rcp_f32_e32 v50, v50
	v_rcp_f32_e32 v51, v51
	s_nop 0
	v_pk_mul_f32 v[42:43], v[42:43], v[50:51]
	s_nop 0
	v_pk_mul_f32 v[42:43], v[42:43], v[46:47]
	v_mul_f32_e32 v46, 0xbfb8aa3b, v44
	v_mul_f32_e32 v47, 0xbfb8aa3b, v45
	v_exp_f32_e32 v46, v46
	v_exp_f32_e32 v47, v47
	v_cvt_pk_bf16_f32 v42, v42, v43
	v_add_f32_e32 v46, 1.0, v46
	v_add_f32_e32 v47, 1.0, v47
	v_rcp_f32_e32 v46, v46
	v_rcp_f32_e32 v47, v47
	s_nop 0
	v_pk_mul_f32 v[44:45], v[44:45], v[46:47]
	s_nop 0
	v_pk_mul_f32 v[44:45], v[44:45], v[48:49]
	s_nop 0
	v_cvt_pk_bf16_f32 v43, v44, v45
	v_mul_f32_e32 v44, 0xbfb8aa3b, v34
	v_mul_f32_e32 v45, 0xbfb8aa3b, v35
	v_exp_f32_e32 v44, v44
	v_exp_f32_e32 v45, v45
	v_add_f32_e32 v44, 1.0, v44
	v_add_f32_e32 v45, 1.0, v45
	v_rcp_f32_e32 v44, v44
	v_rcp_f32_e32 v45, v45
	s_nop 0
	v_pk_mul_f32 v[34:35], v[34:35], v[44:45]
	s_nop 0
	v_pk_mul_f32 v[34:35], v[34:35], v[38:39]
	v_mul_f32_e32 v38, 0xbfb8aa3b, v36
	v_mul_f32_e32 v39, 0xbfb8aa3b, v37
	v_exp_f32_e32 v38, v38
	v_exp_f32_e32 v39, v39
	v_cvt_pk_bf16_f32 v34, v34, v35
	v_add_f32_e32 v38, 1.0, v38
	v_add_f32_e32 v39, 1.0, v39
	v_rcp_f32_e32 v38, v38
	v_rcp_f32_e32 v39, v39
	s_nop 0
	v_pk_mul_f32 v[36:37], v[36:37], v[38:39]
	s_nop 0
	v_pk_mul_f32 v[36:37], v[36:37], v[40:41]
	s_nop 0
	v_cvt_pk_bf16_f32 v35, v36, v37
	ds_write2_b64 v98, v[42:43], v[34:35] offset0:40 offset1:44
	v_mul_f32_e32 v34, 0xbfb8aa3b, v24
	v_mul_f32_e32 v35, 0xbfb8aa3b, v25
	v_exp_f32_e32 v34, v34
	v_exp_f32_e32 v35, v35
	v_add_f32_e32 v34, 1.0, v34
	v_add_f32_e32 v35, 1.0, v35
	v_rcp_f32_e32 v34, v34
	v_rcp_f32_e32 v35, v35
	s_nop 0
	v_pk_mul_f32 v[24:25], v[24:25], v[34:35]
	s_nop 0
	v_pk_mul_f32 v[24:25], v[24:25], v[28:29]
	v_mul_f32_e32 v28, 0xbfb8aa3b, v26
	v_mul_f32_e32 v29, 0xbfb8aa3b, v27
	v_exp_f32_e32 v28, v28
	v_exp_f32_e32 v29, v29
	v_cvt_pk_bf16_f32 v24, v24, v25
	v_add_f32_e32 v28, 1.0, v28
	v_add_f32_e32 v29, 1.0, v29
	v_rcp_f32_e32 v28, v28
	v_rcp_f32_e32 v29, v29
	s_nop 0
	v_pk_mul_f32 v[26:27], v[26:27], v[28:29]
	s_nop 0
	v_pk_mul_f32 v[26:27], v[26:27], v[30:31]
	s_nop 0
	v_cvt_pk_bf16_f32 v25, v26, v27
	v_mul_f32_e32 v26, 0xbfb8aa3b, v16
	v_mul_f32_e32 v27, 0xbfb8aa3b, v17
	v_exp_f32_e32 v26, v26
	v_exp_f32_e32 v27, v27
	v_add_f32_e32 v26, 1.0, v26
	v_add_f32_e32 v27, 1.0, v27
	v_rcp_f32_e32 v26, v26
	v_rcp_f32_e32 v27, v27
	s_nop 0
	v_pk_mul_f32 v[16:17], v[16:17], v[26:27]
	s_nop 0
	v_pk_mul_f32 v[16:17], v[16:17], v[20:21]
	v_mul_f32_e32 v20, 0xbfb8aa3b, v18
	v_mul_f32_e32 v21, 0xbfb8aa3b, v19
	v_exp_f32_e32 v20, v20
	v_exp_f32_e32 v21, v21
	v_cvt_pk_bf16_f32 v16, v16, v17
	v_add_f32_e32 v20, 1.0, v20
	v_add_f32_e32 v21, 1.0, v21
	v_rcp_f32_e32 v20, v20
	v_rcp_f32_e32 v21, v21
	s_nop 0
	v_pk_mul_f32 v[18:19], v[18:19], v[20:21]
	s_nop 0
	v_pk_mul_f32 v[18:19], v[18:19], v[22:23]
	s_nop 0
	v_cvt_pk_bf16_f32 v17, v18, v19
	ds_write2_b64 v82, v[24:25], v[16:17] offset0:72 offset1:76
	v_mul_f32_e32 v16, 0xbfb8aa3b, v8
	v_mul_f32_e32 v17, 0xbfb8aa3b, v9
	v_exp_f32_e32 v16, v16
	v_exp_f32_e32 v17, v17
	v_add_f32_e32 v16, 1.0, v16
	v_add_f32_e32 v17, 1.0, v17
	v_rcp_f32_e32 v16, v16
	v_rcp_f32_e32 v17, v17
	s_nop 0
	v_pk_mul_f32 v[8:9], v[8:9], v[16:17]
	s_nop 0
	v_pk_mul_f32 v[8:9], v[8:9], v[12:13]
	v_mul_f32_e32 v12, 0xbfb8aa3b, v10
	v_mul_f32_e32 v13, 0xbfb8aa3b, v11
	v_exp_f32_e32 v12, v12
	v_exp_f32_e32 v13, v13
	v_cvt_pk_bf16_f32 v8, v8, v9
	v_add_f32_e32 v12, 1.0, v12
	v_add_f32_e32 v13, 1.0, v13
	v_rcp_f32_e32 v12, v12
	v_rcp_f32_e32 v13, v13
	s_nop 0
	v_pk_mul_f32 v[10:11], v[10:11], v[12:13]
	s_nop 0
	v_pk_mul_f32 v[10:11], v[10:11], v[14:15]
	s_nop 0
	v_cvt_pk_bf16_f32 v9, v10, v11
	v_mul_f32_e32 v10, 0xbfb8aa3b, v0
	v_mul_f32_e32 v11, 0xbfb8aa3b, v1
	v_exp_f32_e32 v10, v10
	v_exp_f32_e32 v11, v11
	v_add_f32_e32 v10, 1.0, v10
	v_add_f32_e32 v11, 1.0, v11
	v_rcp_f32_e32 v10, v10
	v_rcp_f32_e32 v11, v11
	s_nop 0
	v_pk_mul_f32 v[0:1], v[0:1], v[10:11]
	s_nop 0
	v_pk_mul_f32 v[0:1], v[0:1], v[4:5]
	v_mul_f32_e32 v4, 0xbfb8aa3b, v2
	v_mul_f32_e32 v5, 0xbfb8aa3b, v3
	v_exp_f32_e32 v4, v4
	v_exp_f32_e32 v5, v5
	v_cvt_pk_bf16_f32 v0, v0, v1
	v_add_f32_e32 v4, 1.0, v4
	v_add_f32_e32 v5, 1.0, v5
	v_rcp_f32_e32 v4, v4
	v_rcp_f32_e32 v5, v5
	s_nop 0
	v_pk_mul_f32 v[2:3], v[2:3], v[4:5]
	s_nop 0
	v_pk_mul_f32 v[2:3], v[2:3], v[6:7]
	v_bfe_u32 v6, v32, 3, 3
	v_cvt_pk_bf16_f32 v1, v2, v3
	ds_write2_b64 v66, v[8:9], v[0:1] offset0:104 offset1:108
	v_ashrrev_i32_e32 v0, 1, v32
	v_and_b32_e32 v0, 0xffffffc0, v0
	v_lshl_add_u32 v2, s17, 7, v0
	v_mov_b64_e32 v[0:1], s[6:7]
	v_mad_i64_i32 v[0:1], s[10:11], v2, s9, v[0:1]
	v_and_or_b32 v2, v32, 64, s8
	v_ashrrev_i32_e32 v3, 31, v2
	v_lshl_add_u64 v[0:1], v[2:3], 2, v[0:1]
	v_lshlrev_b32_e32 v2, 4, v32
	v_and_b32_e32 v32, 0x70, v2
	v_lshl_add_u64 v[4:5], v[0:1], 0, v[32:33]
	v_and_b32_e32 v2, 64, v2
	v_mov_b32_e32 v3, 0
	v_lshl_add_u64 v[4:5], v[4:5], 0, v[2:3]
	v_mul_u32_u24_e32 v0, 0x110, v6
	s_waitcnt lgkmcnt(0)
; template <int NCOLS>
; DEV void wst_flush(const char* wsm, bf16_t* dst, int ld, int lane) {
;     constexpr int CPR = NCOLS / 8, RPI = 64 / CPR;
;     asm volatile("s_waitcnt lgkmcnt(0)" ::: "memory");
;     const int r0 = lane / CPR, ch = lane % CPR;
; #pragma unroll
;     for (int it = 0; it < 64 / RPI; ++it) {
;         const int row = it * RPI + r0;
;         const uint4 v = *(const uint4*)(wsm + row * WST_ROW + ch * 16);
;         *(uint4*)(dst + (size_t)row * ld + ch * 8) = v;
;     }
; }
	v_add3_u32 v10, v118, v32, v0
	ds_read_b128 v[0:3], v10
	v_lshrrev_b32_e32 v32, 1, v6
	v_mul_u32_u24_e32 v32, 0x2c00, v32
	v_and_b32_e32 v6, 1, v6
	v_lshl_or_b32 v32, v6, 6, v32
	v_lshl_add_u64 v[6:7], v[4:5], 0, v[32:33]
	s_mov_b32 s8, 0xb000
	s_waitcnt lgkmcnt(0)
	flat_store_dwordx4 v[6:7], v[0:3]
	ds_read_b128 v[0:3], v10 offset:2176
	v_add_co_u32_e32 v8, vcc, s8, v6
	s_mov_b32 s8, 0x16000
	s_nop 0
	v_addc_co_u32_e32 v9, vcc, 0, v7, vcc
	s_waitcnt lgkmcnt(0)
	flat_store_dwordx4 v[8:9], v[0:3]
	ds_read_b128 v[0:3], v10 offset:4352
	v_add_co_u32_e32 v8, vcc, s8, v6
	s_mov_b32 s8, 0x21000
	s_nop 0
	v_addc_co_u32_e32 v9, vcc, 0, v7, vcc
	s_waitcnt lgkmcnt(0)
	flat_store_dwordx4 v[8:9], v[0:3]
	ds_read_b128 v[0:3], v10 offset:6528
	v_add_co_u32_e32 v8, vcc, s8, v6
	s_mov_b32 s8, 0x2c000
	s_nop 0
	v_addc_co_u32_e32 v9, vcc, 0, v7, vcc
	s_waitcnt lgkmcnt(0)
	flat_store_dwordx4 v[8:9], v[0:3]
	ds_read_b128 v[0:3], v10 offset:8704
	v_add_co_u32_e32 v6, vcc, s8, v6
	v_readlane_b32 s8, v254, 4
	s_nop 0
	v_addc_co_u32_e32 v7, vcc, 0, v7, vcc
	s_waitcnt lgkmcnt(0)
	flat_store_dwordx4 v[6:7], v[0:3]
	ds_read_b128 v[0:3], v10 offset:10880
	v_add_u32_e32 v6, 0x37000, v32
	v_mov_b32_e32 v7, v33
	v_lshl_add_u64 v[6:7], v[4:5], 0, v[6:7]
	s_add_i32 s16, s16, s8
	s_waitcnt lgkmcnt(0)
	flat_store_dwordx4 v[6:7], v[0:3]
	ds_read_b128 v[0:3], v10 offset:13056
	v_add_u32_e32 v6, 0x42000, v32
	v_mov_b32_e32 v7, v33
	v_lshl_add_u64 v[6:7], v[4:5], 0, v[6:7]
	v_add_u32_e32 v32, 0x4d000, v32
	s_waitcnt lgkmcnt(0)
	flat_store_dwordx4 v[6:7], v[0:3]
	ds_read_b128 v[0:3], v10 offset:15232
	v_lshl_add_u64 v[4:5], v[4:5], 0, v[32:33]
	s_cmpk_gt_i32 s16, 0xb15
	v_readlane_b32 s9, v254, 5
	s_waitcnt lgkmcnt(0)
	flat_store_dwordx4 v[4:5], v[0:3]
	s_cbranch_scc0 .LBB0_32

; #define RAW_BARRIER() do { asm volatile("s_waitcnt lgkmcnt(0)" ::: "memory"); __builtin_amdgcn_s_barrier(); } while (0)
; #define GLDS_TILE(kt, st) do { _Pragma("unroll") for (int _i = 0; _i < NP; ++_i) GLDS_PIECE(_i, kt, st); } while (0)
;     ...
;     constexpr int NH = NI >= 4 ? NI / 2 : NI;
;     constexpr int NP = 2 + NB, IVL = (4 * NI) / NP;
;     RAW_BARRIER();
;     GLDS_TILE(0, 0);
;     GLDS_TILE(1, 1);
;     int st = 0;
;     for (int kt = 0; kt < nk - 1; ++kt) {
;         if (NI == 8) asm volatile("s_waitcnt vmcnt(6)" ::: "memory"); else if (NI == 4) asm volatile("s_waitcnt vmcnt(4)" ::: "memory"); else asm volatile("s_waitcnt vmcnt(3)" ::: "memory");
;         RAW_BARRIER();
;         const int s2 = st >= 1 ? st - 1 : 2;
;         const bool ld = kt + 2 < nk;
;         STEP_TILE(st, ld, kt + 2, s2);
;         st = st == 2 ? 0 : st + 1;
;     }
.LBB0_64:
	s_mul_i32 s6, s1, 0x6000
	s_add_i32 s7, s6, 0
	s_waitcnt vmcnt(6)
	v_add_u32_e32 v148, s7, v134
	v_add_u32_e32 v155, s7, v135
	s_waitcnt lgkmcnt(0)
	s_barrier
	ds_read_b128 v[158:161], v155 offset:8192
	ds_read_b128 v[136:139], v148
	ds_read_b128 v[140:143], v148 offset:1024
	ds_read_b128 v[144:147], v148 offset:2048
	ds_read_b128 v[148:151], v148 offset:3072
	ds_read_b128 v[162:165], v155 offset:9216
	ds_read_b128 v[166:169], v155 offset:10240
	ds_read_b128 v[170:173], v155 offset:11264
	s_addk_i32 s6, 0xa000
	s_cmp_gt_i32 s1, 0
	s_setprio 1
	s_waitcnt lgkmcnt(6)
	v_mfma_f32_16x16x32_bf16 v[126:129], v[158:161], v[136:139], v[126:129]
	s_cselect_b32 s6, s6, 0xc000
	v_add_u32_e32 v157, s6, v32
	v_lshl_add_u64 v[152:153], v[132:133], 0, s[4:5]
	s_waitcnt lgkmcnt(5)
	v_mfma_f32_16x16x32_bf16 v[110:113], v[158:161], v[140:143], v[110:113]
	s_mov_b64 s[6:7], 0x1b00080
	v_lshl_add_u64 v[206:207], v[152:153], 0, s[6:7]
	v_lshl_add_u64 v[208:209], v[130:131], 0, s[4:5]
	s_waitcnt lgkmcnt(4)
	v_mfma_f32_16x16x32_bf16 v[82:85], v[158:161], v[144:147], v[82:85]
	s_mov_b64 s[6:7], 0x60ac080
	v_add_u32_e32 v205, 0x2000, v157
	s_waitcnt lgkmcnt(3)
	v_mfma_f32_16x16x32_bf16 v[50:53], v[158:161], v[148:151], v[50:53]
	v_lshl_add_u64 v[158:159], v[208:209], 0, s[6:7]
	s_waitcnt lgkmcnt(2)
	v_mfma_f32_16x16x32_bf16 v[122:125], v[162:165], v[136:139], v[122:125]
	v_readfirstlane_b32 s6, v157
	s_mov_b32 m0, s6
	v_mfma_f32_16x16x32_bf16 v[102:105], v[162:165], v[140:143], v[102:105]
	global_load_lds_dwordx4 v[158:159], off
	ds_read_b128 v[158:161], v155 offset:12288
	ds_read_b128 v[174:177], v155 offset:13312
	ds_read_b128 v[178:181], v155 offset:14336
	ds_read_b128 v[182:185], v155 offset:15360
	v_mfma_f32_16x16x32_bf16 v[70:73], v[162:165], v[144:147], v[70:73]
	v_mfma_f32_16x16x32_bf16 v[38:41], v[162:165], v[148:151], v[38:41]
	s_waitcnt lgkmcnt(5)
	v_mfma_f32_16x16x32_bf16 v[118:121], v[166:169], v[136:139], v[118:121]
	v_mfma_f32_16x16x32_bf16 v[94:97], v[166:169], v[140:143], v[94:97]
	v_add_u32_e32 v155, 0x1000, v157
	s_mov_b64 s[6:7], 0x60cc080
	v_lshl_add_u64 v[162:163], v[208:209], 0, s[6:7]
	v_readfirstlane_b32 s6, v155
	s_mov_b32 m0, s6
	v_mfma_f32_16x16x32_bf16 v[62:65], v[166:169], v[144:147], v[62:65]
	global_load_lds_dwordx4 v[162:163], off
	v_mfma_f32_16x16x32_bf16 v[28:31], v[166:169], v[148:151], v[28:31]
	s_waitcnt lgkmcnt(4)
	v_mfma_f32_16x16x32_bf16 v[114:117], v[170:173], v[136:139], v[114:117]
	v_mfma_f32_16x16x32_bf16 v[86:89], v[170:173], v[140:143], v[86:89]
	v_mfma_f32_16x16x32_bf16 v[54:57], v[170:173], v[144:147], v[54:57]
	v_readfirstlane_b32 s6, v205
	s_mov_b32 m0, s6
	v_mfma_f32_16x16x32_bf16 v[20:23], v[170:173], v[148:151], v[20:23]
	global_load_lds_dwordx4 v[206:207], off
	s_waitcnt lgkmcnt(0)
	v_mfma_f32_16x16x32_bf16 v[106:109], v[158:161], v[136:139], v[106:109]
	v_mfma_f32_16x16x32_bf16 v[74:77], v[158:161], v[140:143], v[74:77]
	v_mfma_f32_16x16x32_bf16 v[42:45], v[158:161], v[144:147], v[42:45]
	v_mfma_f32_16x16x32_bf16 v[12:15], v[158:161], v[148:151], v[12:15]
	v_add_u32_e32 v155, 0x3000, v157
	s_mov_b64 s[6:7], 0x1b20080
	v_lshl_add_u64 v[158:159], v[152:153], 0, s[6:7]
	v_readfirstlane_b32 s6, v155
	s_mov_b32 m0, s6
	v_mfma_f32_16x16x32_bf16 v[98:101], v[174:177], v[136:139], v[98:101]
	global_load_lds_dwordx4 v[158:159], off
	v_mfma_f32_16x16x32_bf16 v[66:69], v[174:177], v[140:143], v[66:69]
	v_mfma_f32_16x16x32_bf16 v[34:37], v[174:177], v[144:147], v[34:37]
	v_mfma_f32_16x16x32_bf16 v[8:11], v[174:177], v[148:151], v[8:11]
	v_mfma_f32_16x16x32_bf16 v[90:93], v[178:181], v[136:139], v[90:93]
	v_add_u32_e32 v155, 0x4000, v157
	s_mov_b64 s[6:7], 0x1b40080
	v_lshl_add_u64 v[158:159], v[152:153], 0, s[6:7]
	v_readfirstlane_b32 s6, v155
	s_mov_b32 m0, s6
	v_mfma_f32_16x16x32_bf16 v[58:61], v[178:181], v[140:143], v[58:61]
	global_load_lds_dwordx4 v[158:159], off
	v_mfma_f32_16x16x32_bf16 v[24:27], v[178:181], v[144:147], v[24:27]
	v_mfma_f32_16x16x32_bf16 v[4:7], v[178:181], v[148:151], v[4:7]
	v_mfma_f32_16x16x32_bf16 v[78:81], v[182:185], v[136:139], v[78:81]
	v_mfma_f32_16x16x32_bf16 v[46:49], v[182:185], v[140:143], v[46:49]
	v_add_u32_e32 v138, 0x5000, v157
	s_mov_b64 s[6:7], 0x1b60080
	v_lshl_add_u64 v[136:137], v[152:153], 0, s[6:7]
	v_readfirstlane_b32 s6, v138
	s_mov_b32 m0, s6
	v_mfma_f32_16x16x32_bf16 v[16:19], v[182:185], v[144:147], v[16:19]
	global_load_lds_dwordx4 v[136:137], off
	v_mfma_f32_16x16x32_bf16 v[0:3], v[182:185], v[148:151], v[0:3]
	s_setprio 0
	s_add_i32 s6, s1, 1
	s_cmp_lg_u32 s1, 2
	s_cselect_b32 s1, s6, 0
	s_add_u32 s4, s4, 64
	s_addc_u32 s5, s5, 0
	s_cmpk_lg_i32 s4, 0x780
	s_cbranch_scc1 .LBB0_64
	s_waitcnt vmcnt(6)
	v_add_u32_e32 v32, 0, v134
	v_add_u32_e32 v152, 0, v135
	s_waitcnt lgkmcnt(0)
	s_barrier
;     __device__ __forceinline__ float* mod() const { return (float*)(ws + OFF_mod); }
; DEV int tid_opaque() { int t = threadIdx.x; asm volatile("" : "+v"(t)); return t; }
; #define RAW_BARRIER() do { asm volatile("s_waitcnt lgkmcnt(0)" ::: "memory"); __builtin_amdgcn_s_barrier(); } while (0)
;     ...
;     asm volatile("s_waitcnt vmcnt(0)" ::: "memory");
;     RAW_BARRIER();
;     STEP_TILE(st, false, 0, 0);
;     RAW_BARRIER();
; DEV void resid_big(const Params& p, int l, int mt, int nt, const bf16_t* A, int K, const bf16_t* W, int gate_off, bool res_from_input, char* smem) {
;     ...
;     const int t = tid_opaque(), lane = t & 63, wid = t >> 6, wm = wid >> 1, wn = wid & 1, fr = lane & 15, fq = lane >> 4;
;     const int rbase = mt * 128 + wm * 64 + fr, c0 = nt * 256 + wn * 128 + fq * 4;
; #pragma unroll
;     for (int mi = 0; mi < 4; ++mi) {
;         const int row = rbase + mi * 16;
;         const float* gt = p.mod() + (size_t)(l * 9 + mod_index(row)) * 6144 + gate_off + c0;
;         const float* res = res_from_input ? xrow(p, l, row) : p.out + (size_t)row * 1024;
;         float* dst = p.out + (size_t)row * 1024;
	ds_read_b128 v[130:133], v32
	ds_read_b128 v[136:139], v32 offset:1024
	ds_read_b128 v[140:143], v32 offset:2048
	ds_read_b128 v[144:147], v32 offset:3072
	ds_read_b128 v[148:151], v152 offset:8192
	ds_read_b128 v[158:161], v152 offset:9216
	ds_read_b128 v[162:165], v152 offset:10240
	ds_read_b128 v[166:169], v152 offset:11264
	s_setprio 1
	s_waitcnt lgkmcnt(0)
	v_mfma_f32_16x16x32_bf16 v[126:129], v[148:151], v[130:133], v[126:129]
	v_mfma_f32_16x16x32_bf16 v[110:113], v[148:151], v[136:139], v[110:113]
	v_mfma_f32_16x16x32_bf16 v[82:85], v[148:151], v[140:143], v[82:85]
	v_mfma_f32_16x16x32_bf16 v[50:53], v[148:151], v[144:147], v[50:53]
	v_mfma_f32_16x16x32_bf16 v[122:125], v[158:161], v[130:133], v[122:125]
	ds_read_b128 v[148:151], v152 offset:12288
	ds_read_b128 v[170:173], v152 offset:13312
	ds_read_b128 v[174:177], v152 offset:14336
	ds_read_b128 v[178:181], v152 offset:15360
	v_mfma_f32_16x16x32_bf16 v[102:105], v[158:161], v[136:139], v[102:105]
	v_mfma_f32_16x16x32_bf16 v[70:73], v[158:161], v[140:143], v[70:73]
	v_mfma_f32_16x16x32_bf16 v[38:41], v[158:161], v[144:147], v[38:41]
	v_mfma_f32_16x16x32_bf16 v[118:121], v[162:165], v[130:133], v[118:121]
	v_mfma_f32_16x16x32_bf16 v[158:161], v[162:165], v[136:139], v[94:97]
	v_mfma_f32_16x16x32_bf16 v[114:117], v[166:169], v[130:133], v[114:117]
	v_mfma_f32_16x16x32_bf16 v[182:185], v[162:165], v[140:143], v[62:65]
	v_mfma_f32_16x16x32_bf16 v[162:165], v[162:165], v[144:147], v[28:31]
	v_mfma_f32_16x16x32_bf16 v[206:209], v[166:169], v[136:139], v[86:89]
	v_mfma_f32_16x16x32_bf16 v[210:213], v[166:169], v[140:143], v[54:57]
	s_waitcnt lgkmcnt(0)
	v_mfma_f32_16x16x32_bf16 v[106:109], v[148:151], v[130:133], v[106:109]
	v_mfma_f32_16x16x32_bf16 v[74:77], v[148:151], v[136:139], v[74:77]
	v_mfma_f32_16x16x32_bf16 v[42:45], v[148:151], v[140:143], v[42:45]
	v_mfma_f32_16x16x32_bf16 v[12:15], v[148:151], v[144:147], v[12:15]
	v_mfma_f32_16x16x32_bf16 v[166:169], v[166:169], v[144:147], v[20:23]
	v_mfma_f32_16x16x32_bf16 v[98:101], v[170:173], v[130:133], v[98:101]
	v_mfma_f32_16x16x32_bf16 v[66:69], v[170:173], v[136:139], v[66:69]
	v_mfma_f32_16x16x32_bf16 v[34:37], v[170:173], v[140:143], v[34:37]
	v_mfma_f32_16x16x32_bf16 v[8:11], v[170:173], v[144:147], v[8:11]
	v_mfma_f32_16x16x32_bf16 v[148:151], v[174:177], v[130:133], v[90:93]
	v_mfma_f32_16x16x32_bf16 v[4:7], v[174:177], v[144:147], v[4:7]
	v_mfma_f32_16x16x32_bf16 v[130:133], v[178:181], v[130:133], v[78:81]
	v_mfma_f32_16x16x32_bf16 v[170:173], v[174:177], v[136:139], v[58:61]
	v_mfma_f32_16x16x32_bf16 v[214:217], v[174:177], v[140:143], v[24:27]
	v_mfma_f32_16x16x32_bf16 v[134:137], v[178:181], v[136:139], v[46:49]
	v_mfma_f32_16x16x32_bf16 v[0:3], v[178:181], v[144:147], v[0:3]
	v_mfma_f32_16x16x32_bf16 v[138:141], v[178:181], v[140:143], v[16:19]
	s_setprio 0
	s_waitcnt vmcnt(0)
	s_waitcnt lgkmcnt(0)
	s_barrier
	ds_read_b128 v[142:145], v32 offset:24576
	ds_read_b128 v[174:177], v32 offset:25600
	ds_read_b128 v[178:181], v32 offset:26624
	ds_read_b128 v[218:221], v32 offset:27648
	ds_read_b128 v[16:19], v152 offset:32768
	ds_read_b128 v[20:23], v152 offset:33792
	ds_read_b128 v[46:49], v152 offset:34816
	ds_read_b128 v[78:81], v152 offset:35840
	s_setprio 1
	s_waitcnt lgkmcnt(0)
	v_mfma_f32_16x16x32_bf16 v[126:129], v[16:19], v[142:145], v[126:129]
	v_mfma_f32_16x16x32_bf16 v[94:97], v[16:19], v[174:177], v[110:113]
	v_mfma_f32_16x16x32_bf16 v[62:65], v[16:19], v[178:181], v[82:85]
	v_mfma_f32_16x16x32_bf16 v[28:31], v[16:19], v[218:221], v[50:53]
	v_mfma_f32_16x16x32_bf16 v[122:125], v[20:23], v[142:145], v[122:125]
	ds_read_b128 v[222:225], v152 offset:36864
	ds_read_b128 v[226:229], v152 offset:37888
	ds_read_b128 v[230:233], v152 offset:38912
	ds_read_b128 v[234:237], v152 offset:39936
	v_mfma_f32_16x16x32_bf16 v[90:93], v[20:23], v[174:177], v[102:105]
	v_mfma_f32_16x16x32_bf16 v[58:61], v[20:23], v[178:181], v[70:73]
	v_mfma_f32_16x16x32_bf16 v[24:27], v[20:23], v[218:221], v[38:41]
	v_mfma_f32_16x16x32_bf16 v[118:121], v[46:49], v[142:145], v[118:121]
	v_mfma_f32_16x16x32_bf16 v[86:89], v[46:49], v[174:177], v[158:161]
	v_mfma_f32_16x16x32_bf16 v[54:57], v[46:49], v[178:181], v[182:185]
	v_mfma_f32_16x16x32_bf16 v[20:23], v[46:49], v[218:221], v[162:165]
	v_mfma_f32_16x16x32_bf16 v[114:117], v[78:81], v[142:145], v[114:117]
	v_mfma_f32_16x16x32_bf16 v[82:85], v[78:81], v[174:177], v[206:209]
	v_mfma_f32_16x16x32_bf16 v[50:53], v[78:81], v[178:181], v[210:213]
	v_mfma_f32_16x16x32_bf16 v[16:19], v[78:81], v[218:221], v[166:169]
	s_waitcnt lgkmcnt(0)
	v_mfma_f32_16x16x32_bf16 v[110:113], v[222:225], v[142:145], v[106:109]
	v_mfma_f32_16x16x32_bf16 v[78:81], v[222:225], v[174:177], v[74:77]
	v_mfma_f32_16x16x32_bf16 v[46:49], v[222:225], v[178:181], v[42:45]
	v_mfma_f32_16x16x32_bf16 v[12:15], v[222:225], v[218:221], v[12:15]
	v_mfma_f32_16x16x32_bf16 v[106:109], v[226:229], v[142:145], v[98:101]
	v_mfma_f32_16x16x32_bf16 v[74:77], v[226:229], v[174:177], v[66:69]
	v_mfma_f32_16x16x32_bf16 v[42:45], v[226:229], v[178:181], v[34:37]
	v_mfma_f32_16x16x32_bf16 v[8:11], v[226:229], v[218:221], v[8:11]
	v_mfma_f32_16x16x32_bf16 v[102:105], v[230:233], v[142:145], v[148:151]
	v_mfma_f32_16x16x32_bf16 v[70:73], v[230:233], v[174:177], v[170:173]
	v_mfma_f32_16x16x32_bf16 v[38:41], v[230:233], v[178:181], v[214:217]
	v_mfma_f32_16x16x32_bf16 v[4:7], v[230:233], v[218:221], v[4:7]
	v_mfma_f32_16x16x32_bf16 v[98:101], v[234:237], v[142:145], v[130:133]
	v_mfma_f32_16x16x32_bf16 v[66:69], v[234:237], v[174:177], v[134:137]
	v_mfma_f32_16x16x32_bf16 v[34:37], v[234:237], v[178:181], v[138:141]
	v_mfma_f32_16x16x32_bf16 v[0:3], v[234:237], v[218:221], v[0:3]
	s_setprio 0
	v_mov_b32_e32 v32, v186
	s_waitcnt lgkmcnt(0)
	s_barrier
	s_movk_i32 s4, 0x3fff
	v_ashrrev_i32_e32 v130, 1, v32
	v_and_b32_e32 v130, 0xffffffc0, v130
	v_lshl_add_u32 v130, s0, 7, v130
	v_and_or_b32 v130, v32, 15, v130
	s_movk_i32 s0, 0x4000
	v_cmp_gt_i32_e64 s[0:1], s0, v130
	v_cmp_lt_i32_e64 s[4:5], s4, v130
	s_mov_b64 s[6:7], -1
	s_and_b64 vcc, exec, s[10:11]
	s_cbranch_vccz .LBB0_67
	v_ashrrev_i32_e32 v131, 31, v130
	s_mov_b64 s[6:7], 0

; DEV int tid_opaque() { int t = threadIdx.x; asm volatile("" : "+v"(t)); return t; }
; #define RAW_BARRIER() do { asm volatile("s_waitcnt lgkmcnt(0)" ::: "memory"); __builtin_amdgcn_s_barrier(); } while (0)
; #define GLDS_TILE(kt, st) do { _Pragma("unroll") for (int _i = 0; _i < NP; ++_i) GLDS_PIECE(_i, kt, st); } while (0)
;     constexpr int BROWS = 32 * NI, STAGE = 8192 + BROWS * 64, NB = BROWS / 64;
;     const int t = tid_opaque(), lane = t & 63, wid = t >> 6, wm = wid >> 1, wn = wid & 1, fr = lane & 15, fq = lane >> 4;
;     const int nk = K >> 5;
;     const int srow = wid * 16 + (lane >> 2), sch = (lane & 3) ^ ((0 - (lane >> 4)) & 3);
;     const bf16_t* ga = A + (size_t)srow * lda + sch * 8;
;     const bf16_t* gb = B + (size_t)srow * ldb + sch * 8;
;     const int rd = fr * 64 + ((fq ^ ((0 - (fr >> 2)) & 3)) << 4);
;     const int rda = (wm * 64) * 64 + rd, rdb = 8192 + (wn * 16 * NI) * 64 + rd;
;     ...
;     constexpr int NH = NI >= 4 ? NI / 2 : NI;
;     constexpr int NP = 2 + NB, IVL = (4 * NI) / NP;
;     RAW_BARRIER();
;     GLDS_TILE(0, 0);
;     GLDS_TILE(1, 1);
;     int st = 0;
;     for (int kt = 0; kt < nk - 1; ++kt) {
;         if (NI == 8) asm volatile("s_waitcnt vmcnt(6)" ::: "memory"); else if (NI == 4) asm volatile("s_waitcnt vmcnt(4)" ::: "memory"); else asm volatile("s_waitcnt vmcnt(3)" ::: "memory");
;         RAW_BARRIER();
;         const int s2 = st >= 1 ? st - 1 : 2;
;         const bool ld = kt + 2 < nk;
;         STEP_TILE(st, ld, kt + 2, s2);
;         st = st == 2 ? 0 : st + 1;
;     }
;     asm volatile("s_waitcnt vmcnt(0)" ::: "memory");
;     RAW_BARRIER();
;     STEP_TILE(st, false, 0, 0);
.LBB0_98:
	s_and_b32 s14, s13, 3
	s_ashr_i32 s6, s13, 2
	s_lshl_b32 s15, s14, 9
	s_add_u32 s16, s10, s15
	s_addc_u32 s17, s11, 0
	s_ashr_i32 s7, s6, 31
	s_lshl_b64 s[18:19], s[6:7], 17
	v_mov_b32_e32 v8, v186
	s_add_u32 s7, s8, s18
	s_addc_u32 s19, s9, s19
	v_ashrrev_i32_e32 v9, 6, v8
	v_bfe_u32 v10, v8, 4, 2
	v_bfe_u32 v0, v8, 2, 4
	v_lshl_or_b32 v0, v9, 4, v0
	v_sub_u32_e32 v1, 0, v10
	s_add_u32 s18, s7, s15
	v_xor_b32_e32 v4, v8, v1
	v_ashrrev_i32_e32 v1, 31, v0
	s_addc_u32 s19, s19, 0
	v_lshlrev_b64 v[2:3], 11, v[0:1]
	v_lshlrev_b32_e32 v4, 4, v4
	v_lshl_add_u64 v[0:1], s[16:17], 0, v[2:3]
	v_and_b32_e32 v32, 48, v4
	v_lshl_add_u64 v[2:3], s[18:19], 0, v[2:3]
	v_lshl_add_u64 v[0:1], v[0:1], 0, v[32:33]
	v_lshl_add_u64 v[2:3], v[2:3], 0, v[32:33]
	v_lshl_add_u32 v32, v9, 10, 0
	v_add_u32_e32 v7, 0x1000, v32
	v_readfirstlane_b32 s19, v32
	v_add_u32_e32 v6, 0x2000, v32
	s_mov_b32 m0, s19
	v_readfirstlane_b32 s18, v7
	s_waitcnt lgkmcnt(0)
	s_barrier
	global_load_lds_dwordx4 v[0:1], off
	v_lshl_add_u64 v[4:5], v[0:1], 0, s[40:41]
	s_mov_b32 m0, s18
	v_readfirstlane_b32 s17, v6
	v_add_u32_e32 v11, 0x3000, v32
	global_load_lds_dwordx4 v[4:5], off
	s_mov_b32 m0, s17
	v_readfirstlane_b32 s16, v11
	v_add_u32_e32 v11, 0x4000, v32
	global_load_lds_dwordx4 v[2:3], off
	v_add_u32_e32 v12, 0x5000, v32
	v_lshl_add_u64 v[6:7], v[0:1], 0, 64
	s_mov_b32 m0, s16
	v_readfirstlane_b32 s15, v11
	global_load_lds_dwordx4 v[6:7], off
	v_lshl_add_u64 v[6:7], v[0:1], 0, s[42:43]
	s_mov_b32 m0, s15
	v_readfirstlane_b32 s7, v12
	v_lshl_add_u64 v[4:5], v[2:3], 0, 64
	global_load_lds_dwordx4 v[6:7], off
	s_mov_b32 m0, s7
	v_lshlrev_b32_e32 v6, 11, v9
	global_load_lds_dwordx4 v[4:5], off
	v_lshrrev_b32_e32 v5, 2, v8
	v_lshlrev_b32_e32 v4, 6, v8
	v_sub_u32_e32 v5, 0, v5
	v_and_b32_e32 v4, 0x3c0, v4
	v_bitop3_b32 v5, v10, v5, 3 bitop3:0x78
	v_lshl_or_b32 v4, v5, 4, v4
	v_lshlrev_b32_e32 v5, 5, v8
	v_and_or_b32 v5, v5, s30, v4
	s_waitcnt vmcnt(3)
	s_waitcnt vmcnt(0)
	v_add_u32_e32 v66, 0, v5
	v_and_or_b32 v20, v6, s34, v4
	s_waitcnt lgkmcnt(0)
	s_barrier
	ds_read_b128 v[4:7], v66
	ds_read_b128 v[8:11], v66 offset:1024
	ds_read_b128 v[12:15], v66 offset:2048
	ds_read_b128 v[16:19], v66 offset:3072
	v_add_u32_e32 v67, 0, v20
	ds_read_b128 v[20:23], v67 offset:8192
	ds_read_b128 v[24:27], v67 offset:9216
	s_setprio 1
	v_add_u32_e32 v40, 0x6000, v32
	s_waitcnt lgkmcnt(0)
	v_mfma_f32_16x16x32_bf16 v[28:31], v[20:23], v[4:7], 0
	v_lshl_add_u64 v[42:43], v[2:3], 0, s[38:39]
	v_add_u32_e32 v46, 0x8000, v32
	v_lshl_add_u64 v[38:39], v[0:1], 0, s[38:39]
	v_mfma_f32_16x16x32_bf16 v[34:37], v[20:23], v[8:11], 0
	v_readfirstlane_b32 s22, v40
	s_mov_b32 m0, s22
	s_nop 0
	global_load_lds_dwordx4 v[38:39], off
	v_mfma_f32_16x16x32_bf16 v[38:41], v[20:23], v[12:15], 0
	v_mfma_f32_16x16x32_bf16 v[20:23], v[20:23], v[16:19], 0
	v_add_u32_e32 v32, 0x7000, v32
	v_lshl_add_u64 v[44:45], v[0:1], 0, s[46:47]
	v_readfirstlane_b32 s23, v32
	s_mov_b32 m0, s23
	s_nop 0
	global_load_lds_dwordx4 v[44:45], off
	v_mfma_f32_16x16x32_bf16 v[4:7], v[24:27], v[4:7], 0
	v_mfma_f32_16x16x32_bf16 v[8:11], v[24:27], v[8:11], 0
	v_readfirstlane_b32 s28, v46
	s_mov_b32 m0, s28
	s_nop 0
	global_load_lds_dwordx4 v[42:43], off
	v_mfma_f32_16x16x32_bf16 v[12:15], v[24:27], v[12:15], 0
	v_mfma_f32_16x16x32_bf16 v[16:19], v[24:27], v[16:19], 0
	s_setprio 0
	s_waitcnt vmcnt(3)
	s_waitcnt lgkmcnt(0)
	s_barrier
	ds_read_b128 v[24:27], v66 offset:12288
	ds_read_b128 v[42:45], v66 offset:13312
	ds_read_b128 v[46:49], v66 offset:14336
	ds_read_b128 v[50:53], v66 offset:15360
	ds_read_b128 v[54:57], v67 offset:20480
	ds_read_b128 v[58:61], v67 offset:21504
	s_setprio 1
	s_waitcnt lgkmcnt(0)
	v_mfma_f32_16x16x32_bf16 v[28:31], v[54:57], v[24:27], v[28:31]
	v_lshl_add_u64 v[62:63], v[2:3], 0, s[48:49]
	v_lshl_add_u64 v[64:65], v[0:1], 0, s[48:49]
	v_mfma_f32_16x16x32_bf16 v[34:37], v[54:57], v[42:45], v[34:37]
	s_mov_b32 m0, s19
	v_mfma_f32_16x16x32_bf16 v[38:41], v[54:57], v[46:49], v[38:41]
	global_load_lds_dwordx4 v[64:65], off
	v_mfma_f32_16x16x32_bf16 v[20:23], v[54:57], v[50:53], v[20:23]
	s_mov_b64 s[20:21], 0x200c0
	v_lshl_add_u64 v[54:55], v[0:1], 0, s[20:21]
	s_mov_b32 m0, s18
	v_mfma_f32_16x16x32_bf16 v[4:7], v[58:61], v[24:27], v[4:7]
	global_load_lds_dwordx4 v[54:55], off
	v_mfma_f32_16x16x32_bf16 v[8:11], v[58:61], v[42:45], v[8:11]
	s_mov_b32 m0, s17
	v_mfma_f32_16x16x32_bf16 v[12:15], v[58:61], v[46:49], v[12:15]
	global_load_lds_dwordx4 v[62:63], off
	v_mfma_f32_16x16x32_bf16 v[16:19], v[58:61], v[50:53], v[16:19]
	s_setprio 0
	s_waitcnt vmcnt(3)
	s_waitcnt lgkmcnt(0)
	s_barrier
	ds_read_b128 v[24:27], v66 offset:24576
	ds_read_b128 v[42:45], v66 offset:25600
	ds_read_b128 v[46:49], v66 offset:26624
	ds_read_b128 v[50:53], v66 offset:27648
	ds_read_b128 v[54:57], v67 offset:32768
	ds_read_b128 v[58:61], v67 offset:33792
	s_setprio 1
	s_waitcnt lgkmcnt(0)
	v_mfma_f32_16x16x32_bf16 v[28:31], v[54:57], v[24:27], v[28:31]
	v_lshl_add_u64 v[62:63], v[2:3], 0, s[50:51]
	v_lshl_add_u64 v[64:65], v[0:1], 0, s[50:51]
	v_mfma_f32_16x16x32_bf16 v[34:37], v[54:57], v[42:45], v[34:37]
	s_mov_b32 m0, s16
	v_mfma_f32_16x16x32_bf16 v[38:41], v[54:57], v[46:49], v[38:41]
	global_load_lds_dwordx4 v[64:65], off
	v_mfma_f32_16x16x32_bf16 v[20:23], v[54:57], v[50:53], v[20:23]
	s_mov_b64 s[20:21], 0x20100
	v_lshl_add_u64 v[54:55], v[0:1], 0, s[20:21]
	s_mov_b32 m0, s15
	v_mfma_f32_16x16x32_bf16 v[4:7], v[58:61], v[24:27], v[4:7]
	global_load_lds_dwordx4 v[54:55], off
	v_mfma_f32_16x16x32_bf16 v[8:11], v[58:61], v[42:45], v[8:11]
	s_mov_b32 m0, s7
	v_mfma_f32_16x16x32_bf16 v[12:15], v[58:61], v[46:49], v[12:15]
	global_load_lds_dwordx4 v[62:63], off
	v_mfma_f32_16x16x32_bf16 v[16:19], v[58:61], v[50:53], v[16:19]
	s_setprio 0
	s_waitcnt vmcnt(3)
	s_waitcnt lgkmcnt(0)
	s_barrier
; #define RAW_BARRIER() do { asm volatile("s_waitcnt lgkmcnt(0)" ::: "memory"); __builtin_amdgcn_s_barrier(); } while (0)
; #define GLDS_TILE(kt, st) do { _Pragma("unroll") for (int _i = 0; _i < NP; ++_i) GLDS_PIECE(_i, kt, st); } while (0)
;     ...
;     constexpr int NH = NI >= 4 ? NI / 2 : NI;
;     constexpr int NP = 2 + NB, IVL = (4 * NI) / NP;
;     RAW_BARRIER();
;     GLDS_TILE(0, 0);
;     GLDS_TILE(1, 1);
;     int st = 0;
;     for (int kt = 0; kt < nk - 1; ++kt) {
;         if (NI == 8) asm volatile("s_waitcnt vmcnt(6)" ::: "memory"); else if (NI == 4) asm volatile("s_waitcnt vmcnt(4)" ::: "memory"); else asm volatile("s_waitcnt vmcnt(3)" ::: "memory");
;         RAW_BARRIER();
;         const int s2 = st >= 1 ? st - 1 : 2;
;         const bool ld = kt + 2 < nk;
;         STEP_TILE(st, ld, kt + 2, s2);
;         st = st == 2 ? 0 : st + 1;
;     }
;     asm volatile("s_waitcnt vmcnt(0)" ::: "memory");
;     RAW_BARRIER();
;     STEP_TILE(st, false, 0, 0);
;     RAW_BARRIER();
	ds_read_b128 v[24:27], v66
	ds_read_b128 v[42:45], v66 offset:1024
	ds_read_b128 v[46:49], v66 offset:2048
	ds_read_b128 v[50:53], v66 offset:3072
	ds_read_b128 v[54:57], v67 offset:8192
	ds_read_b128 v[58:61], v67 offset:9216
	s_setprio 1
	s_waitcnt lgkmcnt(0)
	v_mfma_f32_16x16x32_bf16 v[28:31], v[54:57], v[24:27], v[28:31]
	v_lshl_add_u64 v[62:63], v[2:3], 0, s[52:53]
	v_lshl_add_u64 v[64:65], v[0:1], 0, s[52:53]
	v_mfma_f32_16x16x32_bf16 v[34:37], v[54:57], v[42:45], v[34:37]
	s_mov_b32 m0, s22
	v_mfma_f32_16x16x32_bf16 v[38:41], v[54:57], v[46:49], v[38:41]
	global_load_lds_dwordx4 v[64:65], off
	v_mfma_f32_16x16x32_bf16 v[20:23], v[54:57], v[50:53], v[20:23]
	s_mov_b64 s[20:21], 0x20140
	v_lshl_add_u64 v[54:55], v[0:1], 0, s[20:21]
	s_mov_b32 m0, s23
	v_mfma_f32_16x16x32_bf16 v[4:7], v[58:61], v[24:27], v[4:7]
	global_load_lds_dwordx4 v[54:55], off
	v_mfma_f32_16x16x32_bf16 v[8:11], v[58:61], v[42:45], v[8:11]
	s_mov_b32 m0, s28
	v_mfma_f32_16x16x32_bf16 v[12:15], v[58:61], v[46:49], v[12:15]
	global_load_lds_dwordx4 v[62:63], off
	v_mfma_f32_16x16x32_bf16 v[16:19], v[58:61], v[50:53], v[16:19]
	s_setprio 0
	s_waitcnt vmcnt(3)
	s_waitcnt lgkmcnt(0)
	s_barrier
	ds_read_b128 v[24:27], v66 offset:12288
	ds_read_b128 v[42:45], v66 offset:13312
	ds_read_b128 v[46:49], v66 offset:14336
	ds_read_b128 v[50:53], v66 offset:15360
	ds_read_b128 v[54:57], v67 offset:20480
	ds_read_b128 v[58:61], v67 offset:21504
	s_setprio 1
	s_waitcnt lgkmcnt(0)
	v_mfma_f32_16x16x32_bf16 v[28:31], v[54:57], v[24:27], v[28:31]
	v_lshl_add_u64 v[62:63], v[2:3], 0, s[54:55]
	v_lshl_add_u64 v[64:65], v[0:1], 0, s[54:55]
	v_mfma_f32_16x16x32_bf16 v[34:37], v[54:57], v[42:45], v[34:37]
	s_mov_b32 m0, s19
	v_mfma_f32_16x16x32_bf16 v[38:41], v[54:57], v[46:49], v[38:41]
	global_load_lds_dwordx4 v[64:65], off
	v_mfma_f32_16x16x32_bf16 v[20:23], v[54:57], v[50:53], v[20:23]
	s_mov_b64 s[20:21], 0x20180
	v_lshl_add_u64 v[54:55], v[0:1], 0, s[20:21]
	s_mov_b32 m0, s18
	v_mfma_f32_16x16x32_bf16 v[4:7], v[58:61], v[24:27], v[4:7]
	global_load_lds_dwordx4 v[54:55], off
	v_mfma_f32_16x16x32_bf16 v[8:11], v[58:61], v[42:45], v[8:11]
	s_mov_b32 m0, s17
	v_mfma_f32_16x16x32_bf16 v[12:15], v[58:61], v[46:49], v[12:15]
	global_load_lds_dwordx4 v[62:63], off
	v_mfma_f32_16x16x32_bf16 v[16:19], v[58:61], v[50:53], v[16:19]
	s_setprio 0
	s_waitcnt vmcnt(3)
	s_waitcnt lgkmcnt(0)
	s_barrier
	ds_read_b128 v[24:27], v66 offset:24576
	ds_read_b128 v[42:45], v66 offset:25600
	ds_read_b128 v[46:49], v66 offset:26624
	ds_read_b128 v[50:53], v66 offset:27648
	ds_read_b128 v[54:57], v67 offset:32768
	ds_read_b128 v[58:61], v67 offset:33792
	s_setprio 1
	s_waitcnt lgkmcnt(0)
	v_mfma_f32_16x16x32_bf16 v[28:31], v[54:57], v[24:27], v[28:31]
	v_lshl_add_u64 v[62:63], v[2:3], 0, s[56:57]
	v_lshl_add_u64 v[2:3], v[0:1], 0, s[56:57]
	v_mfma_f32_16x16x32_bf16 v[34:37], v[54:57], v[42:45], v[34:37]
	s_mov_b32 m0, s16
	v_mfma_f32_16x16x32_bf16 v[38:41], v[54:57], v[46:49], v[38:41]
	global_load_lds_dwordx4 v[2:3], off
	v_mfma_f32_16x16x32_bf16 v[20:23], v[54:57], v[50:53], v[20:23]
	s_mov_b64 s[16:17], 0x201c0
	v_lshl_add_u64 v[0:1], v[0:1], 0, s[16:17]
	s_mov_b32 m0, s15
	s_nop 0
	global_load_lds_dwordx4 v[0:1], off
	v_mfma_f32_16x16x32_bf16 v[0:3], v[58:61], v[24:27], v[4:7]
	v_mfma_f32_16x16x32_bf16 v[4:7], v[58:61], v[42:45], v[8:11]
	s_mov_b32 m0, s7
	s_nop 0
	global_load_lds_dwordx4 v[62:63], off
	v_mfma_f32_16x16x32_bf16 v[8:11], v[58:61], v[46:49], v[12:15]
	v_mfma_f32_16x16x32_bf16 v[12:15], v[58:61], v[50:53], v[16:19]
	s_setprio 0
	s_waitcnt vmcnt(3)
	s_waitcnt lgkmcnt(0)
	s_barrier
	s_nop 0
	ds_read_b128 v[16:19], v66
	ds_read_b128 v[24:27], v66 offset:1024
	ds_read_b128 v[42:45], v66 offset:2048
	ds_read_b128 v[46:49], v66 offset:3072
	ds_read_b128 v[50:53], v67 offset:8192
	ds_read_b128 v[54:57], v67 offset:9216
	s_setprio 1
	s_waitcnt lgkmcnt(0)
	v_mfma_f32_16x16x32_bf16 v[28:31], v[50:53], v[16:19], v[28:31]
	v_mfma_f32_16x16x32_bf16 v[34:37], v[50:53], v[24:27], v[34:37]
	v_mfma_f32_16x16x32_bf16 v[38:41], v[50:53], v[42:45], v[38:41]
	v_mfma_f32_16x16x32_bf16 v[20:23], v[50:53], v[46:49], v[20:23]
	v_mfma_f32_16x16x32_bf16 v[0:3], v[54:57], v[16:19], v[0:3]
	v_mfma_f32_16x16x32_bf16 v[16:19], v[54:57], v[24:27], v[4:7]
	v_mfma_f32_16x16x32_bf16 v[8:11], v[54:57], v[42:45], v[8:11]
	v_mfma_f32_16x16x32_bf16 v[24:27], v[54:57], v[46:49], v[12:15]
	s_setprio 0
	s_waitcnt vmcnt(0)
	s_waitcnt lgkmcnt(0)
	s_barrier
	ds_read_b128 v[42:45], v66 offset:12288
	ds_read_b128 v[46:49], v66 offset:13312
	ds_read_b128 v[50:53], v66 offset:14336
	ds_read_b128 v[54:57], v66 offset:15360
	ds_read_b128 v[4:7], v67 offset:20480
	ds_read_b128 v[58:61], v67 offset:21504
	s_setprio 1
	s_waitcnt lgkmcnt(0)
	v_mfma_f32_16x16x32_bf16 v[28:31], v[4:7], v[42:45], v[28:31]
	v_mfma_f32_16x16x32_bf16 v[34:37], v[4:7], v[46:49], v[34:37]
	v_mfma_f32_16x16x32_bf16 v[12:15], v[4:7], v[50:53], v[38:41]
	v_mfma_f32_16x16x32_bf16 v[4:7], v[4:7], v[54:57], v[20:23]
	v_mfma_f32_16x16x32_bf16 v[38:41], v[58:61], v[42:45], v[0:3]
	v_mfma_f32_16x16x32_bf16 v[42:45], v[58:61], v[46:49], v[16:19]
	v_mfma_f32_16x16x32_bf16 v[8:11], v[58:61], v[50:53], v[8:11]
	v_mfma_f32_16x16x32_bf16 v[0:3], v[58:61], v[54:57], v[24:27]
	s_setprio 0
	v_mov_b32_e32 v17, v186
	s_waitcnt lgkmcnt(0)
	s_barrier
;     __device__ __forceinline__ float* mod() const { return (float*)(ws + OFF_mod); }
; DEV int tid_opaque() { int t = threadIdx.x; asm volatile("" : "+v"(t)); return t; }
; DEV void resid_small(const Params& p, int l, int unit, const bf16_t* A, int K, const bf16_t* W, int gate_off, char* smem) {
;     ...
;     const int t = tid_opaque(), lane = t & 63, wid = t >> 6, wm = wid >> 1, wn = wid & 1, fr = lane & 15, fq = lane >> 4;
;     const int rbase = (MT - 1) * 128 + wm * 64 + fr, c0 = nt * 64 + wn * 32 + fq * 4;
; #pragma unroll
;     for (int mi = 0; mi < 4; ++mi) {
;         const int row = rbase + mi * 16;
;         const float* gt = p.mod() + (size_t)(l * 9 + mod_index(row)) * 6144 + gate_off + c0;
;         float* dst = (float*)(p.ws + OFF_part) + ((size_t)kq * 128 + (row - SEQ)) * 1024 + c0;
; #pragma unroll
;         for (int ni = 0; ni < 2; ++ni) {
;             const f32x4 g4 = *(const f32x4*)(gt + ni * 16);
;             *(f32x4*)(dst + ni * 16) = g4 * acc[mi][ni];
;         }
;     }
; }
	s_lshl_b32 s6, s6, 6
	v_ashrrev_i32_e32 v16, 1, v17
	v_and_b32_e32 v20, 0xffffffc0, v16
	v_and_or_b32 v16, v17, 15, v20
	v_lshrrev_b32_e32 v18, 1, v17
	v_lshrrev_b32_e32 v17, 2, v17
	v_and_b32_e32 v18, 32, v18
	v_and_b32_e32 v17, 12, v17
	v_add_u32_e32 v21, 0x4000, v16
	v_or3_b32 v18, v18, s6, v17
	v_lshrrev_b32_e32 v17, 4, v20
	v_or_b32_e32 v17, 1, v17
	v_cmp_lt_i32_e32 vcc, s31, v21
	v_ashrrev_i32_e32 v19, 31, v18
	v_mov_b64_e32 v[20:21], s[0:1]
	v_cndmask_b32_e32 v17, 0, v17, vcc
	v_add_u32_e32 v17, s12, v17
	s_lshl_b32 s92, s14, 7
	v_mad_i64_i32 v[22:23], s[6:7], v17, s33, v[20:21]
	v_lshlrev_b64 v[18:19], 2, v[18:19]
	v_ashrrev_i32_e32 v17, 31, v16
	v_lshl_add_u64 v[22:23], v[22:23], 0, v[18:19]
	v_lshl_add_u64 v[24:25], v[16:17], 0, s[92:93]
	v_lshl_add_u64 v[26:27], v[22:23], 0, s[44:45]
	v_lshlrev_b64 v[24:25], 12, v[24:25]
	v_add_co_u32_e32 v22, vcc, s29, v22
	v_lshl_add_u64 v[24:25], s[4:5], 0, v[24:25]
	s_nop 0
	v_addc_co_u32_e32 v23, vcc, 0, v23, vcc
	v_lshl_add_u64 v[46:47], v[24:25], 0, v[18:19]
	flat_load_dwordx4 v[22:25], v[22:23]
	v_add_u32_e32 v17, 0x4010, v16
	v_cmp_lt_i32_e32 vcc, s31, v17
	s_add_i32 s13, s13, s58
	s_cmp_gt_i32 s13, 63
	s_waitcnt vmcnt(0) lgkmcnt(0)
	v_pk_mul_f32 v[24:25], v[30:31], v[24:25]
	v_pk_mul_f32 v[22:23], v[28:29], v[22:23]
	flat_store_dwordx4 v[46:47], v[22:25]
	flat_load_dwordx4 v[22:25], v[26:27] offset:64
	s_waitcnt vmcnt(0) lgkmcnt(0)
	v_pk_mul_f32 v[24:25], v[40:41], v[24:25]
	v_pk_mul_f32 v[22:23], v[38:39], v[22:23]
	flat_store_dwordx4 v[46:47], v[22:25] offset:64
	s_nop 1
	v_or_b32_e32 v22, 16, v16
	v_lshrrev_b32_e32 v23, 4, v22
	v_add_u32_e32 v23, 1, v23
	v_cndmask_b32_e32 v17, 0, v23, vcc
	v_ashrrev_i32_e32 v23, 31, v22
	v_add_u32_e32 v17, s12, v17
	v_lshl_add_u64 v[22:23], v[22:23], 0, s[92:93]
	v_mad_i64_i32 v[24:25], s[6:7], v17, s33, v[20:21]
	v_lshlrev_b64 v[22:23], 12, v[22:23]
	v_lshl_add_u64 v[24:25], v[24:25], 0, v[18:19]
	v_lshl_add_u64 v[22:23], s[4:5], 0, v[22:23]
	v_lshl_add_u64 v[28:29], v[22:23], 0, v[18:19]
	v_add_co_u32_e32 v22, vcc, s29, v24
	v_lshl_add_u64 v[26:27], v[24:25], 0, s[44:45]
	s_nop 0
	v_addc_co_u32_e32 v23, vcc, 0, v25, vcc
	flat_load_dwordx4 v[22:25], v[22:23]
	v_add_u32_e32 v17, 0x4020, v16
	v_cmp_lt_i32_e32 vcc, s31, v17
	s_waitcnt vmcnt(0) lgkmcnt(0)
	v_pk_mul_f32 v[24:25], v[36:37], v[24:25]
	v_pk_mul_f32 v[22:23], v[34:35], v[22:23]
	flat_store_dwordx4 v[28:29], v[22:25]
	flat_load_dwordx4 v[22:25], v[26:27] offset:64
	s_waitcnt vmcnt(0) lgkmcnt(0)
	v_pk_mul_f32 v[24:25], v[44:45], v[24:25]
	v_pk_mul_f32 v[22:23], v[42:43], v[22:23]
	flat_store_dwordx4 v[28:29], v[22:25] offset:64
	s_nop 1
	v_or_b32_e32 v22, 32, v16
	v_lshrrev_b32_e32 v23, 4, v22
	v_or_b32_e32 v23, 1, v23
	v_cndmask_b32_e32 v17, 0, v23, vcc
	v_ashrrev_i32_e32 v23, 31, v22
	v_add_u32_e32 v17, s12, v17
	v_lshl_add_u64 v[22:23], v[22:23], 0, s[92:93]
	v_mad_i64_i32 v[24:25], s[6:7], v17, s33, v[20:21]
	v_lshlrev_b64 v[22:23], 12, v[22:23]
	v_lshl_add_u64 v[24:25], v[24:25], 0, v[18:19]
	v_lshl_add_u64 v[22:23], s[4:5], 0, v[22:23]
	v_lshl_add_u64 v[28:29], v[22:23], 0, v[18:19]
	v_add_co_u32_e32 v22, vcc, s29, v24
	v_lshl_add_u64 v[26:27], v[24:25], 0, s[44:45]
	s_nop 0
	v_addc_co_u32_e32 v23, vcc, 0, v25, vcc
	flat_load_dwordx4 v[22:25], v[22:23]
	s_waitcnt vmcnt(0) lgkmcnt(0)
	v_pk_mul_f32 v[14:15], v[14:15], v[24:25]
	v_pk_mul_f32 v[12:13], v[12:13], v[22:23]
	flat_store_dwordx4 v[28:29], v[12:15]
	flat_load_dwordx4 v[12:15], v[26:27] offset:64
	s_waitcnt vmcnt(0) lgkmcnt(0)
	v_pk_mul_f32 v[10:11], v[10:11], v[14:15]
	v_pk_mul_f32 v[8:9], v[8:9], v[12:13]
	flat_store_dwordx4 v[28:29], v[8:11] offset:64
	s_nop 1
	v_or_b32_e32 v8, 48, v16
	v_add_u32_e32 v9, 0x4030, v16
	v_lshrrev_b32_e32 v10, 4, v8
	v_add_u32_e32 v10, 1, v10
	v_cmp_lt_i32_e32 vcc, s31, v9
	s_nop 1
	v_cndmask_b32_e32 v9, 0, v10, vcc
	v_add_u32_e32 v9, s12, v9
	v_mad_i64_i32 v[10:11], s[6:7], v9, s33, v[20:21]
	v_ashrrev_i32_e32 v9, 31, v8
	v_lshl_add_u64 v[8:9], v[8:9], 0, s[92:93]
	v_lshlrev_b64 v[8:9], 12, v[8:9]
	v_lshl_add_u64 v[10:11], v[10:11], 0, v[18:19]
	v_lshl_add_u64 v[8:9], s[4:5], 0, v[8:9]
	v_lshl_add_u64 v[14:15], v[8:9], 0, v[18:19]
	v_add_co_u32_e32 v8, vcc, s29, v10
	v_lshl_add_u64 v[12:13], v[10:11], 0, s[44:45]
	s_nop 0
	v_addc_co_u32_e32 v9, vcc, 0, v11, vcc
	flat_load_dwordx4 v[8:11], v[8:9]
	s_waitcnt vmcnt(0) lgkmcnt(0)
	v_pk_mul_f32 v[6:7], v[6:7], v[10:11]
	v_pk_mul_f32 v[4:5], v[4:5], v[8:9]
	flat_store_dwordx4 v[14:15], v[4:7]
	flat_load_dwordx4 v[4:7], v[12:13] offset:64
	s_waitcnt vmcnt(0) lgkmcnt(0)
	v_pk_mul_f32 v[2:3], v[2:3], v[6:7]
	v_pk_mul_f32 v[0:1], v[0:1], v[4:5]
	flat_store_dwordx4 v[14:15], v[0:3] offset:64
	s_cbranch_scc0 .LBB0_98
	v_writelane_b32 v252, s92, 27
	s_nop 1
	v_writelane_b32 v252, s93, 28
	v_readlane_b32 s92, v254, 13
	v_readlane_b32 s93, v254, 14

; DEV int tid_opaque() { int t = threadIdx.x; asm volatile("" : "+v"(t)); return t; }
; #define RAW_BARRIER() do { asm volatile("s_waitcnt lgkmcnt(0)" ::: "memory"); __builtin_amdgcn_s_barrier(); } while (0)
; #define GLDS_TILE(kt, st) do { _Pragma("unroll") for (int _i = 0; _i < NP; ++_i) GLDS_PIECE(_i, kt, st); } while (0)
;     constexpr int BROWS = 32 * NI, STAGE = 8192 + BROWS * 64, NB = BROWS / 64;
;     const int t = tid_opaque(), lane = t & 63, wid = t >> 6, wm = wid >> 1, wn = wid & 1, fr = lane & 15, fq = lane >> 4;
;     const int nk = K >> 5;
;     const int srow = wid * 16 + (lane >> 2), sch = (lane & 3) ^ ((0 - (lane >> 4)) & 3);
;     const bf16_t* ga = A + (size_t)srow * lda + sch * 8;
;     const bf16_t* gb = B + (size_t)srow * ldb + sch * 8;
;     const int rd = fr * 64 + ((fq ^ ((0 - (fr >> 2)) & 3)) << 4);
;     const int rda = (wm * 64) * 64 + rd, rdb = 8192 + (wn * 16 * NI) * 64 + rd;
;     ...
;     constexpr int NH = NI >= 4 ? NI / 2 : NI;
;     constexpr int NP = 2 + NB, IVL = (4 * NI) / NP;
;     RAW_BARRIER();
;     GLDS_TILE(0, 0);
;     GLDS_TILE(1, 1);
;     int st = 0;
;     for (int kt = 0; kt < nk - 1; ++kt) {
;         if (NI == 8) asm volatile("s_waitcnt vmcnt(6)" ::: "memory"); else if (NI == 4) asm volatile("s_waitcnt vmcnt(4)" ::: "memory"); else asm volatile("s_waitcnt vmcnt(3)" ::: "memory");
;         RAW_BARRIER();
;         const int s2 = st >= 1 ? st - 1 : 2;
;         const bool ld = kt + 2 < nk;
;         STEP_TILE(st, ld, kt + 2, s2);
;         st = st == 2 ? 0 : st + 1;
;     }
.LBB0_106:
	s_ashr_i32 s11, s30, 4
	v_mov_b32_e32 v0, v186
	s_and_b32 s10, s30, 7
	s_and_b32 s11, s11, -8
	s_or_b32 s34, s11, s10
	v_ashrrev_i32_e32 v1, 1, v0
	v_and_b32_e32 v1, 0xffffffc0, v1
	v_lshl_add_u32 v1, s34, 7, v1
	s_bfe_u32 s39, s30, 0x40003
	v_and_or_b32 v94, v0, 15, v1
	v_lshrrev_b32_e32 v1, 1, v0
	v_lshrrev_b32_e32 v0, 2, v0
	s_lshl_b32 s10, s39, 6
	v_and_b32_e32 v1, 32, v1
	v_and_b32_e32 v0, 12, v0
	s_ashr_i32 s35, s34, 31
	v_or3_b32 v28, v1, s10, v0
	s_lshl_b64 s[10:11], s[34:35], 16
	s_lshl_b32 s31, s39, 15
	s_mul_i32 s38, s34, 0x18000
	v_mov_b32_e32 v4, v186
	s_mul_hi_i32 s35, s34, 0x18000
	s_add_u32 s40, s12, s38
	s_mul_i32 s34, s39, 0xc000
	v_ashrrev_i32_e32 v5, 6, v4
	v_bfe_u32 v6, v4, 4, 2
	v_bfe_u32 v0, v4, 2, 4
	s_addc_u32 s41, s13, s35
	v_lshl_or_b32 v7, v5, 4, v0
	v_sub_u32_e32 v0, 0, v6
	s_add_u32 s42, s14, s34
	v_xor_b32_e32 v2, v4, v0
	s_addc_u32 s43, s15, 0
	v_lshlrev_b32_e32 v2, 4, v2
	v_mov_b64_e32 v[0:1], s[40:41]
	v_and_b32_e32 v32, 48, v2
	v_mov_b64_e32 v[2:3], s[42:43]
	v_lshrrev_b32_e32 v8, 2, v4
	v_mad_i64_i32 v[0:1], s[40:41], v7, s48, v[0:1]
	v_mad_i64_i32 v[2:3], s[40:41], v7, s48, v[2:3]
	v_lshlrev_b32_e32 v7, 6, v4
	v_sub_u32_e32 v8, 0, v8
	v_lshl_add_u32 v29, v5, 10, 0
	v_and_b32_e32 v7, 0x3c0, v7
	v_bitop3_b32 v6, v6, v8, 3 bitop3:0x78
	v_readfirstlane_b32 s44, v29
	v_add_u32_e32 v10, 0x1000, v29
	v_lshl_add_u64 v[0:1], v[0:1], 0, v[32:33]
	v_lshl_or_b32 v8, v6, 4, v7
	v_add_u32_e32 v7, 0x2000, v29
	s_mov_b32 m0, s44
	v_readfirstlane_b32 s43, v10
	v_lshlrev_b32_e32 v6, 5, v4
	v_lshlrev_b32_e32 v9, 11, v5
	s_waitcnt lgkmcnt(0)
	s_barrier
	global_load_lds_dwordx4 v[0:1], off
	v_lshl_add_u64 v[4:5], v[0:1], 0, s[66:67]
	s_mov_b32 m0, s43
	v_readfirstlane_b32 s42, v7
	v_add_u32_e32 v11, 0x3000, v29
	v_lshl_add_u64 v[2:3], v[2:3], 0, v[32:33]
	global_load_lds_dwordx4 v[4:5], off
	s_mov_b32 m0, s42
	v_readfirstlane_b32 s41, v11
	v_add_u32_e32 v11, 0x4000, v29
	global_load_lds_dwordx4 v[2:3], off
	v_and_or_b32 v10, v6, s49, v8
	v_add_u32_e32 v12, 0x5000, v29
	v_lshl_add_u64 v[6:7], v[0:1], 0, 64
	s_mov_b32 m0, s41
	v_readfirstlane_b32 s40, v11
	global_load_lds_dwordx4 v[6:7], off
	v_lshl_add_u64 v[6:7], v[0:1], 0, s[68:69]
	s_mov_b32 m0, s40
	v_readfirstlane_b32 s39, v12
	v_lshl_add_u64 v[4:5], v[2:3], 0, 64
	global_load_lds_dwordx4 v[6:7], off
	s_mov_b32 m0, s39
	v_add_u32_e32 v32, 0, v10
	global_load_lds_dwordx4 v[4:5], off
	s_waitcnt vmcnt(3)
	v_and_or_b32 v20, v9, s50, v8
	s_waitcnt lgkmcnt(0)
	s_barrier
	ds_read_b128 v[4:7], v32
	ds_read_b128 v[8:11], v32 offset:1024
	ds_read_b128 v[12:15], v32 offset:2048
	ds_read_b128 v[16:19], v32 offset:3072
	s_waitcnt vmcnt(0)
	v_add_u32_e32 v70, 0, v20
	ds_read_b128 v[20:23], v70 offset:8192
	ds_read_b128 v[24:27], v70 offset:9216
	s_setprio 1
	v_add_u32_e32 v44, 0x6000, v29
	s_waitcnt lgkmcnt(0)
	v_mfma_f32_16x16x32_bf16 v[34:37], v[20:23], v[4:7], 0
	v_lshl_add_u64 v[30:31], v[2:3], 0, s[54:55]
	v_add_u32_e32 v48, 0x8000, v29
	v_lshl_add_u64 v[42:43], v[0:1], 0, s[54:55]
	v_mfma_f32_16x16x32_bf16 v[38:41], v[20:23], v[8:11], 0
	v_readfirstlane_b32 s45, v44
	s_mov_b32 m0, s45
	s_nop 0
	global_load_lds_dwordx4 v[42:43], off
	v_mfma_f32_16x16x32_bf16 v[42:45], v[20:23], v[12:15], 0
	v_mfma_f32_16x16x32_bf16 v[20:23], v[20:23], v[16:19], 0
	v_add_u32_e32 v29, 0x7000, v29
	v_lshl_add_u64 v[46:47], v[0:1], 0, s[96:97]
	v_readfirstlane_b32 s46, v29
	s_mov_b32 m0, s46
	s_nop 0
	global_load_lds_dwordx4 v[46:47], off
	v_mfma_f32_16x16x32_bf16 v[4:7], v[24:27], v[4:7], 0
	v_mfma_f32_16x16x32_bf16 v[8:11], v[24:27], v[8:11], 0
	v_readfirstlane_b32 s47, v48
	s_mov_b32 m0, s47
	s_nop 0
	global_load_lds_dwordx4 v[30:31], off
	v_mfma_f32_16x16x32_bf16 v[12:15], v[24:27], v[12:15], 0
	v_mfma_f32_16x16x32_bf16 v[16:19], v[24:27], v[16:19], 0
	s_setprio 0
	s_waitcnt vmcnt(3)
	s_waitcnt lgkmcnt(0)
	s_barrier
	ds_read_b128 v[24:27], v32 offset:12288
	ds_read_b128 v[46:49], v32 offset:13312
	ds_read_b128 v[50:53], v32 offset:14336
	ds_read_b128 v[54:57], v32 offset:15360
	ds_read_b128 v[58:61], v70 offset:20480
	ds_read_b128 v[62:65], v70 offset:21504
	s_setprio 1
	s_waitcnt lgkmcnt(0)
	v_mfma_f32_16x16x32_bf16 v[34:37], v[58:61], v[24:27], v[34:37]
	v_lshl_add_u64 v[30:31], v[2:3], 0, s[56:57]
	v_lshl_add_u64 v[66:67], v[0:1], 0, s[56:57]
	v_mfma_f32_16x16x32_bf16 v[38:41], v[58:61], v[46:49], v[38:41]
	s_mov_b32 m0, s44
	v_mfma_f32_16x16x32_bf16 v[42:45], v[58:61], v[50:53], v[42:45]
	global_load_lds_dwordx4 v[66:67], off
	v_mfma_f32_16x16x32_bf16 v[20:23], v[58:61], v[54:57], v[20:23]
	v_lshl_add_u64 v[58:59], v[0:1], 0, s[94:95]
	s_mov_b32 m0, s43
	v_mfma_f32_16x16x32_bf16 v[4:7], v[62:65], v[24:27], v[4:7]
	global_load_lds_dwordx4 v[58:59], off
	v_mfma_f32_16x16x32_bf16 v[8:11], v[62:65], v[46:49], v[8:11]
	s_mov_b32 m0, s42
	v_mfma_f32_16x16x32_bf16 v[12:15], v[62:65], v[50:53], v[12:15]
	global_load_lds_dwordx4 v[30:31], off
	v_mfma_f32_16x16x32_bf16 v[16:19], v[62:65], v[54:57], v[16:19]
	s_setprio 0
	s_waitcnt vmcnt(3)
	s_waitcnt lgkmcnt(0)
	s_barrier
	ds_read_b128 v[24:27], v32 offset:24576
	ds_read_b128 v[46:49], v32 offset:25600
	ds_read_b128 v[50:53], v32 offset:26624
	ds_read_b128 v[54:57], v32 offset:27648
	ds_read_b128 v[58:61], v70 offset:32768
	ds_read_b128 v[62:65], v70 offset:33792
	s_setprio 1
	s_waitcnt lgkmcnt(0)
	v_mfma_f32_16x16x32_bf16 v[34:37], v[58:61], v[24:27], v[34:37]
	v_lshl_add_u64 v[30:31], v[2:3], 0, s[58:59]
	v_lshl_add_u64 v[66:67], v[0:1], 0, s[58:59]
	v_mfma_f32_16x16x32_bf16 v[38:41], v[58:61], v[46:49], v[38:41]
	s_mov_b32 m0, s41
	v_mfma_f32_16x16x32_bf16 v[42:45], v[58:61], v[50:53], v[42:45]
	global_load_lds_dwordx4 v[66:67], off
	v_mfma_f32_16x16x32_bf16 v[20:23], v[58:61], v[54:57], v[20:23]
	v_lshl_add_u64 v[58:59], v[0:1], 0, s[70:71]
	s_mov_b32 m0, s40
	v_mfma_f32_16x16x32_bf16 v[4:7], v[62:65], v[24:27], v[4:7]
	global_load_lds_dwordx4 v[58:59], off
	v_mfma_f32_16x16x32_bf16 v[8:11], v[62:65], v[46:49], v[8:11]
	s_mov_b32 m0, s39
	v_mfma_f32_16x16x32_bf16 v[12:15], v[62:65], v[50:53], v[12:15]
	global_load_lds_dwordx4 v[30:31], off
	v_mfma_f32_16x16x32_bf16 v[16:19], v[62:65], v[54:57], v[16:19]
	s_setprio 0
	s_waitcnt vmcnt(3)
	s_waitcnt lgkmcnt(0)
	s_barrier
; #define RAW_BARRIER() do { asm volatile("s_waitcnt lgkmcnt(0)" ::: "memory"); __builtin_amdgcn_s_barrier(); } while (0)
; #define GLDS_TILE(kt, st) do { _Pragma("unroll") for (int _i = 0; _i < NP; ++_i) GLDS_PIECE(_i, kt, st); } while (0)
;     ...
;     constexpr int NH = NI >= 4 ? NI / 2 : NI;
;     constexpr int NP = 2 + NB, IVL = (4 * NI) / NP;
;     RAW_BARRIER();
;     GLDS_TILE(0, 0);
;     GLDS_TILE(1, 1);
;     int st = 0;
;     for (int kt = 0; kt < nk - 1; ++kt) {
;         if (NI == 8) asm volatile("s_waitcnt vmcnt(6)" ::: "memory"); else if (NI == 4) asm volatile("s_waitcnt vmcnt(4)" ::: "memory"); else asm volatile("s_waitcnt vmcnt(3)" ::: "memory");
;         RAW_BARRIER();
;         const int s2 = st >= 1 ? st - 1 : 2;
;         const bool ld = kt + 2 < nk;
;         STEP_TILE(st, ld, kt + 2, s2);
;         st = st == 2 ? 0 : st + 1;
;     }
	ds_read_b128 v[24:27], v32
	ds_read_b128 v[46:49], v32 offset:1024
	ds_read_b128 v[50:53], v32 offset:2048
	ds_read_b128 v[54:57], v32 offset:3072
	ds_read_b128 v[58:61], v70 offset:8192
	ds_read_b128 v[62:65], v70 offset:9216
	s_setprio 1
	s_waitcnt lgkmcnt(0)
	v_mfma_f32_16x16x32_bf16 v[34:37], v[58:61], v[24:27], v[34:37]
	v_lshl_add_u64 v[30:31], v[2:3], 0, s[60:61]
	v_lshl_add_u64 v[66:67], v[0:1], 0, s[60:61]
	v_mfma_f32_16x16x32_bf16 v[38:41], v[58:61], v[46:49], v[38:41]
	s_mov_b32 m0, s45
	v_mfma_f32_16x16x32_bf16 v[42:45], v[58:61], v[50:53], v[42:45]
	global_load_lds_dwordx4 v[66:67], off
	v_mfma_f32_16x16x32_bf16 v[20:23], v[58:61], v[54:57], v[20:23]
	v_lshl_add_u64 v[58:59], v[0:1], 0, s[72:73]
	s_mov_b32 m0, s46
	v_mfma_f32_16x16x32_bf16 v[4:7], v[62:65], v[24:27], v[4:7]
	global_load_lds_dwordx4 v[58:59], off
	v_mfma_f32_16x16x32_bf16 v[8:11], v[62:65], v[46:49], v[8:11]
	s_mov_b32 m0, s47
	v_mfma_f32_16x16x32_bf16 v[12:15], v[62:65], v[50:53], v[12:15]
	global_load_lds_dwordx4 v[30:31], off
	v_mfma_f32_16x16x32_bf16 v[16:19], v[62:65], v[54:57], v[16:19]
	s_setprio 0
	s_waitcnt vmcnt(3)
	s_waitcnt lgkmcnt(0)
	s_barrier
	ds_read_b128 v[24:27], v32 offset:12288
	ds_read_b128 v[46:49], v32 offset:13312
	ds_read_b128 v[50:53], v32 offset:14336
	ds_read_b128 v[54:57], v32 offset:15360
	ds_read_b128 v[58:61], v70 offset:20480
	ds_read_b128 v[62:65], v70 offset:21504
	s_setprio 1
	s_waitcnt lgkmcnt(0)
	v_mfma_f32_16x16x32_bf16 v[34:37], v[58:61], v[24:27], v[34:37]
	v_lshl_add_u64 v[30:31], v[2:3], 0, s[62:63]
	v_lshl_add_u64 v[66:67], v[0:1], 0, s[62:63]
	v_mfma_f32_16x16x32_bf16 v[38:41], v[58:61], v[46:49], v[38:41]
	s_mov_b32 m0, s44
	v_mfma_f32_16x16x32_bf16 v[42:45], v[58:61], v[50:53], v[42:45]
	global_load_lds_dwordx4 v[66:67], off
	v_mfma_f32_16x16x32_bf16 v[20:23], v[58:61], v[54:57], v[20:23]
	v_lshl_add_u64 v[58:59], v[0:1], 0, s[84:85]
	s_mov_b32 m0, s43
	v_mfma_f32_16x16x32_bf16 v[4:7], v[62:65], v[24:27], v[4:7]
	global_load_lds_dwordx4 v[58:59], off
	v_mfma_f32_16x16x32_bf16 v[8:11], v[62:65], v[46:49], v[8:11]
	s_mov_b32 m0, s42
	v_mfma_f32_16x16x32_bf16 v[12:15], v[62:65], v[50:53], v[12:15]
	global_load_lds_dwordx4 v[30:31], off
	v_mfma_f32_16x16x32_bf16 v[16:19], v[62:65], v[54:57], v[16:19]
	s_setprio 0
	s_waitcnt vmcnt(3)
	s_waitcnt lgkmcnt(0)
	s_barrier
	ds_read_b128 v[24:27], v32 offset:24576
	ds_read_b128 v[46:49], v32 offset:25600
	ds_read_b128 v[50:53], v32 offset:26624
	ds_read_b128 v[54:57], v32 offset:27648
	ds_read_b128 v[58:61], v70 offset:32768
	ds_read_b128 v[62:65], v70 offset:33792
	s_setprio 1
	s_waitcnt lgkmcnt(0)
	v_mfma_f32_16x16x32_bf16 v[34:37], v[58:61], v[24:27], v[34:37]
	v_lshl_add_u64 v[30:31], v[2:3], 0, s[64:65]
	v_lshl_add_u64 v[66:67], v[0:1], 0, s[64:65]
	v_mfma_f32_16x16x32_bf16 v[38:41], v[58:61], v[46:49], v[38:41]
	s_mov_b32 m0, s41
	v_mfma_f32_16x16x32_bf16 v[42:45], v[58:61], v[50:53], v[42:45]
	global_load_lds_dwordx4 v[66:67], off
	v_mfma_f32_16x16x32_bf16 v[20:23], v[58:61], v[54:57], v[20:23]
	s_mov_b64 vcc, 0xc1c0
	v_lshl_add_u64 v[58:59], v[0:1], 0, vcc
	s_mov_b32 m0, s40
	v_mfma_f32_16x16x32_bf16 v[4:7], v[62:65], v[24:27], v[4:7]
	global_load_lds_dwordx4 v[58:59], off
	v_mfma_f32_16x16x32_bf16 v[8:11], v[62:65], v[46:49], v[8:11]
	s_mov_b32 m0, s39
	v_mfma_f32_16x16x32_bf16 v[12:15], v[62:65], v[50:53], v[12:15]
	global_load_lds_dwordx4 v[30:31], off
	v_mfma_f32_16x16x32_bf16 v[16:19], v[62:65], v[54:57], v[16:19]
	s_setprio 0
	s_waitcnt vmcnt(3)
	s_waitcnt lgkmcnt(0)
	s_barrier
	ds_read_b128 v[24:27], v32
	ds_read_b128 v[46:49], v32 offset:1024
	ds_read_b128 v[50:53], v32 offset:2048
	ds_read_b128 v[54:57], v32 offset:3072
	ds_read_b128 v[58:61], v70 offset:8192
	ds_read_b128 v[62:65], v70 offset:9216
	s_setprio 1
	s_mov_b64 s[76:77], 0x200
	s_waitcnt lgkmcnt(0)
	v_mfma_f32_16x16x32_bf16 v[34:37], v[58:61], v[24:27], v[34:37]
	v_lshl_add_u64 v[30:31], v[2:3], 0, s[76:77]
	v_lshl_add_u64 v[66:67], v[0:1], 0, s[76:77]
	v_mfma_f32_16x16x32_bf16 v[38:41], v[58:61], v[46:49], v[38:41]
	s_mov_b32 m0, s45
	v_mfma_f32_16x16x32_bf16 v[42:45], v[58:61], v[50:53], v[42:45]
	global_load_lds_dwordx4 v[66:67], off
	v_mfma_f32_16x16x32_bf16 v[20:23], v[58:61], v[54:57], v[20:23]
	s_mov_b64 s[16:17], 0xc200
	v_lshl_add_u64 v[58:59], v[0:1], 0, s[16:17]
	s_mov_b32 m0, s46
	v_mfma_f32_16x16x32_bf16 v[4:7], v[62:65], v[24:27], v[4:7]
	global_load_lds_dwordx4 v[58:59], off
	v_mfma_f32_16x16x32_bf16 v[8:11], v[62:65], v[46:49], v[8:11]
	s_mov_b32 m0, s47
	v_mfma_f32_16x16x32_bf16 v[12:15], v[62:65], v[50:53], v[12:15]
	global_load_lds_dwordx4 v[30:31], off
	v_mfma_f32_16x16x32_bf16 v[16:19], v[62:65], v[54:57], v[16:19]
	s_setprio 0
	s_waitcnt vmcnt(3)
	s_waitcnt lgkmcnt(0)
	s_barrier
	ds_read_b128 v[24:27], v32 offset:12288
	ds_read_b128 v[46:49], v32 offset:13312
	ds_read_b128 v[50:53], v32 offset:14336
	ds_read_b128 v[54:57], v32 offset:15360
	ds_read_b128 v[58:61], v70 offset:20480
	ds_read_b128 v[62:65], v70 offset:21504
	s_setprio 1
	s_waitcnt lgkmcnt(0)
	v_mfma_f32_16x16x32_bf16 v[34:37], v[58:61], v[24:27], v[34:37]
	v_lshl_add_u64 v[30:31], v[2:3], 0, s[86:87]
	v_lshl_add_u64 v[66:67], v[0:1], 0, s[86:87]
	v_mfma_f32_16x16x32_bf16 v[38:41], v[58:61], v[46:49], v[38:41]
	s_mov_b32 m0, s44
	v_mfma_f32_16x16x32_bf16 v[42:45], v[58:61], v[50:53], v[42:45]
	global_load_lds_dwordx4 v[66:67], off
	v_mfma_f32_16x16x32_bf16 v[20:23], v[58:61], v[54:57], v[20:23]
	v_lshl_add_u64 v[58:59], v[0:1], 0, s[90:91]
	s_mov_b32 m0, s43
	v_mfma_f32_16x16x32_bf16 v[4:7], v[62:65], v[24:27], v[4:7]
	global_load_lds_dwordx4 v[58:59], off
	v_mfma_f32_16x16x32_bf16 v[8:11], v[62:65], v[46:49], v[8:11]
	s_mov_b32 m0, s42
	v_mfma_f32_16x16x32_bf16 v[12:15], v[62:65], v[50:53], v[12:15]
	global_load_lds_dwordx4 v[30:31], off
	v_mfma_f32_16x16x32_bf16 v[16:19], v[62:65], v[54:57], v[16:19]
	s_setprio 0
	s_waitcnt vmcnt(3)
	s_waitcnt lgkmcnt(0)
	s_barrier
;     __device__ __forceinline__ bf16_t* G() const { return (bf16_t*)(ws + OFF_G); }
; DEV void ld_bf4(const bf16_t* p, float (&v)[4]) { uint2 w = *(const uint2*)p; v[0] = bf_lo(w.x); v[1] = bf_hi(w.x); v[2] = bf_lo(w.y); v[3] = bf_hi(w.y); }
; #define RAW_BARRIER() do { asm volatile("s_waitcnt lgkmcnt(0)" ::: "memory"); __builtin_amdgcn_s_barrier(); } while (0)
;     ...
;     for (int kt = 0; kt < nk - 1; ++kt) {
;         if (NI == 8) asm volatile("s_waitcnt vmcnt(6)" ::: "memory"); else if (NI == 4) asm volatile("s_waitcnt vmcnt(4)" ::: "memory"); else asm volatile("s_waitcnt vmcnt(3)" ::: "memory");
;         RAW_BARRIER();
;         const int s2 = st >= 1 ? st - 1 : 2;
;         const bool ld = kt + 2 < nk;
;         STEP_TILE(st, ld, kt + 2, s2);
;         st = st == 2 ? 0 : st + 1;
;     }
;     asm volatile("s_waitcnt vmcnt(0)" ::: "memory");
;     RAW_BARRIER();
;     STEP_TILE(st, false, 0, 0);
;     RAW_BARRIER();
; DEV void merge_big(const Params& p, int l, int mt, int nt, char* smem) {
;     ...
; #pragma unroll
;         for (int mi = 0; mi < 4; ++mi)
; #pragma unroll
;             for (int ni = 0; ni < 2; ++ni) {
;                 float g[4]; ld_bf4(p.G() + (size_t)(rbase + mi * 16) * 3072 + br * 1024 + c0 + ni * 16, g);
;                 const f32x4 gv = (f32x4){g[0], g[1], g[2], g[3]};
;                 if (br == 0) mg[mi][ni] = gv * acc[mi][ni]; else mg[mi][ni] += gv * acc[mi][ni];
;             }
	ds_read_b128 v[24:27], v32 offset:24576
	ds_read_b128 v[46:49], v32 offset:25600
	ds_read_b128 v[50:53], v32 offset:26624
	ds_read_b128 v[54:57], v32 offset:27648
	ds_read_b128 v[58:61], v70 offset:32768
	ds_read_b128 v[62:65], v70 offset:33792
	s_setprio 1
	s_waitcnt lgkmcnt(0)
	v_mfma_f32_16x16x32_bf16 v[34:37], v[58:61], v[24:27], v[34:37]
	v_lshl_add_u64 v[30:31], v[2:3], 0, s[88:89]
	v_lshl_add_u64 v[66:67], v[0:1], 0, s[88:89]
	v_mfma_f32_16x16x32_bf16 v[38:41], v[58:61], v[46:49], v[38:41]
	s_mov_b32 m0, s41
	v_mfma_f32_16x16x32_bf16 v[42:45], v[58:61], v[50:53], v[42:45]
	global_load_lds_dwordx4 v[66:67], off
	v_mfma_f32_16x16x32_bf16 v[20:23], v[58:61], v[54:57], v[20:23]
	s_mov_b64 s[92:93], 0xc280
	v_lshl_add_u64 v[58:59], v[0:1], 0, s[92:93]
	s_mov_b32 m0, s40
	v_mfma_f32_16x16x32_bf16 v[4:7], v[62:65], v[24:27], v[4:7]
	global_load_lds_dwordx4 v[58:59], off
	v_mfma_f32_16x16x32_bf16 v[8:11], v[62:65], v[46:49], v[8:11]
	s_mov_b32 m0, s39
	v_mfma_f32_16x16x32_bf16 v[12:15], v[62:65], v[50:53], v[12:15]
	global_load_lds_dwordx4 v[30:31], off
	v_mfma_f32_16x16x32_bf16 v[16:19], v[62:65], v[54:57], v[16:19]
	s_setprio 0
	s_waitcnt vmcnt(3)
	s_waitcnt lgkmcnt(0)
	s_barrier
	ds_read_b128 v[24:27], v32
	ds_read_b128 v[46:49], v32 offset:1024
	ds_read_b128 v[50:53], v32 offset:2048
	ds_read_b128 v[54:57], v32 offset:3072
	ds_read_b128 v[58:61], v70 offset:8192
	ds_read_b128 v[62:65], v70 offset:9216
	s_setprio 1
	s_mov_b64 s[78:79], 0x2c0
	s_waitcnt lgkmcnt(0)
	v_mfma_f32_16x16x32_bf16 v[34:37], v[58:61], v[24:27], v[34:37]
	v_lshl_add_u64 v[30:31], v[2:3], 0, s[78:79]
	v_lshl_add_u64 v[2:3], v[0:1], 0, s[78:79]
	v_mfma_f32_16x16x32_bf16 v[38:41], v[58:61], v[46:49], v[38:41]
	s_mov_b32 m0, s45
	v_mfma_f32_16x16x32_bf16 v[42:45], v[58:61], v[50:53], v[42:45]
	global_load_lds_dwordx4 v[2:3], off
	v_mfma_f32_16x16x32_bf16 v[20:23], v[58:61], v[54:57], v[20:23]
	s_mov_b64 s[80:81], 0xc2c0
	v_lshl_add_u64 v[0:1], v[0:1], 0, s[80:81]
	s_mov_b32 m0, s46
	s_nop 0
	global_load_lds_dwordx4 v[0:1], off
	v_mfma_f32_16x16x32_bf16 v[0:3], v[62:65], v[24:27], v[4:7]
	v_mfma_f32_16x16x32_bf16 v[4:7], v[62:65], v[46:49], v[8:11]
	s_mov_b32 m0, s47
	s_nop 0
	global_load_lds_dwordx4 v[30:31], off
	v_mfma_f32_16x16x32_bf16 v[8:11], v[62:65], v[50:53], v[12:15]
	v_mfma_f32_16x16x32_bf16 v[12:15], v[62:65], v[54:57], v[16:19]
	s_setprio 0
	s_waitcnt vmcnt(3)
	s_waitcnt lgkmcnt(0)
	s_barrier
	s_nop 0
	ds_read_b128 v[16:19], v32 offset:12288
	ds_read_b128 v[24:27], v32 offset:13312
	ds_read_b128 v[46:49], v32 offset:14336
	ds_read_b128 v[50:53], v32 offset:15360
	ds_read_b128 v[54:57], v70 offset:20480
	ds_read_b128 v[58:61], v70 offset:21504
	s_setprio 1
	s_waitcnt lgkmcnt(0)
	v_mfma_f32_16x16x32_bf16 v[34:37], v[54:57], v[16:19], v[34:37]
	v_mfma_f32_16x16x32_bf16 v[38:41], v[54:57], v[24:27], v[38:41]
	v_mfma_f32_16x16x32_bf16 v[42:45], v[54:57], v[46:49], v[42:45]
	v_mfma_f32_16x16x32_bf16 v[20:23], v[54:57], v[50:53], v[20:23]
	v_mfma_f32_16x16x32_bf16 v[54:57], v[58:61], v[16:19], v[0:3]
	v_mfma_f32_16x16x32_bf16 v[62:65], v[58:61], v[24:27], v[4:7]
	v_mfma_f32_16x16x32_bf16 v[46:49], v[58:61], v[46:49], v[8:11]
	v_mfma_f32_16x16x32_bf16 v[50:53], v[58:61], v[50:53], v[12:15]
	s_setprio 0
	s_waitcnt vmcnt(0)
	s_waitcnt lgkmcnt(0)
	s_barrier
	ds_read_b128 v[4:7], v32 offset:24576
	ds_read_b128 v[12:15], v32 offset:25600
	ds_read_b128 v[58:61], v32 offset:26624
	ds_read_b128 v[66:69], v32 offset:27648
	ds_read_b128 v[24:27], v70 offset:32768
	ds_read_b128 v[70:73], v70 offset:33792
	s_setprio 1
	s_waitcnt lgkmcnt(0)
	v_mfma_f32_16x16x32_bf16 v[0:3], v[24:27], v[4:7], v[34:37]
	v_mfma_f32_16x16x32_bf16 v[8:11], v[24:27], v[12:15], v[38:41]
	v_mfma_f32_16x16x32_bf16 v[16:19], v[24:27], v[58:61], v[42:45]
	v_mfma_f32_16x16x32_bf16 v[24:27], v[24:27], v[66:69], v[20:23]
	v_mfma_f32_16x16x32_bf16 v[4:7], v[70:73], v[4:7], v[54:57]
	v_mfma_f32_16x16x32_bf16 v[12:15], v[70:73], v[12:15], v[62:65]
	v_mfma_f32_16x16x32_bf16 v[20:23], v[70:73], v[58:61], v[46:49]
	v_mfma_f32_16x16x32_bf16 v[38:41], v[70:73], v[66:69], v[50:53]
	s_setprio 0
	v_lshlrev_b32_e32 v32, 1, v28
	v_lshl_add_u64 v[28:29], s[0:1], 0, v[32:33]
	v_mad_i64_i32 v[30:31], s[40:41], v94, s51, v[28:29]
	v_or_b32_e32 v100, 16, v94
	v_or_b32_e32 v98, 32, v94
	v_or_b32_e32 v96, 48, v94
	s_waitcnt lgkmcnt(0)
	s_barrier
	v_mad_i64_i32 v[34:35], s[40:41], v100, s51, v[28:29]
	s_waitcnt vmcnt(0)
	flat_load_dwordx2 v[102:103], v[30:31]
	flat_load_dwordx2 v[104:105], v[30:31] offset:32
	flat_load_dwordx2 v[106:107], v[34:35]
	flat_load_dwordx2 v[108:109], v[34:35] offset:32
	v_mad_i64_i32 v[30:31], s[40:41], v98, s51, v[28:29]
	v_mad_i64_i32 v[28:29], s[40:41], v96, s51, v[28:29]
	v_mov_b32_e32 v42, v186
	flat_load_dwordx2 v[110:111], v[30:31]
	flat_load_dwordx2 v[112:113], v[30:31] offset:32
	flat_load_dwordx2 v[114:115], v[28:29]
	flat_load_dwordx2 v[122:123], v[28:29] offset:32
	s_add_u32 s38, s18, s38
	s_addc_u32 s39, s19, s35
	v_ashrrev_i32_e32 v43, 6, v42
	v_bfe_u32 v44, v42, 4, 2
	v_bfe_u32 v28, v42, 2, 4
	v_lshl_or_b32 v36, v43, 4, v28
	v_sub_u32_e32 v28, 0, v44
	s_add_u32 s34, s20, s34
	v_xor_b32_e32 v30, v42, v28
	s_addc_u32 s35, s21, 0
	v_mov_b64_e32 v[28:29], s[38:39]
	v_lshlrev_b32_e32 v30, 4, v30
	v_lshl_add_u32 v78, v43, 10, 0
	v_mad_i64_i32 v[28:29], s[38:39], v36, s48, v[28:29]
	v_and_b32_e32 v30, 48, v30
	v_mov_b32_e32 v31, v33
	v_mov_b64_e32 v[34:35], s[34:35]
	v_readfirstlane_b32 s44, v78
	v_add_u32_e32 v37, 0x1000, v78
	v_lshl_add_u64 v[28:29], v[28:29], 0, v[30:31]
	v_mad_i64_i32 v[34:35], s[34:35], v36, s48, v[34:35]
	v_add_u32_e32 v36, 0x2000, v78
	s_mov_b32 m0, s44
	v_readfirstlane_b32 s43, v37
	v_lshl_add_u64 v[30:31], v[34:35], 0, v[30:31]
	s_waitcnt lgkmcnt(0)
	s_barrier
; DEV int tid_opaque() { int t = threadIdx.x; asm volatile("" : "+v"(t)); return t; }
; #define RAW_BARRIER() do { asm volatile("s_waitcnt lgkmcnt(0)" ::: "memory"); __builtin_amdgcn_s_barrier(); } while (0)
; #define GLDS_TILE(kt, st) do { _Pragma("unroll") for (int _i = 0; _i < NP; ++_i) GLDS_PIECE(_i, kt, st); } while (0)
;     constexpr int BROWS = 32 * NI, STAGE = 8192 + BROWS * 64, NB = BROWS / 64;
;     const int t = tid_opaque(), lane = t & 63, wid = t >> 6, wm = wid >> 1, wn = wid & 1, fr = lane & 15, fq = lane >> 4;
;     const int nk = K >> 5;
;     const int srow = wid * 16 + (lane >> 2), sch = (lane & 3) ^ ((0 - (lane >> 4)) & 3);
;     const bf16_t* ga = A + (size_t)srow * lda + sch * 8;
;     const bf16_t* gb = B + (size_t)srow * ldb + sch * 8;
;     const int rd = fr * 64 + ((fq ^ ((0 - (fr >> 2)) & 3)) << 4);
;     const int rda = (wm * 64) * 64 + rd, rdb = 8192 + (wn * 16 * NI) * 64 + rd;
;     ...
;     constexpr int NH = NI >= 4 ? NI / 2 : NI;
;     constexpr int NP = 2 + NB, IVL = (4 * NI) / NP;
;     RAW_BARRIER();
;     GLDS_TILE(0, 0);
;     GLDS_TILE(1, 1);
;     int st = 0;
;     for (int kt = 0; kt < nk - 1; ++kt) {
;         if (NI == 8) asm volatile("s_waitcnt vmcnt(6)" ::: "memory"); else if (NI == 4) asm volatile("s_waitcnt vmcnt(4)" ::: "memory"); else asm volatile("s_waitcnt vmcnt(3)" ::: "memory");
;         RAW_BARRIER();
;         const int s2 = st >= 1 ? st - 1 : 2;
;         const bool ld = kt + 2 < nk;
;         STEP_TILE(st, ld, kt + 2, s2);
;         st = st == 2 ? 0 : st + 1;
;     }
	global_load_lds_dwordx4 v[28:29], off
	v_lshl_add_u64 v[34:35], v[28:29], 0, s[66:67]
	s_mov_b32 m0, s43
	v_readfirstlane_b32 s42, v36
	v_add_u32_e32 v45, 0x3000, v78
	global_load_lds_dwordx4 v[34:35], off
	s_mov_b32 m0, s42
	v_readfirstlane_b32 s38, v45
	v_add_u32_e32 v45, 0x4000, v78
	global_load_lds_dwordx4 v[30:31], off
	v_add_u32_e32 v46, 0x5000, v78
	v_lshl_add_u64 v[36:37], v[28:29], 0, 64
	s_mov_b32 m0, s38
	v_readfirstlane_b32 s35, v45
	global_load_lds_dwordx4 v[36:37], off
	v_lshl_add_u64 v[36:37], v[28:29], 0, s[68:69]
	s_mov_b32 m0, s35
	v_readfirstlane_b32 s34, v46
	v_lshl_add_u64 v[34:35], v[30:31], 0, 64
	global_load_lds_dwordx4 v[36:37], off
	s_mov_b32 m0, s34
	v_lshlrev_b32_e32 v36, 11, v43
	global_load_lds_dwordx4 v[34:35], off
	v_lshrrev_b32_e32 v35, 2, v42
	v_lshlrev_b32_e32 v34, 6, v42
	v_sub_u32_e32 v35, 0, v35
	v_and_b32_e32 v34, 0x3c0, v34
	v_bitop3_b32 v35, v44, v35, 3 bitop3:0x78
	v_lshl_or_b32 v34, v35, 4, v34
	v_lshlrev_b32_e32 v35, 5, v42
	v_and_or_b32 v35, v35, s49, v34
	s_waitcnt vmcnt(3)
	v_add_u32_e32 v120, 0, v35
	v_and_or_b32 v54, v36, s50, v34
	s_waitcnt lgkmcnt(0)
	s_barrier
	ds_read_b128 v[34:37], v120
	ds_read_b128 v[42:45], v120 offset:1024
	ds_read_b128 v[46:49], v120 offset:2048
	ds_read_b128 v[50:53], v120 offset:3072
	v_add_u32_e32 v121, 0, v54
	ds_read_b128 v[54:57], v121 offset:8192
	ds_read_b128 v[58:61], v121 offset:9216
	v_ashrrev_i32_e32 v95, 31, v94
	v_ashrrev_i32_e32 v101, 31, v100
	v_ashrrev_i32_e32 v99, 31, v98
	v_ashrrev_i32_e32 v97, 31, v96
	s_setprio 1
	v_add_u32_e32 v72, 0x6000, v78
	s_waitcnt lgkmcnt(0)
	v_mfma_f32_16x16x32_bf16 v[62:65], v[54:57], v[34:37], 0
	v_lshl_add_u64 v[74:75], v[30:31], 0, s[54:55]
	v_add_u32_e32 v79, 0x8000, v78
	v_lshl_add_u64 v[70:71], v[28:29], 0, s[54:55]
	v_mfma_f32_16x16x32_bf16 v[66:69], v[54:57], v[42:45], 0
	v_readfirstlane_b32 s39, v72
	s_mov_b32 m0, s39
	s_nop 0
	global_load_lds_dwordx4 v[70:71], off
	v_mfma_f32_16x16x32_bf16 v[70:73], v[54:57], v[46:49], 0
	v_mfma_f32_16x16x32_bf16 v[54:57], v[54:57], v[50:53], 0
	v_add_u32_e32 v78, 0x7000, v78
	v_lshl_add_u64 v[76:77], v[28:29], 0, s[96:97]
	v_readfirstlane_b32 s40, v78
	s_mov_b32 m0, s40
	s_nop 0
	global_load_lds_dwordx4 v[76:77], off
	v_mfma_f32_16x16x32_bf16 v[34:37], v[58:61], v[34:37], 0
	v_mfma_f32_16x16x32_bf16 v[42:45], v[58:61], v[42:45], 0
	v_readfirstlane_b32 s41, v79
	s_mov_b32 m0, s41
	s_nop 0
	global_load_lds_dwordx4 v[74:75], off
	v_mfma_f32_16x16x32_bf16 v[46:49], v[58:61], v[46:49], 0
	v_mfma_f32_16x16x32_bf16 v[50:53], v[58:61], v[50:53], 0
	s_setprio 0
	s_waitcnt vmcnt(3)
	s_waitcnt lgkmcnt(0)
	s_barrier
	ds_read_b128 v[58:61], v120 offset:12288
	ds_read_b128 v[74:77], v120 offset:13312
	ds_read_b128 v[78:81], v120 offset:14336
	ds_read_b128 v[82:85], v120 offset:15360
	ds_read_b128 v[86:89], v121 offset:20480
	ds_read_b128 v[90:93], v121 offset:21504
	s_setprio 1
	s_waitcnt lgkmcnt(0)
	v_mfma_f32_16x16x32_bf16 v[62:65], v[86:89], v[58:61], v[62:65]
	v_lshl_add_u64 v[116:117], v[30:31], 0, s[56:57]
	v_lshl_add_u64 v[118:119], v[28:29], 0, s[56:57]
	v_mfma_f32_16x16x32_bf16 v[66:69], v[86:89], v[74:77], v[66:69]
	s_mov_b32 m0, s44
	v_mfma_f32_16x16x32_bf16 v[70:73], v[86:89], v[78:81], v[70:73]
	global_load_lds_dwordx4 v[118:119], off
	v_mfma_f32_16x16x32_bf16 v[54:57], v[86:89], v[82:85], v[54:57]
	v_lshl_add_u64 v[86:87], v[28:29], 0, s[94:95]
	s_mov_b32 m0, s43
	v_mfma_f32_16x16x32_bf16 v[34:37], v[90:93], v[58:61], v[34:37]
	global_load_lds_dwordx4 v[86:87], off
	v_mfma_f32_16x16x32_bf16 v[42:45], v[90:93], v[74:77], v[42:45]
	s_mov_b32 m0, s42
	v_mfma_f32_16x16x32_bf16 v[46:49], v[90:93], v[78:81], v[46:49]
	global_load_lds_dwordx4 v[116:117], off
	v_mfma_f32_16x16x32_bf16 v[50:53], v[90:93], v[82:85], v[50:53]
	s_setprio 0
	s_waitcnt vmcnt(3)
	s_waitcnt lgkmcnt(0)
	s_barrier
	ds_read_b128 v[58:61], v120 offset:24576
	ds_read_b128 v[74:77], v120 offset:25600
	ds_read_b128 v[78:81], v120 offset:26624
	ds_read_b128 v[82:85], v120 offset:27648
	ds_read_b128 v[86:89], v121 offset:32768
	ds_read_b128 v[90:93], v121 offset:33792
	s_setprio 1
	s_waitcnt lgkmcnt(0)
	v_mfma_f32_16x16x32_bf16 v[62:65], v[86:89], v[58:61], v[62:65]
	v_lshl_add_u64 v[116:117], v[30:31], 0, s[58:59]
	v_lshl_add_u64 v[118:119], v[28:29], 0, s[58:59]
	v_mfma_f32_16x16x32_bf16 v[66:69], v[86:89], v[74:77], v[66:69]
	s_mov_b32 m0, s38
	v_mfma_f32_16x16x32_bf16 v[70:73], v[86:89], v[78:81], v[70:73]
	global_load_lds_dwordx4 v[118:119], off
	v_mfma_f32_16x16x32_bf16 v[54:57], v[86:89], v[82:85], v[54:57]
	v_lshl_add_u64 v[86:87], v[28:29], 0, s[70:71]
	s_mov_b32 m0, s35
	v_mfma_f32_16x16x32_bf16 v[34:37], v[90:93], v[58:61], v[34:37]
	global_load_lds_dwordx4 v[86:87], off
	v_mfma_f32_16x16x32_bf16 v[42:45], v[90:93], v[74:77], v[42:45]
	s_mov_b32 m0, s34
	v_mfma_f32_16x16x32_bf16 v[46:49], v[90:93], v[78:81], v[46:49]
	global_load_lds_dwordx4 v[116:117], off
	v_mfma_f32_16x16x32_bf16 v[50:53], v[90:93], v[82:85], v[50:53]
	s_setprio 0
	s_waitcnt vmcnt(3)
	s_waitcnt lgkmcnt(0)
	s_barrier
	ds_read_b128 v[58:61], v120
	ds_read_b128 v[74:77], v120 offset:1024
	ds_read_b128 v[78:81], v120 offset:2048
	ds_read_b128 v[82:85], v120 offset:3072
	ds_read_b128 v[86:89], v121 offset:8192
	ds_read_b128 v[90:93], v121 offset:9216
	s_setprio 1
	s_waitcnt lgkmcnt(0)
	v_mfma_f32_16x16x32_bf16 v[62:65], v[86:89], v[58:61], v[62:65]
	v_lshl_add_u64 v[116:117], v[30:31], 0, s[60:61]
	v_lshl_add_u64 v[118:119], v[28:29], 0, s[60:61]
	v_mfma_f32_16x16x32_bf16 v[66:69], v[86:89], v[74:77], v[66:69]
	s_mov_b32 m0, s39
	v_mfma_f32_16x16x32_bf16 v[70:73], v[86:89], v[78:81], v[70:73]
	global_load_lds_dwordx4 v[118:119], off
	v_mfma_f32_16x16x32_bf16 v[54:57], v[86:89], v[82:85], v[54:57]
	v_lshl_add_u64 v[86:87], v[28:29], 0, s[72:73]
	s_mov_b32 m0, s40
	v_mfma_f32_16x16x32_bf16 v[34:37], v[90:93], v[58:61], v[34:37]
	global_load_lds_dwordx4 v[86:87], off
	v_mfma_f32_16x16x32_bf16 v[42:45], v[90:93], v[74:77], v[42:45]
	s_mov_b32 m0, s41
	v_mfma_f32_16x16x32_bf16 v[46:49], v[90:93], v[78:81], v[46:49]
	global_load_lds_dwordx4 v[116:117], off
	v_mfma_f32_16x16x32_bf16 v[50:53], v[90:93], v[82:85], v[50:53]
	s_setprio 0
	s_waitcnt vmcnt(3)
	s_waitcnt lgkmcnt(0)
	s_barrier
; #define RAW_BARRIER() do { asm volatile("s_waitcnt lgkmcnt(0)" ::: "memory"); __builtin_amdgcn_s_barrier(); } while (0)
; #define GLDS_TILE(kt, st) do { _Pragma("unroll") for (int _i = 0; _i < NP; ++_i) GLDS_PIECE(_i, kt, st); } while (0)
;     ...
;     constexpr int NH = NI >= 4 ? NI / 2 : NI;
;     constexpr int NP = 2 + NB, IVL = (4 * NI) / NP;
;     RAW_BARRIER();
;     GLDS_TILE(0, 0);
;     GLDS_TILE(1, 1);
;     int st = 0;
;     for (int kt = 0; kt < nk - 1; ++kt) {
;         if (NI == 8) asm volatile("s_waitcnt vmcnt(6)" ::: "memory"); else if (NI == 4) asm volatile("s_waitcnt vmcnt(4)" ::: "memory"); else asm volatile("s_waitcnt vmcnt(3)" ::: "memory");
;         RAW_BARRIER();
;         const int s2 = st >= 1 ? st - 1 : 2;
;         const bool ld = kt + 2 < nk;
;         STEP_TILE(st, ld, kt + 2, s2);
;         st = st == 2 ? 0 : st + 1;
;     }
	ds_read_b128 v[58:61], v120 offset:12288
	ds_read_b128 v[74:77], v120 offset:13312
	ds_read_b128 v[78:81], v120 offset:14336
	ds_read_b128 v[82:85], v120 offset:15360
	ds_read_b128 v[86:89], v121 offset:20480
	ds_read_b128 v[90:93], v121 offset:21504
	s_setprio 1
	s_waitcnt lgkmcnt(0)
	v_mfma_f32_16x16x32_bf16 v[62:65], v[86:89], v[58:61], v[62:65]
	v_lshl_add_u64 v[116:117], v[30:31], 0, s[62:63]
	v_lshl_add_u64 v[118:119], v[28:29], 0, s[62:63]
	v_mfma_f32_16x16x32_bf16 v[66:69], v[86:89], v[74:77], v[66:69]
	s_mov_b32 m0, s44
	v_mfma_f32_16x16x32_bf16 v[70:73], v[86:89], v[78:81], v[70:73]
	global_load_lds_dwordx4 v[118:119], off
	v_mfma_f32_16x16x32_bf16 v[54:57], v[86:89], v[82:85], v[54:57]
	v_lshl_add_u64 v[86:87], v[28:29], 0, s[84:85]
	s_mov_b32 m0, s43
	v_mfma_f32_16x16x32_bf16 v[34:37], v[90:93], v[58:61], v[34:37]
	global_load_lds_dwordx4 v[86:87], off
	v_mfma_f32_16x16x32_bf16 v[42:45], v[90:93], v[74:77], v[42:45]
	s_mov_b32 m0, s42
	v_mfma_f32_16x16x32_bf16 v[46:49], v[90:93], v[78:81], v[46:49]
	global_load_lds_dwordx4 v[116:117], off
	v_mfma_f32_16x16x32_bf16 v[50:53], v[90:93], v[82:85], v[50:53]
	s_setprio 0
	s_waitcnt vmcnt(3)
	s_waitcnt lgkmcnt(0)
	s_barrier
	ds_read_b128 v[58:61], v120 offset:24576
	ds_read_b128 v[74:77], v120 offset:25600
	ds_read_b128 v[78:81], v120 offset:26624
	ds_read_b128 v[82:85], v120 offset:27648
	ds_read_b128 v[86:89], v121 offset:32768
	ds_read_b128 v[90:93], v121 offset:33792
	s_setprio 1
	s_waitcnt lgkmcnt(0)
	v_mfma_f32_16x16x32_bf16 v[62:65], v[86:89], v[58:61], v[62:65]
	v_lshl_add_u64 v[116:117], v[30:31], 0, s[64:65]
	v_lshl_add_u64 v[118:119], v[28:29], 0, s[64:65]
	v_mfma_f32_16x16x32_bf16 v[66:69], v[86:89], v[74:77], v[66:69]
	s_mov_b32 m0, s38
	v_mfma_f32_16x16x32_bf16 v[70:73], v[86:89], v[78:81], v[70:73]
	global_load_lds_dwordx4 v[118:119], off
	v_mfma_f32_16x16x32_bf16 v[54:57], v[86:89], v[82:85], v[54:57]
	v_lshl_add_u64 v[86:87], v[28:29], 0, vcc
	s_mov_b32 m0, s35
	v_mfma_f32_16x16x32_bf16 v[34:37], v[90:93], v[58:61], v[34:37]
	global_load_lds_dwordx4 v[86:87], off
	v_mfma_f32_16x16x32_bf16 v[42:45], v[90:93], v[74:77], v[42:45]
	s_mov_b32 m0, s34
	v_mfma_f32_16x16x32_bf16 v[46:49], v[90:93], v[78:81], v[46:49]
	global_load_lds_dwordx4 v[116:117], off
	v_mfma_f32_16x16x32_bf16 v[50:53], v[90:93], v[82:85], v[50:53]
	s_setprio 0
	s_waitcnt vmcnt(3)
	s_waitcnt lgkmcnt(0)
	s_barrier
	ds_read_b128 v[58:61], v120
	ds_read_b128 v[74:77], v120 offset:1024
	ds_read_b128 v[78:81], v120 offset:2048
	ds_read_b128 v[82:85], v120 offset:3072
	ds_read_b128 v[86:89], v121 offset:8192
	ds_read_b128 v[90:93], v121 offset:9216
	s_setprio 1
	s_waitcnt lgkmcnt(0)
	v_mfma_f32_16x16x32_bf16 v[62:65], v[86:89], v[58:61], v[62:65]
	v_lshl_add_u64 v[116:117], v[30:31], 0, s[76:77]
	v_lshl_add_u64 v[118:119], v[28:29], 0, s[76:77]
	s_mov_b64 s[76:77], 0x8040
	s_mov_b64 s[46:47], 0x8000
	v_mfma_f32_16x16x32_bf16 v[66:69], v[86:89], v[74:77], v[66:69]
	s_mov_b32 m0, s39
	v_mfma_f32_16x16x32_bf16 v[70:73], v[86:89], v[78:81], v[70:73]
	global_load_lds_dwordx4 v[118:119], off
	v_mfma_f32_16x16x32_bf16 v[54:57], v[86:89], v[82:85], v[54:57]
	v_lshl_add_u64 v[86:87], v[28:29], 0, s[16:17]
	s_mov_b32 m0, s40
	v_mfma_f32_16x16x32_bf16 v[34:37], v[90:93], v[58:61], v[34:37]
	global_load_lds_dwordx4 v[86:87], off
	v_mfma_f32_16x16x32_bf16 v[42:45], v[90:93], v[74:77], v[42:45]
	s_mov_b32 m0, s41
	v_mfma_f32_16x16x32_bf16 v[46:49], v[90:93], v[78:81], v[46:49]
	global_load_lds_dwordx4 v[116:117], off
	v_mfma_f32_16x16x32_bf16 v[50:53], v[90:93], v[82:85], v[50:53]
	s_setprio 0
	s_waitcnt vmcnt(3)
	s_waitcnt lgkmcnt(0)
	s_barrier
	ds_read_b128 v[58:61], v120 offset:12288
	ds_read_b128 v[74:77], v120 offset:13312
	ds_read_b128 v[78:81], v120 offset:14336
	ds_read_b128 v[82:85], v120 offset:15360
	ds_read_b128 v[86:89], v121 offset:20480
	ds_read_b128 v[90:93], v121 offset:21504
	s_setprio 1
	s_waitcnt lgkmcnt(0)
	v_mfma_f32_16x16x32_bf16 v[62:65], v[86:89], v[58:61], v[62:65]
	v_lshl_add_u64 v[116:117], v[30:31], 0, s[86:87]
	v_lshl_add_u64 v[118:119], v[28:29], 0, s[86:87]
	v_mfma_f32_16x16x32_bf16 v[66:69], v[86:89], v[74:77], v[66:69]
	s_mov_b32 m0, s44
	v_mfma_f32_16x16x32_bf16 v[70:73], v[86:89], v[78:81], v[70:73]
	global_load_lds_dwordx4 v[118:119], off
	v_mfma_f32_16x16x32_bf16 v[54:57], v[86:89], v[82:85], v[54:57]
	v_lshl_add_u64 v[86:87], v[28:29], 0, s[90:91]
	s_mov_b32 m0, s43
	v_mfma_f32_16x16x32_bf16 v[34:37], v[90:93], v[58:61], v[34:37]
	global_load_lds_dwordx4 v[86:87], off
	v_mfma_f32_16x16x32_bf16 v[42:45], v[90:93], v[74:77], v[42:45]
	s_mov_b32 m0, s42
	v_mfma_f32_16x16x32_bf16 v[46:49], v[90:93], v[78:81], v[46:49]
	global_load_lds_dwordx4 v[116:117], off
	v_mfma_f32_16x16x32_bf16 v[50:53], v[90:93], v[82:85], v[50:53]
	s_setprio 0
	s_waitcnt vmcnt(3)
	s_waitcnt lgkmcnt(0)
	s_barrier
	ds_read_b128 v[58:61], v120 offset:24576
	ds_read_b128 v[74:77], v120 offset:25600
	ds_read_b128 v[78:81], v120 offset:26624
	ds_read_b128 v[82:85], v120 offset:27648
	ds_read_b128 v[86:89], v121 offset:32768
	ds_read_b128 v[90:93], v121 offset:33792
	s_setprio 1
	s_waitcnt lgkmcnt(0)
	v_mfma_f32_16x16x32_bf16 v[62:65], v[86:89], v[58:61], v[62:65]
	v_lshl_add_u64 v[116:117], v[30:31], 0, s[88:89]
	v_lshl_add_u64 v[118:119], v[28:29], 0, s[88:89]
	v_mfma_f32_16x16x32_bf16 v[66:69], v[86:89], v[74:77], v[66:69]
	s_mov_b32 m0, s38
	v_mfma_f32_16x16x32_bf16 v[70:73], v[86:89], v[78:81], v[70:73]
	global_load_lds_dwordx4 v[118:119], off
	v_mfma_f32_16x16x32_bf16 v[54:57], v[86:89], v[82:85], v[54:57]
	v_lshl_add_u64 v[86:87], v[28:29], 0, s[92:93]
	s_mov_b32 m0, s35
	v_mfma_f32_16x16x32_bf16 v[34:37], v[90:93], v[58:61], v[34:37]
	global_load_lds_dwordx4 v[86:87], off
	v_mfma_f32_16x16x32_bf16 v[42:45], v[90:93], v[74:77], v[42:45]
	s_mov_b32 m0, s34
	v_mfma_f32_16x16x32_bf16 v[46:49], v[90:93], v[78:81], v[46:49]
	global_load_lds_dwordx4 v[116:117], off
	v_mfma_f32_16x16x32_bf16 v[50:53], v[90:93], v[82:85], v[50:53]
	s_setprio 0
	s_waitcnt vmcnt(3)
	s_waitcnt lgkmcnt(0)
	s_barrier
;     __device__ __forceinline__ bf16_t* G() const { return (bf16_t*)(ws + OFF_G); }
; DEV void ld_bf4(const bf16_t* p, float (&v)[4]) { uint2 w = *(const uint2*)p; v[0] = bf_lo(w.x); v[1] = bf_hi(w.x); v[2] = bf_lo(w.y); v[3] = bf_hi(w.y); }
; #define RAW_BARRIER() do { asm volatile("s_waitcnt lgkmcnt(0)" ::: "memory"); __builtin_amdgcn_s_barrier(); } while (0)
;     ...
;     for (int kt = 0; kt < nk - 1; ++kt) {
;         if (NI == 8) asm volatile("s_waitcnt vmcnt(6)" ::: "memory"); else if (NI == 4) asm volatile("s_waitcnt vmcnt(4)" ::: "memory"); else asm volatile("s_waitcnt vmcnt(3)" ::: "memory");
;         RAW_BARRIER();
;         const int s2 = st >= 1 ? st - 1 : 2;
;         const bool ld = kt + 2 < nk;
;         STEP_TILE(st, ld, kt + 2, s2);
;         st = st == 2 ? 0 : st + 1;
;     }
;     asm volatile("s_waitcnt vmcnt(0)" ::: "memory");
;     RAW_BARRIER();
;     STEP_TILE(st, false, 0, 0);
;     RAW_BARRIER();
; DEV void merge_big(const Params& p, int l, int mt, int nt, char* smem) {
;     ...
; #pragma unroll
;         for (int mi = 0; mi < 4; ++mi)
; #pragma unroll
;             for (int ni = 0; ni < 2; ++ni) {
;                 float g[4]; ld_bf4(p.G() + (size_t)(rbase + mi * 16) * 3072 + br * 1024 + c0 + ni * 16, g);
;                 const f32x4 gv = (f32x4){g[0], g[1], g[2], g[3]};
;                 if (br == 0) mg[mi][ni] = gv * acc[mi][ni]; else mg[mi][ni] += gv * acc[mi][ni];
;             }
	ds_read_b128 v[58:61], v120
	ds_read_b128 v[74:77], v120 offset:1024
	ds_read_b128 v[78:81], v120 offset:2048
	ds_read_b128 v[82:85], v120 offset:3072
	ds_read_b128 v[86:89], v121 offset:8192
	ds_read_b128 v[90:93], v121 offset:9216
	s_setprio 1
	s_waitcnt lgkmcnt(0)
	v_mfma_f32_16x16x32_bf16 v[62:65], v[86:89], v[58:61], v[62:65]
	v_lshl_add_u64 v[116:117], v[30:31], 0, s[78:79]
	v_lshl_add_u64 v[30:31], v[28:29], 0, s[78:79]
	v_mfma_f32_16x16x32_bf16 v[66:69], v[86:89], v[74:77], v[66:69]
	s_mov_b32 m0, s39
	v_mfma_f32_16x16x32_bf16 v[70:73], v[86:89], v[78:81], v[70:73]
	global_load_lds_dwordx4 v[30:31], off
	v_mfma_f32_16x16x32_bf16 v[54:57], v[86:89], v[82:85], v[54:57]
	v_lshl_add_u64 v[28:29], v[28:29], 0, s[80:81]
	s_mov_b32 m0, s40
	s_nop 0
	global_load_lds_dwordx4 v[28:29], off
	v_mfma_f32_16x16x32_bf16 v[28:31], v[90:93], v[58:61], v[34:37]
	v_mfma_f32_16x16x32_bf16 v[34:37], v[90:93], v[74:77], v[42:45]
	s_mov_b32 m0, s41
	s_nop 0
	global_load_lds_dwordx4 v[116:117], off
	v_mfma_f32_16x16x32_bf16 v[42:45], v[90:93], v[78:81], v[46:49]
	v_mfma_f32_16x16x32_bf16 v[46:49], v[90:93], v[82:85], v[50:53]
	s_setprio 0
	s_waitcnt vmcnt(3)
	s_waitcnt lgkmcnt(0)
	s_barrier
	s_nop 0
	ds_read_b128 v[50:53], v120 offset:12288
	ds_read_b128 v[58:61], v120 offset:13312
	ds_read_b128 v[74:77], v120 offset:14336
	ds_read_b128 v[78:81], v120 offset:15360
	ds_read_b128 v[82:85], v121 offset:20480
	ds_read_b128 v[86:89], v121 offset:21504
	s_setprio 1
	s_waitcnt lgkmcnt(0)
	v_mfma_f32_16x16x32_bf16 v[62:65], v[82:85], v[50:53], v[62:65]
	v_mfma_f32_16x16x32_bf16 v[66:69], v[82:85], v[58:61], v[66:69]
	v_mfma_f32_16x16x32_bf16 v[70:73], v[82:85], v[74:77], v[70:73]
	v_mfma_f32_16x16x32_bf16 v[54:57], v[82:85], v[78:81], v[54:57]
	v_mfma_f32_16x16x32_bf16 v[82:85], v[86:89], v[50:53], v[28:31]
	v_mfma_f32_16x16x32_bf16 v[58:61], v[86:89], v[58:61], v[34:37]
	v_mfma_f32_16x16x32_bf16 v[74:77], v[86:89], v[74:77], v[42:45]
	v_mfma_f32_16x16x32_bf16 v[78:81], v[86:89], v[78:81], v[46:49]
	s_setprio 0
	s_waitcnt vmcnt(0)
	s_waitcnt lgkmcnt(0)
	s_barrier
	ds_read_b128 v[34:37], v120 offset:24576
	ds_read_b128 v[46:49], v120 offset:25600
	ds_read_b128 v[86:89], v120 offset:26624
	ds_read_b128 v[90:93], v120 offset:27648
	ds_read_b128 v[116:119], v121 offset:32768
	ds_read_b128 v[124:127], v121 offset:33792
	s_setprio 1
	s_waitcnt lgkmcnt(0)
	v_mfma_f32_16x16x32_bf16 v[28:31], v[116:119], v[34:37], v[62:65]
	v_mfma_f32_16x16x32_bf16 v[42:45], v[116:119], v[46:49], v[66:69]
	v_mfma_f32_16x16x32_bf16 v[50:53], v[116:119], v[86:89], v[70:73]
	v_mfma_f32_16x16x32_bf16 v[66:69], v[116:119], v[90:93], v[54:57]
	v_mfma_f32_16x16x32_bf16 v[34:37], v[124:127], v[34:37], v[82:85]
	v_mfma_f32_16x16x32_bf16 v[46:49], v[124:127], v[46:49], v[58:61]
	v_mfma_f32_16x16x32_bf16 v[54:57], v[124:127], v[86:89], v[74:77]
	v_mfma_f32_16x16x32_bf16 v[82:85], v[124:127], v[90:93], v[78:81]
	s_setprio 0
	v_lshl_add_u64 v[58:59], s[4:5], 0, v[32:33]
	v_mad_i64_i32 v[60:61], s[34:35], v94, s51, v[58:59]
	s_waitcnt lgkmcnt(0)
	s_barrier
	v_mad_i64_i32 v[62:63], s[34:35], v100, s51, v[58:59]
	s_waitcnt vmcnt(0)
	flat_load_dwordx2 v[116:117], v[60:61]
	flat_load_dwordx2 v[118:119], v[60:61] offset:32
	flat_load_dwordx2 v[120:121], v[62:63]
	flat_load_dwordx2 v[124:125], v[62:63] offset:32
	v_mad_i64_i32 v[60:61], s[34:35], v98, s51, v[58:59]
	v_mad_i64_i32 v[58:59], s[34:35], v96, s51, v[58:59]
	v_mov_b32_e32 v70, v186
	flat_load_dwordx2 v[126:127], v[60:61]
	flat_load_dwordx2 v[128:129], v[60:61] offset:32
	flat_load_dwordx2 v[134:135], v[58:59]
	flat_load_dwordx2 v[142:143], v[58:59] offset:32
	s_add_u32 s10, s22, s10
	v_ashrrev_i32_e32 v71, 6, v70
	v_bfe_u32 v72, v70, 4, 2
	v_bfe_u32 v58, v70, 2, 4
	v_lshl_or_b32 v58, v71, 4, v58
	v_sub_u32_e32 v59, 0, v72
	s_addc_u32 s11, s23, s11
	v_xor_b32_e32 v62, v70, v59
	v_ashrrev_i32_e32 v59, 31, v58
	s_add_u32 s34, s28, s31
	v_lshlrev_b64 v[60:61], 9, v[58:59]
	v_lshlrev_b32_e32 v62, 4, v62
	v_lshl_add_u32 v150, v71, 10, 0
	s_addc_u32 s35, s29, 0
	v_lshl_add_u64 v[58:59], s[10:11], 0, v[60:61]
	v_and_b32_e32 v62, 48, v62
	v_mov_b32_e32 v63, v33
	v_readfirstlane_b32 s38, v150
	v_add_u32_e32 v65, 0x1000, v150
	v_lshl_add_u64 v[58:59], v[58:59], 0, v[62:63]
	v_lshl_add_u64 v[60:61], s[34:35], 0, v[60:61]
	v_add_u32_e32 v64, 0x2000, v150
	s_mov_b32 m0, s38
	v_readfirstlane_b32 s35, v65
	v_lshl_add_u64 v[60:61], v[60:61], 0, v[62:63]
	s_waitcnt lgkmcnt(0)
	s_barrier
	global_load_lds_dwordx4 v[58:59], off
	v_lshl_add_u64 v[62:63], v[58:59], 0, s[46:47]
	s_mov_b32 m0, s35
	v_readfirstlane_b32 s34, v64
	v_add_u32_e32 v73, 0x3000, v150
	global_load_lds_dwordx4 v[62:63], off
	s_mov_b32 m0, s34
	v_readfirstlane_b32 s31, v73
	v_add_u32_e32 v73, 0x4000, v150
	global_load_lds_dwordx4 v[60:61], off
	v_add_u32_e32 v74, 0x5000, v150
	v_lshl_add_u64 v[64:65], v[58:59], 0, 64
	s_mov_b32 m0, s31
	v_readfirstlane_b32 s11, v73
	global_load_lds_dwordx4 v[64:65], off
	v_lshl_add_u64 v[64:65], v[58:59], 0, s[76:77]
	s_mov_b32 m0, s11
	v_readfirstlane_b32 s10, v74
	v_lshl_add_u64 v[62:63], v[60:61], 0, 64
	global_load_lds_dwordx4 v[64:65], off
	s_mov_b32 m0, s10
	v_lshlrev_b32_e32 v64, 11, v71
	global_load_lds_dwordx4 v[62:63], off
	v_lshrrev_b32_e32 v63, 2, v70
	v_lshlrev_b32_e32 v62, 6, v70
	v_sub_u32_e32 v63, 0, v63
	v_and_b32_e32 v62, 0x3c0, v62
	v_bitop3_b32 v63, v72, v63, 3 bitop3:0x78
	v_lshl_or_b32 v62, v63, 4, v62
	v_lshlrev_b32_e32 v63, 5, v70
	v_and_or_b32 v63, v63, s49, v62
	s_waitcnt vmcnt(3)
	v_add_u32_e32 v155, 0, v63
	v_and_or_b32 v86, v64, s50, v62
	s_waitcnt lgkmcnt(0)
	s_barrier
; #define RAW_BARRIER() do { asm volatile("s_waitcnt lgkmcnt(0)" ::: "memory"); __builtin_amdgcn_s_barrier(); } while (0)
; #define GLDS_TILE(kt, st) do { _Pragma("unroll") for (int _i = 0; _i < NP; ++_i) GLDS_PIECE(_i, kt, st); } while (0)
;     ...
;     constexpr int NH = NI >= 4 ? NI / 2 : NI;
;     constexpr int NP = 2 + NB, IVL = (4 * NI) / NP;
;     RAW_BARRIER();
;     GLDS_TILE(0, 0);
;     GLDS_TILE(1, 1);
;     int st = 0;
;     for (int kt = 0; kt < nk - 1; ++kt) {
;         if (NI == 8) asm volatile("s_waitcnt vmcnt(6)" ::: "memory"); else if (NI == 4) asm volatile("s_waitcnt vmcnt(4)" ::: "memory"); else asm volatile("s_waitcnt vmcnt(3)" ::: "memory");
;         RAW_BARRIER();
;         const int s2 = st >= 1 ? st - 1 : 2;
;         const bool ld = kt + 2 < nk;
;         STEP_TILE(st, ld, kt + 2, s2);
;         st = st == 2 ? 0 : st + 1;
;     }
	ds_read_b128 v[62:65], v155
	ds_read_b128 v[70:73], v155 offset:1024
	ds_read_b128 v[74:77], v155 offset:2048
	ds_read_b128 v[78:81], v155 offset:3072
	v_add_u32_e32 v157, 0, v86
	ds_read_b128 v[86:89], v157 offset:8192
	ds_read_b128 v[90:93], v157 offset:9216
	s_mov_b64 s[76:77], 0x8180
	s_mov_b64 s[46:47], 0x8140
	s_mov_b64 s[44:45], 0x8100
	s_mov_b64 s[42:43], 0x80c0
	s_mov_b64 s[16:17], 0x8080
	s_setprio 1
	v_add_u32_e32 v146, 0x6000, v150
	s_waitcnt lgkmcnt(0)
	v_mfma_f32_16x16x32_bf16 v[130:133], v[86:89], v[62:65], 0
	v_lshl_add_u64 v[140:141], v[60:61], 0, s[54:55]
	v_add_u32_e32 v151, 0x8000, v150
	v_lshl_add_u64 v[144:145], v[58:59], 0, s[54:55]
	v_mfma_f32_16x16x32_bf16 v[136:139], v[86:89], v[70:73], 0
	v_readfirstlane_b32 s39, v146
	s_mov_b32 m0, s39
	s_nop 0
	global_load_lds_dwordx4 v[144:145], off
	v_mfma_f32_16x16x32_bf16 v[144:147], v[86:89], v[74:77], 0
	v_mfma_f32_16x16x32_bf16 v[86:89], v[86:89], v[78:81], 0
	v_add_u32_e32 v150, 0x7000, v150
	v_lshl_add_u64 v[148:149], v[58:59], 0, s[16:17]
	v_readfirstlane_b32 s40, v150
	s_mov_b32 m0, s40
	s_nop 0
	global_load_lds_dwordx4 v[148:149], off
	v_mfma_f32_16x16x32_bf16 v[62:65], v[90:93], v[62:65], 0
	v_mfma_f32_16x16x32_bf16 v[70:73], v[90:93], v[70:73], 0
	v_readfirstlane_b32 s41, v151
	s_mov_b32 m0, s41
	s_nop 0
	global_load_lds_dwordx4 v[140:141], off
	v_mfma_f32_16x16x32_bf16 v[74:77], v[90:93], v[74:77], 0
	v_mfma_f32_16x16x32_bf16 v[78:81], v[90:93], v[78:81], 0
	s_setprio 0
	s_waitcnt vmcnt(3)
	s_waitcnt lgkmcnt(0)
	s_barrier
	ds_read_b128 v[90:93], v155 offset:12288
	ds_read_b128 v[148:151], v155 offset:13312
	ds_read_b128 v[158:161], v155 offset:14336
	ds_read_b128 v[162:165], v155 offset:15360
	ds_read_b128 v[166:169], v157 offset:20480
	ds_read_b128 v[170:173], v157 offset:21504
	s_setprio 1
	s_waitcnt lgkmcnt(0)
	v_mfma_f32_16x16x32_bf16 v[130:133], v[166:169], v[90:93], v[130:133]
	v_lshl_add_u64 v[140:141], v[60:61], 0, s[56:57]
	v_lshl_add_u64 v[152:153], v[58:59], 0, s[56:57]
	v_mfma_f32_16x16x32_bf16 v[136:139], v[166:169], v[148:151], v[136:139]
	s_mov_b32 m0, s38
	v_mfma_f32_16x16x32_bf16 v[144:147], v[166:169], v[158:161], v[144:147]
	global_load_lds_dwordx4 v[152:153], off
	v_mfma_f32_16x16x32_bf16 v[86:89], v[166:169], v[162:165], v[86:89]
	v_lshl_add_u64 v[152:153], v[58:59], 0, s[42:43]
	s_mov_b32 m0, s35
	v_mfma_f32_16x16x32_bf16 v[62:65], v[170:173], v[90:93], v[62:65]
	global_load_lds_dwordx4 v[152:153], off
	v_mfma_f32_16x16x32_bf16 v[70:73], v[170:173], v[148:151], v[70:73]
	s_mov_b32 m0, s34
	v_mfma_f32_16x16x32_bf16 v[74:77], v[170:173], v[158:161], v[74:77]
	global_load_lds_dwordx4 v[140:141], off
	v_mfma_f32_16x16x32_bf16 v[78:81], v[170:173], v[162:165], v[78:81]
	s_setprio 0
	s_waitcnt vmcnt(3)
	s_waitcnt lgkmcnt(0)
	s_barrier
	ds_read_b128 v[90:93], v155 offset:24576
	ds_read_b128 v[148:151], v155 offset:25600
	ds_read_b128 v[158:161], v155 offset:26624
	ds_read_b128 v[162:165], v155 offset:27648
	ds_read_b128 v[166:169], v157 offset:32768
	ds_read_b128 v[170:173], v157 offset:33792
	s_setprio 1
	s_waitcnt lgkmcnt(0)
	v_mfma_f32_16x16x32_bf16 v[130:133], v[166:169], v[90:93], v[130:133]
	v_lshl_add_u64 v[140:141], v[60:61], 0, s[58:59]
	v_lshl_add_u64 v[152:153], v[58:59], 0, s[58:59]
	v_mfma_f32_16x16x32_bf16 v[136:139], v[166:169], v[148:151], v[136:139]
	s_mov_b32 m0, s31
	v_mfma_f32_16x16x32_bf16 v[144:147], v[166:169], v[158:161], v[144:147]
	global_load_lds_dwordx4 v[152:153], off
	v_mfma_f32_16x16x32_bf16 v[86:89], v[166:169], v[162:165], v[86:89]
	v_lshl_add_u64 v[152:153], v[58:59], 0, s[44:45]
	s_mov_b32 m0, s11
	v_mfma_f32_16x16x32_bf16 v[62:65], v[170:173], v[90:93], v[62:65]
	global_load_lds_dwordx4 v[152:153], off
	v_mfma_f32_16x16x32_bf16 v[70:73], v[170:173], v[148:151], v[70:73]
	s_mov_b32 m0, s10
	v_mfma_f32_16x16x32_bf16 v[74:77], v[170:173], v[158:161], v[74:77]
	global_load_lds_dwordx4 v[140:141], off
	v_mfma_f32_16x16x32_bf16 v[78:81], v[170:173], v[162:165], v[78:81]
	s_setprio 0
	s_waitcnt vmcnt(3)
	s_waitcnt lgkmcnt(0)
	s_barrier
	ds_read_b128 v[90:93], v155
	ds_read_b128 v[148:151], v155 offset:1024
	ds_read_b128 v[158:161], v155 offset:2048
	ds_read_b128 v[162:165], v155 offset:3072
	ds_read_b128 v[166:169], v157 offset:8192
	ds_read_b128 v[170:173], v157 offset:9216
	s_setprio 1
	s_waitcnt lgkmcnt(0)
	v_mfma_f32_16x16x32_bf16 v[130:133], v[166:169], v[90:93], v[130:133]
	v_lshl_add_u64 v[140:141], v[60:61], 0, s[60:61]
	v_lshl_add_u64 v[152:153], v[58:59], 0, s[60:61]
	v_mfma_f32_16x16x32_bf16 v[136:139], v[166:169], v[148:151], v[136:139]
	s_mov_b32 m0, s39
	v_mfma_f32_16x16x32_bf16 v[144:147], v[166:169], v[158:161], v[144:147]
	global_load_lds_dwordx4 v[152:153], off
	v_mfma_f32_16x16x32_bf16 v[86:89], v[166:169], v[162:165], v[86:89]
	v_lshl_add_u64 v[152:153], v[58:59], 0, s[46:47]
	s_mov_b32 m0, s40
	v_mfma_f32_16x16x32_bf16 v[62:65], v[170:173], v[90:93], v[62:65]
	global_load_lds_dwordx4 v[152:153], off
	v_mfma_f32_16x16x32_bf16 v[70:73], v[170:173], v[148:151], v[70:73]
	s_mov_b32 m0, s41
	v_mfma_f32_16x16x32_bf16 v[74:77], v[170:173], v[158:161], v[74:77]
	global_load_lds_dwordx4 v[140:141], off
	v_mfma_f32_16x16x32_bf16 v[78:81], v[170:173], v[162:165], v[78:81]
	s_setprio 0
	s_waitcnt vmcnt(3)
	s_waitcnt lgkmcnt(0)
	s_barrier
;     __device__ __forceinline__ bf16_t* G() const { return (bf16_t*)(ws + OFF_G); }
; DEV void ld_bf4(const bf16_t* p, float (&v)[4]) { uint2 w = *(const uint2*)p; v[0] = bf_lo(w.x); v[1] = bf_hi(w.x); v[2] = bf_lo(w.y); v[3] = bf_hi(w.y); }
; #define RAW_BARRIER() do { asm volatile("s_waitcnt lgkmcnt(0)" ::: "memory"); __builtin_amdgcn_s_barrier(); } while (0)
;     ...
;     for (int kt = 0; kt < nk - 1; ++kt) {
;         if (NI == 8) asm volatile("s_waitcnt vmcnt(6)" ::: "memory"); else if (NI == 4) asm volatile("s_waitcnt vmcnt(4)" ::: "memory"); else asm volatile("s_waitcnt vmcnt(3)" ::: "memory");
;         RAW_BARRIER();
;         const int s2 = st >= 1 ? st - 1 : 2;
;         const bool ld = kt + 2 < nk;
;         STEP_TILE(st, ld, kt + 2, s2);
;         st = st == 2 ? 0 : st + 1;
;     }
;     asm volatile("s_waitcnt vmcnt(0)" ::: "memory");
;     RAW_BARRIER();
;     STEP_TILE(st, false, 0, 0);
;     RAW_BARRIER();
; DEV void merge_big(const Params& p, int l, int mt, int nt, char* smem) {
;     ...
; #pragma unroll
;         for (int mi = 0; mi < 4; ++mi)
; #pragma unroll
;             for (int ni = 0; ni < 2; ++ni) {
;                 float g[4]; ld_bf4(p.G() + (size_t)(rbase + mi * 16) * 3072 + br * 1024 + c0 + ni * 16, g);
;                 const f32x4 gv = (f32x4){g[0], g[1], g[2], g[3]};
;                 if (br == 0) mg[mi][ni] = gv * acc[mi][ni]; else mg[mi][ni] += gv * acc[mi][ni];
;             }
	ds_read_b128 v[90:93], v155 offset:12288
	ds_read_b128 v[148:151], v155 offset:13312
	ds_read_b128 v[158:161], v155 offset:14336
	ds_read_b128 v[162:165], v155 offset:15360
	ds_read_b128 v[166:169], v157 offset:20480
	ds_read_b128 v[170:173], v157 offset:21504
	s_setprio 1
	s_waitcnt lgkmcnt(0)
	v_mfma_f32_16x16x32_bf16 v[130:133], v[166:169], v[90:93], v[130:133]
	v_lshl_add_u64 v[140:141], v[60:61], 0, s[62:63]
	v_lshl_add_u64 v[152:153], v[58:59], 0, s[62:63]
	v_mfma_f32_16x16x32_bf16 v[136:139], v[166:169], v[148:151], v[136:139]
	s_mov_b32 m0, s38
	v_mfma_f32_16x16x32_bf16 v[144:147], v[166:169], v[158:161], v[144:147]
	global_load_lds_dwordx4 v[152:153], off
	v_mfma_f32_16x16x32_bf16 v[86:89], v[166:169], v[162:165], v[86:89]
	v_lshl_add_u64 v[152:153], v[58:59], 0, s[76:77]
	s_mov_b32 m0, s35
	s_mov_b64 s[16:17], 0x81c0
	global_load_lds_dwordx4 v[152:153], off
	v_mfma_f32_16x16x32_bf16 v[62:65], v[170:173], v[90:93], v[62:65]
	v_mfma_f32_16x16x32_bf16 v[70:73], v[170:173], v[148:151], v[70:73]
	s_mov_b32 m0, s34
	v_mfma_f32_16x16x32_bf16 v[74:77], v[170:173], v[158:161], v[74:77]
	global_load_lds_dwordx4 v[140:141], off
	v_mfma_f32_16x16x32_bf16 v[78:81], v[170:173], v[162:165], v[78:81]
	s_setprio 0
	s_waitcnt vmcnt(3)
	s_waitcnt lgkmcnt(0)
	s_barrier
	ds_read_b128 v[90:93], v155 offset:24576
	ds_read_b128 v[148:151], v155 offset:25600
	ds_read_b128 v[158:161], v155 offset:26624
	ds_read_b128 v[162:165], v155 offset:27648
	ds_read_b128 v[166:169], v157 offset:32768
	ds_read_b128 v[170:173], v157 offset:33792
	s_setprio 1
	s_waitcnt lgkmcnt(0)
	v_mfma_f32_16x16x32_bf16 v[130:133], v[166:169], v[90:93], v[130:133]
	v_lshl_add_u64 v[140:141], v[60:61], 0, s[64:65]
	v_lshl_add_u64 v[60:61], v[58:59], 0, s[64:65]
	v_mfma_f32_16x16x32_bf16 v[136:139], v[166:169], v[148:151], v[136:139]
	s_mov_b32 m0, s31
	v_mfma_f32_16x16x32_bf16 v[144:147], v[166:169], v[158:161], v[144:147]
	global_load_lds_dwordx4 v[60:61], off
	v_mfma_f32_16x16x32_bf16 v[86:89], v[166:169], v[162:165], v[86:89]
	v_lshl_add_u64 v[58:59], v[58:59], 0, s[16:17]
	s_mov_b32 m0, s11
	s_nop 0
	global_load_lds_dwordx4 v[58:59], off
	v_mfma_f32_16x16x32_bf16 v[58:61], v[170:173], v[90:93], v[62:65]
	v_mfma_f32_16x16x32_bf16 v[62:65], v[170:173], v[148:151], v[70:73]
	s_mov_b32 m0, s10
	s_nop 0
	global_load_lds_dwordx4 v[140:141], off
	v_mfma_f32_16x16x32_bf16 v[70:73], v[170:173], v[158:161], v[74:77]
	v_mfma_f32_16x16x32_bf16 v[74:77], v[170:173], v[162:165], v[78:81]
	s_setprio 0
	s_waitcnt vmcnt(3)
	s_waitcnt lgkmcnt(0)
	s_barrier
	s_nop 0
	ds_read_b128 v[78:81], v155
	ds_read_b128 v[90:93], v155 offset:1024
	ds_read_b128 v[148:151], v155 offset:2048
	ds_read_b128 v[158:161], v155 offset:3072
	ds_read_b128 v[162:165], v157 offset:8192
	ds_read_b128 v[166:169], v157 offset:9216
	s_setprio 1
	s_waitcnt lgkmcnt(0)
	v_mfma_f32_16x16x32_bf16 v[130:133], v[162:165], v[78:81], v[130:133]
	v_mfma_f32_16x16x32_bf16 v[136:139], v[162:165], v[90:93], v[136:139]
	v_mfma_f32_16x16x32_bf16 v[144:147], v[162:165], v[148:151], v[144:147]
	v_mfma_f32_16x16x32_bf16 v[86:89], v[162:165], v[158:161], v[86:89]
	v_mfma_f32_16x16x32_bf16 v[162:165], v[166:169], v[78:81], v[58:61]
	v_mfma_f32_16x16x32_bf16 v[170:173], v[166:169], v[90:93], v[62:65]
	v_mfma_f32_16x16x32_bf16 v[148:151], v[166:169], v[148:151], v[70:73]
	v_mfma_f32_16x16x32_bf16 v[158:161], v[166:169], v[158:161], v[74:77]
	s_setprio 0
	s_waitcnt vmcnt(0)
	s_waitcnt lgkmcnt(0)
	s_barrier
	ds_read_b128 v[62:65], v155 offset:12288
	ds_read_b128 v[74:77], v155 offset:13312
	ds_read_b128 v[166:169], v155 offset:14336
	ds_read_b128 v[174:177], v155 offset:15360
	ds_read_b128 v[90:93], v157 offset:20480
	ds_read_b128 v[178:181], v157 offset:21504
	s_setprio 1
	s_waitcnt lgkmcnt(0)
	v_mfma_f32_16x16x32_bf16 v[58:61], v[90:93], v[62:65], v[130:133]
	v_mfma_f32_16x16x32_bf16 v[70:73], v[90:93], v[74:77], v[136:139]
	v_mfma_f32_16x16x32_bf16 v[78:81], v[90:93], v[166:169], v[144:147]
	v_mfma_f32_16x16x32_bf16 v[90:93], v[90:93], v[174:177], v[86:89]
	v_mfma_f32_16x16x32_bf16 v[62:65], v[178:181], v[62:65], v[162:165]
	v_mfma_f32_16x16x32_bf16 v[74:77], v[178:181], v[74:77], v[170:173]
	v_mfma_f32_16x16x32_bf16 v[86:89], v[178:181], v[166:169], v[148:151]
	v_mfma_f32_16x16x32_bf16 v[146:149], v[178:181], v[174:177], v[158:161]
	s_setprio 0
	s_nop 0
	v_lshl_add_u64 v[150:151], s[6:7], 0, v[32:33]
	s_waitcnt vmcnt(0)
	v_lshlrev_b32_e32 v160, 16, v142
	v_and_b32_e32 v161, 0xffff0000, v142
	v_lshlrev_b32_e32 v142, 16, v143
	v_and_b32_e32 v143, 0xffff0000, v143
	v_mad_i64_i32 v[132:133], s[10:11], v94, s51, v[150:151]
	v_mad_i64_i32 v[138:139], s[10:11], v100, s51, v[150:151]
	v_mad_i64_i32 v[144:145], s[10:11], v98, s51, v[150:151]
	v_mad_i64_i32 v[150:151], s[10:11], v96, s51, v[150:151]
	v_lshlrev_b32_e32 v158, 16, v122
	v_and_b32_e32 v159, 0xffff0000, v122
	v_lshlrev_b32_e32 v122, 16, v123
	v_and_b32_e32 v123, 0xffff0000, v123
	v_pk_mul_f32 v[84:85], v[84:85], v[142:143]
	v_pk_mul_f32 v[82:83], v[82:83], v[160:161]
	s_waitcnt lgkmcnt(0)
	s_barrier
;     __device__ __forceinline__ bf16_t* G() const { return (bf16_t*)(ws + OFF_G); }
; DEV void ld_bf4(const bf16_t* p, float (&v)[4]) { uint2 w = *(const uint2*)p; v[0] = bf_lo(w.x); v[1] = bf_hi(w.x); v[2] = bf_lo(w.y); v[3] = bf_hi(w.y); }
; DEV void merge_big(const Params& p, int l, int mt, int nt, char* smem) {
;     ...
; #pragma unroll
;         for (int mi = 0; mi < 4; ++mi)
; #pragma unroll
;             for (int ni = 0; ni < 2; ++ni) {
;                 float g[4]; ld_bf4(p.G() + (size_t)(rbase + mi * 16) * 3072 + br * 1024 + c0 + ni * 16, g);
;                 const f32x4 gv = (f32x4){g[0], g[1], g[2], g[3]};
;                 if (br == 0) mg[mi][ni] = gv * acc[mi][ni]; else mg[mi][ni] += gv * acc[mi][ni];
;             }
	flat_load_dwordx2 v[130:131], v[132:133]
	s_nop 0
	flat_load_dwordx2 v[132:133], v[132:133] offset:32
	s_nop 0
	flat_load_dwordx2 v[136:137], v[138:139]
	s_nop 0
	flat_load_dwordx2 v[138:139], v[138:139] offset:32
	s_nop 0
	flat_load_dwordx2 v[140:141], v[144:145]
	s_nop 0
	flat_load_dwordx2 v[144:145], v[144:145] offset:32
	v_pk_fma_f32 v[82:83], v[38:39], v[158:159], v[82:83]
	flat_load_dwordx2 v[152:153], v[150:151]
	v_pk_fma_f32 v[38:39], v[40:41], v[122:123], v[84:85]
	flat_load_dwordx2 v[40:41], v[150:151] offset:32
	v_lshlrev_b32_e32 v122, 16, v135
	v_and_b32_e32 v123, 0xffff0000, v135
	v_pk_mul_f32 v[68:69], v[68:69], v[122:123]
	v_readlane_b32 s2, v254, 1
	v_readlane_b32 s3, v254, 2
	s_add_i32 s30, s30, s82
	s_cmpk_gt_i32 s30, 0x7ff
	s_waitcnt vmcnt(0) lgkmcnt(0)
	v_lshlrev_b32_e32 v84, 16, v40
	v_and_b32_e32 v85, 0xffff0000, v40
	v_lshlrev_b32_e32 v40, 16, v41
	v_and_b32_e32 v41, 0xffff0000, v41
	v_pk_fma_f32 v[38:39], v[148:149], v[40:41], v[38:39]
	v_pk_fma_f32 v[40:41], v[146:147], v[84:85], v[82:83]
	v_lshlrev_b32_e32 v82, 16, v114
	v_and_b32_e32 v83, 0xffff0000, v114
	v_lshlrev_b32_e32 v84, 16, v115
	v_and_b32_e32 v85, 0xffff0000, v115
	v_lshlrev_b32_e32 v114, 16, v134
	v_and_b32_e32 v115, 0xffff0000, v134
	v_pk_mul_f32 v[66:67], v[66:67], v[114:115]
	s_nop 0
	v_pk_fma_f32 v[66:67], v[24:25], v[82:83], v[66:67]
	v_pk_fma_f32 v[24:25], v[26:27], v[84:85], v[68:69]
	v_lshlrev_b32_e32 v26, 16, v152
	v_and_b32_e32 v27, 0xffff0000, v152
	v_lshlrev_b32_e32 v68, 16, v153
	v_and_b32_e32 v69, 0xffff0000, v153
	v_lshlrev_b32_e32 v82, 16, v128
	v_and_b32_e32 v83, 0xffff0000, v128
	v_lshlrev_b32_e32 v84, 16, v129
	v_and_b32_e32 v85, 0xffff0000, v129
	v_pk_fma_f32 v[24:25], v[92:93], v[68:69], v[24:25]
	v_pk_fma_f32 v[26:27], v[90:91], v[26:27], v[66:67]
	v_lshlrev_b32_e32 v66, 16, v112
	v_and_b32_e32 v67, 0xffff0000, v112
	v_lshlrev_b32_e32 v68, 16, v113
	v_and_b32_e32 v69, 0xffff0000, v113
	v_pk_mul_f32 v[56:57], v[56:57], v[84:85]
	v_pk_mul_f32 v[54:55], v[54:55], v[82:83]
	s_nop 0
	v_pk_fma_f32 v[54:55], v[20:21], v[66:67], v[54:55]
	v_pk_fma_f32 v[20:21], v[22:23], v[68:69], v[56:57]
	v_lshlrev_b32_e32 v22, 16, v144
	v_and_b32_e32 v23, 0xffff0000, v144
	v_lshlrev_b32_e32 v66, 16, v126
	v_and_b32_e32 v67, 0xffff0000, v126
	v_lshlrev_b32_e32 v56, 16, v145
	v_and_b32_e32 v57, 0xffff0000, v145
	v_pk_fma_f32 v[22:23], v[86:87], v[22:23], v[54:55]
	v_lshlrev_b32_e32 v54, 16, v110
	v_and_b32_e32 v55, 0xffff0000, v110
	v_lshlrev_b32_e32 v68, 16, v127
	v_and_b32_e32 v69, 0xffff0000, v127
	v_pk_mul_f32 v[50:51], v[50:51], v[66:67]
	v_pk_fma_f32 v[20:21], v[88:89], v[56:57], v[20:21]
	v_lshlrev_b32_e32 v56, 16, v111
	v_and_b32_e32 v57, 0xffff0000, v111
	v_pk_mul_f32 v[52:53], v[52:53], v[68:69]
	v_pk_fma_f32 v[16:17], v[16:17], v[54:55], v[50:51]
	v_lshlrev_b32_e32 v50, 16, v140
	v_and_b32_e32 v51, 0xffff0000, v140
	v_lshlrev_b32_e32 v54, 16, v124
	v_and_b32_e32 v55, 0xffff0000, v124
	v_pk_fma_f32 v[18:19], v[18:19], v[56:57], v[52:53]
	v_lshlrev_b32_e32 v52, 16, v141
	v_and_b32_e32 v53, 0xffff0000, v141
	v_pk_fma_f32 v[16:17], v[78:79], v[50:51], v[16:17]
	v_lshlrev_b32_e32 v50, 16, v108
	v_and_b32_e32 v51, 0xffff0000, v108
	v_lshlrev_b32_e32 v56, 16, v125
	v_and_b32_e32 v57, 0xffff0000, v125
	v_pk_mul_f32 v[46:47], v[46:47], v[54:55]
	v_pk_fma_f32 v[18:19], v[80:81], v[52:53], v[18:19]
	v_lshlrev_b32_e32 v52, 16, v109
	v_and_b32_e32 v53, 0xffff0000, v109
	v_pk_mul_f32 v[48:49], v[48:49], v[56:57]
	v_pk_fma_f32 v[12:13], v[12:13], v[50:51], v[46:47]
	v_lshlrev_b32_e32 v46, 16, v138
	v_and_b32_e32 v47, 0xffff0000, v138
	v_lshlrev_b32_e32 v50, 16, v120
	v_and_b32_e32 v51, 0xffff0000, v120
	v_pk_fma_f32 v[14:15], v[14:15], v[52:53], v[48:49]
	v_lshlrev_b32_e32 v48, 16, v139
	v_and_b32_e32 v49, 0xffff0000, v139
	v_pk_fma_f32 v[12:13], v[74:75], v[46:47], v[12:13]
	v_lshlrev_b32_e32 v46, 16, v106
	v_and_b32_e32 v47, 0xffff0000, v106
	v_lshlrev_b32_e32 v52, 16, v121
	v_and_b32_e32 v53, 0xffff0000, v121
;     __device__ __forceinline__ bf16_t* G() const { return (bf16_t*)(ws + OFF_G); }
;     __device__ __forceinline__ bf16_t* Mg() const { return (bf16_t*)(ws + OFF_Mg); }
; DEV void st_bf4(bf16_t* p, float a, float b, float c, float d) { uint2 w; w.x = pk_bf16(a, b); w.y = pk_bf16(c, d); *(uint2*)p = w; }
; DEV void ld_bf4(const bf16_t* p, float (&v)[4]) { uint2 w = *(const uint2*)p; v[0] = bf_lo(w.x); v[1] = bf_hi(w.x); v[2] = bf_lo(w.y); v[3] = bf_hi(w.y); }
; DEV void merge_big(const Params& p, int l, int mt, int nt, char* smem) {
;     ...
;         for (int mi = 0; mi < 4; ++mi)
; #pragma unroll
;             for (int ni = 0; ni < 2; ++ni) {
;                 float g[4]; ld_bf4(p.G() + (size_t)(rbase + mi * 16) * 3072 + br * 1024 + c0 + ni * 16, g);
;                 const f32x4 gv = (f32x4){g[0], g[1], g[2], g[3]};
;                 if (br == 0) mg[mi][ni] = gv * acc[mi][ni]; else mg[mi][ni] += gv * acc[mi][ni];
;             }
;     }
; #pragma unroll
;     for (int mi = 0; mi < 4; ++mi)
; #pragma unroll
;         for (int ni = 0; ni < 2; ++ni) st_bf4(p.Mg() + (size_t)(rbase + mi * 16) * 1024 + c0 + ni * 16, mg[mi][ni][0], mg[mi][ni][1], mg[mi][ni][2], mg[mi][ni][3]);
	v_pk_mul_f32 v[42:43], v[42:43], v[50:51]
	v_pk_fma_f32 v[14:15], v[76:77], v[48:49], v[14:15]
	v_lshlrev_b32_e32 v48, 16, v107
	v_and_b32_e32 v49, 0xffff0000, v107
	v_pk_mul_f32 v[44:45], v[44:45], v[52:53]
	v_pk_fma_f32 v[8:9], v[8:9], v[46:47], v[42:43]
	v_lshlrev_b32_e32 v42, 16, v136
	v_and_b32_e32 v43, 0xffff0000, v136
	v_lshlrev_b32_e32 v46, 16, v118
	v_and_b32_e32 v47, 0xffff0000, v118
	v_pk_fma_f32 v[10:11], v[10:11], v[48:49], v[44:45]
	v_lshlrev_b32_e32 v44, 16, v137
	v_and_b32_e32 v45, 0xffff0000, v137
	v_pk_fma_f32 v[8:9], v[70:71], v[42:43], v[8:9]
	v_lshlrev_b32_e32 v42, 16, v104
	v_and_b32_e32 v43, 0xffff0000, v104
	v_lshlrev_b32_e32 v48, 16, v119
	v_and_b32_e32 v49, 0xffff0000, v119
	v_pk_mul_f32 v[34:35], v[34:35], v[46:47]
	v_pk_fma_f32 v[10:11], v[72:73], v[44:45], v[10:11]
	v_lshlrev_b32_e32 v44, 16, v105
	v_and_b32_e32 v45, 0xffff0000, v105
	v_pk_mul_f32 v[36:37], v[36:37], v[48:49]
	v_pk_fma_f32 v[4:5], v[4:5], v[42:43], v[34:35]
	v_lshlrev_b32_e32 v34, 16, v132
	v_and_b32_e32 v35, 0xffff0000, v132
	v_lshlrev_b32_e32 v42, 16, v116
	v_and_b32_e32 v43, 0xffff0000, v116
	v_pk_fma_f32 v[6:7], v[6:7], v[44:45], v[36:37]
	v_lshlrev_b32_e32 v36, 16, v133
	v_and_b32_e32 v37, 0xffff0000, v133
	v_pk_fma_f32 v[4:5], v[62:63], v[34:35], v[4:5]
	v_lshlrev_b32_e32 v34, 16, v102
	v_and_b32_e32 v35, 0xffff0000, v102
	v_lshlrev_b32_e32 v44, 16, v117
	v_and_b32_e32 v45, 0xffff0000, v117
	v_pk_mul_f32 v[28:29], v[28:29], v[42:43]
	v_pk_fma_f32 v[6:7], v[64:65], v[36:37], v[6:7]
	v_lshlrev_b32_e32 v36, 16, v103
	v_and_b32_e32 v37, 0xffff0000, v103
	v_pk_mul_f32 v[30:31], v[30:31], v[44:45]
	v_pk_fma_f32 v[0:1], v[0:1], v[34:35], v[28:29]
	v_lshlrev_b32_e32 v28, 16, v130
	v_and_b32_e32 v29, 0xffff0000, v130
	v_pk_fma_f32 v[2:3], v[2:3], v[36:37], v[30:31]
	v_lshlrev_b32_e32 v30, 16, v131
	v_and_b32_e32 v31, 0xffff0000, v131
	v_pk_fma_f32 v[0:1], v[58:59], v[28:29], v[0:1]
	v_lshlrev_b64 v[28:29], 11, v[94:95]
	v_pk_fma_f32 v[2:3], v[60:61], v[30:31], v[2:3]
	v_lshl_add_u64 v[30:31], s[8:9], 0, v[28:29]
	v_lshl_add_u64 v[30:31], v[30:31], 0, v[32:33]
	v_cvt_pk_bf16_f32 v0, v0, v1
	v_cvt_pk_bf16_f32 v1, v2, v3
	flat_store_dwordx2 v[30:31], v[0:1]
	v_lshl_add_u64 v[0:1], s[2:3], 0, v[28:29]
	v_lshl_add_u64 v[0:1], v[0:1], 0, v[32:33]
	v_add_co_u32_e32 v0, vcc, s52, v0
	v_cvt_pk_bf16_f32 v2, v4, v5
	v_cvt_pk_bf16_f32 v3, v6, v7
	v_addc_co_u32_e32 v1, vcc, 0, v1, vcc
	flat_store_dwordx2 v[0:1], v[2:3] offset:32
	v_lshlrev_b64 v[0:1], 11, v[100:101]
	v_lshl_add_u64 v[2:3], s[8:9], 0, v[0:1]
	v_lshl_add_u64 v[0:1], s[2:3], 0, v[0:1]
	v_lshl_add_u64 v[0:1], v[0:1], 0, v[32:33]
	v_lshl_add_u64 v[2:3], v[2:3], 0, v[32:33]
	v_cvt_pk_bf16_f32 v4, v8, v9
	v_cvt_pk_bf16_f32 v5, v10, v11
	v_add_co_u32_e32 v0, vcc, s52, v0
	flat_store_dwordx2 v[2:3], v[4:5]
	v_cvt_pk_bf16_f32 v2, v12, v13
	v_cvt_pk_bf16_f32 v3, v14, v15
	v_addc_co_u32_e32 v1, vcc, 0, v1, vcc
	flat_store_dwordx2 v[0:1], v[2:3] offset:32
	v_lshlrev_b64 v[0:1], 11, v[98:99]
	v_lshl_add_u64 v[2:3], s[8:9], 0, v[0:1]
	v_lshl_add_u64 v[0:1], s[2:3], 0, v[0:1]
	v_lshl_add_u64 v[0:1], v[0:1], 0, v[32:33]
	v_lshl_add_u64 v[2:3], v[2:3], 0, v[32:33]
	v_cvt_pk_bf16_f32 v4, v16, v17
	v_cvt_pk_bf16_f32 v5, v18, v19
	v_add_co_u32_e32 v0, vcc, s52, v0
	flat_store_dwordx2 v[2:3], v[4:5]
	v_cvt_pk_bf16_f32 v2, v22, v23
	v_cvt_pk_bf16_f32 v3, v20, v21
	v_addc_co_u32_e32 v1, vcc, 0, v1, vcc
	flat_store_dwordx2 v[0:1], v[2:3] offset:32
	v_lshlrev_b64 v[0:1], 11, v[96:97]
	v_lshl_add_u64 v[2:3], s[8:9], 0, v[0:1]
	v_lshl_add_u64 v[0:1], s[2:3], 0, v[0:1]
	v_lshl_add_u64 v[0:1], v[0:1], 0, v[32:33]
	v_lshl_add_u64 v[2:3], v[2:3], 0, v[32:33]
	v_cvt_pk_bf16_f32 v4, v26, v27
	v_cvt_pk_bf16_f32 v5, v24, v25
	v_add_co_u32_e32 v0, vcc, 0x60ac000, v0
	flat_store_dwordx2 v[2:3], v[4:5]
	v_cvt_pk_bf16_f32 v2, v40, v41
	v_cvt_pk_bf16_f32 v3, v38, v39
	v_addc_co_u32_e32 v1, vcc, 0, v1, vcc
	flat_store_dwordx2 v[0:1], v[2:3] offset:32
	s_cbranch_scc0 .LBB0_106

;     __device__ __forceinline__ bf16_t* WbrA() const { return (bf16_t*)(ws + OFF_WbrA); }
;     __device__ __forceinline__ bf16_t* Y() const { return (bf16_t*)(ws + OFF_Y); }
; DEV int tid_opaque() { int t = threadIdx.x; asm volatile("" : "+v"(t)); return t; }
; #define RAW_BARRIER() do { asm volatile("s_waitcnt lgkmcnt(0)" ::: "memory"); __builtin_amdgcn_s_barrier(); } while (0)
; #define GLDS_TILE(kt, st) do { _Pragma("unroll") for (int _i = 0; _i < NP; ++_i) GLDS_PIECE(_i, kt, st); } while (0)
;     ...
;     const int t = tid_opaque(), lane = t & 63, wid = t >> 6, wm = wid >> 1, wn = wid & 1, fr = lane & 15, fq = lane >> 4;
;     const int nk = K >> 5;
;     const int srow = wid * 16 + (lane >> 2), sch = (lane & 3) ^ ((0 - (lane >> 4)) & 3);
;     const bf16_t* ga = A + (size_t)srow * lda + sch * 8;
;     const bf16_t* gb = B + (size_t)srow * ldb + sch * 8;
;     const int rd = fr * 64 + ((fq ^ ((0 - (fr >> 2)) & 3)) << 4);
;     const int rda = (wm * 64) * 64 + rd, rdb = 8192 + (wn * 16 * NI) * 64 + rd;
;     ...
;     constexpr int NH = NI >= 4 ? NI / 2 : NI;
;     constexpr int NP = 2 + NB, IVL = (4 * NI) / NP;
;     RAW_BARRIER();
;     GLDS_TILE(0, 0);
;     GLDS_TILE(1, 1);
;     int st = 0;
;     for (int kt = 0; kt < nk - 1; ++kt) {
;         if (NI == 8) asm volatile("s_waitcnt vmcnt(6)" ::: "memory"); else if (NI == 4) asm volatile("s_waitcnt vmcnt(4)" ::: "memory"); else asm volatile("s_waitcnt vmcnt(3)" ::: "memory");
;         RAW_BARRIER();
;         const int s2 = st >= 1 ? st - 1 : 2;
;         const bool ld = kt + 2 < nk;
;         STEP_TILE(st, ld, kt + 2, s2);
;         st = st == 2 ? 0 : st + 1;
;     }
;     asm volatile("s_waitcnt vmcnt(0)" ::: "memory");
;     RAW_BARRIER();
;     STEP_TILE(st, false, 0, 0);
; DEV void merge_big(const Params& p, int l, int mt, int nt, char* smem) {
;     ...
;         if (br == 0) gemm_glds<2>(p.Y() + (size_t)mt * 128 * 384, 384, p.WbrA() + (size_t)l * 1024 * 384 + (size_t)nt * 64 * 384, 384, 384, acc, smem);
.LBB0_109:
	v_mov_b32_e32 v0, v186
	s_movk_i32 s18, 0xffc0
	v_and_b32_e32 v1, 15, v0
	v_ashrrev_i32_e32 v2, 1, v0
	v_and_or_b32 v30, v2, s18, v1
	v_lshrrev_b32_e32 v1, 1, v0
	v_lshrrev_b32_e32 v0, 2, v0
	v_mov_b32_e32 v6, v186
	v_and_b32_e32 v0, 12, v0
	v_and_or_b32 v0, v1, 32, v0
	v_bfe_u32 v8, v6, 4, 2
	v_sub_u32_e32 v4, 0, v8
	v_add_u32_e32 v28, s20, v0
	v_ashrrev_i32_e32 v7, 6, v6
	v_bfe_u32 v0, v6, 2, 4
	v_xor_b32_e32 v3, v6, v4
	v_lshl_or_b32 v2, v7, 4, v0
	v_mov_b64_e32 v[0:1], s[0:1]
	v_lshlrev_b32_e32 v3, 4, v3
	v_mad_i64_i32 v[0:1], s[18:19], v2, s48, v[0:1]
	v_and_b32_e32 v32, 48, v3
	v_mad_i64_i32 v[2:3], s[18:19], v2, s48, 0
	v_readlane_b32 s2, v254, 1
	v_lshrrev_b32_e32 v10, 2, v6
	v_lshl_add_u32 v31, v7, 10, 0
	v_bitop3_b32 v4, v6, 3, v4 bitop3:0x48
	v_readlane_b32 s3, v254, 2
	s_add_u32 s18, s2, s22
	v_lshlrev_b32_e32 v9, 6, v6
	v_sub_u32_e32 v10, 0, v10
	v_readfirstlane_b32 s40, v31
	v_add_u32_e32 v12, 0x1000, v31
	v_lshl_add_u64 v[0:1], v[0:1], 0, v[32:33]
	v_lshl_or_b32 v2, v4, 4, v2
	s_addc_u32 s19, s3, s23
	v_and_b32_e32 v9, 0x3c0, v9
	v_bitop3_b32 v8, v8, v10, 3 bitop3:0x78
	v_add_u32_e32 v11, 0x2000, v31
	s_mov_b32 m0, s40
	v_readfirstlane_b32 s39, v12
	v_lshl_add_u64 v[2:3], s[18:19], 0, v[2:3]
	s_mov_b64 s[34:35], 0x1700000
	v_lshl_or_b32 v8, v8, 4, v9
	v_lshlrev_b32_e32 v9, 5, v6
	v_lshlrev_b32_e32 v10, 11, v7
	s_waitcnt lgkmcnt(0)
	s_barrier
	global_load_lds_dwordx4 v[0:1], off
	v_lshl_add_u64 v[6:7], v[0:1], 0, s[66:67]
	s_mov_b32 m0, s39
	v_readfirstlane_b32 s38, v11
	v_lshl_add_u64 v[4:5], v[2:3], 0, s[34:35]
	global_load_lds_dwordx4 v[6:7], off
	s_mov_b32 m0, s38
	v_add_u32_e32 v11, 0x3000, v31
	s_mov_b64 s[34:35], 0x1700040
	global_load_lds_dwordx4 v[4:5], off
	v_lshl_add_u64 v[4:5], v[2:3], 0, s[34:35]
	v_readfirstlane_b32 s35, v11
	v_add_u32_e32 v11, 0x4000, v31
	v_add_u32_e32 v12, 0x5000, v31
	v_lshl_add_u64 v[6:7], v[0:1], 0, 64
	s_mov_b32 m0, s35
	v_readfirstlane_b32 s34, v11
	global_load_lds_dwordx4 v[6:7], off
	v_lshl_add_u64 v[6:7], v[0:1], 0, s[68:69]
	s_mov_b32 m0, s34
	v_readfirstlane_b32 s31, v12
	global_load_lds_dwordx4 v[6:7], off
	s_mov_b32 m0, s31
	v_and_or_b32 v9, v9, s49, v8
	global_load_lds_dwordx4 v[4:5], off
	s_waitcnt vmcnt(3)
	v_add_u32_e32 v32, 0, v9
	v_and_or_b32 v20, v10, s50, v8
	s_waitcnt lgkmcnt(0)
	s_barrier
	ds_read_b128 v[4:7], v32
	ds_read_b128 v[8:11], v32 offset:1024
	ds_read_b128 v[12:15], v32 offset:2048
	ds_read_b128 v[16:19], v32 offset:3072
	s_waitcnt vmcnt(0)
	v_add_u32_e32 v70, 0, v20
	ds_read_b128 v[20:23], v70 offset:8192
	ds_read_b128 v[24:27], v70 offset:9216
	v_add_u32_e32 v94, 0x4000, v30
	v_ashrrev_i32_e32 v29, 31, v28
	s_setprio 1
	s_mov_b64 s[42:43], 0x1700080
	v_add_u32_e32 v44, 0x6000, v31
	s_waitcnt lgkmcnt(0)
	v_mfma_f32_16x16x32_bf16 v[34:37], v[20:23], v[4:7], 0
	v_lshl_add_u64 v[46:47], v[2:3], 0, s[42:43]
	v_add_u32_e32 v50, 0x8000, v31
	v_lshl_add_u64 v[42:43], v[0:1], 0, s[54:55]
	v_mfma_f32_16x16x32_bf16 v[38:41], v[20:23], v[8:11], 0
	v_readfirstlane_b32 s41, v44
	s_mov_b32 m0, s41
	s_nop 0
	global_load_lds_dwordx4 v[42:43], off
	v_mfma_f32_16x16x32_bf16 v[42:45], v[20:23], v[12:15], 0
	v_mfma_f32_16x16x32_bf16 v[20:23], v[20:23], v[16:19], 0
	v_add_u32_e32 v31, 0x7000, v31
	v_lshl_add_u64 v[48:49], v[0:1], 0, s[96:97]
	v_readfirstlane_b32 s42, v31
	s_mov_b32 m0, s42
	s_nop 0
	global_load_lds_dwordx4 v[48:49], off
	v_mfma_f32_16x16x32_bf16 v[4:7], v[24:27], v[4:7], 0
	v_mfma_f32_16x16x32_bf16 v[8:11], v[24:27], v[8:11], 0
	v_readfirstlane_b32 s43, v50
	s_mov_b32 m0, s43
	s_nop 0
	global_load_lds_dwordx4 v[46:47], off
	v_mfma_f32_16x16x32_bf16 v[12:15], v[24:27], v[12:15], 0
	v_mfma_f32_16x16x32_bf16 v[16:19], v[24:27], v[16:19], 0
	s_setprio 0
	s_waitcnt vmcnt(3)
	s_waitcnt lgkmcnt(0)
	s_barrier
	ds_read_b128 v[24:27], v32 offset:12288
	ds_read_b128 v[46:49], v32 offset:13312
	ds_read_b128 v[50:53], v32 offset:14336
	ds_read_b128 v[54:57], v32 offset:15360
	ds_read_b128 v[58:61], v70 offset:20480
	ds_read_b128 v[62:65], v70 offset:21504
	s_setprio 1
	s_mov_b64 s[44:45], 0x17000c0
	s_waitcnt lgkmcnt(0)
	v_mfma_f32_16x16x32_bf16 v[34:37], v[58:61], v[24:27], v[34:37]
	v_lshl_add_u64 v[66:67], v[2:3], 0, s[44:45]
	v_lshl_add_u64 v[68:69], v[0:1], 0, s[56:57]
	v_mfma_f32_16x16x32_bf16 v[38:41], v[58:61], v[46:49], v[38:41]
	s_mov_b32 m0, s40
	v_mfma_f32_16x16x32_bf16 v[42:45], v[58:61], v[50:53], v[42:45]
	global_load_lds_dwordx4 v[68:69], off
	v_mfma_f32_16x16x32_bf16 v[20:23], v[58:61], v[54:57], v[20:23]
	v_lshl_add_u64 v[58:59], v[0:1], 0, s[94:95]
	s_mov_b32 m0, s39
	v_mfma_f32_16x16x32_bf16 v[4:7], v[62:65], v[24:27], v[4:7]
	global_load_lds_dwordx4 v[58:59], off
	v_mfma_f32_16x16x32_bf16 v[8:11], v[62:65], v[46:49], v[8:11]
	s_mov_b32 m0, s38
	v_mfma_f32_16x16x32_bf16 v[12:15], v[62:65], v[50:53], v[12:15]
	global_load_lds_dwordx4 v[66:67], off
	v_mfma_f32_16x16x32_bf16 v[16:19], v[62:65], v[54:57], v[16:19]
	s_setprio 0
	s_waitcnt vmcnt(3)
	s_waitcnt lgkmcnt(0)
	s_barrier
	ds_read_b128 v[24:27], v32 offset:24576
	ds_read_b128 v[46:49], v32 offset:25600
	ds_read_b128 v[50:53], v32 offset:26624
	ds_read_b128 v[54:57], v32 offset:27648
	ds_read_b128 v[58:61], v70 offset:32768
	ds_read_b128 v[62:65], v70 offset:33792
	s_setprio 1
	s_mov_b64 s[44:45], 0x1700100
	s_waitcnt lgkmcnt(0)
	v_mfma_f32_16x16x32_bf16 v[34:37], v[58:61], v[24:27], v[34:37]
	v_lshl_add_u64 v[66:67], v[2:3], 0, s[44:45]
	v_lshl_add_u64 v[68:69], v[0:1], 0, s[58:59]
	v_mfma_f32_16x16x32_bf16 v[38:41], v[58:61], v[46:49], v[38:41]
	s_mov_b32 m0, s35
	v_mfma_f32_16x16x32_bf16 v[42:45], v[58:61], v[50:53], v[42:45]
	global_load_lds_dwordx4 v[68:69], off
	v_mfma_f32_16x16x32_bf16 v[20:23], v[58:61], v[54:57], v[20:23]
	v_lshl_add_u64 v[58:59], v[0:1], 0, s[70:71]
	s_mov_b32 m0, s34
	v_mfma_f32_16x16x32_bf16 v[4:7], v[62:65], v[24:27], v[4:7]
	global_load_lds_dwordx4 v[58:59], off
	v_mfma_f32_16x16x32_bf16 v[8:11], v[62:65], v[46:49], v[8:11]
	s_mov_b32 m0, s31
	v_mfma_f32_16x16x32_bf16 v[12:15], v[62:65], v[50:53], v[12:15]
	global_load_lds_dwordx4 v[66:67], off
	v_mfma_f32_16x16x32_bf16 v[16:19], v[62:65], v[54:57], v[16:19]
	s_setprio 0
	s_waitcnt vmcnt(3)
	s_waitcnt lgkmcnt(0)
	s_barrier
; #define RAW_BARRIER() do { asm volatile("s_waitcnt lgkmcnt(0)" ::: "memory"); __builtin_amdgcn_s_barrier(); } while (0)
; #define GLDS_TILE(kt, st) do { _Pragma("unroll") for (int _i = 0; _i < NP; ++_i) GLDS_PIECE(_i, kt, st); } while (0)
;     ...
;     constexpr int NH = NI >= 4 ? NI / 2 : NI;
;     constexpr int NP = 2 + NB, IVL = (4 * NI) / NP;
;     RAW_BARRIER();
;     GLDS_TILE(0, 0);
;     GLDS_TILE(1, 1);
;     int st = 0;
;     for (int kt = 0; kt < nk - 1; ++kt) {
;         if (NI == 8) asm volatile("s_waitcnt vmcnt(6)" ::: "memory"); else if (NI == 4) asm volatile("s_waitcnt vmcnt(4)" ::: "memory"); else asm volatile("s_waitcnt vmcnt(3)" ::: "memory");
;         RAW_BARRIER();
;         const int s2 = st >= 1 ? st - 1 : 2;
;         const bool ld = kt + 2 < nk;
;         STEP_TILE(st, ld, kt + 2, s2);
;         st = st == 2 ? 0 : st + 1;
;     }
	ds_read_b128 v[24:27], v32
	ds_read_b128 v[46:49], v32 offset:1024
	ds_read_b128 v[50:53], v32 offset:2048
	ds_read_b128 v[54:57], v32 offset:3072
	ds_read_b128 v[58:61], v70 offset:8192
	ds_read_b128 v[62:65], v70 offset:9216
	s_setprio 1
	s_mov_b64 s[44:45], 0x1700140
	s_waitcnt lgkmcnt(0)
	v_mfma_f32_16x16x32_bf16 v[34:37], v[58:61], v[24:27], v[34:37]
	v_lshl_add_u64 v[66:67], v[2:3], 0, s[44:45]
	v_lshl_add_u64 v[68:69], v[0:1], 0, s[60:61]
	v_mfma_f32_16x16x32_bf16 v[38:41], v[58:61], v[46:49], v[38:41]
	s_mov_b32 m0, s41
	v_mfma_f32_16x16x32_bf16 v[42:45], v[58:61], v[50:53], v[42:45]
	global_load_lds_dwordx4 v[68:69], off
	v_mfma_f32_16x16x32_bf16 v[20:23], v[58:61], v[54:57], v[20:23]
	v_lshl_add_u64 v[58:59], v[0:1], 0, s[72:73]
	s_mov_b32 m0, s42
	v_mfma_f32_16x16x32_bf16 v[4:7], v[62:65], v[24:27], v[4:7]
	global_load_lds_dwordx4 v[58:59], off
	v_mfma_f32_16x16x32_bf16 v[8:11], v[62:65], v[46:49], v[8:11]
	s_mov_b32 m0, s43
	v_mfma_f32_16x16x32_bf16 v[12:15], v[62:65], v[50:53], v[12:15]
	global_load_lds_dwordx4 v[66:67], off
	v_mfma_f32_16x16x32_bf16 v[16:19], v[62:65], v[54:57], v[16:19]
	s_setprio 0
	s_waitcnt vmcnt(3)
	s_waitcnt lgkmcnt(0)
	s_barrier
	ds_read_b128 v[24:27], v32 offset:12288
	ds_read_b128 v[46:49], v32 offset:13312
	ds_read_b128 v[50:53], v32 offset:14336
	ds_read_b128 v[54:57], v32 offset:15360
	ds_read_b128 v[58:61], v70 offset:20480
	ds_read_b128 v[62:65], v70 offset:21504
	s_setprio 1
	s_mov_b64 s[44:45], 0x1700180
	s_waitcnt lgkmcnt(0)
	v_mfma_f32_16x16x32_bf16 v[34:37], v[58:61], v[24:27], v[34:37]
	v_lshl_add_u64 v[66:67], v[2:3], 0, s[44:45]
	v_lshl_add_u64 v[68:69], v[0:1], 0, s[62:63]
	v_mfma_f32_16x16x32_bf16 v[38:41], v[58:61], v[46:49], v[38:41]
	s_mov_b32 m0, s40
	v_mfma_f32_16x16x32_bf16 v[42:45], v[58:61], v[50:53], v[42:45]
	global_load_lds_dwordx4 v[68:69], off
	v_mfma_f32_16x16x32_bf16 v[20:23], v[58:61], v[54:57], v[20:23]
	v_lshl_add_u64 v[58:59], v[0:1], 0, s[84:85]
	s_mov_b32 m0, s39
	v_mfma_f32_16x16x32_bf16 v[4:7], v[62:65], v[24:27], v[4:7]
	global_load_lds_dwordx4 v[58:59], off
	v_mfma_f32_16x16x32_bf16 v[8:11], v[62:65], v[46:49], v[8:11]
	s_mov_b32 m0, s38
	v_mfma_f32_16x16x32_bf16 v[12:15], v[62:65], v[50:53], v[12:15]
	global_load_lds_dwordx4 v[66:67], off
	v_mfma_f32_16x16x32_bf16 v[16:19], v[62:65], v[54:57], v[16:19]
	s_setprio 0
	s_waitcnt vmcnt(3)
	s_waitcnt lgkmcnt(0)
	s_barrier
	ds_read_b128 v[24:27], v32 offset:24576
	ds_read_b128 v[46:49], v32 offset:25600
	ds_read_b128 v[50:53], v32 offset:26624
	ds_read_b128 v[54:57], v32 offset:27648
	ds_read_b128 v[58:61], v70 offset:32768
	ds_read_b128 v[62:65], v70 offset:33792
	s_setprio 1
	s_mov_b64 s[44:45], 0x17001c0
	s_waitcnt lgkmcnt(0)
	v_mfma_f32_16x16x32_bf16 v[34:37], v[58:61], v[24:27], v[34:37]
	v_lshl_add_u64 v[66:67], v[2:3], 0, s[44:45]
	v_lshl_add_u64 v[68:69], v[0:1], 0, s[64:65]
	v_mfma_f32_16x16x32_bf16 v[38:41], v[58:61], v[46:49], v[38:41]
	s_mov_b32 m0, s35
	v_mfma_f32_16x16x32_bf16 v[42:45], v[58:61], v[50:53], v[42:45]
	global_load_lds_dwordx4 v[68:69], off
	v_mfma_f32_16x16x32_bf16 v[20:23], v[58:61], v[54:57], v[20:23]
	s_mov_b64 s[46:47], 0xc1c0
	v_lshl_add_u64 v[58:59], v[0:1], 0, s[46:47]
	s_mov_b32 m0, s34
	v_mfma_f32_16x16x32_bf16 v[4:7], v[62:65], v[24:27], v[4:7]
	global_load_lds_dwordx4 v[58:59], off
	v_mfma_f32_16x16x32_bf16 v[8:11], v[62:65], v[46:49], v[8:11]
	s_mov_b32 m0, s31
	v_mfma_f32_16x16x32_bf16 v[12:15], v[62:65], v[50:53], v[12:15]
	global_load_lds_dwordx4 v[66:67], off
	v_mfma_f32_16x16x32_bf16 v[16:19], v[62:65], v[54:57], v[16:19]
	s_setprio 0
	s_waitcnt vmcnt(3)
	s_waitcnt lgkmcnt(0)
	s_barrier
	ds_read_b128 v[24:27], v32
	ds_read_b128 v[46:49], v32 offset:1024
	ds_read_b128 v[50:53], v32 offset:2048
	ds_read_b128 v[54:57], v32 offset:3072
	ds_read_b128 v[58:61], v70 offset:8192
	ds_read_b128 v[62:65], v70 offset:9216
	s_setprio 1
	s_mov_b64 s[44:45], 0x1700200
	s_mov_b64 s[76:77], 0x200
	s_waitcnt lgkmcnt(0)
	v_mfma_f32_16x16x32_bf16 v[34:37], v[58:61], v[24:27], v[34:37]
	v_lshl_add_u64 v[66:67], v[2:3], 0, s[44:45]
	v_lshl_add_u64 v[68:69], v[0:1], 0, s[76:77]
	v_mfma_f32_16x16x32_bf16 v[38:41], v[58:61], v[46:49], v[38:41]
	s_mov_b32 m0, s41
	v_mfma_f32_16x16x32_bf16 v[42:45], v[58:61], v[50:53], v[42:45]
	global_load_lds_dwordx4 v[68:69], off
	v_mfma_f32_16x16x32_bf16 v[20:23], v[58:61], v[54:57], v[20:23]
	s_mov_b64 vcc, 0xc200
	v_lshl_add_u64 v[58:59], v[0:1], 0, vcc
	s_mov_b32 m0, s42
	v_mfma_f32_16x16x32_bf16 v[4:7], v[62:65], v[24:27], v[4:7]
	global_load_lds_dwordx4 v[58:59], off
	v_mfma_f32_16x16x32_bf16 v[8:11], v[62:65], v[46:49], v[8:11]
	s_mov_b32 m0, s43
	v_mfma_f32_16x16x32_bf16 v[12:15], v[62:65], v[50:53], v[12:15]
	global_load_lds_dwordx4 v[66:67], off
	v_mfma_f32_16x16x32_bf16 v[16:19], v[62:65], v[54:57], v[16:19]
	s_setprio 0
	s_waitcnt vmcnt(3)
	s_waitcnt lgkmcnt(0)
	s_barrier
	ds_read_b128 v[24:27], v32 offset:12288
	ds_read_b128 v[46:49], v32 offset:13312
	ds_read_b128 v[50:53], v32 offset:14336
	ds_read_b128 v[54:57], v32 offset:15360
	ds_read_b128 v[58:61], v70 offset:20480
	ds_read_b128 v[62:65], v70 offset:21504
	s_setprio 1
	s_mov_b64 s[44:45], 0x1700240
	s_waitcnt lgkmcnt(0)
	v_mfma_f32_16x16x32_bf16 v[34:37], v[58:61], v[24:27], v[34:37]
	v_lshl_add_u64 v[66:67], v[2:3], 0, s[44:45]
	v_lshl_add_u64 v[68:69], v[0:1], 0, s[86:87]
	v_mfma_f32_16x16x32_bf16 v[38:41], v[58:61], v[46:49], v[38:41]
	s_mov_b32 m0, s40
	v_mfma_f32_16x16x32_bf16 v[42:45], v[58:61], v[50:53], v[42:45]
	global_load_lds_dwordx4 v[68:69], off
	v_mfma_f32_16x16x32_bf16 v[20:23], v[58:61], v[54:57], v[20:23]
	v_lshl_add_u64 v[58:59], v[0:1], 0, s[90:91]
	s_mov_b32 m0, s39
	v_mfma_f32_16x16x32_bf16 v[4:7], v[62:65], v[24:27], v[4:7]
	global_load_lds_dwordx4 v[58:59], off
	v_mfma_f32_16x16x32_bf16 v[8:11], v[62:65], v[46:49], v[8:11]
	s_mov_b32 m0, s38
	v_mfma_f32_16x16x32_bf16 v[12:15], v[62:65], v[50:53], v[12:15]
	global_load_lds_dwordx4 v[66:67], off
	v_mfma_f32_16x16x32_bf16 v[16:19], v[62:65], v[54:57], v[16:19]
	s_setprio 0
	s_waitcnt vmcnt(3)
	s_waitcnt lgkmcnt(0)
	s_barrier
;     __device__ __forceinline__ bf16_t* G() const { return (bf16_t*)(ws + OFF_G); }
; DEV void ld_bf4(const bf16_t* p, float (&v)[4]) { uint2 w = *(const uint2*)p; v[0] = bf_lo(w.x); v[1] = bf_hi(w.x); v[2] = bf_lo(w.y); v[3] = bf_hi(w.y); }
; #define RAW_BARRIER() do { asm volatile("s_waitcnt lgkmcnt(0)" ::: "memory"); __builtin_amdgcn_s_barrier(); } while (0)
;     ...
;     for (int kt = 0; kt < nk - 1; ++kt) {
;         if (NI == 8) asm volatile("s_waitcnt vmcnt(6)" ::: "memory"); else if (NI == 4) asm volatile("s_waitcnt vmcnt(4)" ::: "memory"); else asm volatile("s_waitcnt vmcnt(3)" ::: "memory");
;         RAW_BARRIER();
;         const int s2 = st >= 1 ? st - 1 : 2;
;         const bool ld = kt + 2 < nk;
;         STEP_TILE(st, ld, kt + 2, s2);
;         st = st == 2 ? 0 : st + 1;
;     }
;     asm volatile("s_waitcnt vmcnt(0)" ::: "memory");
;     RAW_BARRIER();
;     STEP_TILE(st, false, 0, 0);
;     RAW_BARRIER();
; DEV void merge_big(const Params& p, int l, int mt, int nt, char* smem) {
;     ...
; #pragma unroll
;         for (int mi = 0; mi < 4; ++mi)
; #pragma unroll
;             for (int ni = 0; ni < 2; ++ni) {
;                 float g[4]; ld_bf4(p.G() + (size_t)(rbase + mi * 16) * 3072 + br * 1024 + c0 + ni * 16, g);
;                 const f32x4 gv = (f32x4){g[0], g[1], g[2], g[3]};
;                 if (br == 0) mg[mi][ni] = gv * acc[mi][ni]; else mg[mi][ni] += gv * acc[mi][ni];
	ds_read_b128 v[24:27], v32 offset:24576
	ds_read_b128 v[46:49], v32 offset:25600
	ds_read_b128 v[50:53], v32 offset:26624
	ds_read_b128 v[54:57], v32 offset:27648
	ds_read_b128 v[58:61], v70 offset:32768
	ds_read_b128 v[62:65], v70 offset:33792
	s_setprio 1
	s_mov_b64 s[38:39], 0x1700280
	s_waitcnt lgkmcnt(0)
	v_mfma_f32_16x16x32_bf16 v[34:37], v[58:61], v[24:27], v[34:37]
	v_lshl_add_u64 v[66:67], v[2:3], 0, s[38:39]
	v_lshl_add_u64 v[68:69], v[0:1], 0, s[88:89]
	v_mfma_f32_16x16x32_bf16 v[38:41], v[58:61], v[46:49], v[38:41]
	s_mov_b32 m0, s35
	v_mfma_f32_16x16x32_bf16 v[42:45], v[58:61], v[50:53], v[42:45]
	global_load_lds_dwordx4 v[68:69], off
	v_mfma_f32_16x16x32_bf16 v[20:23], v[58:61], v[54:57], v[20:23]
	s_mov_b64 s[80:81], 0xc280
	v_lshl_add_u64 v[58:59], v[0:1], 0, s[80:81]
	s_mov_b32 m0, s34
	v_mfma_f32_16x16x32_bf16 v[4:7], v[62:65], v[24:27], v[4:7]
	global_load_lds_dwordx4 v[58:59], off
	v_mfma_f32_16x16x32_bf16 v[8:11], v[62:65], v[46:49], v[8:11]
	s_mov_b32 m0, s31
	v_mfma_f32_16x16x32_bf16 v[12:15], v[62:65], v[50:53], v[12:15]
	global_load_lds_dwordx4 v[66:67], off
	v_mfma_f32_16x16x32_bf16 v[16:19], v[62:65], v[54:57], v[16:19]
	s_setprio 0
	s_waitcnt vmcnt(3)
	s_waitcnt lgkmcnt(0)
	s_barrier
	ds_read_b128 v[24:27], v32
	ds_read_b128 v[46:49], v32 offset:1024
	ds_read_b128 v[50:53], v32 offset:2048
	ds_read_b128 v[54:57], v32 offset:3072
	ds_read_b128 v[58:61], v70 offset:8192
	ds_read_b128 v[62:65], v70 offset:9216
	s_setprio 1
	s_mov_b64 s[34:35], 0x17002c0
	s_mov_b64 s[92:93], 0x2c0
	s_waitcnt lgkmcnt(0)
	v_mfma_f32_16x16x32_bf16 v[34:37], v[58:61], v[24:27], v[34:37]
	v_lshl_add_u64 v[66:67], v[2:3], 0, s[34:35]
	v_lshl_add_u64 v[2:3], v[0:1], 0, s[92:93]
	v_mfma_f32_16x16x32_bf16 v[38:41], v[58:61], v[46:49], v[38:41]
	s_mov_b32 m0, s41
	v_mfma_f32_16x16x32_bf16 v[42:45], v[58:61], v[50:53], v[42:45]
	global_load_lds_dwordx4 v[2:3], off
	v_mfma_f32_16x16x32_bf16 v[20:23], v[58:61], v[54:57], v[20:23]
	s_mov_b64 s[78:79], 0xc2c0
	v_lshl_add_u64 v[0:1], v[0:1], 0, s[78:79]
	s_mov_b32 m0, s42
	s_nop 0
	global_load_lds_dwordx4 v[0:1], off
	v_mfma_f32_16x16x32_bf16 v[0:3], v[62:65], v[24:27], v[4:7]
	v_mfma_f32_16x16x32_bf16 v[4:7], v[62:65], v[46:49], v[8:11]
	s_mov_b32 m0, s43
	s_nop 0
	global_load_lds_dwordx4 v[66:67], off
	v_mfma_f32_16x16x32_bf16 v[8:11], v[62:65], v[50:53], v[12:15]
	v_mfma_f32_16x16x32_bf16 v[12:15], v[62:65], v[54:57], v[16:19]
	s_setprio 0
	s_waitcnt vmcnt(3)
	s_waitcnt lgkmcnt(0)
	s_barrier
	s_nop 0
	ds_read_b128 v[16:19], v32 offset:12288
	ds_read_b128 v[24:27], v32 offset:13312
	ds_read_b128 v[46:49], v32 offset:14336
	ds_read_b128 v[50:53], v32 offset:15360
	ds_read_b128 v[54:57], v70 offset:20480
	ds_read_b128 v[58:61], v70 offset:21504
	s_setprio 1
	s_waitcnt lgkmcnt(0)
	v_mfma_f32_16x16x32_bf16 v[34:37], v[54:57], v[16:19], v[34:37]
	v_mfma_f32_16x16x32_bf16 v[38:41], v[54:57], v[24:27], v[38:41]
	v_mfma_f32_16x16x32_bf16 v[42:45], v[54:57], v[46:49], v[42:45]
	v_mfma_f32_16x16x32_bf16 v[20:23], v[54:57], v[50:53], v[20:23]
	v_mfma_f32_16x16x32_bf16 v[54:57], v[58:61], v[16:19], v[0:3]
	v_mfma_f32_16x16x32_bf16 v[62:65], v[58:61], v[24:27], v[4:7]
	v_mfma_f32_16x16x32_bf16 v[46:49], v[58:61], v[46:49], v[8:11]
	v_mfma_f32_16x16x32_bf16 v[50:53], v[58:61], v[50:53], v[12:15]
	s_setprio 0
	s_waitcnt vmcnt(0)
	s_waitcnt lgkmcnt(0)
	s_barrier
	ds_read_b128 v[4:7], v32 offset:24576
	ds_read_b128 v[12:15], v32 offset:25600
	ds_read_b128 v[58:61], v32 offset:26624
	ds_read_b128 v[66:69], v32 offset:27648
	ds_read_b128 v[24:27], v70 offset:32768
	ds_read_b128 v[70:73], v70 offset:33792
	s_setprio 1
	s_waitcnt lgkmcnt(0)
	v_mfma_f32_16x16x32_bf16 v[0:3], v[24:27], v[4:7], v[34:37]
	v_mfma_f32_16x16x32_bf16 v[8:11], v[24:27], v[12:15], v[38:41]
	v_mfma_f32_16x16x32_bf16 v[16:19], v[24:27], v[58:61], v[42:45]
	v_mfma_f32_16x16x32_bf16 v[24:27], v[24:27], v[66:69], v[20:23]
	v_mfma_f32_16x16x32_bf16 v[4:7], v[70:73], v[4:7], v[54:57]
	v_mfma_f32_16x16x32_bf16 v[12:15], v[70:73], v[12:15], v[62:65]
	v_mfma_f32_16x16x32_bf16 v[20:23], v[70:73], v[58:61], v[46:49]
	v_mfma_f32_16x16x32_bf16 v[38:41], v[70:73], v[66:69], v[50:53]
	s_setprio 0
	v_lshlrev_b64 v[96:97], 1, v[28:29]
	v_lshl_add_u64 v[28:29], s[4:5], 0, v[96:97]
	v_mad_i64_i32 v[34:35], s[34:35], v94, s51, v[28:29]
	v_add_u32_e32 v102, 0x4010, v30
	v_add_u32_e32 v100, 0x4020, v30
	s_waitcnt lgkmcnt(0)
	s_barrier
	v_mad_i64_i32 v[36:37], s[34:35], v102, s51, v[28:29]
	s_waitcnt vmcnt(0)
	flat_load_dwordx2 v[104:105], v[34:35]
	flat_load_dwordx2 v[106:107], v[34:35] offset:32
	flat_load_dwordx2 v[108:109], v[36:37]
	flat_load_dwordx2 v[110:111], v[36:37] offset:32
	v_mad_i64_i32 v[34:35], s[34:35], v100, s51, v[28:29]
	v_add_u32_e32 v98, 0x4030, v30
	v_mov_b32_e32 v42, v186
	v_mad_i64_i32 v[28:29], s[34:35], v98, s51, v[28:29]
	flat_load_dwordx2 v[112:113], v[34:35]
	flat_load_dwordx2 v[114:115], v[34:35] offset:32
	flat_load_dwordx2 v[116:117], v[28:29]
	flat_load_dwordx2 v[122:123], v[28:29] offset:32
	s_waitcnt lgkmcnt(0)
	s_barrier
;     __device__ __forceinline__ bf16_t* WbrB() const { return (bf16_t*)(ws + OFF_WbrB); }
;     __device__ __forceinline__ bf16_t* Of() const { return (bf16_t*)(ws + OFF_Of); }
; DEV int tid_opaque() { int t = threadIdx.x; asm volatile("" : "+v"(t)); return t; }
; #define RAW_BARRIER() do { asm volatile("s_waitcnt lgkmcnt(0)" ::: "memory"); __builtin_amdgcn_s_barrier(); } while (0)
; #define GLDS_TILE(kt, st) do { _Pragma("unroll") for (int _i = 0; _i < NP; ++_i) GLDS_PIECE(_i, kt, st); } while (0)
;     constexpr int BROWS = 32 * NI, STAGE = 8192 + BROWS * 64, NB = BROWS / 64;
;     const int t = tid_opaque(), lane = t & 63, wid = t >> 6, wm = wid >> 1, wn = wid & 1, fr = lane & 15, fq = lane >> 4;
;     const int nk = K >> 5;
;     const int srow = wid * 16 + (lane >> 2), sch = (lane & 3) ^ ((0 - (lane >> 4)) & 3);
;     const bf16_t* ga = A + (size_t)srow * lda + sch * 8;
;     const bf16_t* gb = B + (size_t)srow * ldb + sch * 8;
;     const int rd = fr * 64 + ((fq ^ ((0 - (fr >> 2)) & 3)) << 4);
;     const int rda = (wm * 64) * 64 + rd, rdb = 8192 + (wn * 16 * NI) * 64 + rd;
;     ...
;     constexpr int NH = NI >= 4 ? NI / 2 : NI;
;     constexpr int NP = 2 + NB, IVL = (4 * NI) / NP;
;     RAW_BARRIER();
;     GLDS_TILE(0, 0);
;     GLDS_TILE(1, 1);
;     int st = 0;
;     for (int kt = 0; kt < nk - 1; ++kt) {
;         if (NI == 8) asm volatile("s_waitcnt vmcnt(6)" ::: "memory"); else if (NI == 4) asm volatile("s_waitcnt vmcnt(4)" ::: "memory"); else asm volatile("s_waitcnt vmcnt(3)" ::: "memory");
;         RAW_BARRIER();
;         const int s2 = st >= 1 ? st - 1 : 2;
;         const bool ld = kt + 2 < nk;
;         STEP_TILE(st, ld, kt + 2, s2);
;         st = st == 2 ? 0 : st + 1;
;     }
; DEV void merge_big(const Params& p, int l, int mt, int nt, char* smem) {
;     ...
;         else if (br == 1) gemm_glds<2>(p.Of() + (size_t)mt * 128 * 384, 384, p.WbrB() + (size_t)l * 1024 * 384 + (size_t)nt * 64 * 384, 384, 384, acc, smem);
	v_bfe_u32 v44, v42, 4, 2
	v_sub_u32_e32 v34, 0, v44
	v_ashrrev_i32_e32 v43, 6, v42
	v_bfe_u32 v28, v42, 2, 4
	v_xor_b32_e32 v31, v42, v34
	v_lshl_or_b32 v30, v43, 4, v28
	v_mov_b64_e32 v[28:29], s[6:7]
	v_lshlrev_b32_e32 v31, 4, v31
	v_mad_i64_i32 v[28:29], s[34:35], v30, s48, v[28:29]
	v_and_b32_e32 v32, 48, v31
	v_lshl_add_u64 v[28:29], v[28:29], 0, v[32:33]
	v_mad_i64_i32 v[30:31], s[34:35], v30, s48, 0
	v_bitop3_b32 v32, v42, 3, v34 bitop3:0x48
	v_lshl_or_b32 v30, v32, 4, v30
	v_lshl_add_u32 v32, v43, 10, 0
	v_add_u32_e32 v46, 0x1000, v32
	v_readfirstlane_b32 s41, v32
	v_add_u32_e32 v45, 0x2000, v32
	s_mov_b32 m0, s41
	v_readfirstlane_b32 s40, v46
	v_lshl_add_u64 v[30:31], s[18:19], 0, v[30:31]
	s_mov_b64 s[18:19], 0x1880000
	global_load_lds_dwordx4 v[28:29], off
	v_lshl_add_u64 v[36:37], v[28:29], 0, s[66:67]
	s_mov_b32 m0, s40
	v_readfirstlane_b32 s39, v45
	v_add_u32_e32 v45, 0x3000, v32
	v_lshl_add_u64 v[34:35], v[30:31], 0, s[18:19]
	global_load_lds_dwordx4 v[36:37], off
	s_mov_b32 m0, s39
	s_mov_b64 s[18:19], 0x1880040
	v_readfirstlane_b32 s31, v45
	v_add_u32_e32 v45, 0x4000, v32
	global_load_lds_dwordx4 v[34:35], off
	v_lshl_add_u64 v[34:35], v[30:31], 0, s[18:19]
	v_add_u32_e32 v46, 0x5000, v32
	v_lshl_add_u64 v[36:37], v[28:29], 0, 64
	s_mov_b32 m0, s31
	v_readfirstlane_b32 s19, v45
	global_load_lds_dwordx4 v[36:37], off
	v_lshl_add_u64 v[36:37], v[28:29], 0, s[68:69]
	s_mov_b32 m0, s19
	v_readfirstlane_b32 s18, v46
	global_load_lds_dwordx4 v[36:37], off
	s_mov_b32 m0, s18
	v_lshlrev_b32_e32 v36, 11, v43
	global_load_lds_dwordx4 v[34:35], off
	v_lshrrev_b32_e32 v35, 2, v42
	v_lshlrev_b32_e32 v34, 6, v42
	v_sub_u32_e32 v35, 0, v35
	v_and_b32_e32 v34, 0x3c0, v34
	v_bitop3_b32 v35, v44, v35, 3 bitop3:0x78
	v_lshl_or_b32 v34, v35, 4, v34
	v_lshlrev_b32_e32 v35, 5, v42
	v_and_or_b32 v35, v35, s49, v34
	s_waitcnt vmcnt(3)
	v_add_u32_e32 v124, 0, v35
	v_and_or_b32 v54, v36, s50, v34
	s_waitcnt lgkmcnt(0)
	s_barrier
	ds_read_b128 v[34:37], v124
	ds_read_b128 v[42:45], v124 offset:1024
	ds_read_b128 v[46:49], v124 offset:2048
	ds_read_b128 v[50:53], v124 offset:3072
	v_add_u32_e32 v125, 0, v54
	ds_read_b128 v[54:57], v125 offset:8192
	ds_read_b128 v[58:61], v125 offset:9216
	v_ashrrev_i32_e32 v95, 31, v94
	v_ashrrev_i32_e32 v103, 31, v102
	v_ashrrev_i32_e32 v101, 31, v100
	v_ashrrev_i32_e32 v99, 31, v98
	s_setprio 1
	s_mov_b64 s[34:35], 0x1880080
	v_add_u32_e32 v72, 0x6000, v32
	s_waitcnt lgkmcnt(0)
	v_mfma_f32_16x16x32_bf16 v[62:65], v[54:57], v[34:37], 0
	v_lshl_add_u64 v[74:75], v[30:31], 0, s[34:35]
	v_add_u32_e32 v78, 0x8000, v32
	v_lshl_add_u64 v[70:71], v[28:29], 0, s[54:55]
	v_mfma_f32_16x16x32_bf16 v[66:69], v[54:57], v[42:45], 0
	v_readfirstlane_b32 s34, v72
	s_mov_b32 m0, s34
	s_nop 0
	global_load_lds_dwordx4 v[70:71], off
	v_mfma_f32_16x16x32_bf16 v[70:73], v[54:57], v[46:49], 0
	v_mfma_f32_16x16x32_bf16 v[54:57], v[54:57], v[50:53], 0
	v_add_u32_e32 v32, 0x7000, v32
	v_lshl_add_u64 v[76:77], v[28:29], 0, s[96:97]
	v_readfirstlane_b32 s35, v32
	s_mov_b32 m0, s35
	s_nop 0
	global_load_lds_dwordx4 v[76:77], off
	v_mfma_f32_16x16x32_bf16 v[34:37], v[58:61], v[34:37], 0
	v_mfma_f32_16x16x32_bf16 v[42:45], v[58:61], v[42:45], 0
	v_readfirstlane_b32 s38, v78
	s_mov_b32 m0, s38
	s_nop 0
	global_load_lds_dwordx4 v[74:75], off
	v_mfma_f32_16x16x32_bf16 v[46:49], v[58:61], v[46:49], 0
	v_mfma_f32_16x16x32_bf16 v[50:53], v[58:61], v[50:53], 0
	s_setprio 0
	s_waitcnt vmcnt(3)
	s_waitcnt lgkmcnt(0)
	s_barrier
	ds_read_b128 v[58:61], v124 offset:12288
	ds_read_b128 v[74:77], v124 offset:13312
	ds_read_b128 v[78:81], v124 offset:14336
	ds_read_b128 v[82:85], v124 offset:15360
	ds_read_b128 v[86:89], v125 offset:20480
	ds_read_b128 v[90:93], v125 offset:21504
	s_setprio 1
	s_mov_b64 s[42:43], 0x18800c0
	s_waitcnt lgkmcnt(0)
	v_mfma_f32_16x16x32_bf16 v[62:65], v[86:89], v[58:61], v[62:65]
	v_lshl_add_u64 v[118:119], v[30:31], 0, s[42:43]
	v_lshl_add_u64 v[120:121], v[28:29], 0, s[56:57]
	v_mfma_f32_16x16x32_bf16 v[66:69], v[86:89], v[74:77], v[66:69]
	s_mov_b32 m0, s41
	v_mfma_f32_16x16x32_bf16 v[70:73], v[86:89], v[78:81], v[70:73]
	global_load_lds_dwordx4 v[120:121], off
	v_mfma_f32_16x16x32_bf16 v[54:57], v[86:89], v[82:85], v[54:57]
	v_lshl_add_u64 v[86:87], v[28:29], 0, s[94:95]
	s_mov_b32 m0, s40
	v_mfma_f32_16x16x32_bf16 v[34:37], v[90:93], v[58:61], v[34:37]
	global_load_lds_dwordx4 v[86:87], off
	v_mfma_f32_16x16x32_bf16 v[42:45], v[90:93], v[74:77], v[42:45]
	s_mov_b32 m0, s39
	v_mfma_f32_16x16x32_bf16 v[46:49], v[90:93], v[78:81], v[46:49]
	global_load_lds_dwordx4 v[118:119], off
	v_mfma_f32_16x16x32_bf16 v[50:53], v[90:93], v[82:85], v[50:53]
	s_setprio 0
	s_waitcnt vmcnt(3)
	s_waitcnt lgkmcnt(0)
	s_barrier
	ds_read_b128 v[58:61], v124 offset:24576
	ds_read_b128 v[74:77], v124 offset:25600
	ds_read_b128 v[78:81], v124 offset:26624
	ds_read_b128 v[82:85], v124 offset:27648
	ds_read_b128 v[86:89], v125 offset:32768
	ds_read_b128 v[90:93], v125 offset:33792
	s_setprio 1
	s_mov_b64 s[42:43], 0x1880100
	s_waitcnt lgkmcnt(0)
	v_mfma_f32_16x16x32_bf16 v[62:65], v[86:89], v[58:61], v[62:65]
	v_lshl_add_u64 v[118:119], v[30:31], 0, s[42:43]
	v_lshl_add_u64 v[120:121], v[28:29], 0, s[58:59]
	v_mfma_f32_16x16x32_bf16 v[66:69], v[86:89], v[74:77], v[66:69]
	s_mov_b32 m0, s31
	v_mfma_f32_16x16x32_bf16 v[70:73], v[86:89], v[78:81], v[70:73]
	global_load_lds_dwordx4 v[120:121], off
	v_mfma_f32_16x16x32_bf16 v[54:57], v[86:89], v[82:85], v[54:57]
	v_lshl_add_u64 v[86:87], v[28:29], 0, s[70:71]
	s_mov_b32 m0, s19
	v_mfma_f32_16x16x32_bf16 v[34:37], v[90:93], v[58:61], v[34:37]
	global_load_lds_dwordx4 v[86:87], off
	v_mfma_f32_16x16x32_bf16 v[42:45], v[90:93], v[74:77], v[42:45]
	s_mov_b32 m0, s18
	v_mfma_f32_16x16x32_bf16 v[46:49], v[90:93], v[78:81], v[46:49]
	global_load_lds_dwordx4 v[118:119], off
	v_mfma_f32_16x16x32_bf16 v[50:53], v[90:93], v[82:85], v[50:53]
	s_setprio 0
	s_waitcnt vmcnt(3)
	s_waitcnt lgkmcnt(0)
	s_barrier
; #define RAW_BARRIER() do { asm volatile("s_waitcnt lgkmcnt(0)" ::: "memory"); __builtin_amdgcn_s_barrier(); } while (0)
; #define GLDS_TILE(kt, st) do { _Pragma("unroll") for (int _i = 0; _i < NP; ++_i) GLDS_PIECE(_i, kt, st); } while (0)
;     ...
;     constexpr int NH = NI >= 4 ? NI / 2 : NI;
;     constexpr int NP = 2 + NB, IVL = (4 * NI) / NP;
;     RAW_BARRIER();
;     GLDS_TILE(0, 0);
;     GLDS_TILE(1, 1);
;     int st = 0;
;     for (int kt = 0; kt < nk - 1; ++kt) {
;         if (NI == 8) asm volatile("s_waitcnt vmcnt(6)" ::: "memory"); else if (NI == 4) asm volatile("s_waitcnt vmcnt(4)" ::: "memory"); else asm volatile("s_waitcnt vmcnt(3)" ::: "memory");
;         RAW_BARRIER();
;         const int s2 = st >= 1 ? st - 1 : 2;
;         const bool ld = kt + 2 < nk;
;         STEP_TILE(st, ld, kt + 2, s2);
;         st = st == 2 ? 0 : st + 1;
;     }
	ds_read_b128 v[58:61], v124
	ds_read_b128 v[74:77], v124 offset:1024
	ds_read_b128 v[78:81], v124 offset:2048
	ds_read_b128 v[82:85], v124 offset:3072
	ds_read_b128 v[86:89], v125 offset:8192
	ds_read_b128 v[90:93], v125 offset:9216
	s_setprio 1
	s_mov_b64 s[42:43], 0x1880140
	s_waitcnt lgkmcnt(0)
	v_mfma_f32_16x16x32_bf16 v[62:65], v[86:89], v[58:61], v[62:65]
	v_lshl_add_u64 v[118:119], v[30:31], 0, s[42:43]
	v_lshl_add_u64 v[120:121], v[28:29], 0, s[60:61]
	v_mfma_f32_16x16x32_bf16 v[66:69], v[86:89], v[74:77], v[66:69]
	s_mov_b32 m0, s34
	v_mfma_f32_16x16x32_bf16 v[70:73], v[86:89], v[78:81], v[70:73]
	global_load_lds_dwordx4 v[120:121], off
	v_mfma_f32_16x16x32_bf16 v[54:57], v[86:89], v[82:85], v[54:57]
	v_lshl_add_u64 v[86:87], v[28:29], 0, s[72:73]
	s_mov_b32 m0, s35
	v_mfma_f32_16x16x32_bf16 v[34:37], v[90:93], v[58:61], v[34:37]
	global_load_lds_dwordx4 v[86:87], off
	v_mfma_f32_16x16x32_bf16 v[42:45], v[90:93], v[74:77], v[42:45]
	s_mov_b32 m0, s38
	v_mfma_f32_16x16x32_bf16 v[46:49], v[90:93], v[78:81], v[46:49]
	global_load_lds_dwordx4 v[118:119], off
	v_mfma_f32_16x16x32_bf16 v[50:53], v[90:93], v[82:85], v[50:53]
	s_setprio 0
	s_waitcnt vmcnt(3)
	s_waitcnt lgkmcnt(0)
	s_barrier
	ds_read_b128 v[58:61], v124 offset:12288
	ds_read_b128 v[74:77], v124 offset:13312
	ds_read_b128 v[78:81], v124 offset:14336
	ds_read_b128 v[82:85], v124 offset:15360
	ds_read_b128 v[86:89], v125 offset:20480
	ds_read_b128 v[90:93], v125 offset:21504
	s_setprio 1
	s_mov_b64 s[42:43], 0x1880180
	s_waitcnt lgkmcnt(0)
	v_mfma_f32_16x16x32_bf16 v[62:65], v[86:89], v[58:61], v[62:65]
	v_lshl_add_u64 v[118:119], v[30:31], 0, s[42:43]
	v_lshl_add_u64 v[120:121], v[28:29], 0, s[62:63]
	v_mfma_f32_16x16x32_bf16 v[66:69], v[86:89], v[74:77], v[66:69]
	s_mov_b32 m0, s41
	v_mfma_f32_16x16x32_bf16 v[70:73], v[86:89], v[78:81], v[70:73]
	global_load_lds_dwordx4 v[120:121], off
	v_mfma_f32_16x16x32_bf16 v[54:57], v[86:89], v[82:85], v[54:57]
	v_lshl_add_u64 v[86:87], v[28:29], 0, s[84:85]
	s_mov_b32 m0, s40
	v_mfma_f32_16x16x32_bf16 v[34:37], v[90:93], v[58:61], v[34:37]
	global_load_lds_dwordx4 v[86:87], off
	v_mfma_f32_16x16x32_bf16 v[42:45], v[90:93], v[74:77], v[42:45]
	s_mov_b32 m0, s39
	v_mfma_f32_16x16x32_bf16 v[46:49], v[90:93], v[78:81], v[46:49]
	global_load_lds_dwordx4 v[118:119], off
	v_mfma_f32_16x16x32_bf16 v[50:53], v[90:93], v[82:85], v[50:53]
	s_setprio 0
	s_waitcnt vmcnt(3)
	s_waitcnt lgkmcnt(0)
	s_barrier
	ds_read_b128 v[58:61], v124 offset:24576
	ds_read_b128 v[74:77], v124 offset:25600
	ds_read_b128 v[78:81], v124 offset:26624
	ds_read_b128 v[82:85], v124 offset:27648
	ds_read_b128 v[86:89], v125 offset:32768
	ds_read_b128 v[90:93], v125 offset:33792
	s_setprio 1
	s_mov_b64 s[42:43], 0x18801c0
	s_waitcnt lgkmcnt(0)
	v_mfma_f32_16x16x32_bf16 v[62:65], v[86:89], v[58:61], v[62:65]
	v_lshl_add_u64 v[118:119], v[30:31], 0, s[42:43]
	v_lshl_add_u64 v[120:121], v[28:29], 0, s[64:65]
	v_mfma_f32_16x16x32_bf16 v[66:69], v[86:89], v[74:77], v[66:69]
	s_mov_b32 m0, s31
	v_mfma_f32_16x16x32_bf16 v[70:73], v[86:89], v[78:81], v[70:73]
	global_load_lds_dwordx4 v[120:121], off
	v_mfma_f32_16x16x32_bf16 v[54:57], v[86:89], v[82:85], v[54:57]
	v_lshl_add_u64 v[86:87], v[28:29], 0, s[46:47]
	s_mov_b32 m0, s19
	v_mfma_f32_16x16x32_bf16 v[34:37], v[90:93], v[58:61], v[34:37]
	global_load_lds_dwordx4 v[86:87], off
	v_mfma_f32_16x16x32_bf16 v[42:45], v[90:93], v[74:77], v[42:45]
	s_mov_b32 m0, s18
	v_mfma_f32_16x16x32_bf16 v[46:49], v[90:93], v[78:81], v[46:49]
	global_load_lds_dwordx4 v[118:119], off
	v_mfma_f32_16x16x32_bf16 v[50:53], v[90:93], v[82:85], v[50:53]
	s_setprio 0
	s_waitcnt vmcnt(3)
	s_waitcnt lgkmcnt(0)
	s_barrier
	ds_read_b128 v[58:61], v124
	ds_read_b128 v[74:77], v124 offset:1024
	ds_read_b128 v[78:81], v124 offset:2048
	ds_read_b128 v[82:85], v124 offset:3072
	ds_read_b128 v[86:89], v125 offset:8192
	ds_read_b128 v[90:93], v125 offset:9216
	s_setprio 1
	s_mov_b64 s[42:43], 0x1880200
	s_waitcnt lgkmcnt(0)
	v_mfma_f32_16x16x32_bf16 v[62:65], v[86:89], v[58:61], v[62:65]
	v_lshl_add_u64 v[118:119], v[30:31], 0, s[42:43]
	v_lshl_add_u64 v[120:121], v[28:29], 0, s[76:77]
	s_mov_b64 s[76:77], 0x8080
	s_mov_b64 s[46:47], 0x8040
	s_mov_b64 s[44:45], 0x8000
	v_mfma_f32_16x16x32_bf16 v[66:69], v[86:89], v[74:77], v[66:69]
	s_mov_b32 m0, s34
	v_mfma_f32_16x16x32_bf16 v[70:73], v[86:89], v[78:81], v[70:73]
	global_load_lds_dwordx4 v[120:121], off
	v_mfma_f32_16x16x32_bf16 v[54:57], v[86:89], v[82:85], v[54:57]
	v_lshl_add_u64 v[86:87], v[28:29], 0, vcc
	s_mov_b32 m0, s35
	v_mfma_f32_16x16x32_bf16 v[34:37], v[90:93], v[58:61], v[34:37]
	global_load_lds_dwordx4 v[86:87], off
	v_mfma_f32_16x16x32_bf16 v[42:45], v[90:93], v[74:77], v[42:45]
	s_mov_b32 m0, s38
	v_mfma_f32_16x16x32_bf16 v[46:49], v[90:93], v[78:81], v[46:49]
	global_load_lds_dwordx4 v[118:119], off
	v_mfma_f32_16x16x32_bf16 v[50:53], v[90:93], v[82:85], v[50:53]
	s_setprio 0
	s_waitcnt vmcnt(3)
	s_waitcnt lgkmcnt(0)
	s_barrier
	ds_read_b128 v[58:61], v124 offset:12288
	ds_read_b128 v[74:77], v124 offset:13312
	ds_read_b128 v[78:81], v124 offset:14336
	ds_read_b128 v[82:85], v124 offset:15360
	ds_read_b128 v[86:89], v125 offset:20480
	ds_read_b128 v[90:93], v125 offset:21504
	s_setprio 1
	s_mov_b64 s[42:43], 0x1880240
	s_waitcnt lgkmcnt(0)
	v_mfma_f32_16x16x32_bf16 v[62:65], v[86:89], v[58:61], v[62:65]
	v_lshl_add_u64 v[118:119], v[30:31], 0, s[42:43]
	v_lshl_add_u64 v[120:121], v[28:29], 0, s[86:87]
	v_mfma_f32_16x16x32_bf16 v[66:69], v[86:89], v[74:77], v[66:69]
	s_mov_b32 m0, s41
	v_mfma_f32_16x16x32_bf16 v[70:73], v[86:89], v[78:81], v[70:73]
	global_load_lds_dwordx4 v[120:121], off
	v_mfma_f32_16x16x32_bf16 v[54:57], v[86:89], v[82:85], v[54:57]
	v_lshl_add_u64 v[86:87], v[28:29], 0, s[90:91]
	s_mov_b32 m0, s40
	v_mfma_f32_16x16x32_bf16 v[34:37], v[90:93], v[58:61], v[34:37]
	global_load_lds_dwordx4 v[86:87], off
	v_mfma_f32_16x16x32_bf16 v[42:45], v[90:93], v[74:77], v[42:45]
	s_mov_b32 m0, s39
	v_mfma_f32_16x16x32_bf16 v[46:49], v[90:93], v[78:81], v[46:49]
	global_load_lds_dwordx4 v[118:119], off
	v_mfma_f32_16x16x32_bf16 v[50:53], v[90:93], v[82:85], v[50:53]
	s_setprio 0
	s_waitcnt vmcnt(3)
	s_waitcnt lgkmcnt(0)
	s_barrier
;     __device__ __forceinline__ bf16_t* WbrC() const { return (bf16_t*)(ws + OFF_WbrC); }
;     __device__ __forceinline__ bf16_t* G() const { return (bf16_t*)(ws + OFF_G); }
;     __device__ __forceinline__ bf16_t* Ob() const { return (bf16_t*)(ws + OFF_Ob); }
; DEV void ld_bf4(const bf16_t* p, float (&v)[4]) { uint2 w = *(const uint2*)p; v[0] = bf_lo(w.x); v[1] = bf_hi(w.x); v[2] = bf_lo(w.y); v[3] = bf_hi(w.y); }
; #define RAW_BARRIER() do { asm volatile("s_waitcnt lgkmcnt(0)" ::: "memory"); __builtin_amdgcn_s_barrier(); } while (0)
;     ...
;     for (int kt = 0; kt < nk - 1; ++kt) {
;         if (NI == 8) asm volatile("s_waitcnt vmcnt(6)" ::: "memory"); else if (NI == 4) asm volatile("s_waitcnt vmcnt(4)" ::: "memory"); else asm volatile("s_waitcnt vmcnt(3)" ::: "memory");
;         RAW_BARRIER();
;         const int s2 = st >= 1 ? st - 1 : 2;
;         const bool ld = kt + 2 < nk;
;         STEP_TILE(st, ld, kt + 2, s2);
;         st = st == 2 ? 0 : st + 1;
;     }
;     asm volatile("s_waitcnt vmcnt(0)" ::: "memory");
;     RAW_BARRIER();
;     STEP_TILE(st, false, 0, 0);
;     RAW_BARRIER();
; DEV void merge_big(const Params& p, int l, int mt, int nt, char* smem) {
;     ...
;         else gemm_glds<2>(p.Ob() + (size_t)mt * 128 * 256, 256, p.WbrC() + (size_t)l * 1024 * 256 + (size_t)nt * 64 * 256, 256, 256, acc, smem);
; #pragma unroll
;         for (int mi = 0; mi < 4; ++mi)
; #pragma unroll
;             for (int ni = 0; ni < 2; ++ni) {
;                 float g[4]; ld_bf4(p.G() + (size_t)(rbase + mi * 16) * 3072 + br * 1024 + c0 + ni * 16, g);
;                 const f32x4 gv = (f32x4){g[0], g[1], g[2], g[3]};
;                 if (br == 0) mg[mi][ni] = gv * acc[mi][ni]; else mg[mi][ni] += gv * acc[mi][ni];
	ds_read_b128 v[58:61], v124 offset:24576
	ds_read_b128 v[74:77], v124 offset:25600
	ds_read_b128 v[78:81], v124 offset:26624
	ds_read_b128 v[82:85], v124 offset:27648
	ds_read_b128 v[86:89], v125 offset:32768
	ds_read_b128 v[90:93], v125 offset:33792
	s_setprio 1
	s_mov_b64 s[40:41], 0x1880280
	s_waitcnt lgkmcnt(0)
	v_mfma_f32_16x16x32_bf16 v[62:65], v[86:89], v[58:61], v[62:65]
	v_lshl_add_u64 v[118:119], v[30:31], 0, s[40:41]
	v_lshl_add_u64 v[120:121], v[28:29], 0, s[88:89]
	v_mfma_f32_16x16x32_bf16 v[66:69], v[86:89], v[74:77], v[66:69]
	s_mov_b32 m0, s31
	v_mfma_f32_16x16x32_bf16 v[70:73], v[86:89], v[78:81], v[70:73]
	global_load_lds_dwordx4 v[120:121], off
	v_mfma_f32_16x16x32_bf16 v[54:57], v[86:89], v[82:85], v[54:57]
	v_lshl_add_u64 v[86:87], v[28:29], 0, s[80:81]
	s_mov_b32 m0, s19
	v_mfma_f32_16x16x32_bf16 v[34:37], v[90:93], v[58:61], v[34:37]
	global_load_lds_dwordx4 v[86:87], off
	v_mfma_f32_16x16x32_bf16 v[42:45], v[90:93], v[74:77], v[42:45]
	s_mov_b32 m0, s18
	v_mfma_f32_16x16x32_bf16 v[46:49], v[90:93], v[78:81], v[46:49]
	global_load_lds_dwordx4 v[118:119], off
	v_mfma_f32_16x16x32_bf16 v[50:53], v[90:93], v[82:85], v[50:53]
	s_setprio 0
	s_waitcnt vmcnt(3)
	s_waitcnt lgkmcnt(0)
	s_barrier
	ds_read_b128 v[58:61], v124
	ds_read_b128 v[74:77], v124 offset:1024
	ds_read_b128 v[78:81], v124 offset:2048
	ds_read_b128 v[82:85], v124 offset:3072
	ds_read_b128 v[86:89], v125 offset:8192
	ds_read_b128 v[90:93], v125 offset:9216
	s_setprio 1
	s_mov_b64 s[18:19], 0x18802c0
	s_waitcnt lgkmcnt(0)
	v_mfma_f32_16x16x32_bf16 v[62:65], v[86:89], v[58:61], v[62:65]
	v_lshl_add_u64 v[118:119], v[30:31], 0, s[18:19]
	v_lshl_add_u64 v[30:31], v[28:29], 0, s[92:93]
	v_mfma_f32_16x16x32_bf16 v[66:69], v[86:89], v[74:77], v[66:69]
	s_mov_b32 m0, s34
	v_mfma_f32_16x16x32_bf16 v[70:73], v[86:89], v[78:81], v[70:73]
	global_load_lds_dwordx4 v[30:31], off
	v_mfma_f32_16x16x32_bf16 v[54:57], v[86:89], v[82:85], v[54:57]
	v_lshl_add_u64 v[28:29], v[28:29], 0, s[78:79]
	s_mov_b32 m0, s35
	s_nop 0
	global_load_lds_dwordx4 v[28:29], off
	v_mfma_f32_16x16x32_bf16 v[28:31], v[90:93], v[58:61], v[34:37]
	v_mfma_f32_16x16x32_bf16 v[34:37], v[90:93], v[74:77], v[42:45]
	s_mov_b32 m0, s38
	s_nop 0
	global_load_lds_dwordx4 v[118:119], off
	v_mfma_f32_16x16x32_bf16 v[42:45], v[90:93], v[78:81], v[46:49]
	v_mfma_f32_16x16x32_bf16 v[46:49], v[90:93], v[82:85], v[50:53]
	s_setprio 0
	s_waitcnt vmcnt(3)
	s_waitcnt lgkmcnt(0)
	s_barrier
	s_nop 0
	ds_read_b128 v[50:53], v124 offset:12288
	ds_read_b128 v[58:61], v124 offset:13312
	ds_read_b128 v[74:77], v124 offset:14336
	ds_read_b128 v[78:81], v124 offset:15360
	ds_read_b128 v[82:85], v125 offset:20480
	ds_read_b128 v[86:89], v125 offset:21504
	s_setprio 1
	s_waitcnt lgkmcnt(0)
	v_mfma_f32_16x16x32_bf16 v[62:65], v[82:85], v[50:53], v[62:65]
	v_mfma_f32_16x16x32_bf16 v[66:69], v[82:85], v[58:61], v[66:69]
	v_mfma_f32_16x16x32_bf16 v[70:73], v[82:85], v[74:77], v[70:73]
	v_mfma_f32_16x16x32_bf16 v[54:57], v[82:85], v[78:81], v[54:57]
	v_mfma_f32_16x16x32_bf16 v[82:85], v[86:89], v[50:53], v[28:31]
	v_mfma_f32_16x16x32_bf16 v[58:61], v[86:89], v[58:61], v[34:37]
	v_mfma_f32_16x16x32_bf16 v[74:77], v[86:89], v[74:77], v[42:45]
	v_mfma_f32_16x16x32_bf16 v[78:81], v[86:89], v[78:81], v[46:49]
	s_setprio 0
	s_waitcnt vmcnt(0)
	s_waitcnt lgkmcnt(0)
	s_barrier
	ds_read_b128 v[34:37], v124 offset:24576
	ds_read_b128 v[46:49], v124 offset:25600
	ds_read_b128 v[86:89], v124 offset:26624
	ds_read_b128 v[90:93], v124 offset:27648
	ds_read_b128 v[118:121], v125 offset:32768
	ds_read_b128 v[124:127], v125 offset:33792
	s_setprio 1
	s_waitcnt lgkmcnt(0)
	v_mfma_f32_16x16x32_bf16 v[28:31], v[118:121], v[34:37], v[62:65]
	v_mfma_f32_16x16x32_bf16 v[42:45], v[118:121], v[46:49], v[66:69]
	v_mfma_f32_16x16x32_bf16 v[50:53], v[118:121], v[86:89], v[70:73]
	v_mfma_f32_16x16x32_bf16 v[66:69], v[118:121], v[90:93], v[54:57]
	v_mfma_f32_16x16x32_bf16 v[34:37], v[124:127], v[34:37], v[82:85]
	v_mfma_f32_16x16x32_bf16 v[46:49], v[124:127], v[46:49], v[58:61]
	v_mfma_f32_16x16x32_bf16 v[54:57], v[124:127], v[86:89], v[74:77]
	v_mfma_f32_16x16x32_bf16 v[82:85], v[124:127], v[90:93], v[78:81]
	s_setprio 0
	v_lshl_add_u64 v[58:59], s[8:9], 0, v[96:97]
	v_mad_i64_i32 v[60:61], s[18:19], v94, s51, v[58:59]
	s_waitcnt lgkmcnt(0)
	s_barrier
	v_mad_i64_i32 v[62:63], s[18:19], v102, s51, v[58:59]
	s_waitcnt vmcnt(0)
	flat_load_dwordx2 v[118:119], v[60:61]
	flat_load_dwordx2 v[120:121], v[60:61] offset:32
	flat_load_dwordx2 v[124:125], v[62:63]
	flat_load_dwordx2 v[126:127], v[62:63] offset:32
	v_mad_i64_i32 v[60:61], s[18:19], v100, s51, v[58:59]
	v_mov_b32_e32 v70, v186
	v_mad_i64_i32 v[58:59], s[18:19], v98, s51, v[58:59]
	flat_load_dwordx2 v[128:129], v[60:61]
	flat_load_dwordx2 v[130:131], v[60:61] offset:32
	flat_load_dwordx2 v[136:137], v[58:59]
	flat_load_dwordx2 v[144:145], v[58:59] offset:32
	s_add_u32 s18, s2, s28
	v_ashrrev_i32_e32 v71, 6, v70
	v_bfe_u32 v72, v70, 4, 2
	v_bfe_u32 v32, v70, 2, 4
	v_lshl_or_b32 v58, v71, 4, v32
	v_sub_u32_e32 v62, 0, v72
	v_xor_b32_e32 v32, v70, v62
	v_ashrrev_i32_e32 v59, 31, v58
	v_lshlrev_b64 v[60:61], 9, v[58:59]
	v_lshlrev_b32_e32 v32, 4, v32
	v_lshl_add_u64 v[58:59], s[10:11], 0, v[60:61]
	v_and_b32_e32 v32, 48, v32
	v_lshl_add_u64 v[58:59], v[58:59], 0, v[32:33]
	v_bitop3_b32 v32, v70, 3, v62 bitop3:0x48
	v_lshl_or_b32 v60, v32, 4, v60
	v_lshl_add_u32 v32, v71, 10, 0
	v_add_u32_e32 v74, 0x1000, v32
	v_readfirstlane_b32 s38, v32
	s_addc_u32 s19, s3, s29
	v_add_u32_e32 v73, 0x2000, v32
	s_mov_b32 m0, s38
	v_readfirstlane_b32 s35, v74
	v_lshl_add_u64 v[60:61], s[18:19], 0, v[60:61]
	s_mov_b64 s[18:19], 0x1a00000
	s_waitcnt lgkmcnt(0)
	s_barrier
;     __device__ __forceinline__ bf16_t* WbrC() const { return (bf16_t*)(ws + OFF_WbrC); }
;     __device__ __forceinline__ bf16_t* Ob() const { return (bf16_t*)(ws + OFF_Ob); }
; DEV int tid_opaque() { int t = threadIdx.x; asm volatile("" : "+v"(t)); return t; }
; #define RAW_BARRIER() do { asm volatile("s_waitcnt lgkmcnt(0)" ::: "memory"); __builtin_amdgcn_s_barrier(); } while (0)
; #define GLDS_TILE(kt, st) do { _Pragma("unroll") for (int _i = 0; _i < NP; ++_i) GLDS_PIECE(_i, kt, st); } while (0)
;     ...
;     const int t = tid_opaque(), lane = t & 63, wid = t >> 6, wm = wid >> 1, wn = wid & 1, fr = lane & 15, fq = lane >> 4;
;     const int nk = K >> 5;
;     const int srow = wid * 16 + (lane >> 2), sch = (lane & 3) ^ ((0 - (lane >> 4)) & 3);
;     const bf16_t* ga = A + (size_t)srow * lda + sch * 8;
;     const bf16_t* gb = B + (size_t)srow * ldb + sch * 8;
;     const int rd = fr * 64 + ((fq ^ ((0 - (fr >> 2)) & 3)) << 4);
;     const int rda = (wm * 64) * 64 + rd, rdb = 8192 + (wn * 16 * NI) * 64 + rd;
;     ...
;     constexpr int NH = NI >= 4 ? NI / 2 : NI;
;     constexpr int NP = 2 + NB, IVL = (4 * NI) / NP;
;     RAW_BARRIER();
;     GLDS_TILE(0, 0);
;     GLDS_TILE(1, 1);
;     int st = 0;
;     for (int kt = 0; kt < nk - 1; ++kt) {
;         if (NI == 8) asm volatile("s_waitcnt vmcnt(6)" ::: "memory"); else if (NI == 4) asm volatile("s_waitcnt vmcnt(4)" ::: "memory"); else asm volatile("s_waitcnt vmcnt(3)" ::: "memory");
;         RAW_BARRIER();
;         const int s2 = st >= 1 ? st - 1 : 2;
;         const bool ld = kt + 2 < nk;
;         STEP_TILE(st, ld, kt + 2, s2);
;         st = st == 2 ? 0 : st + 1;
;     }
; DEV void merge_big(const Params& p, int l, int mt, int nt, char* smem) {
;     ...
;         else gemm_glds<2>(p.Ob() + (size_t)mt * 128 * 256, 256, p.WbrC() + (size_t)l * 1024 * 256 + (size_t)nt * 64 * 256, 256, 256, acc, smem);
	global_load_lds_dwordx4 v[58:59], off
	v_lshl_add_u64 v[64:65], v[58:59], 0, s[44:45]
	s_mov_b32 m0, s35
	v_readfirstlane_b32 s34, v73
	v_add_u32_e32 v73, 0x3000, v32
	v_lshl_add_u64 v[62:63], v[60:61], 0, s[18:19]
	global_load_lds_dwordx4 v[64:65], off
	s_mov_b32 m0, s34
	s_mov_b64 s[18:19], 0x1a00040
	v_readfirstlane_b32 s31, v73
	v_add_u32_e32 v73, 0x4000, v32
	global_load_lds_dwordx4 v[62:63], off
	v_lshl_add_u64 v[62:63], v[60:61], 0, s[18:19]
	v_add_u32_e32 v74, 0x5000, v32
	v_lshl_add_u64 v[64:65], v[58:59], 0, 64
	s_mov_b32 m0, s31
	v_readfirstlane_b32 s19, v73
	global_load_lds_dwordx4 v[64:65], off
	v_lshl_add_u64 v[64:65], v[58:59], 0, s[46:47]
	s_mov_b32 m0, s19
	v_readfirstlane_b32 s18, v74
	global_load_lds_dwordx4 v[64:65], off
	s_mov_b32 m0, s18
	v_lshlrev_b32_e32 v64, 11, v71
	global_load_lds_dwordx4 v[62:63], off
	v_lshrrev_b32_e32 v63, 2, v70
	v_lshlrev_b32_e32 v62, 6, v70
	v_sub_u32_e32 v63, 0, v63
	v_and_b32_e32 v62, 0x3c0, v62
	v_bitop3_b32 v63, v72, v63, 3 bitop3:0x78
	v_lshl_or_b32 v62, v63, 4, v62
	v_lshlrev_b32_e32 v63, 5, v70
	v_and_or_b32 v63, v63, s49, v62
	s_waitcnt vmcnt(3)
	v_add_u32_e32 v155, 0, v63
	v_and_or_b32 v86, v64, s50, v62
	s_waitcnt lgkmcnt(0)
	s_barrier
	ds_read_b128 v[62:65], v155
	ds_read_b128 v[70:73], v155 offset:1024
	ds_read_b128 v[74:77], v155 offset:2048
	ds_read_b128 v[78:81], v155 offset:3072
	v_add_u32_e32 v157, 0, v86
	ds_read_b128 v[86:89], v157 offset:8192
	ds_read_b128 v[90:93], v157 offset:9216
	s_setprio 1
	s_mov_b64 s[40:41], 0x1a00080
	v_add_u32_e32 v148, 0x6000, v32
	s_waitcnt lgkmcnt(0)
	v_mfma_f32_16x16x32_bf16 v[132:135], v[86:89], v[62:65], 0
	v_lshl_add_u64 v[142:143], v[60:61], 0, s[40:41]
	v_add_u32_e32 v152, 0x8000, v32
	v_lshl_add_u64 v[146:147], v[58:59], 0, s[54:55]
	v_mfma_f32_16x16x32_bf16 v[138:141], v[86:89], v[70:73], 0
	v_readfirstlane_b32 s39, v148
	s_mov_b32 m0, s39
	s_nop 0
	global_load_lds_dwordx4 v[146:147], off
	v_mfma_f32_16x16x32_bf16 v[146:149], v[86:89], v[74:77], 0
	v_mfma_f32_16x16x32_bf16 v[86:89], v[86:89], v[78:81], 0
	v_add_u32_e32 v32, 0x7000, v32
	v_lshl_add_u64 v[150:151], v[58:59], 0, s[76:77]
	v_readfirstlane_b32 s42, v32
	s_mov_b32 m0, s42
	s_mov_b64 s[76:77], 0x8140
	global_load_lds_dwordx4 v[150:151], off
	s_mov_b64 s[46:47], 0x8100
	s_mov_b64 s[44:45], 0x80c0
	v_mfma_f32_16x16x32_bf16 v[62:65], v[90:93], v[62:65], 0
	v_mfma_f32_16x16x32_bf16 v[70:73], v[90:93], v[70:73], 0
	v_readfirstlane_b32 s43, v152
	s_mov_b32 m0, s43
	s_nop 0
	global_load_lds_dwordx4 v[142:143], off
	v_mfma_f32_16x16x32_bf16 v[74:77], v[90:93], v[74:77], 0
	v_mfma_f32_16x16x32_bf16 v[78:81], v[90:93], v[78:81], 0
	s_setprio 0
	s_waitcnt vmcnt(3)
	s_waitcnt lgkmcnt(0)
	s_barrier
	ds_read_b128 v[90:93], v155 offset:12288
	ds_read_b128 v[150:153], v155 offset:13312
	ds_read_b128 v[158:161], v155 offset:14336
	ds_read_b128 v[162:165], v155 offset:15360
	ds_read_b128 v[166:169], v157 offset:20480
	ds_read_b128 v[170:173], v157 offset:21504
	s_setprio 1
	s_mov_b64 s[40:41], 0x1a000c0
	s_waitcnt lgkmcnt(0)
	v_mfma_f32_16x16x32_bf16 v[132:135], v[166:169], v[90:93], v[132:135]
	v_lshl_add_u64 v[142:143], v[60:61], 0, s[40:41]
	v_lshl_add_u64 v[174:175], v[58:59], 0, s[56:57]
	v_mfma_f32_16x16x32_bf16 v[138:141], v[166:169], v[150:153], v[138:141]
	s_mov_b32 m0, s38
	v_mfma_f32_16x16x32_bf16 v[146:149], v[166:169], v[158:161], v[146:149]
	global_load_lds_dwordx4 v[174:175], off
	v_mfma_f32_16x16x32_bf16 v[86:89], v[166:169], v[162:165], v[86:89]
	v_lshl_add_u64 v[166:167], v[58:59], 0, s[44:45]
	s_mov_b32 m0, s35
	v_mfma_f32_16x16x32_bf16 v[62:65], v[170:173], v[90:93], v[62:65]
	global_load_lds_dwordx4 v[166:167], off
	v_mfma_f32_16x16x32_bf16 v[70:73], v[170:173], v[150:153], v[70:73]
	s_mov_b32 m0, s34
	v_mfma_f32_16x16x32_bf16 v[74:77], v[170:173], v[158:161], v[74:77]
	global_load_lds_dwordx4 v[142:143], off
	v_mfma_f32_16x16x32_bf16 v[78:81], v[170:173], v[162:165], v[78:81]
	s_setprio 0
	s_waitcnt vmcnt(3)
	s_waitcnt lgkmcnt(0)
	s_barrier
	ds_read_b128 v[90:93], v155 offset:24576
	ds_read_b128 v[150:153], v155 offset:25600
	ds_read_b128 v[158:161], v155 offset:26624
	ds_read_b128 v[162:165], v155 offset:27648
	ds_read_b128 v[166:169], v157 offset:32768
	ds_read_b128 v[170:173], v157 offset:33792
	s_setprio 1
	s_mov_b64 s[40:41], 0x1a00100
	s_waitcnt lgkmcnt(0)
	v_mfma_f32_16x16x32_bf16 v[132:135], v[166:169], v[90:93], v[132:135]
	v_lshl_add_u64 v[142:143], v[60:61], 0, s[40:41]
	v_lshl_add_u64 v[174:175], v[58:59], 0, s[58:59]
	v_mfma_f32_16x16x32_bf16 v[138:141], v[166:169], v[150:153], v[138:141]
	s_mov_b32 m0, s31
	v_mfma_f32_16x16x32_bf16 v[146:149], v[166:169], v[158:161], v[146:149]
	global_load_lds_dwordx4 v[174:175], off
	v_mfma_f32_16x16x32_bf16 v[86:89], v[166:169], v[162:165], v[86:89]
	v_lshl_add_u64 v[166:167], v[58:59], 0, s[46:47]
	s_mov_b32 m0, s19
	v_mfma_f32_16x16x32_bf16 v[62:65], v[170:173], v[90:93], v[62:65]
	global_load_lds_dwordx4 v[166:167], off
	v_mfma_f32_16x16x32_bf16 v[70:73], v[170:173], v[150:153], v[70:73]
	s_mov_b32 m0, s18
	v_mfma_f32_16x16x32_bf16 v[74:77], v[170:173], v[158:161], v[74:77]
	global_load_lds_dwordx4 v[142:143], off
	v_mfma_f32_16x16x32_bf16 v[78:81], v[170:173], v[162:165], v[78:81]
	s_setprio 0
	s_waitcnt vmcnt(3)
	s_waitcnt lgkmcnt(0)
	s_barrier
;     __device__ __forceinline__ bf16_t* G() const { return (bf16_t*)(ws + OFF_G); }
; DEV void ld_bf4(const bf16_t* p, float (&v)[4]) { uint2 w = *(const uint2*)p; v[0] = bf_lo(w.x); v[1] = bf_hi(w.x); v[2] = bf_lo(w.y); v[3] = bf_hi(w.y); }
; #define RAW_BARRIER() do { asm volatile("s_waitcnt lgkmcnt(0)" ::: "memory"); __builtin_amdgcn_s_barrier(); } while (0)
;     ...
;     for (int kt = 0; kt < nk - 1; ++kt) {
;         if (NI == 8) asm volatile("s_waitcnt vmcnt(6)" ::: "memory"); else if (NI == 4) asm volatile("s_waitcnt vmcnt(4)" ::: "memory"); else asm volatile("s_waitcnt vmcnt(3)" ::: "memory");
;         RAW_BARRIER();
;         const int s2 = st >= 1 ? st - 1 : 2;
;         const bool ld = kt + 2 < nk;
;         STEP_TILE(st, ld, kt + 2, s2);
;         st = st == 2 ? 0 : st + 1;
;     }
;     asm volatile("s_waitcnt vmcnt(0)" ::: "memory");
;     RAW_BARRIER();
;     STEP_TILE(st, false, 0, 0);
;     RAW_BARRIER();
; DEV void merge_big(const Params& p, int l, int mt, int nt, char* smem) {
;     ...
; #pragma unroll
;         for (int mi = 0; mi < 4; ++mi)
; #pragma unroll
;             for (int ni = 0; ni < 2; ++ni) {
;                 float g[4]; ld_bf4(p.G() + (size_t)(rbase + mi * 16) * 3072 + br * 1024 + c0 + ni * 16, g);
;                 const f32x4 gv = (f32x4){g[0], g[1], g[2], g[3]};
;                 if (br == 0) mg[mi][ni] = gv * acc[mi][ni]; else mg[mi][ni] += gv * acc[mi][ni];
	ds_read_b128 v[90:93], v155
	ds_read_b128 v[150:153], v155 offset:1024
	ds_read_b128 v[158:161], v155 offset:2048
	ds_read_b128 v[162:165], v155 offset:3072
	ds_read_b128 v[166:169], v157 offset:8192
	ds_read_b128 v[170:173], v157 offset:9216
	s_setprio 1
	s_mov_b64 s[40:41], 0x1a00140
	s_waitcnt lgkmcnt(0)
	v_mfma_f32_16x16x32_bf16 v[132:135], v[166:169], v[90:93], v[132:135]
	v_lshl_add_u64 v[142:143], v[60:61], 0, s[40:41]
	v_lshl_add_u64 v[174:175], v[58:59], 0, s[60:61]
	v_mfma_f32_16x16x32_bf16 v[138:141], v[166:169], v[150:153], v[138:141]
	s_mov_b32 m0, s39
	v_mfma_f32_16x16x32_bf16 v[146:149], v[166:169], v[158:161], v[146:149]
	global_load_lds_dwordx4 v[174:175], off
	v_mfma_f32_16x16x32_bf16 v[86:89], v[166:169], v[162:165], v[86:89]
	v_lshl_add_u64 v[166:167], v[58:59], 0, s[76:77]
	s_mov_b32 m0, s42
	s_mov_b64 s[46:47], 0x81c0
	global_load_lds_dwordx4 v[166:167], off
	s_mov_b64 s[44:45], 0x8180
	v_mfma_f32_16x16x32_bf16 v[62:65], v[170:173], v[90:93], v[62:65]
	v_mfma_f32_16x16x32_bf16 v[70:73], v[170:173], v[150:153], v[70:73]
	s_mov_b32 m0, s43
	v_mfma_f32_16x16x32_bf16 v[74:77], v[170:173], v[158:161], v[74:77]
	global_load_lds_dwordx4 v[142:143], off
	v_mfma_f32_16x16x32_bf16 v[78:81], v[170:173], v[162:165], v[78:81]
	s_setprio 0
	s_waitcnt vmcnt(3)
	s_waitcnt lgkmcnt(0)
	s_barrier
	ds_read_b128 v[90:93], v155 offset:12288
	ds_read_b128 v[150:153], v155 offset:13312
	ds_read_b128 v[158:161], v155 offset:14336
	ds_read_b128 v[162:165], v155 offset:15360
	ds_read_b128 v[166:169], v157 offset:20480
	ds_read_b128 v[170:173], v157 offset:21504
	s_setprio 1
	s_mov_b64 s[40:41], 0x1a00180
	s_waitcnt lgkmcnt(0)
	v_mfma_f32_16x16x32_bf16 v[132:135], v[166:169], v[90:93], v[132:135]
	v_lshl_add_u64 v[142:143], v[60:61], 0, s[40:41]
	v_lshl_add_u64 v[174:175], v[58:59], 0, s[62:63]
	v_mfma_f32_16x16x32_bf16 v[138:141], v[166:169], v[150:153], v[138:141]
	s_mov_b32 m0, s38
	v_mfma_f32_16x16x32_bf16 v[146:149], v[166:169], v[158:161], v[146:149]
	global_load_lds_dwordx4 v[174:175], off
	v_mfma_f32_16x16x32_bf16 v[86:89], v[166:169], v[162:165], v[86:89]
	v_lshl_add_u64 v[166:167], v[58:59], 0, s[44:45]
	s_mov_b32 m0, s35
	v_mfma_f32_16x16x32_bf16 v[62:65], v[170:173], v[90:93], v[62:65]
	global_load_lds_dwordx4 v[166:167], off
	v_mfma_f32_16x16x32_bf16 v[70:73], v[170:173], v[150:153], v[70:73]
	s_mov_b32 m0, s34
	v_mfma_f32_16x16x32_bf16 v[74:77], v[170:173], v[158:161], v[74:77]
	global_load_lds_dwordx4 v[142:143], off
	v_mfma_f32_16x16x32_bf16 v[78:81], v[170:173], v[162:165], v[78:81]
	s_setprio 0
	s_waitcnt vmcnt(3)
	s_waitcnt lgkmcnt(0)
	s_barrier
	ds_read_b128 v[90:93], v155 offset:24576
	ds_read_b128 v[150:153], v155 offset:25600
	ds_read_b128 v[158:161], v155 offset:26624
	ds_read_b128 v[162:165], v155 offset:27648
	ds_read_b128 v[166:169], v157 offset:32768
	ds_read_b128 v[170:173], v157 offset:33792
	s_setprio 1
	s_mov_b64 s[34:35], 0x1a001c0
	s_waitcnt lgkmcnt(0)
	v_mfma_f32_16x16x32_bf16 v[132:135], v[166:169], v[90:93], v[132:135]
	v_lshl_add_u64 v[142:143], v[60:61], 0, s[34:35]
	v_lshl_add_u64 v[60:61], v[58:59], 0, s[64:65]
	v_mfma_f32_16x16x32_bf16 v[138:141], v[166:169], v[150:153], v[138:141]
	s_mov_b32 m0, s31
	v_mfma_f32_16x16x32_bf16 v[146:149], v[166:169], v[158:161], v[146:149]
	global_load_lds_dwordx4 v[60:61], off
	v_mfma_f32_16x16x32_bf16 v[86:89], v[166:169], v[162:165], v[86:89]
	v_lshl_add_u64 v[58:59], v[58:59], 0, s[46:47]
	s_mov_b32 m0, s19
	s_nop 0
	global_load_lds_dwordx4 v[58:59], off
	v_mfma_f32_16x16x32_bf16 v[58:61], v[170:173], v[90:93], v[62:65]
	v_mfma_f32_16x16x32_bf16 v[62:65], v[170:173], v[150:153], v[70:73]
	s_mov_b32 m0, s18
	s_nop 0
	global_load_lds_dwordx4 v[142:143], off
	v_mfma_f32_16x16x32_bf16 v[70:73], v[170:173], v[158:161], v[74:77]
	v_mfma_f32_16x16x32_bf16 v[74:77], v[170:173], v[162:165], v[78:81]
	s_setprio 0
	s_waitcnt vmcnt(3)
	s_waitcnt lgkmcnt(0)
	s_barrier
	s_nop 0
	ds_read_b128 v[78:81], v155
	ds_read_b128 v[90:93], v155 offset:1024
	ds_read_b128 v[150:153], v155 offset:2048
	ds_read_b128 v[158:161], v155 offset:3072
	ds_read_b128 v[162:165], v157 offset:8192
	ds_read_b128 v[166:169], v157 offset:9216
	s_setprio 1
	s_waitcnt lgkmcnt(0)
	v_mfma_f32_16x16x32_bf16 v[132:135], v[162:165], v[78:81], v[132:135]
	v_mfma_f32_16x16x32_bf16 v[138:141], v[162:165], v[90:93], v[138:141]
	v_mfma_f32_16x16x32_bf16 v[146:149], v[162:165], v[150:153], v[146:149]
	v_mfma_f32_16x16x32_bf16 v[86:89], v[162:165], v[158:161], v[86:89]
	v_mfma_f32_16x16x32_bf16 v[162:165], v[166:169], v[78:81], v[58:61]
	v_mfma_f32_16x16x32_bf16 v[170:173], v[166:169], v[90:93], v[62:65]
	v_mfma_f32_16x16x32_bf16 v[150:153], v[166:169], v[150:153], v[70:73]
	v_mfma_f32_16x16x32_bf16 v[158:161], v[166:169], v[158:161], v[74:77]
	s_setprio 0
	s_waitcnt vmcnt(0)
	s_waitcnt lgkmcnt(0)
	s_barrier
	ds_read_b128 v[62:65], v155 offset:12288
	ds_read_b128 v[74:77], v155 offset:13312
	ds_read_b128 v[166:169], v155 offset:14336
	ds_read_b128 v[174:177], v155 offset:15360
	ds_read_b128 v[90:93], v157 offset:20480
	ds_read_b128 v[178:181], v157 offset:21504
	s_setprio 1
	s_waitcnt lgkmcnt(0)
	v_mfma_f32_16x16x32_bf16 v[58:61], v[90:93], v[62:65], v[132:135]
	v_mfma_f32_16x16x32_bf16 v[70:73], v[90:93], v[74:77], v[138:141]
	v_mfma_f32_16x16x32_bf16 v[78:81], v[90:93], v[166:169], v[146:149]
	v_mfma_f32_16x16x32_bf16 v[90:93], v[90:93], v[174:177], v[86:89]
	v_mfma_f32_16x16x32_bf16 v[62:65], v[178:181], v[62:65], v[162:165]
	v_mfma_f32_16x16x32_bf16 v[74:77], v[178:181], v[74:77], v[170:173]
	v_mfma_f32_16x16x32_bf16 v[86:89], v[178:181], v[166:169], v[150:153]
	v_mfma_f32_16x16x32_bf16 v[148:151], v[178:181], v[174:177], v[158:161]
	s_setprio 0
	s_nop 0
	v_lshl_add_u64 v[152:153], s[12:13], 0, v[96:97]
	s_waitcnt vmcnt(0)
	v_lshlrev_b32_e32 v162, 16, v144
	v_and_b32_e32 v163, 0xffff0000, v144
	v_lshlrev_b32_e32 v144, 16, v145
	v_and_b32_e32 v145, 0xffff0000, v145
	v_mad_i64_i32 v[134:135], s[18:19], v94, s51, v[152:153]
	v_mad_i64_i32 v[140:141], s[18:19], v102, s51, v[152:153]
	v_mad_i64_i32 v[146:147], s[18:19], v100, s51, v[152:153]
	v_mad_i64_i32 v[152:153], s[18:19], v98, s51, v[152:153]
	v_lshlrev_b32_e32 v160, 16, v122
	v_and_b32_e32 v161, 0xffff0000, v122
	v_lshlrev_b32_e32 v122, 16, v123
	v_and_b32_e32 v123, 0xffff0000, v123
	v_pk_mul_f32 v[84:85], v[84:85], v[144:145]
	v_pk_mul_f32 v[82:83], v[82:83], v[162:163]
	s_waitcnt lgkmcnt(0)
	s_barrier
;     __device__ __forceinline__ bf16_t* G() const { return (bf16_t*)(ws + OFF_G); }
; DEV void ld_bf4(const bf16_t* p, float (&v)[4]) { uint2 w = *(const uint2*)p; v[0] = bf_lo(w.x); v[1] = bf_hi(w.x); v[2] = bf_lo(w.y); v[3] = bf_hi(w.y); }
; DEV void merge_big(const Params& p, int l, int mt, int nt, char* smem) {
;     ...
; #pragma unroll
;         for (int mi = 0; mi < 4; ++mi)
; #pragma unroll
;             for (int ni = 0; ni < 2; ++ni) {
;                 float g[4]; ld_bf4(p.G() + (size_t)(rbase + mi * 16) * 3072 + br * 1024 + c0 + ni * 16, g);
;                 const f32x4 gv = (f32x4){g[0], g[1], g[2], g[3]};
;                 if (br == 0) mg[mi][ni] = gv * acc[mi][ni]; else mg[mi][ni] += gv * acc[mi][ni];
;             }
	flat_load_dwordx2 v[132:133], v[134:135]
	s_nop 0
	flat_load_dwordx2 v[134:135], v[134:135] offset:32
	s_nop 0
	flat_load_dwordx2 v[138:139], v[140:141]
	s_nop 0
	flat_load_dwordx2 v[140:141], v[140:141] offset:32
	s_nop 0
	flat_load_dwordx2 v[142:143], v[146:147]
	s_nop 0
	flat_load_dwordx2 v[146:147], v[146:147] offset:32
	v_pk_fma_f32 v[82:83], v[38:39], v[160:161], v[82:83]
	flat_load_dwordx2 v[158:159], v[152:153]
	v_pk_fma_f32 v[38:39], v[40:41], v[122:123], v[84:85]
	flat_load_dwordx2 v[40:41], v[152:153] offset:32
	v_lshlrev_b32_e32 v122, 16, v137
	v_and_b32_e32 v123, 0xffff0000, v137
	v_pk_mul_f32 v[68:69], v[68:69], v[122:123]
	s_add_i32 s30, s30, s82
	s_add_i32 s20, s20, s21
	s_mul_i32 s18, s82, 0xc000
	s_add_u32 s22, s22, s18
	s_mul_hi_i32 s18, s82, 0xc000
	s_addc_u32 s23, s23, s18
	s_add_u32 s28, s28, s16
	s_addc_u32 s29, s29, s17
	s_cmp_gt_i32 s30, 15
	s_waitcnt vmcnt(0) lgkmcnt(0)
	v_lshlrev_b32_e32 v84, 16, v40
	v_and_b32_e32 v85, 0xffff0000, v40
	v_lshlrev_b32_e32 v40, 16, v41
	v_and_b32_e32 v41, 0xffff0000, v41
	v_pk_fma_f32 v[38:39], v[150:151], v[40:41], v[38:39]
	v_pk_fma_f32 v[40:41], v[148:149], v[84:85], v[82:83]
	v_lshlrev_b32_e32 v82, 16, v116
	v_and_b32_e32 v83, 0xffff0000, v116
	v_lshlrev_b32_e32 v84, 16, v117
	v_and_b32_e32 v85, 0xffff0000, v117
	v_lshlrev_b32_e32 v116, 16, v136
	v_and_b32_e32 v117, 0xffff0000, v136
	v_pk_mul_f32 v[66:67], v[66:67], v[116:117]
	s_nop 0
	v_pk_fma_f32 v[66:67], v[24:25], v[82:83], v[66:67]
	v_pk_fma_f32 v[24:25], v[26:27], v[84:85], v[68:69]
	v_lshlrev_b32_e32 v26, 16, v158
	v_and_b32_e32 v27, 0xffff0000, v158
	v_lshlrev_b32_e32 v68, 16, v159
	v_and_b32_e32 v69, 0xffff0000, v159
	v_lshlrev_b32_e32 v82, 16, v130
	v_and_b32_e32 v83, 0xffff0000, v130
	v_lshlrev_b32_e32 v84, 16, v131
	v_and_b32_e32 v85, 0xffff0000, v131
	v_pk_fma_f32 v[24:25], v[92:93], v[68:69], v[24:25]
	v_pk_fma_f32 v[26:27], v[90:91], v[26:27], v[66:67]
	v_lshlrev_b32_e32 v66, 16, v114
	v_and_b32_e32 v67, 0xffff0000, v114
	v_lshlrev_b32_e32 v68, 16, v115
	v_and_b32_e32 v69, 0xffff0000, v115
	v_pk_mul_f32 v[56:57], v[56:57], v[84:85]
	v_pk_mul_f32 v[54:55], v[54:55], v[82:83]
	s_nop 0
	v_pk_fma_f32 v[54:55], v[20:21], v[66:67], v[54:55]
	v_pk_fma_f32 v[20:21], v[22:23], v[68:69], v[56:57]
	v_lshlrev_b32_e32 v22, 16, v146
	v_and_b32_e32 v23, 0xffff0000, v146
	v_lshlrev_b32_e32 v66, 16, v128
	v_and_b32_e32 v67, 0xffff0000, v128
	v_lshlrev_b32_e32 v56, 16, v147
	v_and_b32_e32 v57, 0xffff0000, v147
	v_pk_fma_f32 v[22:23], v[86:87], v[22:23], v[54:55]
	v_lshlrev_b32_e32 v54, 16, v112
	v_and_b32_e32 v55, 0xffff0000, v112
	v_lshlrev_b32_e32 v68, 16, v129
	v_and_b32_e32 v69, 0xffff0000, v129
	v_pk_mul_f32 v[50:51], v[50:51], v[66:67]
	v_pk_fma_f32 v[20:21], v[88:89], v[56:57], v[20:21]
	v_lshlrev_b32_e32 v56, 16, v113
	v_and_b32_e32 v57, 0xffff0000, v113
	v_pk_mul_f32 v[52:53], v[52:53], v[68:69]
	v_pk_fma_f32 v[16:17], v[16:17], v[54:55], v[50:51]
	v_lshlrev_b32_e32 v50, 16, v142
	v_and_b32_e32 v51, 0xffff0000, v142
	v_lshlrev_b32_e32 v54, 16, v126
	v_and_b32_e32 v55, 0xffff0000, v126
	v_pk_fma_f32 v[18:19], v[18:19], v[56:57], v[52:53]
	v_lshlrev_b32_e32 v52, 16, v143
	v_and_b32_e32 v53, 0xffff0000, v143
	v_pk_fma_f32 v[16:17], v[78:79], v[50:51], v[16:17]
	v_lshlrev_b32_e32 v50, 16, v110
	v_and_b32_e32 v51, 0xffff0000, v110
	v_lshlrev_b32_e32 v56, 16, v127
	v_and_b32_e32 v57, 0xffff0000, v127
	v_pk_mul_f32 v[46:47], v[46:47], v[54:55]
	v_pk_fma_f32 v[18:19], v[80:81], v[52:53], v[18:19]
	v_lshlrev_b32_e32 v52, 16, v111
	v_and_b32_e32 v53, 0xffff0000, v111
	v_pk_mul_f32 v[48:49], v[48:49], v[56:57]
	v_pk_fma_f32 v[12:13], v[12:13], v[50:51], v[46:47]
	v_lshlrev_b32_e32 v46, 16, v140
	v_and_b32_e32 v47, 0xffff0000, v140
	v_lshlrev_b32_e32 v50, 16, v124
	v_and_b32_e32 v51, 0xffff0000, v124
	v_pk_fma_f32 v[14:15], v[14:15], v[52:53], v[48:49]
	v_lshlrev_b32_e32 v48, 16, v141
	v_and_b32_e32 v49, 0xffff0000, v141
	v_pk_fma_f32 v[12:13], v[74:75], v[46:47], v[12:13]
	v_lshlrev_b32_e32 v46, 16, v108
	v_and_b32_e32 v47, 0xffff0000, v108
;     __device__ __forceinline__ bf16_t* G() const { return (bf16_t*)(ws + OFF_G); }
;     __device__ __forceinline__ bf16_t* Mg() const { return (bf16_t*)(ws + OFF_Mg); }
; DEV void st_bf4(bf16_t* p, float a, float b, float c, float d) { uint2 w; w.x = pk_bf16(a, b); w.y = pk_bf16(c, d); *(uint2*)p = w; }
; DEV void ld_bf4(const bf16_t* p, float (&v)[4]) { uint2 w = *(const uint2*)p; v[0] = bf_lo(w.x); v[1] = bf_hi(w.x); v[2] = bf_lo(w.y); v[3] = bf_hi(w.y); }
; DEV void merge_big(const Params& p, int l, int mt, int nt, char* smem) {
;     ...
;         for (int mi = 0; mi < 4; ++mi)
; #pragma unroll
;             for (int ni = 0; ni < 2; ++ni) {
;                 float g[4]; ld_bf4(p.G() + (size_t)(rbase + mi * 16) * 3072 + br * 1024 + c0 + ni * 16, g);
;                 const f32x4 gv = (f32x4){g[0], g[1], g[2], g[3]};
;                 if (br == 0) mg[mi][ni] = gv * acc[mi][ni]; else mg[mi][ni] += gv * acc[mi][ni];
;             }
;     }
; #pragma unroll
;     for (int mi = 0; mi < 4; ++mi)
; #pragma unroll
;         for (int ni = 0; ni < 2; ++ni) st_bf4(p.Mg() + (size_t)(rbase + mi * 16) * 1024 + c0 + ni * 16, mg[mi][ni][0], mg[mi][ni][1], mg[mi][ni][2], mg[mi][ni][3]);
	v_lshlrev_b32_e32 v52, 16, v125
	v_and_b32_e32 v53, 0xffff0000, v125
	v_pk_mul_f32 v[42:43], v[42:43], v[50:51]
	v_pk_fma_f32 v[14:15], v[76:77], v[48:49], v[14:15]
	v_lshlrev_b32_e32 v48, 16, v109
	v_and_b32_e32 v49, 0xffff0000, v109
	v_pk_mul_f32 v[44:45], v[44:45], v[52:53]
	v_pk_fma_f32 v[8:9], v[8:9], v[46:47], v[42:43]
	v_lshlrev_b32_e32 v42, 16, v138
	v_and_b32_e32 v43, 0xffff0000, v138
	v_lshlrev_b32_e32 v46, 16, v120
	v_and_b32_e32 v47, 0xffff0000, v120
	v_pk_fma_f32 v[10:11], v[10:11], v[48:49], v[44:45]
	v_lshlrev_b32_e32 v44, 16, v139
	v_and_b32_e32 v45, 0xffff0000, v139
	v_pk_fma_f32 v[8:9], v[70:71], v[42:43], v[8:9]
	v_lshlrev_b32_e32 v42, 16, v106
	v_and_b32_e32 v43, 0xffff0000, v106
	v_lshlrev_b32_e32 v48, 16, v121
	v_and_b32_e32 v49, 0xffff0000, v121
	v_pk_mul_f32 v[34:35], v[34:35], v[46:47]
	v_pk_fma_f32 v[10:11], v[72:73], v[44:45], v[10:11]
	v_lshlrev_b32_e32 v44, 16, v107
	v_and_b32_e32 v45, 0xffff0000, v107
	v_pk_mul_f32 v[36:37], v[36:37], v[48:49]
	v_pk_fma_f32 v[4:5], v[4:5], v[42:43], v[34:35]
	v_lshlrev_b32_e32 v34, 16, v134
	v_and_b32_e32 v35, 0xffff0000, v134
	v_lshlrev_b32_e32 v42, 16, v118
	v_and_b32_e32 v43, 0xffff0000, v118
	v_pk_fma_f32 v[6:7], v[6:7], v[44:45], v[36:37]
	v_lshlrev_b32_e32 v36, 16, v135
	v_and_b32_e32 v37, 0xffff0000, v135
	v_pk_fma_f32 v[4:5], v[62:63], v[34:35], v[4:5]
	v_lshlrev_b32_e32 v34, 16, v104
	v_and_b32_e32 v35, 0xffff0000, v104
	v_lshlrev_b32_e32 v44, 16, v119
	v_and_b32_e32 v45, 0xffff0000, v119
	v_pk_mul_f32 v[28:29], v[28:29], v[42:43]
	v_pk_fma_f32 v[6:7], v[64:65], v[36:37], v[6:7]
	v_lshlrev_b32_e32 v36, 16, v105
	v_and_b32_e32 v37, 0xffff0000, v105
	v_pk_mul_f32 v[30:31], v[30:31], v[44:45]
	v_pk_fma_f32 v[0:1], v[0:1], v[34:35], v[28:29]
	v_lshlrev_b32_e32 v28, 16, v132
	v_and_b32_e32 v29, 0xffff0000, v132
	v_pk_fma_f32 v[2:3], v[2:3], v[36:37], v[30:31]
	v_lshlrev_b32_e32 v30, 16, v133
	v_and_b32_e32 v31, 0xffff0000, v133
	v_pk_fma_f32 v[0:1], v[58:59], v[28:29], v[0:1]
	v_lshlrev_b64 v[28:29], 11, v[94:95]
	v_pk_fma_f32 v[2:3], v[60:61], v[30:31], v[2:3]
	v_lshl_add_u64 v[30:31], s[14:15], 0, v[28:29]
	v_lshl_add_u64 v[30:31], v[30:31], 0, v[96:97]
	v_cvt_pk_bf16_f32 v0, v0, v1
	v_cvt_pk_bf16_f32 v1, v2, v3
	flat_store_dwordx2 v[30:31], v[0:1]
	v_lshl_add_u64 v[0:1], s[2:3], 0, v[28:29]
	v_lshl_add_u64 v[0:1], v[0:1], 0, v[96:97]
	v_add_co_u32_e32 v0, vcc, s52, v0
	v_cvt_pk_bf16_f32 v2, v4, v5
	v_cvt_pk_bf16_f32 v3, v6, v7
	v_addc_co_u32_e32 v1, vcc, 0, v1, vcc
	flat_store_dwordx2 v[0:1], v[2:3] offset:32
	v_lshlrev_b64 v[0:1], 11, v[102:103]
	v_lshl_add_u64 v[2:3], s[14:15], 0, v[0:1]
	v_lshl_add_u64 v[0:1], s[2:3], 0, v[0:1]
	v_lshl_add_u64 v[0:1], v[0:1], 0, v[96:97]
	v_lshl_add_u64 v[2:3], v[2:3], 0, v[96:97]
	v_cvt_pk_bf16_f32 v4, v8, v9
	v_cvt_pk_bf16_f32 v5, v10, v11
	v_add_co_u32_e32 v0, vcc, s52, v0
	flat_store_dwordx2 v[2:3], v[4:5]
	v_cvt_pk_bf16_f32 v2, v12, v13
	v_cvt_pk_bf16_f32 v3, v14, v15
	v_addc_co_u32_e32 v1, vcc, 0, v1, vcc
	flat_store_dwordx2 v[0:1], v[2:3] offset:32
	v_lshlrev_b64 v[0:1], 11, v[100:101]
	v_lshl_add_u64 v[2:3], s[14:15], 0, v[0:1]
	v_lshl_add_u64 v[0:1], s[2:3], 0, v[0:1]
	v_lshl_add_u64 v[0:1], v[0:1], 0, v[96:97]
	v_lshl_add_u64 v[2:3], v[2:3], 0, v[96:97]
	v_cvt_pk_bf16_f32 v4, v16, v17
	v_cvt_pk_bf16_f32 v5, v18, v19
	v_add_co_u32_e32 v0, vcc, s52, v0
	flat_store_dwordx2 v[2:3], v[4:5]
	v_cvt_pk_bf16_f32 v2, v22, v23
	v_cvt_pk_bf16_f32 v3, v20, v21
	v_addc_co_u32_e32 v1, vcc, 0, v1, vcc
	flat_store_dwordx2 v[0:1], v[2:3] offset:32
	v_lshlrev_b64 v[0:1], 11, v[98:99]
	v_lshl_add_u64 v[2:3], s[14:15], 0, v[0:1]
	v_lshl_add_u64 v[0:1], s[2:3], 0, v[0:1]
	v_lshl_add_u64 v[0:1], v[0:1], 0, v[96:97]
	v_lshl_add_u64 v[2:3], v[2:3], 0, v[96:97]
	v_cvt_pk_bf16_f32 v4, v26, v27
	v_cvt_pk_bf16_f32 v5, v24, v25
	v_add_co_u32_e32 v0, vcc, s52, v0
	flat_store_dwordx2 v[2:3], v[4:5]
	v_cvt_pk_bf16_f32 v2, v40, v41
	v_cvt_pk_bf16_f32 v3, v38, v39
	v_addc_co_u32_e32 v1, vcc, 0, v1, vcc
	flat_store_dwordx2 v[0:1], v[2:3] offset:32
	s_cbranch_scc0 .LBB0_109

; #define RAW_BARRIER() do { asm volatile("s_waitcnt lgkmcnt(0)" ::: "memory"); __builtin_amdgcn_s_barrier(); } while (0)
; #define GLDS_TILE(kt, st) do { _Pragma("unroll") for (int _i = 0; _i < NP; ++_i) GLDS_PIECE(_i, kt, st); } while (0)
;     ...
;     constexpr int NH = NI >= 4 ? NI / 2 : NI;
;     constexpr int NP = 2 + NB, IVL = (4 * NI) / NP;
;     RAW_BARRIER();
;     GLDS_TILE(0, 0);
;     GLDS_TILE(1, 1);
;     int st = 0;
;     for (int kt = 0; kt < nk - 1; ++kt) {
;         if (NI == 8) asm volatile("s_waitcnt vmcnt(6)" ::: "memory"); else if (NI == 4) asm volatile("s_waitcnt vmcnt(4)" ::: "memory"); else asm volatile("s_waitcnt vmcnt(3)" ::: "memory");
;         RAW_BARRIER();
;         const int s2 = st >= 1 ? st - 1 : 2;
;         const bool ld = kt + 2 < nk;
;         STEP_TILE(st, ld, kt + 2, s2);
;         st = st == 2 ? 0 : st + 1;
;     }
.LBB0_146:
	s_mul_i32 s6, s1, 0x6000
	s_add_i32 s7, s6, 0
	s_waitcnt vmcnt(6)
	v_add_u32_e32 v148, s7, v134
	v_add_u32_e32 v155, s7, v135
	s_waitcnt lgkmcnt(0)
	s_barrier
	ds_read_b128 v[158:161], v155 offset:8192
	ds_read_b128 v[136:139], v148
	ds_read_b128 v[140:143], v148 offset:1024
	ds_read_b128 v[144:147], v148 offset:2048
	ds_read_b128 v[148:151], v148 offset:3072
	ds_read_b128 v[162:165], v155 offset:9216
	ds_read_b128 v[166:169], v155 offset:10240
	ds_read_b128 v[170:173], v155 offset:11264
	s_addk_i32 s6, 0xa000
	s_cmp_gt_i32 s1, 0
	s_setprio 1
	s_waitcnt lgkmcnt(6)
	v_mfma_f32_16x16x32_bf16 v[126:129], v[158:161], v[136:139], v[126:129]
	s_cselect_b32 s6, s6, 0xc000
	v_add_u32_e32 v216, s6, v32
	v_lshl_add_u64 v[152:153], v[132:133], 0, s[4:5]
	s_waitcnt lgkmcnt(5)
	v_mfma_f32_16x16x32_bf16 v[110:113], v[158:161], v[140:143], v[110:113]
	v_lshl_add_u64 v[214:215], v[130:131], 0, s[4:5]
	v_lshl_add_u64 v[182:183], v[152:153], 0, s[10:11]
	v_add_u32_e32 v217, 0x2000, v216
	s_waitcnt lgkmcnt(4)
	v_mfma_f32_16x16x32_bf16 v[82:85], v[158:161], v[144:147], v[82:85]
	s_waitcnt lgkmcnt(3)
	v_mfma_f32_16x16x32_bf16 v[50:53], v[158:161], v[148:151], v[50:53]
	v_lshl_add_u64 v[158:159], v[214:215], 0, s[12:13]
	s_waitcnt lgkmcnt(2)
	v_mfma_f32_16x16x32_bf16 v[122:125], v[162:165], v[136:139], v[122:125]
	v_readfirstlane_b32 s6, v216
	s_mov_b32 m0, s6
	v_mfma_f32_16x16x32_bf16 v[102:105], v[162:165], v[140:143], v[102:105]
	global_load_lds_dwordx4 v[158:159], off
	ds_read_b128 v[158:161], v155 offset:12288
	ds_read_b128 v[174:177], v155 offset:13312
	ds_read_b128 v[178:181], v155 offset:14336
	ds_read_b128 v[210:213], v155 offset:15360
	v_mfma_f32_16x16x32_bf16 v[70:73], v[162:165], v[144:147], v[70:73]
	v_mfma_f32_16x16x32_bf16 v[38:41], v[162:165], v[148:151], v[38:41]
	s_waitcnt lgkmcnt(5)
	v_mfma_f32_16x16x32_bf16 v[118:121], v[166:169], v[136:139], v[118:121]
	v_mfma_f32_16x16x32_bf16 v[94:97], v[166:169], v[140:143], v[94:97]
	v_add_u32_e32 v155, 0x1000, v216
	v_lshl_add_u64 v[162:163], v[214:215], 0, s[14:15]
	v_readfirstlane_b32 s6, v155
	s_mov_b32 m0, s6
	v_mfma_f32_16x16x32_bf16 v[62:65], v[166:169], v[144:147], v[62:65]
	global_load_lds_dwordx4 v[162:163], off
	v_mfma_f32_16x16x32_bf16 v[28:31], v[166:169], v[148:151], v[28:31]
	s_waitcnt lgkmcnt(4)
	v_mfma_f32_16x16x32_bf16 v[114:117], v[170:173], v[136:139], v[114:117]
	v_mfma_f32_16x16x32_bf16 v[86:89], v[170:173], v[140:143], v[86:89]
	v_mfma_f32_16x16x32_bf16 v[54:57], v[170:173], v[144:147], v[54:57]
	v_readfirstlane_b32 s6, v217
	s_mov_b32 m0, s6
	v_mfma_f32_16x16x32_bf16 v[20:23], v[170:173], v[148:151], v[20:23]
	global_load_lds_dwordx4 v[182:183], off
	s_waitcnt lgkmcnt(0)
	v_mfma_f32_16x16x32_bf16 v[106:109], v[158:161], v[136:139], v[106:109]
	v_mfma_f32_16x16x32_bf16 v[74:77], v[158:161], v[140:143], v[74:77]
	v_mfma_f32_16x16x32_bf16 v[42:45], v[158:161], v[144:147], v[42:45]
	v_mfma_f32_16x16x32_bf16 v[12:15], v[158:161], v[148:151], v[12:15]
	v_add_u32_e32 v155, 0x3000, v216
	v_lshl_add_u64 v[158:159], v[152:153], 0, s[16:17]
	v_readfirstlane_b32 s6, v155
	s_mov_b32 m0, s6
	v_mfma_f32_16x16x32_bf16 v[98:101], v[174:177], v[136:139], v[98:101]
	global_load_lds_dwordx4 v[158:159], off
	v_mfma_f32_16x16x32_bf16 v[66:69], v[174:177], v[140:143], v[66:69]
	v_mfma_f32_16x16x32_bf16 v[34:37], v[174:177], v[144:147], v[34:37]
	v_mfma_f32_16x16x32_bf16 v[8:11], v[174:177], v[148:151], v[8:11]
	v_mfma_f32_16x16x32_bf16 v[90:93], v[178:181], v[136:139], v[90:93]
	v_add_u32_e32 v155, 0x4000, v216
	v_lshl_add_u64 v[158:159], v[152:153], 0, s[76:77]
	v_readfirstlane_b32 s6, v155
	s_mov_b32 m0, s6
	v_mfma_f32_16x16x32_bf16 v[58:61], v[178:181], v[140:143], v[58:61]
	global_load_lds_dwordx4 v[158:159], off
	v_mfma_f32_16x16x32_bf16 v[24:27], v[178:181], v[144:147], v[24:27]
	v_mfma_f32_16x16x32_bf16 v[4:7], v[178:181], v[148:151], v[4:7]
	v_mfma_f32_16x16x32_bf16 v[78:81], v[210:213], v[136:139], v[78:81]
	v_mfma_f32_16x16x32_bf16 v[46:49], v[210:213], v[140:143], v[46:49]
	v_add_u32_e32 v138, 0x5000, v216
	v_lshl_add_u64 v[136:137], v[152:153], 0, s[84:85]
	v_readfirstlane_b32 s6, v138
	s_mov_b32 m0, s6
	v_mfma_f32_16x16x32_bf16 v[16:19], v[210:213], v[144:147], v[16:19]
	global_load_lds_dwordx4 v[136:137], off
	v_mfma_f32_16x16x32_bf16 v[0:3], v[210:213], v[148:151], v[0:3]
	s_setprio 0
	s_add_i32 s6, s1, 1
	s_cmp_lg_u32 s1, 2
	s_cselect_b32 s1, s6, 0
	s_add_u32 s4, s4, 0x80
	s_addc_u32 s5, s5, 0
	s_cmpk_lg_i32 s4, 0xf00
	s_cbranch_scc1 .LBB0_146
	s_waitcnt vmcnt(6)
	v_add_u32_e32 v32, 0, v134
	v_add_u32_e32 v152, 0, v135
	s_waitcnt lgkmcnt(0)
	s_barrier
; #define RAW_BARRIER() do { asm volatile("s_waitcnt lgkmcnt(0)" ::: "memory"); __builtin_amdgcn_s_barrier(); } while (0)
;     ...
;     for (int kt = 0; kt < nk - 1; ++kt) {
;         if (NI == 8) asm volatile("s_waitcnt vmcnt(6)" ::: "memory"); else if (NI == 4) asm volatile("s_waitcnt vmcnt(4)" ::: "memory"); else asm volatile("s_waitcnt vmcnt(3)" ::: "memory");
;         RAW_BARRIER();
;         const int s2 = st >= 1 ? st - 1 : 2;
;         const bool ld = kt + 2 < nk;
;         STEP_TILE(st, ld, kt + 2, s2);
;         st = st == 2 ? 0 : st + 1;
;     }
;     asm volatile("s_waitcnt vmcnt(0)" ::: "memory");
;     RAW_BARRIER();
;     STEP_TILE(st, false, 0, 0);
;     RAW_BARRIER();
	ds_read_b128 v[130:133], v32
	ds_read_b128 v[136:139], v32 offset:1024
	ds_read_b128 v[140:143], v32 offset:2048
	ds_read_b128 v[144:147], v32 offset:3072
	ds_read_b128 v[148:151], v152 offset:8192
	ds_read_b128 v[158:161], v152 offset:9216
	ds_read_b128 v[162:165], v152 offset:10240
	ds_read_b128 v[166:169], v152 offset:11264
	s_sext_i32_i16 s0, s0
	s_setprio 1
	s_waitcnt lgkmcnt(0)
	v_mfma_f32_16x16x32_bf16 v[126:129], v[148:151], v[130:133], v[126:129]
	v_mfma_f32_16x16x32_bf16 v[110:113], v[148:151], v[136:139], v[110:113]
	v_mfma_f32_16x16x32_bf16 v[82:85], v[148:151], v[140:143], v[82:85]
	v_mfma_f32_16x16x32_bf16 v[50:53], v[148:151], v[144:147], v[50:53]
	v_mfma_f32_16x16x32_bf16 v[122:125], v[158:161], v[130:133], v[122:125]
	ds_read_b128 v[148:151], v152 offset:12288
	ds_read_b128 v[170:173], v152 offset:13312
	ds_read_b128 v[174:177], v152 offset:14336
	ds_read_b128 v[178:181], v152 offset:15360
	v_mfma_f32_16x16x32_bf16 v[102:105], v[158:161], v[136:139], v[102:105]
	v_mfma_f32_16x16x32_bf16 v[70:73], v[158:161], v[140:143], v[70:73]
	v_mfma_f32_16x16x32_bf16 v[38:41], v[158:161], v[144:147], v[38:41]
	v_mfma_f32_16x16x32_bf16 v[94:97], v[162:165], v[136:139], v[94:97]
	v_mfma_f32_16x16x32_bf16 v[158:161], v[162:165], v[130:133], v[118:121]
	v_mfma_f32_16x16x32_bf16 v[62:65], v[162:165], v[140:143], v[62:65]
	v_mfma_f32_16x16x32_bf16 v[28:31], v[162:165], v[144:147], v[28:31]
	v_mfma_f32_16x16x32_bf16 v[210:213], v[166:169], v[136:139], v[86:89]
	v_mfma_f32_16x16x32_bf16 v[54:57], v[166:169], v[140:143], v[54:57]
	v_mfma_f32_16x16x32_bf16 v[162:165], v[166:169], v[130:133], v[114:117]
	v_mfma_f32_16x16x32_bf16 v[20:23], v[166:169], v[144:147], v[20:23]
	s_waitcnt lgkmcnt(0)
	v_mfma_f32_16x16x32_bf16 v[42:45], v[148:151], v[140:143], v[42:45]
	v_mfma_f32_16x16x32_bf16 v[12:15], v[148:151], v[144:147], v[12:15]
	v_mfma_f32_16x16x32_bf16 v[166:169], v[148:151], v[130:133], v[106:109]
	v_mfma_f32_16x16x32_bf16 v[214:217], v[148:151], v[136:139], v[74:77]
	v_mfma_f32_16x16x32_bf16 v[148:151], v[170:173], v[130:133], v[98:101]
	v_mfma_f32_16x16x32_bf16 v[8:11], v[170:173], v[144:147], v[8:11]
	v_mfma_f32_16x16x32_bf16 v[218:221], v[170:173], v[136:139], v[66:69]
	v_mfma_f32_16x16x32_bf16 v[222:225], v[170:173], v[140:143], v[34:37]
	v_mfma_f32_16x16x32_bf16 v[170:173], v[174:177], v[130:133], v[90:93]
	v_mfma_f32_16x16x32_bf16 v[24:27], v[174:177], v[140:143], v[24:27]
	v_mfma_f32_16x16x32_bf16 v[46:49], v[178:181], v[136:139], v[46:49]
	v_mfma_f32_16x16x32_bf16 v[226:229], v[174:177], v[136:139], v[58:61]
	v_mfma_f32_16x16x32_bf16 v[174:177], v[174:177], v[144:147], v[4:7]
	v_mfma_f32_16x16x32_bf16 v[130:133], v[178:181], v[130:133], v[78:81]
	v_mfma_f32_16x16x32_bf16 v[134:137], v[178:181], v[140:143], v[16:19]
	v_mfma_f32_16x16x32_bf16 v[138:141], v[178:181], v[144:147], v[0:3]
	s_setprio 0
	s_waitcnt vmcnt(0)
	s_waitcnt lgkmcnt(0)
	s_barrier
	ds_read_b128 v[142:145], v32 offset:24576
	ds_read_b128 v[178:181], v32 offset:25600
	ds_read_b128 v[230:233], v32 offset:26624
	ds_read_b128 v[234:237], v32 offset:27648
	ds_read_b128 v[0:3], v152 offset:32768
	ds_read_b128 v[4:7], v152 offset:33792
	ds_read_b128 v[16:19], v152 offset:34816
	ds_read_b128 v[34:37], v152 offset:35840
	s_setprio 1
	s_waitcnt lgkmcnt(0)
	v_mfma_f32_16x16x32_bf16 v[118:121], v[0:3], v[142:145], v[126:129]
	v_mfma_f32_16x16x32_bf16 v[98:101], v[0:3], v[178:181], v[110:113]
	v_mfma_f32_16x16x32_bf16 v[82:85], v[0:3], v[230:233], v[82:85]
	v_mfma_f32_16x16x32_bf16 v[66:69], v[0:3], v[234:237], v[50:53]
	v_mfma_f32_16x16x32_bf16 v[114:117], v[4:7], v[142:145], v[122:125]
	ds_read_b128 v[0:3], v152 offset:36864
	ds_read_b128 v[238:241], v152 offset:37888
	ds_read_b128 v[242:245], v152 offset:38912
	ds_read_b128 v[246:249], v152 offset:39936
	v_mfma_f32_16x16x32_bf16 v[106:109], v[4:7], v[178:181], v[102:105]
	v_mfma_f32_16x16x32_bf16 v[86:89], v[4:7], v[230:233], v[70:73]
	v_mfma_f32_16x16x32_bf16 v[70:73], v[4:7], v[234:237], v[38:41]
	v_mfma_f32_16x16x32_bf16 v[122:125], v[16:19], v[142:145], v[158:161]
	v_mfma_f32_16x16x32_bf16 v[102:105], v[16:19], v[178:181], v[94:97]
	v_mfma_f32_16x16x32_bf16 v[90:93], v[16:19], v[230:233], v[62:65]
	v_mfma_f32_16x16x32_bf16 v[74:77], v[16:19], v[234:237], v[28:31]
	v_mfma_f32_16x16x32_bf16 v[126:129], v[34:37], v[142:145], v[162:165]
	v_mfma_f32_16x16x32_bf16 v[110:113], v[34:37], v[178:181], v[210:213]
	v_mfma_f32_16x16x32_bf16 v[94:97], v[34:37], v[230:233], v[54:57]
	v_mfma_f32_16x16x32_bf16 v[78:81], v[34:37], v[234:237], v[20:23]
	s_waitcnt lgkmcnt(0)
	v_mfma_f32_16x16x32_bf16 v[50:53], v[0:3], v[142:145], v[166:169]
	v_mfma_f32_16x16x32_bf16 v[34:37], v[0:3], v[178:181], v[214:217]
	v_mfma_f32_16x16x32_bf16 v[16:19], v[0:3], v[230:233], v[42:45]
	v_mfma_f32_16x16x32_bf16 v[0:3], v[0:3], v[234:237], v[12:15]
	v_mfma_f32_16x16x32_bf16 v[58:61], v[238:241], v[142:145], v[148:151]
	v_mfma_f32_16x16x32_bf16 v[38:41], v[238:241], v[178:181], v[218:221]
	v_mfma_f32_16x16x32_bf16 v[20:23], v[238:241], v[230:233], v[222:225]
	v_mfma_f32_16x16x32_bf16 v[4:7], v[238:241], v[234:237], v[8:11]
	v_mfma_f32_16x16x32_bf16 v[54:57], v[242:245], v[142:145], v[170:173]
	v_mfma_f32_16x16x32_bf16 v[42:45], v[242:245], v[178:181], v[226:229]
	v_mfma_f32_16x16x32_bf16 v[24:27], v[242:245], v[230:233], v[24:27]
	v_mfma_f32_16x16x32_bf16 v[8:11], v[242:245], v[234:237], v[174:177]
	v_mfma_f32_16x16x32_bf16 v[62:65], v[246:249], v[142:145], v[130:133]
	v_mfma_f32_16x16x32_bf16 v[46:49], v[246:249], v[178:181], v[46:49]
	v_mfma_f32_16x16x32_bf16 v[28:31], v[246:249], v[230:233], v[134:137]
	v_mfma_f32_16x16x32_bf16 v[12:15], v[246:249], v[234:237], v[138:141]
	s_setprio 0
	v_mov_b32_e32 v32, v186
	s_waitcnt lgkmcnt(0)
	s_barrier
;     __device__ __forceinline__ bf16_t* H() const { return (bf16_t*)(ws + OFF_H); }
; DEV int tid_opaque() { int t = threadIdx.x; asm volatile("" : "+v"(t)); return t; }
; DEV void wst_put4(char* wsm, int row, int col, float a, float b, float c, float d) { uint2 w; w.x = pk_bf16(a, b); w.y = pk_bf16(c, d); *(uint2*)(wsm + row * WST_ROW + col * 2) = w; }
; template <int H>
; DEV void epi1_group(const Params& p, int l, bool samp, int rbase, int g64, int fq, int fr, char* wsm, const f32x4 (&acc)[4][8]) {
;     ...
;     } else if (g64 < 90) {
;         const int c0 = (g64 - 42) * 64 + cl;
;         const float* bg = p.b_gate + l * 3072 + c0;
; #pragma unroll
;         for (int ni = 0; ni < 4; ++ni) {
;             const f32x4 b4 = *(const f32x4*)(bg + ni * 16);
; #pragma unroll
;             for (int mi = 0; mi < 4; ++mi) {
;                 f32x4 v = acc[mi][H * 4 + ni] + b4;
; #pragma unroll
;                 for (int j = 0; j < 4; ++j) v[j] = __builtin_amdgcn_rcpf(1.f + __expf(-v[j]));
;                 wst_put4(wsm, mi * 16 + fr, sc + ni * 16, v[0], v[1], v[2], v[3]);
; DEV void gemm1_big(const Params& p, int l, int mt, int nt, char* smem) {
;     ...
;     const int t = tid_opaque(), lane = t & 63, wid = t >> 6, wm = wid >> 1, wn = wid & 1, fr = lane & 15, fq = lane >> 4;
;     const int rbase = mt * 128 + wm * 64 + fr, g0 = nt * 4 + wn * 2;
;     char* wsm = smem + wid * WST_BYTES;
;     epi1_group<0>(p, l, mt == MT - 1, rbase, g0, fq, fr, wsm, acc);
	v_readlane_b32 s4, v252, 27
	v_ashrrev_i32_e32 v130, 6, v32
	v_and_b32_e32 v210, 15, v32
	v_bfe_u32 v155, v32, 4, 2
	v_ashrrev_i32_e32 v32, 1, v32
	v_and_b32_e32 v32, 0xffffffc0, v32
	v_lshl_add_u32 v150, s0, 7, v32
	s_lshl_b32 s0, s4, 2
	v_lshlrev_b32_e32 v32, 1, v130
	v_and_or_b32 v212, v32, 2, s0
	s_movk_i32 s0, 0x4400
	v_mul_lo_u32 v32, v130, s0
	s_add_i32 s0, s8, 0xfa00
	s_and_b32 s0, s0, 0xffff
	s_cmp_gt_u32 s0, 11
	v_readlane_b32 s5, v252, 28
	s_cselect_b64 s[6:7], -1, 0
	s_cmp_gt_u32 s4, 2
	s_cselect_b64 s[4:5], -1, 0
	v_or_b32_e32 v152, v150, v210
	v_add_u32_e32 v211, 0, v32
	v_lshlrev_b32_e32 v151, 2, v155
	s_mov_b64 s[0:1], -1
	s_and_b64 vcc, exec, s[4:5]
	s_cbranch_vccz .LBB0_797
	v_readlane_b32 s0, v252, 27
	v_readlane_b32 s1, v252, 28
	s_cmp_gt_u32 s0, 5
	s_mov_b64 s[0:1], -1
	s_cbranch_scc0 .LBB0_357
	v_cmp_lt_u32_e32 vcc, 29, v212
	s_and_saveexec_b64 s[0:1], vcc
	s_xor_b64 s[8:9], exec, s[0:1]
	s_cbranch_execz .LBB0_291
	v_cmp_lt_u32_e32 vcc, 33, v212
	s_and_saveexec_b64 s[0:1], vcc
	s_xor_b64 s[10:11], exec, s[0:1]
	s_cbranch_execz .LBB0_288
	v_cmp_lt_u32_e32 vcc, 37, v212
	s_and_saveexec_b64 s[0:1], vcc
	s_xor_b64 s[0:1], exec, s[0:1]
	s_cbranch_execz .LBB0_222
	v_cmp_lt_u32_e32 vcc, 41, v212
	s_and_saveexec_b64 s[12:13], vcc
	s_xor_b64 s[12:13], exec, s[12:13]
	s_cbranch_execz .LBB0_156
	s_movk_i32 s14, 0x5a
	v_cmp_gt_u32_e32 vcc, s14, v212
	s_and_saveexec_b64 s[14:15], vcc
	s_cbranch_execz .LBB0_155
	v_lshl_or_b32 v32, v212, 6, v151
	v_readlane_b32 s16, v250, 10
	v_add_u32_e32 v32, 0xfffff580, v32
	v_readlane_b32 s17, v250, 11
	s_nop 1
	v_lshl_add_u64 v[134:135], v[32:33], 2, s[16:17]
	flat_load_dwordx4 v[130:133], v[134:135]
	v_lshlrev_b32_e32 v32, 3, v155
	s_waitcnt vmcnt(0) lgkmcnt(0)
	v_pk_add_f32 v[136:137], v[120:121], v[132:133]
	s_nop 0
	v_mul_f32_e32 v136, 0xbfb8aa3b, v136
	v_exp_f32_e32 v136, v136
	v_pk_add_f32 v[138:139], v[118:119], v[130:131]
	v_add_f32_e32 v136, 1.0, v136
	v_mul_f32_e32 v138, 0xbfb8aa3b, v138
	v_mul_f32_e32 v139, 0xbfb8aa3b, v139
	v_exp_f32_e32 v138, v138
	v_exp_f32_e32 v139, v139
	v_rcp_f32_e32 v140, v136
	v_mul_f32_e32 v136, 0xbfb8aa3b, v137
	v_exp_f32_e32 v136, v136
	v_add_f32_e32 v138, 1.0, v138
	v_add_f32_e32 v139, 1.0, v139
	v_rcp_f32_e32 v138, v138
	v_rcp_f32_e32 v139, v139
	v_add_f32_e32 v136, 1.0, v136
	v_rcp_f32_e32 v137, v136
	v_cvt_pk_bf16_f32 v136, v138, v139
	v_mul_u32_u24_e32 v138, 0x110, v210
	v_cvt_pk_bf16_f32 v137, v140, v137
	v_add3_u32 v32, v211, v32, v138
	ds_write_b64 v32, v[136:137]
	v_pk_add_f32 v[136:137], v[100:101], v[132:133]
	v_pk_add_f32 v[138:139], v[98:99], v[130:131]
	v_mul_f32_e32 v136, 0xbfb8aa3b, v136
	v_exp_f32_e32 v136, v136
	v_mul_f32_e32 v138, 0xbfb8aa3b, v138
	v_mul_f32_e32 v139, 0xbfb8aa3b, v139
	v_exp_f32_e32 v138, v138
	v_add_f32_e32 v136, 1.0, v136
	v_rcp_f32_e32 v140, v136
	v_mul_f32_e32 v136, 0xbfb8aa3b, v137
	v_exp_f32_e32 v139, v139
	v_exp_f32_e32 v136, v136
	v_add_f32_e32 v138, 1.0, v138
	v_rcp_f32_e32 v138, v138
	v_add_f32_e32 v139, 1.0, v139
	v_add_f32_e32 v136, 1.0, v136
	v_rcp_f32_e32 v139, v139
	v_rcp_f32_e32 v137, v136
	v_cvt_pk_bf16_f32 v136, v138, v139
	v_cvt_pk_bf16_f32 v137, v140, v137
	ds_write_b64 v32, v[136:137] offset:4352
	v_pk_add_f32 v[136:137], v[84:85], v[132:133]
	v_pk_add_f32 v[138:139], v[82:83], v[130:131]
	v_mul_f32_e32 v136, 0xbfb8aa3b, v136
	v_exp_f32_e32 v136, v136
	v_pk_add_f32 v[132:133], v[68:69], v[132:133]
	v_pk_add_f32 v[130:131], v[66:67], v[130:131]
	v_mul_f32_e32 v138, 0xbfb8aa3b, v138
	v_add_f32_e32 v136, 1.0, v136
	v_mul_f32_e32 v139, 0xbfb8aa3b, v139
	v_rcp_f32_e32 v140, v136
	v_mul_f32_e32 v136, 0xbfb8aa3b, v137
	v_mul_f32_e32 v130, 0xbfb8aa3b, v130
	v_mul_f32_e32 v131, 0xbfb8aa3b, v131
	v_mul_f32_e32 v132, 0xbfb8aa3b, v132
	v_mul_f32_e32 v133, 0xbfb8aa3b, v133
	v_exp_f32_e32 v138, v138
	v_exp_f32_e32 v139, v139
	v_exp_f32_e32 v136, v136
	v_exp_f32_e32 v130, v130
	v_exp_f32_e32 v131, v131
	v_exp_f32_e32 v132, v132
	v_exp_f32_e32 v133, v133
	v_add_f32_e32 v138, 1.0, v138
	v_add_f32_e32 v139, 1.0, v139
	v_add_f32_e32 v136, 1.0, v136
	v_add_f32_e32 v130, 1.0, v130
	v_add_f32_e32 v131, 1.0, v131
	v_add_f32_e32 v132, 1.0, v132
	v_add_f32_e32 v133, 1.0, v133
	v_rcp_f32_e32 v138, v138
	v_rcp_f32_e32 v139, v139
	v_rcp_f32_e32 v137, v136
	v_rcp_f32_e32 v130, v130
	v_rcp_f32_e32 v131, v131
	v_rcp_f32_e32 v132, v132
	v_rcp_f32_e32 v133, v133
	v_cvt_pk_bf16_f32 v136, v138, v139
	v_cvt_pk_bf16_f32 v137, v140, v137
	v_cvt_pk_bf16_f32 v130, v130, v131
	v_cvt_pk_bf16_f32 v131, v132, v133
	ds_write_b64 v32, v[136:137] offset:8704
	ds_write_b64 v32, v[130:131] offset:13056
	flat_load_dwordx4 v[130:133], v[134:135] offset:64
	s_waitcnt vmcnt(0) lgkmcnt(0)
;     __device__ __forceinline__ bf16_t* H() const { return (bf16_t*)(ws + OFF_H); }
; DEV void wst_put4(char* wsm, int row, int col, float a, float b, float c, float d) { uint2 w; w.x = pk_bf16(a, b); w.y = pk_bf16(c, d); *(uint2*)(wsm + row * WST_ROW + col * 2) = w; }
; template <int H>
; DEV void epi1_group(const Params& p, int l, bool samp, int rbase, int g64, int fq, int fr, char* wsm, const f32x4 (&acc)[4][8]) {
;     ...
;     } else if (g64 < 90) {
;         const int c0 = (g64 - 42) * 64 + cl;
;         const float* bg = p.b_gate + l * 3072 + c0;
; #pragma unroll
;         for (int ni = 0; ni < 4; ++ni) {
;             const f32x4 b4 = *(const f32x4*)(bg + ni * 16);
; #pragma unroll
;             for (int mi = 0; mi < 4; ++mi) {
;                 f32x4 v = acc[mi][H * 4 + ni] + b4;
; #pragma unroll
;                 for (int j = 0; j < 4; ++j) v[j] = __builtin_amdgcn_rcpf(1.f + __expf(-v[j]));
;                 wst_put4(wsm, mi * 16 + fr, sc + ni * 16, v[0], v[1], v[2], v[3]);
;             }
;         }
	v_pk_add_f32 v[136:137], v[116:117], v[132:133]
	s_nop 0
	v_mul_f32_e32 v136, 0xbfb8aa3b, v136
	v_exp_f32_e32 v136, v136
	v_pk_add_f32 v[138:139], v[114:115], v[130:131]
	v_add_f32_e32 v136, 1.0, v136
	v_mul_f32_e32 v138, 0xbfb8aa3b, v138
	v_mul_f32_e32 v139, 0xbfb8aa3b, v139
	v_rcp_f32_e32 v140, v136
	v_mul_f32_e32 v136, 0xbfb8aa3b, v137
	v_exp_f32_e32 v138, v138
	v_exp_f32_e32 v139, v139
	v_exp_f32_e32 v136, v136
	v_add_f32_e32 v138, 1.0, v138
	v_add_f32_e32 v139, 1.0, v139
	v_add_f32_e32 v136, 1.0, v136
	v_rcp_f32_e32 v138, v138
	v_rcp_f32_e32 v139, v139
	v_rcp_f32_e32 v137, v136
	v_cvt_pk_bf16_f32 v136, v138, v139
	v_cvt_pk_bf16_f32 v137, v140, v137
	ds_write_b64 v32, v[136:137] offset:32
	v_pk_add_f32 v[136:137], v[108:109], v[132:133]
	v_pk_add_f32 v[138:139], v[106:107], v[130:131]
	v_mul_f32_e32 v136, 0xbfb8aa3b, v136
	v_exp_f32_e32 v136, v136
	v_mul_f32_e32 v138, 0xbfb8aa3b, v138
	v_mul_f32_e32 v139, 0xbfb8aa3b, v139
	v_exp_f32_e32 v138, v138
	v_add_f32_e32 v136, 1.0, v136
	v_rcp_f32_e32 v140, v136
	v_mul_f32_e32 v136, 0xbfb8aa3b, v137
	v_exp_f32_e32 v139, v139
	v_exp_f32_e32 v136, v136
	v_add_f32_e32 v138, 1.0, v138
	v_rcp_f32_e32 v138, v138
	v_add_f32_e32 v139, 1.0, v139
	v_add_f32_e32 v136, 1.0, v136
	v_rcp_f32_e32 v139, v139
	v_rcp_f32_e32 v137, v136
	v_cvt_pk_bf16_f32 v136, v138, v139
	v_cvt_pk_bf16_f32 v137, v140, v137
	ds_write_b64 v32, v[136:137] offset:4384
	v_pk_add_f32 v[136:137], v[88:89], v[132:133]
	v_pk_add_f32 v[138:139], v[86:87], v[130:131]
	v_mul_f32_e32 v136, 0xbfb8aa3b, v136
	v_exp_f32_e32 v136, v136
	v_pk_add_f32 v[132:133], v[72:73], v[132:133]
	v_pk_add_f32 v[130:131], v[70:71], v[130:131]
	v_mul_f32_e32 v138, 0xbfb8aa3b, v138
	v_add_f32_e32 v136, 1.0, v136
	v_mul_f32_e32 v139, 0xbfb8aa3b, v139
	v_rcp_f32_e32 v140, v136
	v_mul_f32_e32 v136, 0xbfb8aa3b, v137
	v_mul_f32_e32 v130, 0xbfb8aa3b, v130
	v_mul_f32_e32 v131, 0xbfb8aa3b, v131
	v_mul_f32_e32 v132, 0xbfb8aa3b, v132
	v_mul_f32_e32 v133, 0xbfb8aa3b, v133
	v_exp_f32_e32 v138, v138
	v_exp_f32_e32 v139, v139
	v_exp_f32_e32 v136, v136
	v_exp_f32_e32 v130, v130
	v_exp_f32_e32 v131, v131
	v_exp_f32_e32 v132, v132
	v_exp_f32_e32 v133, v133
	v_add_f32_e32 v138, 1.0, v138
	v_add_f32_e32 v139, 1.0, v139
	v_add_f32_e32 v136, 1.0, v136
	v_add_f32_e32 v130, 1.0, v130
	v_add_f32_e32 v131, 1.0, v131
	v_add_f32_e32 v132, 1.0, v132
	v_add_f32_e32 v133, 1.0, v133
	v_rcp_f32_e32 v138, v138
	v_rcp_f32_e32 v139, v139
	v_rcp_f32_e32 v137, v136
	v_rcp_f32_e32 v130, v130
	v_rcp_f32_e32 v131, v131
	v_rcp_f32_e32 v132, v132
	v_rcp_f32_e32 v133, v133
	v_cvt_pk_bf16_f32 v136, v138, v139
	v_cvt_pk_bf16_f32 v137, v140, v137
	v_cvt_pk_bf16_f32 v130, v130, v131
	v_cvt_pk_bf16_f32 v131, v132, v133
	ds_write_b64 v32, v[136:137] offset:8736
	ds_write_b64 v32, v[130:131] offset:13088
	flat_load_dwordx4 v[130:133], v[134:135] offset:128
	s_waitcnt vmcnt(0) lgkmcnt(0)
;     __device__ __forceinline__ bf16_t* H() const { return (bf16_t*)(ws + OFF_H); }
; DEV void wst_put4(char* wsm, int row, int col, float a, float b, float c, float d) { uint2 w; w.x = pk_bf16(a, b); w.y = pk_bf16(c, d); *(uint2*)(wsm + row * WST_ROW + col * 2) = w; }
; template <int H>
; DEV void epi1_group(const Params& p, int l, bool samp, int rbase, int g64, int fq, int fr, char* wsm, const f32x4 (&acc)[4][8]) {
;     ...
;     } else if (g64 < 90) {
;         const int c0 = (g64 - 42) * 64 + cl;
;         const float* bg = p.b_gate + l * 3072 + c0;
; #pragma unroll
;         for (int ni = 0; ni < 4; ++ni) {
;             const f32x4 b4 = *(const f32x4*)(bg + ni * 16);
; #pragma unroll
;             for (int mi = 0; mi < 4; ++mi) {
;                 f32x4 v = acc[mi][H * 4 + ni] + b4;
; #pragma unroll
;                 for (int j = 0; j < 4; ++j) v[j] = __builtin_amdgcn_rcpf(1.f + __expf(-v[j]));
;                 wst_put4(wsm, mi * 16 + fr, sc + ni * 16, v[0], v[1], v[2], v[3]);
;             }
;         }
	v_pk_add_f32 v[136:137], v[124:125], v[132:133]
	s_nop 0
	v_mul_f32_e32 v136, 0xbfb8aa3b, v136
	v_exp_f32_e32 v136, v136
	v_pk_add_f32 v[138:139], v[122:123], v[130:131]
	v_add_f32_e32 v136, 1.0, v136
	v_mul_f32_e32 v138, 0xbfb8aa3b, v138
	v_mul_f32_e32 v139, 0xbfb8aa3b, v139
	v_rcp_f32_e32 v140, v136
	v_mul_f32_e32 v136, 0xbfb8aa3b, v137
	v_exp_f32_e32 v138, v138
	v_exp_f32_e32 v139, v139
	v_exp_f32_e32 v136, v136
	v_add_f32_e32 v138, 1.0, v138
	v_add_f32_e32 v139, 1.0, v139
	v_add_f32_e32 v136, 1.0, v136
	v_rcp_f32_e32 v138, v138
	v_rcp_f32_e32 v139, v139
	v_rcp_f32_e32 v137, v136
	v_cvt_pk_bf16_f32 v136, v138, v139
	v_cvt_pk_bf16_f32 v137, v140, v137
	ds_write_b64 v32, v[136:137] offset:64
	v_pk_add_f32 v[136:137], v[104:105], v[132:133]
	v_pk_add_f32 v[138:139], v[102:103], v[130:131]
	v_mul_f32_e32 v136, 0xbfb8aa3b, v136
	v_exp_f32_e32 v136, v136
	v_mul_f32_e32 v138, 0xbfb8aa3b, v138
	v_mul_f32_e32 v139, 0xbfb8aa3b, v139
	v_exp_f32_e32 v138, v138
	v_add_f32_e32 v136, 1.0, v136
	v_rcp_f32_e32 v140, v136
	v_mul_f32_e32 v136, 0xbfb8aa3b, v137
	v_exp_f32_e32 v139, v139
	v_exp_f32_e32 v136, v136
	v_add_f32_e32 v138, 1.0, v138
	v_rcp_f32_e32 v138, v138
	v_add_f32_e32 v139, 1.0, v139
	v_add_f32_e32 v136, 1.0, v136
	v_rcp_f32_e32 v139, v139
	v_rcp_f32_e32 v137, v136
	v_cvt_pk_bf16_f32 v136, v138, v139
	v_cvt_pk_bf16_f32 v137, v140, v137
	ds_write_b64 v32, v[136:137] offset:4416
	v_pk_add_f32 v[136:137], v[92:93], v[132:133]
	v_pk_add_f32 v[138:139], v[90:91], v[130:131]
	v_mul_f32_e32 v136, 0xbfb8aa3b, v136
	v_exp_f32_e32 v136, v136
	v_pk_add_f32 v[132:133], v[76:77], v[132:133]
	v_pk_add_f32 v[130:131], v[74:75], v[130:131]
	v_mul_f32_e32 v138, 0xbfb8aa3b, v138
	v_add_f32_e32 v136, 1.0, v136
	v_mul_f32_e32 v139, 0xbfb8aa3b, v139
	v_rcp_f32_e32 v140, v136
	v_mul_f32_e32 v136, 0xbfb8aa3b, v137
	v_mul_f32_e32 v130, 0xbfb8aa3b, v130
	v_mul_f32_e32 v131, 0xbfb8aa3b, v131
	v_mul_f32_e32 v132, 0xbfb8aa3b, v132
	v_mul_f32_e32 v133, 0xbfb8aa3b, v133
	v_exp_f32_e32 v138, v138
	v_exp_f32_e32 v139, v139
	v_exp_f32_e32 v136, v136
	v_exp_f32_e32 v130, v130
	v_exp_f32_e32 v131, v131
	v_exp_f32_e32 v132, v132
	v_exp_f32_e32 v133, v133
	v_add_f32_e32 v138, 1.0, v138
	v_add_f32_e32 v139, 1.0, v139
	v_add_f32_e32 v136, 1.0, v136
	v_add_f32_e32 v130, 1.0, v130
	v_add_f32_e32 v131, 1.0, v131
	v_add_f32_e32 v132, 1.0, v132
	v_add_f32_e32 v133, 1.0, v133
	v_rcp_f32_e32 v138, v138
	v_rcp_f32_e32 v139, v139
	v_rcp_f32_e32 v137, v136
	v_rcp_f32_e32 v130, v130
	v_rcp_f32_e32 v131, v131
	v_rcp_f32_e32 v132, v132
	v_rcp_f32_e32 v133, v133
	v_cvt_pk_bf16_f32 v136, v138, v139
	v_cvt_pk_bf16_f32 v137, v140, v137
	v_cvt_pk_bf16_f32 v130, v130, v131
	v_cvt_pk_bf16_f32 v131, v132, v133
	ds_write_b64 v32, v[136:137] offset:8768
	ds_write_b64 v32, v[130:131] offset:13120
	flat_load_dwordx4 v[130:133], v[134:135] offset:192
	s_waitcnt vmcnt(0) lgkmcnt(0)
	v_pk_add_f32 v[134:135], v[128:129], v[132:133]
	s_nop 0
	v_mul_f32_e32 v134, 0xbfb8aa3b, v134
	v_exp_f32_e32 v134, v134
	v_pk_add_f32 v[136:137], v[126:127], v[130:131]
	v_add_f32_e32 v134, 1.0, v134
	v_mul_f32_e32 v136, 0xbfb8aa3b, v136
	v_mul_f32_e32 v137, 0xbfb8aa3b, v137
	v_rcp_f32_e32 v138, v134
	v_mul_f32_e32 v134, 0xbfb8aa3b, v135
	v_exp_f32_e32 v136, v136
	v_exp_f32_e32 v137, v137
	v_exp_f32_e32 v134, v134
	v_add_f32_e32 v136, 1.0, v136
	v_add_f32_e32 v137, 1.0, v137
	v_add_f32_e32 v134, 1.0, v134
	v_rcp_f32_e32 v136, v136
	v_rcp_f32_e32 v137, v137
	v_rcp_f32_e32 v135, v134
	v_cvt_pk_bf16_f32 v134, v136, v137
	v_cvt_pk_bf16_f32 v135, v138, v135
	ds_write_b64 v32, v[134:135] offset:96
	v_pk_add_f32 v[134:135], v[112:113], v[132:133]
	v_pk_add_f32 v[136:137], v[110:111], v[130:131]
	v_mul_f32_e32 v134, 0xbfb8aa3b, v134
	v_exp_f32_e32 v134, v134
	v_mul_f32_e32 v136, 0xbfb8aa3b, v136
	v_mul_f32_e32 v137, 0xbfb8aa3b, v137
	v_exp_f32_e32 v136, v136
	v_add_f32_e32 v134, 1.0, v134
	v_rcp_f32_e32 v138, v134
	v_mul_f32_e32 v134, 0xbfb8aa3b, v135
	v_exp_f32_e32 v137, v137
	v_exp_f32_e32 v134, v134
	v_add_f32_e32 v136, 1.0, v136
	v_rcp_f32_e32 v136, v136
	v_add_f32_e32 v137, 1.0, v137
	v_add_f32_e32 v134, 1.0, v134
	v_rcp_f32_e32 v137, v137
	v_rcp_f32_e32 v135, v134
	v_cvt_pk_bf16_f32 v134, v136, v137
	v_cvt_pk_bf16_f32 v135, v138, v135
	ds_write_b64 v32, v[134:135] offset:4448
	v_pk_add_f32 v[134:135], v[96:97], v[132:133]
	v_pk_add_f32 v[136:137], v[94:95], v[130:131]
	v_mul_f32_e32 v134, 0xbfb8aa3b, v134
	v_exp_f32_e32 v134, v134
	v_pk_add_f32 v[132:133], v[80:81], v[132:133]
	v_pk_add_f32 v[130:131], v[78:79], v[130:131]
	v_mul_f32_e32 v136, 0xbfb8aa3b, v136
	v_add_f32_e32 v134, 1.0, v134
	v_mul_f32_e32 v137, 0xbfb8aa3b, v137
	v_rcp_f32_e32 v138, v134
	v_mul_f32_e32 v134, 0xbfb8aa3b, v135
	v_mul_f32_e32 v130, 0xbfb8aa3b, v130
	v_mul_f32_e32 v131, 0xbfb8aa3b, v131
	v_mul_f32_e32 v132, 0xbfb8aa3b, v132
	v_mul_f32_e32 v133, 0xbfb8aa3b, v133
	v_exp_f32_e32 v136, v136
	v_exp_f32_e32 v137, v137
	v_exp_f32_e32 v134, v134
	v_exp_f32_e32 v130, v130
	v_exp_f32_e32 v131, v131
	v_exp_f32_e32 v132, v132
	v_exp_f32_e32 v133, v133
	v_add_f32_e32 v136, 1.0, v136
	v_add_f32_e32 v137, 1.0, v137
	v_add_f32_e32 v134, 1.0, v134
	v_add_f32_e32 v130, 1.0, v130
	v_add_f32_e32 v131, 1.0, v131
	v_add_f32_e32 v132, 1.0, v132
	v_add_f32_e32 v133, 1.0, v133
	v_rcp_f32_e32 v136, v136
	v_rcp_f32_e32 v137, v137
	v_rcp_f32_e32 v135, v134
	v_rcp_f32_e32 v130, v130
	v_rcp_f32_e32 v131, v131
	v_rcp_f32_e32 v132, v132
	v_rcp_f32_e32 v133, v133
	v_cvt_pk_bf16_f32 v134, v136, v137
	v_cvt_pk_bf16_f32 v135, v138, v135
	v_cvt_pk_bf16_f32 v130, v130, v131
	v_cvt_pk_bf16_f32 v131, v132, v133
	ds_write_b64 v32, v[134:135] offset:8800
	ds_write_b64 v32, v[130:131] offset:13152

; #define RAW_BARRIER() do { asm volatile("s_waitcnt lgkmcnt(0)" ::: "memory"); __builtin_amdgcn_s_barrier(); } while (0)
; #define GLDS_TILE(kt, st) do { _Pragma("unroll") for (int _i = 0; _i < NP; ++_i) GLDS_PIECE(_i, kt, st); } while (0)
;     ...
;     constexpr int NH = NI >= 4 ? NI / 2 : NI;
;     constexpr int NP = 2 + NB, IVL = (4 * NI) / NP;
;     RAW_BARRIER();
;     GLDS_TILE(0, 0);
;     GLDS_TILE(1, 1);
;     int st = 0;
;     for (int kt = 0; kt < nk - 1; ++kt) {
;         if (NI == 8) asm volatile("s_waitcnt vmcnt(6)" ::: "memory"); else if (NI == 4) asm volatile("s_waitcnt vmcnt(4)" ::: "memory"); else asm volatile("s_waitcnt vmcnt(3)" ::: "memory");
;         RAW_BARRIER();
;         const int s2 = st >= 1 ? st - 1 : 2;
;         const bool ld = kt + 2 < nk;
;         STEP_TILE(st, ld, kt + 2, s2);
;         st = st == 2 ? 0 : st + 1;
;     }
.LBB0_977:
	s_mul_i32 s6, s1, 0x6000
	s_add_i32 s7, s6, 0
	s_waitcnt vmcnt(6)
	v_add_u32_e32 v148, s7, v134
	v_add_u32_e32 v155, s7, v135
	s_waitcnt lgkmcnt(0)
	s_barrier
	ds_read_b128 v[158:161], v155 offset:8192
	ds_read_b128 v[136:139], v148
	ds_read_b128 v[140:143], v148 offset:1024
	ds_read_b128 v[144:147], v148 offset:2048
	ds_read_b128 v[148:151], v148 offset:3072
	ds_read_b128 v[162:165], v155 offset:9216
	ds_read_b128 v[166:169], v155 offset:10240
	ds_read_b128 v[170:173], v155 offset:11264
	s_addk_i32 s6, 0xa000
	s_cmp_gt_i32 s1, 0
	s_setprio 1
	s_waitcnt lgkmcnt(6)
	v_mfma_f32_16x16x32_bf16 v[126:129], v[158:161], v[136:139], v[126:129]
	s_cselect_b32 s6, s6, 0xc000
	v_add_u32_e32 v214, s6, v32
	v_lshl_add_u64 v[152:153], v[132:133], 0, s[4:5]
	s_waitcnt lgkmcnt(5)
	v_mfma_f32_16x16x32_bf16 v[110:113], v[158:161], v[140:143], v[110:113]
	v_lshl_add_u64 v[212:213], v[130:131], 0, s[4:5]
	v_lshl_add_u64 v[182:183], v[152:153], 0, s[10:11]
	v_add_u32_e32 v215, 0x2000, v214
	s_waitcnt lgkmcnt(4)
	v_mfma_f32_16x16x32_bf16 v[82:85], v[158:161], v[144:147], v[82:85]
	s_waitcnt lgkmcnt(3)
	v_mfma_f32_16x16x32_bf16 v[50:53], v[158:161], v[148:151], v[50:53]
	v_lshl_add_u64 v[158:159], v[212:213], 0, s[12:13]
	s_waitcnt lgkmcnt(2)
	v_mfma_f32_16x16x32_bf16 v[122:125], v[162:165], v[136:139], v[122:125]
	v_readfirstlane_b32 s6, v214
	s_mov_b32 m0, s6
	v_mfma_f32_16x16x32_bf16 v[102:105], v[162:165], v[140:143], v[102:105]
	global_load_lds_dwordx4 v[158:159], off
	ds_read_b128 v[158:161], v155 offset:12288
	ds_read_b128 v[174:177], v155 offset:13312
	ds_read_b128 v[178:181], v155 offset:14336
	ds_read_b128 v[208:211], v155 offset:15360
	v_mfma_f32_16x16x32_bf16 v[70:73], v[162:165], v[144:147], v[70:73]
	v_mfma_f32_16x16x32_bf16 v[38:41], v[162:165], v[148:151], v[38:41]
	s_waitcnt lgkmcnt(5)
	v_mfma_f32_16x16x32_bf16 v[118:121], v[166:169], v[136:139], v[118:121]
	v_mfma_f32_16x16x32_bf16 v[94:97], v[166:169], v[140:143], v[94:97]
	v_add_u32_e32 v155, 0x1000, v214
	v_lshl_add_u64 v[162:163], v[212:213], 0, s[14:15]
	v_readfirstlane_b32 s6, v155
	s_mov_b32 m0, s6
	v_mfma_f32_16x16x32_bf16 v[62:65], v[166:169], v[144:147], v[62:65]
	global_load_lds_dwordx4 v[162:163], off
	v_mfma_f32_16x16x32_bf16 v[28:31], v[166:169], v[148:151], v[28:31]
	s_waitcnt lgkmcnt(4)
	v_mfma_f32_16x16x32_bf16 v[114:117], v[170:173], v[136:139], v[114:117]
	v_mfma_f32_16x16x32_bf16 v[86:89], v[170:173], v[140:143], v[86:89]
	v_mfma_f32_16x16x32_bf16 v[54:57], v[170:173], v[144:147], v[54:57]
	v_readfirstlane_b32 s6, v215
	s_mov_b32 m0, s6
	v_mfma_f32_16x16x32_bf16 v[20:23], v[170:173], v[148:151], v[20:23]
	global_load_lds_dwordx4 v[182:183], off
	s_waitcnt lgkmcnt(0)
	v_mfma_f32_16x16x32_bf16 v[106:109], v[158:161], v[136:139], v[106:109]
	v_mfma_f32_16x16x32_bf16 v[74:77], v[158:161], v[140:143], v[74:77]
	v_mfma_f32_16x16x32_bf16 v[42:45], v[158:161], v[144:147], v[42:45]
	v_mfma_f32_16x16x32_bf16 v[12:15], v[158:161], v[148:151], v[12:15]
	v_add_u32_e32 v155, 0x3000, v214
	v_lshl_add_u64 v[158:159], v[152:153], 0, s[16:17]
	v_readfirstlane_b32 s6, v155
	s_mov_b32 m0, s6
	v_mfma_f32_16x16x32_bf16 v[98:101], v[174:177], v[136:139], v[98:101]
	global_load_lds_dwordx4 v[158:159], off
	v_mfma_f32_16x16x32_bf16 v[66:69], v[174:177], v[140:143], v[66:69]
	v_mfma_f32_16x16x32_bf16 v[34:37], v[174:177], v[144:147], v[34:37]
	v_mfma_f32_16x16x32_bf16 v[8:11], v[174:177], v[148:151], v[8:11]
	v_mfma_f32_16x16x32_bf16 v[90:93], v[178:181], v[136:139], v[90:93]
	v_add_u32_e32 v155, 0x4000, v214
	v_lshl_add_u64 v[158:159], v[152:153], 0, s[76:77]
	v_readfirstlane_b32 s6, v155
	s_mov_b32 m0, s6
	v_mfma_f32_16x16x32_bf16 v[58:61], v[178:181], v[140:143], v[58:61]
	global_load_lds_dwordx4 v[158:159], off
	v_mfma_f32_16x16x32_bf16 v[24:27], v[178:181], v[144:147], v[24:27]
	v_mfma_f32_16x16x32_bf16 v[4:7], v[178:181], v[148:151], v[4:7]
	v_mfma_f32_16x16x32_bf16 v[78:81], v[208:211], v[136:139], v[78:81]
	v_mfma_f32_16x16x32_bf16 v[46:49], v[208:211], v[140:143], v[46:49]
	v_add_u32_e32 v138, 0x5000, v214
	v_lshl_add_u64 v[136:137], v[152:153], 0, s[84:85]
	v_readfirstlane_b32 s6, v138
	s_mov_b32 m0, s6
	v_mfma_f32_16x16x32_bf16 v[16:19], v[208:211], v[144:147], v[16:19]
	global_load_lds_dwordx4 v[136:137], off
	v_mfma_f32_16x16x32_bf16 v[0:3], v[208:211], v[148:151], v[0:3]
	s_setprio 0
	s_add_i32 s6, s1, 1
	s_cmp_lg_u32 s1, 2
	s_cselect_b32 s1, s6, 0
	s_add_u32 s4, s4, 0x80
	s_addc_u32 s5, s5, 0
	s_cmpk_lg_i32 s4, 0xf00
	s_cbranch_scc1 .LBB0_977
	s_waitcnt vmcnt(6)
	v_add_u32_e32 v32, 0, v134
	v_add_u32_e32 v152, 0, v135
	s_waitcnt lgkmcnt(0)
	s_barrier
; #define RAW_BARRIER() do { asm volatile("s_waitcnt lgkmcnt(0)" ::: "memory"); __builtin_amdgcn_s_barrier(); } while (0)
;     ...
;     for (int kt = 0; kt < nk - 1; ++kt) {
;         if (NI == 8) asm volatile("s_waitcnt vmcnt(6)" ::: "memory"); else if (NI == 4) asm volatile("s_waitcnt vmcnt(4)" ::: "memory"); else asm volatile("s_waitcnt vmcnt(3)" ::: "memory");
;         RAW_BARRIER();
;         const int s2 = st >= 1 ? st - 1 : 2;
;         const bool ld = kt + 2 < nk;
;         STEP_TILE(st, ld, kt + 2, s2);
;         st = st == 2 ? 0 : st + 1;
;     }
;     asm volatile("s_waitcnt vmcnt(0)" ::: "memory");
;     RAW_BARRIER();
;     STEP_TILE(st, false, 0, 0);
;     RAW_BARRIER();
	ds_read_b128 v[130:133], v32
	ds_read_b128 v[136:139], v32 offset:1024
	ds_read_b128 v[140:143], v32 offset:2048
	ds_read_b128 v[144:147], v32 offset:3072
	ds_read_b128 v[148:151], v152 offset:8192
	ds_read_b128 v[158:161], v152 offset:9216
	ds_read_b128 v[162:165], v152 offset:10240
	ds_read_b128 v[166:169], v152 offset:11264
	s_sext_i32_i16 s0, s0
	s_setprio 1
	s_waitcnt lgkmcnt(0)
	v_mfma_f32_16x16x32_bf16 v[126:129], v[148:151], v[130:133], v[126:129]
	v_mfma_f32_16x16x32_bf16 v[110:113], v[148:151], v[136:139], v[110:113]
	v_mfma_f32_16x16x32_bf16 v[82:85], v[148:151], v[140:143], v[82:85]
	v_mfma_f32_16x16x32_bf16 v[50:53], v[148:151], v[144:147], v[50:53]
	v_mfma_f32_16x16x32_bf16 v[122:125], v[158:161], v[130:133], v[122:125]
	ds_read_b128 v[148:151], v152 offset:12288
	ds_read_b128 v[170:173], v152 offset:13312
	ds_read_b128 v[174:177], v152 offset:14336
	ds_read_b128 v[178:181], v152 offset:15360
	v_mfma_f32_16x16x32_bf16 v[102:105], v[158:161], v[136:139], v[102:105]
	v_mfma_f32_16x16x32_bf16 v[70:73], v[158:161], v[140:143], v[70:73]
	v_mfma_f32_16x16x32_bf16 v[38:41], v[158:161], v[144:147], v[38:41]
	v_mfma_f32_16x16x32_bf16 v[94:97], v[162:165], v[136:139], v[94:97]
	v_mfma_f32_16x16x32_bf16 v[158:161], v[162:165], v[130:133], v[118:121]
	v_mfma_f32_16x16x32_bf16 v[62:65], v[162:165], v[140:143], v[62:65]
	v_mfma_f32_16x16x32_bf16 v[28:31], v[162:165], v[144:147], v[28:31]
	v_mfma_f32_16x16x32_bf16 v[208:211], v[166:169], v[136:139], v[86:89]
	v_mfma_f32_16x16x32_bf16 v[54:57], v[166:169], v[140:143], v[54:57]
	v_mfma_f32_16x16x32_bf16 v[162:165], v[166:169], v[130:133], v[114:117]
	v_mfma_f32_16x16x32_bf16 v[20:23], v[166:169], v[144:147], v[20:23]
	s_waitcnt lgkmcnt(0)
	v_mfma_f32_16x16x32_bf16 v[42:45], v[148:151], v[140:143], v[42:45]
	v_mfma_f32_16x16x32_bf16 v[12:15], v[148:151], v[144:147], v[12:15]
	v_mfma_f32_16x16x32_bf16 v[166:169], v[148:151], v[130:133], v[106:109]
	v_mfma_f32_16x16x32_bf16 v[212:215], v[148:151], v[136:139], v[74:77]
	v_mfma_f32_16x16x32_bf16 v[148:151], v[170:173], v[130:133], v[98:101]
	v_mfma_f32_16x16x32_bf16 v[8:11], v[170:173], v[144:147], v[8:11]
	v_mfma_f32_16x16x32_bf16 v[216:219], v[170:173], v[136:139], v[66:69]
	v_mfma_f32_16x16x32_bf16 v[220:223], v[170:173], v[140:143], v[34:37]
	v_mfma_f32_16x16x32_bf16 v[170:173], v[174:177], v[130:133], v[90:93]
	v_mfma_f32_16x16x32_bf16 v[24:27], v[174:177], v[140:143], v[24:27]
	v_mfma_f32_16x16x32_bf16 v[46:49], v[178:181], v[136:139], v[46:49]
	v_mfma_f32_16x16x32_bf16 v[224:227], v[174:177], v[136:139], v[58:61]
	v_mfma_f32_16x16x32_bf16 v[174:177], v[174:177], v[144:147], v[4:7]
	v_mfma_f32_16x16x32_bf16 v[130:133], v[178:181], v[130:133], v[78:81]
	v_mfma_f32_16x16x32_bf16 v[134:137], v[178:181], v[140:143], v[16:19]
	v_mfma_f32_16x16x32_bf16 v[138:141], v[178:181], v[144:147], v[0:3]
	s_setprio 0
	s_waitcnt vmcnt(0)
	s_waitcnt lgkmcnt(0)
	s_barrier
	ds_read_b128 v[142:145], v32 offset:24576
	ds_read_b128 v[178:181], v32 offset:25600
	ds_read_b128 v[228:231], v32 offset:26624
	ds_read_b128 v[232:235], v32 offset:27648
	ds_read_b128 v[0:3], v152 offset:32768
	ds_read_b128 v[4:7], v152 offset:33792
	ds_read_b128 v[16:19], v152 offset:34816
	ds_read_b128 v[34:37], v152 offset:35840
	s_setprio 1
	s_waitcnt lgkmcnt(0)
	v_mfma_f32_16x16x32_bf16 v[118:121], v[0:3], v[142:145], v[126:129]
	v_mfma_f32_16x16x32_bf16 v[98:101], v[0:3], v[178:181], v[110:113]
	v_mfma_f32_16x16x32_bf16 v[82:85], v[0:3], v[228:231], v[82:85]
	v_mfma_f32_16x16x32_bf16 v[66:69], v[0:3], v[232:235], v[50:53]
	v_mfma_f32_16x16x32_bf16 v[114:117], v[4:7], v[142:145], v[122:125]
	ds_read_b128 v[0:3], v152 offset:36864
	ds_read_b128 v[236:239], v152 offset:37888
	ds_read_b128 v[240:243], v152 offset:38912
	ds_read_b128 v[244:247], v152 offset:39936
	v_mfma_f32_16x16x32_bf16 v[106:109], v[4:7], v[178:181], v[102:105]
	v_mfma_f32_16x16x32_bf16 v[86:89], v[4:7], v[228:231], v[70:73]
	v_mfma_f32_16x16x32_bf16 v[70:73], v[4:7], v[232:235], v[38:41]
	v_mfma_f32_16x16x32_bf16 v[122:125], v[16:19], v[142:145], v[158:161]
	v_mfma_f32_16x16x32_bf16 v[102:105], v[16:19], v[178:181], v[94:97]
	v_mfma_f32_16x16x32_bf16 v[90:93], v[16:19], v[228:231], v[62:65]
	v_mfma_f32_16x16x32_bf16 v[74:77], v[16:19], v[232:235], v[28:31]
	v_mfma_f32_16x16x32_bf16 v[126:129], v[34:37], v[142:145], v[162:165]
	v_mfma_f32_16x16x32_bf16 v[110:113], v[34:37], v[178:181], v[208:211]
	v_mfma_f32_16x16x32_bf16 v[94:97], v[34:37], v[228:231], v[54:57]
	v_mfma_f32_16x16x32_bf16 v[78:81], v[34:37], v[232:235], v[20:23]
	s_waitcnt lgkmcnt(0)
	v_mfma_f32_16x16x32_bf16 v[50:53], v[0:3], v[142:145], v[166:169]
	v_mfma_f32_16x16x32_bf16 v[34:37], v[0:3], v[178:181], v[212:215]
	v_mfma_f32_16x16x32_bf16 v[16:19], v[0:3], v[228:231], v[42:45]
	v_mfma_f32_16x16x32_bf16 v[0:3], v[0:3], v[232:235], v[12:15]
	v_mfma_f32_16x16x32_bf16 v[58:61], v[236:239], v[142:145], v[148:151]
	v_mfma_f32_16x16x32_bf16 v[38:41], v[236:239], v[178:181], v[216:219]
	v_mfma_f32_16x16x32_bf16 v[20:23], v[236:239], v[228:231], v[220:223]
	v_mfma_f32_16x16x32_bf16 v[4:7], v[236:239], v[232:235], v[8:11]
	v_mfma_f32_16x16x32_bf16 v[54:57], v[240:243], v[142:145], v[170:173]
	v_mfma_f32_16x16x32_bf16 v[42:45], v[240:243], v[178:181], v[224:227]
	v_mfma_f32_16x16x32_bf16 v[24:27], v[240:243], v[228:231], v[24:27]
	v_mfma_f32_16x16x32_bf16 v[8:11], v[240:243], v[232:235], v[174:177]
	v_mfma_f32_16x16x32_bf16 v[62:65], v[244:247], v[142:145], v[130:133]
	v_mfma_f32_16x16x32_bf16 v[46:49], v[244:247], v[178:181], v[46:49]
	v_mfma_f32_16x16x32_bf16 v[28:31], v[244:247], v[228:231], v[134:137]
	v_mfma_f32_16x16x32_bf16 v[12:15], v[244:247], v[232:235], v[138:141]
	s_setprio 0
	v_mov_b32_e32 v32, v186
	s_waitcnt lgkmcnt(0)
	s_barrier
;     __device__ __forceinline__ bf16_t* H() const { return (bf16_t*)(ws + OFF_H); }
; DEV int tid_opaque() { int t = threadIdx.x; asm volatile("" : "+v"(t)); return t; }
; DEV void wst_put4(char* wsm, int row, int col, float a, float b, float c, float d) { uint2 w; w.x = pk_bf16(a, b); w.y = pk_bf16(c, d); *(uint2*)(wsm + row * WST_ROW + col * 2) = w; }
; template <int H>
; DEV void epi1_group(const Params& p, int l, bool samp, int rbase, int g64, int fq, int fr, char* wsm, const f32x4 (&acc)[4][8]) {
;     ...
;     } else if (g64 < 90) {
;         const int c0 = (g64 - 42) * 64 + cl;
;         const float* bg = p.b_gate + l * 3072 + c0;
; #pragma unroll
;         for (int ni = 0; ni < 4; ++ni) {
;             const f32x4 b4 = *(const f32x4*)(bg + ni * 16);
; #pragma unroll
;             for (int mi = 0; mi < 4; ++mi) {
;                 f32x4 v = acc[mi][H * 4 + ni] + b4;
; #pragma unroll
;                 for (int j = 0; j < 4; ++j) v[j] = __builtin_amdgcn_rcpf(1.f + __expf(-v[j]));
;                 wst_put4(wsm, mi * 16 + fr, sc + ni * 16, v[0], v[1], v[2], v[3]);
; DEV void gemm1_big(const Params& p, int l, int mt, int nt, char* smem) {
;     ...
;     const int t = tid_opaque(), lane = t & 63, wid = t >> 6, wm = wid >> 1, wn = wid & 1, fr = lane & 15, fq = lane >> 4;
;     const int rbase = mt * 128 + wm * 64 + fr, g0 = nt * 4 + wn * 2;
;     char* wsm = smem + wid * WST_BYTES;
;     epi1_group<0>(p, l, mt == MT - 1, rbase, g0, fq, fr, wsm, acc);
	v_readlane_b32 s4, v252, 27
	v_ashrrev_i32_e32 v130, 6, v32
	v_and_b32_e32 v208, 15, v32
	v_bfe_u32 v155, v32, 4, 2
	v_ashrrev_i32_e32 v32, 1, v32
	v_and_b32_e32 v32, 0xffffffc0, v32
	v_lshl_add_u32 v150, s0, 7, v32
	s_lshl_b32 s0, s4, 2
	v_lshlrev_b32_e32 v32, 1, v130
	v_and_or_b32 v210, v32, 2, s0
	s_movk_i32 s0, 0x4400
	v_mul_lo_u32 v32, v130, s0
	s_add_i32 s0, s8, 0xfa00
	s_and_b32 s0, s0, 0xffff
	s_cmp_gt_u32 s0, 11
	v_readlane_b32 s5, v252, 28
	s_cselect_b64 s[6:7], -1, 0
	s_cmp_gt_u32 s4, 2
	s_cselect_b64 s[4:5], -1, 0
	v_or_b32_e32 v152, v150, v208
	v_add_u32_e32 v209, 0, v32
	v_lshlrev_b32_e32 v151, 2, v155
	s_mov_b64 s[0:1], -1
	s_and_b64 vcc, exec, s[4:5]
	s_cbranch_vccz .LBB0_1628
	v_readlane_b32 s0, v252, 27
	v_readlane_b32 s1, v252, 28
	s_cmp_gt_u32 s0, 5
	s_mov_b64 s[0:1], -1
	s_cbranch_scc0 .LBB0_1188
	v_cmp_lt_u32_e32 vcc, 29, v210
	s_and_saveexec_b64 s[0:1], vcc
	s_xor_b64 s[8:9], exec, s[0:1]
	s_cbranch_execz .LBB0_1122
	v_cmp_lt_u32_e32 vcc, 33, v210
	s_and_saveexec_b64 s[0:1], vcc
	s_xor_b64 s[10:11], exec, s[0:1]
	s_cbranch_execz .LBB0_1119
	v_cmp_lt_u32_e32 vcc, 37, v210
	s_and_saveexec_b64 s[0:1], vcc
	s_xor_b64 s[0:1], exec, s[0:1]
	s_cbranch_execz .LBB0_1053
	v_cmp_lt_u32_e32 vcc, 41, v210
	s_and_saveexec_b64 s[12:13], vcc
	s_xor_b64 s[12:13], exec, s[12:13]
	s_cbranch_execz .LBB0_987
	s_movk_i32 s14, 0x5a
	v_cmp_gt_u32_e32 vcc, s14, v210
	s_and_saveexec_b64 s[14:15], vcc
	s_cbranch_execz .LBB0_986
	v_lshl_or_b32 v32, v210, 6, v151
	v_readlane_b32 s2, v250, 42
	v_add_u32_e32 v32, 0xfffff580, v32
	v_readlane_b32 s3, v250, 43
	s_nop 1
	v_lshl_add_u64 v[134:135], v[32:33], 2, s[2:3]
	flat_load_dwordx4 v[130:133], v[134:135]
	v_lshlrev_b32_e32 v32, 3, v155
	s_waitcnt vmcnt(0) lgkmcnt(0)
	v_pk_add_f32 v[136:137], v[120:121], v[132:133]
	s_nop 0
	v_mul_f32_e32 v136, 0xbfb8aa3b, v136
	v_exp_f32_e32 v136, v136
	v_pk_add_f32 v[138:139], v[118:119], v[130:131]
	v_add_f32_e32 v136, 1.0, v136
	v_mul_f32_e32 v138, 0xbfb8aa3b, v138
	v_mul_f32_e32 v139, 0xbfb8aa3b, v139
	v_exp_f32_e32 v138, v138
	v_exp_f32_e32 v139, v139
	v_rcp_f32_e32 v140, v136
	v_mul_f32_e32 v136, 0xbfb8aa3b, v137
	v_exp_f32_e32 v136, v136
	v_add_f32_e32 v138, 1.0, v138
	v_add_f32_e32 v139, 1.0, v139
	v_rcp_f32_e32 v138, v138
	v_rcp_f32_e32 v139, v139
	v_add_f32_e32 v136, 1.0, v136
	v_rcp_f32_e32 v137, v136
	v_cvt_pk_bf16_f32 v136, v138, v139
	v_mul_u32_u24_e32 v138, 0x110, v208
	v_cvt_pk_bf16_f32 v137, v140, v137
	v_add3_u32 v32, v209, v32, v138
	ds_write_b64 v32, v[136:137]
	v_pk_add_f32 v[136:137], v[100:101], v[132:133]
	v_pk_add_f32 v[138:139], v[98:99], v[130:131]
	v_mul_f32_e32 v136, 0xbfb8aa3b, v136
	v_exp_f32_e32 v136, v136
	v_mul_f32_e32 v138, 0xbfb8aa3b, v138
	v_mul_f32_e32 v139, 0xbfb8aa3b, v139
	v_exp_f32_e32 v138, v138
	v_add_f32_e32 v136, 1.0, v136
	v_rcp_f32_e32 v140, v136
	v_mul_f32_e32 v136, 0xbfb8aa3b, v137
	v_exp_f32_e32 v139, v139
	v_exp_f32_e32 v136, v136
	v_add_f32_e32 v138, 1.0, v138
	v_rcp_f32_e32 v138, v138
	v_add_f32_e32 v139, 1.0, v139
	v_add_f32_e32 v136, 1.0, v136
	v_rcp_f32_e32 v139, v139
	v_rcp_f32_e32 v137, v136
	v_cvt_pk_bf16_f32 v136, v138, v139
	v_cvt_pk_bf16_f32 v137, v140, v137
	ds_write_b64 v32, v[136:137] offset:4352
	v_pk_add_f32 v[136:137], v[84:85], v[132:133]
	v_pk_add_f32 v[138:139], v[82:83], v[130:131]
	v_mul_f32_e32 v136, 0xbfb8aa3b, v136
	v_exp_f32_e32 v136, v136
	v_pk_add_f32 v[132:133], v[68:69], v[132:133]
	v_pk_add_f32 v[130:131], v[66:67], v[130:131]
	v_mul_f32_e32 v138, 0xbfb8aa3b, v138
	v_add_f32_e32 v136, 1.0, v136
	v_mul_f32_e32 v139, 0xbfb8aa3b, v139
	v_rcp_f32_e32 v140, v136
	v_mul_f32_e32 v136, 0xbfb8aa3b, v137
	v_mul_f32_e32 v130, 0xbfb8aa3b, v130
	v_mul_f32_e32 v131, 0xbfb8aa3b, v131
	v_mul_f32_e32 v132, 0xbfb8aa3b, v132
	v_mul_f32_e32 v133, 0xbfb8aa3b, v133
	v_exp_f32_e32 v138, v138
	v_exp_f32_e32 v139, v139
	v_exp_f32_e32 v136, v136
	v_exp_f32_e32 v130, v130
	v_exp_f32_e32 v131, v131
	v_exp_f32_e32 v132, v132
	v_exp_f32_e32 v133, v133
	v_add_f32_e32 v138, 1.0, v138
	v_add_f32_e32 v139, 1.0, v139
	v_add_f32_e32 v136, 1.0, v136
	v_add_f32_e32 v130, 1.0, v130
	v_add_f32_e32 v131, 1.0, v131
	v_add_f32_e32 v132, 1.0, v132
	v_add_f32_e32 v133, 1.0, v133
	v_rcp_f32_e32 v138, v138
	v_rcp_f32_e32 v139, v139
	v_rcp_f32_e32 v137, v136
	v_rcp_f32_e32 v130, v130
	v_rcp_f32_e32 v131, v131
	v_rcp_f32_e32 v132, v132
	v_rcp_f32_e32 v133, v133
	v_cvt_pk_bf16_f32 v136, v138, v139
	v_cvt_pk_bf16_f32 v137, v140, v137
	v_cvt_pk_bf16_f32 v130, v130, v131
	v_cvt_pk_bf16_f32 v131, v132, v133
	ds_write_b64 v32, v[136:137] offset:8704
	ds_write_b64 v32, v[130:131] offset:13056
	flat_load_dwordx4 v[130:133], v[134:135] offset:64
	s_waitcnt vmcnt(0) lgkmcnt(0)
;     __device__ __forceinline__ bf16_t* H() const { return (bf16_t*)(ws + OFF_H); }
; DEV void wst_put4(char* wsm, int row, int col, float a, float b, float c, float d) { uint2 w; w.x = pk_bf16(a, b); w.y = pk_bf16(c, d); *(uint2*)(wsm + row * WST_ROW + col * 2) = w; }
; template <int H>
; DEV void epi1_group(const Params& p, int l, bool samp, int rbase, int g64, int fq, int fr, char* wsm, const f32x4 (&acc)[4][8]) {
;     ...
;     } else if (g64 < 90) {
;         const int c0 = (g64 - 42) * 64 + cl;
;         const float* bg = p.b_gate + l * 3072 + c0;
; #pragma unroll
;         for (int ni = 0; ni < 4; ++ni) {
;             const f32x4 b4 = *(const f32x4*)(bg + ni * 16);
; #pragma unroll
;             for (int mi = 0; mi < 4; ++mi) {
;                 f32x4 v = acc[mi][H * 4 + ni] + b4;
; #pragma unroll
;                 for (int j = 0; j < 4; ++j) v[j] = __builtin_amdgcn_rcpf(1.f + __expf(-v[j]));
;                 wst_put4(wsm, mi * 16 + fr, sc + ni * 16, v[0], v[1], v[2], v[3]);
;             }
;         }
	v_pk_add_f32 v[136:137], v[116:117], v[132:133]
	s_nop 0
	v_mul_f32_e32 v136, 0xbfb8aa3b, v136
	v_exp_f32_e32 v136, v136
	v_pk_add_f32 v[138:139], v[114:115], v[130:131]
	v_add_f32_e32 v136, 1.0, v136
	v_mul_f32_e32 v138, 0xbfb8aa3b, v138
	v_mul_f32_e32 v139, 0xbfb8aa3b, v139
	v_rcp_f32_e32 v140, v136
	v_mul_f32_e32 v136, 0xbfb8aa3b, v137
	v_exp_f32_e32 v138, v138
	v_exp_f32_e32 v139, v139
	v_exp_f32_e32 v136, v136
	v_add_f32_e32 v138, 1.0, v138
	v_add_f32_e32 v139, 1.0, v139
	v_add_f32_e32 v136, 1.0, v136
	v_rcp_f32_e32 v138, v138
	v_rcp_f32_e32 v139, v139
	v_rcp_f32_e32 v137, v136
	v_cvt_pk_bf16_f32 v136, v138, v139
	v_cvt_pk_bf16_f32 v137, v140, v137
	ds_write_b64 v32, v[136:137] offset:32
	v_pk_add_f32 v[136:137], v[108:109], v[132:133]
	v_pk_add_f32 v[138:139], v[106:107], v[130:131]
	v_mul_f32_e32 v136, 0xbfb8aa3b, v136
	v_exp_f32_e32 v136, v136
	v_mul_f32_e32 v138, 0xbfb8aa3b, v138
	v_mul_f32_e32 v139, 0xbfb8aa3b, v139
	v_exp_f32_e32 v138, v138
	v_add_f32_e32 v136, 1.0, v136
	v_rcp_f32_e32 v140, v136
	v_mul_f32_e32 v136, 0xbfb8aa3b, v137
	v_exp_f32_e32 v139, v139
	v_exp_f32_e32 v136, v136
	v_add_f32_e32 v138, 1.0, v138
	v_rcp_f32_e32 v138, v138
	v_add_f32_e32 v139, 1.0, v139
	v_add_f32_e32 v136, 1.0, v136
	v_rcp_f32_e32 v139, v139
	v_rcp_f32_e32 v137, v136
	v_cvt_pk_bf16_f32 v136, v138, v139
	v_cvt_pk_bf16_f32 v137, v140, v137
	ds_write_b64 v32, v[136:137] offset:4384
	v_pk_add_f32 v[136:137], v[88:89], v[132:133]
	v_pk_add_f32 v[138:139], v[86:87], v[130:131]
	v_mul_f32_e32 v136, 0xbfb8aa3b, v136
	v_exp_f32_e32 v136, v136
	v_pk_add_f32 v[132:133], v[72:73], v[132:133]
	v_pk_add_f32 v[130:131], v[70:71], v[130:131]
	v_mul_f32_e32 v138, 0xbfb8aa3b, v138
	v_add_f32_e32 v136, 1.0, v136
	v_mul_f32_e32 v139, 0xbfb8aa3b, v139
	v_rcp_f32_e32 v140, v136
	v_mul_f32_e32 v136, 0xbfb8aa3b, v137
	v_mul_f32_e32 v130, 0xbfb8aa3b, v130
	v_mul_f32_e32 v131, 0xbfb8aa3b, v131
	v_mul_f32_e32 v132, 0xbfb8aa3b, v132
	v_mul_f32_e32 v133, 0xbfb8aa3b, v133
	v_exp_f32_e32 v138, v138
	v_exp_f32_e32 v139, v139
	v_exp_f32_e32 v136, v136
	v_exp_f32_e32 v130, v130
	v_exp_f32_e32 v131, v131
	v_exp_f32_e32 v132, v132
	v_exp_f32_e32 v133, v133
	v_add_f32_e32 v138, 1.0, v138
	v_add_f32_e32 v139, 1.0, v139
	v_add_f32_e32 v136, 1.0, v136
	v_add_f32_e32 v130, 1.0, v130
	v_add_f32_e32 v131, 1.0, v131
	v_add_f32_e32 v132, 1.0, v132
	v_add_f32_e32 v133, 1.0, v133
	v_rcp_f32_e32 v138, v138
	v_rcp_f32_e32 v139, v139
	v_rcp_f32_e32 v137, v136
	v_rcp_f32_e32 v130, v130
	v_rcp_f32_e32 v131, v131
	v_rcp_f32_e32 v132, v132
	v_rcp_f32_e32 v133, v133
	v_cvt_pk_bf16_f32 v136, v138, v139
	v_cvt_pk_bf16_f32 v137, v140, v137
	v_cvt_pk_bf16_f32 v130, v130, v131
	v_cvt_pk_bf16_f32 v131, v132, v133
	ds_write_b64 v32, v[136:137] offset:8736
	ds_write_b64 v32, v[130:131] offset:13088
	flat_load_dwordx4 v[130:133], v[134:135] offset:128
	s_waitcnt vmcnt(0) lgkmcnt(0)
;     __device__ __forceinline__ bf16_t* H() const { return (bf16_t*)(ws + OFF_H); }
; DEV void wst_put4(char* wsm, int row, int col, float a, float b, float c, float d) { uint2 w; w.x = pk_bf16(a, b); w.y = pk_bf16(c, d); *(uint2*)(wsm + row * WST_ROW + col * 2) = w; }
; template <int H>
; DEV void epi1_group(const Params& p, int l, bool samp, int rbase, int g64, int fq, int fr, char* wsm, const f32x4 (&acc)[4][8]) {
;     ...
;     } else if (g64 < 90) {
;         const int c0 = (g64 - 42) * 64 + cl;
;         const float* bg = p.b_gate + l * 3072 + c0;
; #pragma unroll
;         for (int ni = 0; ni < 4; ++ni) {
;             const f32x4 b4 = *(const f32x4*)(bg + ni * 16);
; #pragma unroll
;             for (int mi = 0; mi < 4; ++mi) {
;                 f32x4 v = acc[mi][H * 4 + ni] + b4;
; #pragma unroll
;                 for (int j = 0; j < 4; ++j) v[j] = __builtin_amdgcn_rcpf(1.f + __expf(-v[j]));
;                 wst_put4(wsm, mi * 16 + fr, sc + ni * 16, v[0], v[1], v[2], v[3]);
;             }
;         }
	v_pk_add_f32 v[136:137], v[124:125], v[132:133]
	s_nop 0
	v_mul_f32_e32 v136, 0xbfb8aa3b, v136
	v_exp_f32_e32 v136, v136
	v_pk_add_f32 v[138:139], v[122:123], v[130:131]
	v_add_f32_e32 v136, 1.0, v136
	v_mul_f32_e32 v138, 0xbfb8aa3b, v138
	v_mul_f32_e32 v139, 0xbfb8aa3b, v139
	v_rcp_f32_e32 v140, v136
	v_mul_f32_e32 v136, 0xbfb8aa3b, v137
	v_exp_f32_e32 v138, v138
	v_exp_f32_e32 v139, v139
	v_exp_f32_e32 v136, v136
	v_add_f32_e32 v138, 1.0, v138
	v_add_f32_e32 v139, 1.0, v139
	v_add_f32_e32 v136, 1.0, v136
	v_rcp_f32_e32 v138, v138
	v_rcp_f32_e32 v139, v139
	v_rcp_f32_e32 v137, v136
	v_cvt_pk_bf16_f32 v136, v138, v139
	v_cvt_pk_bf16_f32 v137, v140, v137
	ds_write_b64 v32, v[136:137] offset:64
	v_pk_add_f32 v[136:137], v[104:105], v[132:133]
	v_pk_add_f32 v[138:139], v[102:103], v[130:131]
	v_mul_f32_e32 v136, 0xbfb8aa3b, v136
	v_exp_f32_e32 v136, v136
	v_mul_f32_e32 v138, 0xbfb8aa3b, v138
	v_mul_f32_e32 v139, 0xbfb8aa3b, v139
	v_exp_f32_e32 v138, v138
	v_add_f32_e32 v136, 1.0, v136
	v_rcp_f32_e32 v140, v136
	v_mul_f32_e32 v136, 0xbfb8aa3b, v137
	v_exp_f32_e32 v139, v139
	v_exp_f32_e32 v136, v136
	v_add_f32_e32 v138, 1.0, v138
	v_rcp_f32_e32 v138, v138
	v_add_f32_e32 v139, 1.0, v139
	v_add_f32_e32 v136, 1.0, v136
	v_rcp_f32_e32 v139, v139
	v_rcp_f32_e32 v137, v136
	v_cvt_pk_bf16_f32 v136, v138, v139
	v_cvt_pk_bf16_f32 v137, v140, v137
	ds_write_b64 v32, v[136:137] offset:4416
	v_pk_add_f32 v[136:137], v[92:93], v[132:133]
	v_pk_add_f32 v[138:139], v[90:91], v[130:131]
	v_mul_f32_e32 v136, 0xbfb8aa3b, v136
	v_exp_f32_e32 v136, v136
	v_pk_add_f32 v[132:133], v[76:77], v[132:133]
	v_pk_add_f32 v[130:131], v[74:75], v[130:131]
	v_mul_f32_e32 v138, 0xbfb8aa3b, v138
	v_add_f32_e32 v136, 1.0, v136
	v_mul_f32_e32 v139, 0xbfb8aa3b, v139
	v_rcp_f32_e32 v140, v136
	v_mul_f32_e32 v136, 0xbfb8aa3b, v137
	v_mul_f32_e32 v130, 0xbfb8aa3b, v130
	v_mul_f32_e32 v131, 0xbfb8aa3b, v131
	v_mul_f32_e32 v132, 0xbfb8aa3b, v132
	v_mul_f32_e32 v133, 0xbfb8aa3b, v133
	v_exp_f32_e32 v138, v138
	v_exp_f32_e32 v139, v139
	v_exp_f32_e32 v136, v136
	v_exp_f32_e32 v130, v130
	v_exp_f32_e32 v131, v131
	v_exp_f32_e32 v132, v132
	v_exp_f32_e32 v133, v133
	v_add_f32_e32 v138, 1.0, v138
	v_add_f32_e32 v139, 1.0, v139
	v_add_f32_e32 v136, 1.0, v136
	v_add_f32_e32 v130, 1.0, v130
	v_add_f32_e32 v131, 1.0, v131
	v_add_f32_e32 v132, 1.0, v132
	v_add_f32_e32 v133, 1.0, v133
	v_rcp_f32_e32 v138, v138
	v_rcp_f32_e32 v139, v139
	v_rcp_f32_e32 v137, v136
	v_rcp_f32_e32 v130, v130
	v_rcp_f32_e32 v131, v131
	v_rcp_f32_e32 v132, v132
	v_rcp_f32_e32 v133, v133
	v_cvt_pk_bf16_f32 v136, v138, v139
	v_cvt_pk_bf16_f32 v137, v140, v137
	v_cvt_pk_bf16_f32 v130, v130, v131
	v_cvt_pk_bf16_f32 v131, v132, v133
	ds_write_b64 v32, v[136:137] offset:8768
	ds_write_b64 v32, v[130:131] offset:13120
	flat_load_dwordx4 v[130:133], v[134:135] offset:192
	s_waitcnt vmcnt(0) lgkmcnt(0)
	v_pk_add_f32 v[134:135], v[128:129], v[132:133]
	s_nop 0
	v_mul_f32_e32 v134, 0xbfb8aa3b, v134
	v_exp_f32_e32 v134, v134
	v_pk_add_f32 v[136:137], v[126:127], v[130:131]
	v_add_f32_e32 v134, 1.0, v134
	v_mul_f32_e32 v136, 0xbfb8aa3b, v136
	v_mul_f32_e32 v137, 0xbfb8aa3b, v137
	v_rcp_f32_e32 v138, v134
	v_mul_f32_e32 v134, 0xbfb8aa3b, v135
	v_exp_f32_e32 v136, v136
	v_exp_f32_e32 v137, v137
	v_exp_f32_e32 v134, v134
	v_add_f32_e32 v136, 1.0, v136
	v_add_f32_e32 v137, 1.0, v137
	v_add_f32_e32 v134, 1.0, v134
	v_rcp_f32_e32 v136, v136
	v_rcp_f32_e32 v137, v137
	v_rcp_f32_e32 v135, v134
	v_cvt_pk_bf16_f32 v134, v136, v137
	v_cvt_pk_bf16_f32 v135, v138, v135
	ds_write_b64 v32, v[134:135] offset:96
	v_pk_add_f32 v[134:135], v[112:113], v[132:133]
	v_pk_add_f32 v[136:137], v[110:111], v[130:131]
	v_mul_f32_e32 v134, 0xbfb8aa3b, v134
	v_exp_f32_e32 v134, v134
	v_mul_f32_e32 v136, 0xbfb8aa3b, v136
	v_mul_f32_e32 v137, 0xbfb8aa3b, v137
	v_exp_f32_e32 v136, v136
	v_add_f32_e32 v134, 1.0, v134
	v_rcp_f32_e32 v138, v134
	v_mul_f32_e32 v134, 0xbfb8aa3b, v135
	v_exp_f32_e32 v137, v137
	v_exp_f32_e32 v134, v134
	v_add_f32_e32 v136, 1.0, v136
	v_rcp_f32_e32 v136, v136
	v_add_f32_e32 v137, 1.0, v137
	v_add_f32_e32 v134, 1.0, v134
	v_rcp_f32_e32 v137, v137
	v_rcp_f32_e32 v135, v134
	v_cvt_pk_bf16_f32 v134, v136, v137
	v_cvt_pk_bf16_f32 v135, v138, v135
	ds_write_b64 v32, v[134:135] offset:4448
	v_pk_add_f32 v[134:135], v[96:97], v[132:133]
	v_pk_add_f32 v[136:137], v[94:95], v[130:131]
	v_mul_f32_e32 v134, 0xbfb8aa3b, v134
	v_exp_f32_e32 v134, v134
	v_pk_add_f32 v[132:133], v[80:81], v[132:133]
	v_pk_add_f32 v[130:131], v[78:79], v[130:131]
	v_mul_f32_e32 v136, 0xbfb8aa3b, v136
	v_add_f32_e32 v134, 1.0, v134
	v_mul_f32_e32 v137, 0xbfb8aa3b, v137
	v_rcp_f32_e32 v138, v134
	v_mul_f32_e32 v134, 0xbfb8aa3b, v135
	v_mul_f32_e32 v130, 0xbfb8aa3b, v130
	v_mul_f32_e32 v131, 0xbfb8aa3b, v131
	v_mul_f32_e32 v132, 0xbfb8aa3b, v132
	v_mul_f32_e32 v133, 0xbfb8aa3b, v133
	v_exp_f32_e32 v136, v136
	v_exp_f32_e32 v137, v137
	v_exp_f32_e32 v134, v134
	v_exp_f32_e32 v130, v130
	v_exp_f32_e32 v131, v131
	v_exp_f32_e32 v132, v132
	v_exp_f32_e32 v133, v133
	v_add_f32_e32 v136, 1.0, v136
	v_add_f32_e32 v137, 1.0, v137
	v_add_f32_e32 v134, 1.0, v134
	v_add_f32_e32 v130, 1.0, v130
	v_add_f32_e32 v131, 1.0, v131
	v_add_f32_e32 v132, 1.0, v132
	v_add_f32_e32 v133, 1.0, v133
	v_rcp_f32_e32 v136, v136
	v_rcp_f32_e32 v137, v137
	v_rcp_f32_e32 v135, v134
	v_rcp_f32_e32 v130, v130
	v_rcp_f32_e32 v131, v131
	v_rcp_f32_e32 v132, v132
	v_rcp_f32_e32 v133, v133
	v_cvt_pk_bf16_f32 v134, v136, v137
	v_cvt_pk_bf16_f32 v135, v138, v135
	v_cvt_pk_bf16_f32 v130, v130, v131
	v_cvt_pk_bf16_f32 v131, v132, v133
	ds_write_b64 v32, v[134:135] offset:8800
	ds_write_b64 v32, v[130:131] offset:13152

; #define RAW_BARRIER() do { asm volatile("s_waitcnt lgkmcnt(0)" ::: "memory"); __builtin_amdgcn_s_barrier(); } while (0)
; #define GLDS_TILE(kt, st) do { _Pragma("unroll") for (int _i = 0; _i < NP; ++_i) GLDS_PIECE(_i, kt, st); } while (0)
;     ...
;     constexpr int NH = NI >= 4 ? NI / 2 : NI;
;     constexpr int NP = 2 + NB, IVL = (4 * NI) / NP;
;     RAW_BARRIER();
;     GLDS_TILE(0, 0);
;     GLDS_TILE(1, 1);
;     int st = 0;
;     for (int kt = 0; kt < nk - 1; ++kt) {
;         if (NI == 8) asm volatile("s_waitcnt vmcnt(6)" ::: "memory"); else if (NI == 4) asm volatile("s_waitcnt vmcnt(4)" ::: "memory"); else asm volatile("s_waitcnt vmcnt(3)" ::: "memory");
;         RAW_BARRIER();
;         const int s2 = st >= 1 ? st - 1 : 2;
;         const bool ld = kt + 2 < nk;
;         STEP_TILE(st, ld, kt + 2, s2);
;         st = st == 2 ? 0 : st + 1;
;     }
.LBB0_1940:
	s_mul_i32 s29, s1, 0x6000
	s_add_i32 s30, s29, 0
	s_waitcnt vmcnt(6)
	v_add_u32_e32 v148, s30, v134
	v_add_u32_e32 v155, s30, v135
	s_waitcnt lgkmcnt(0)
	s_barrier
	ds_read_b128 v[158:161], v155 offset:8192
	ds_read_b128 v[136:139], v148
	ds_read_b128 v[140:143], v148 offset:1024
	ds_read_b128 v[144:147], v148 offset:2048
	ds_read_b128 v[148:151], v148 offset:3072
	ds_read_b128 v[162:165], v155 offset:9216
	ds_read_b128 v[166:169], v155 offset:10240
	ds_read_b128 v[170:173], v155 offset:11264
	s_addk_i32 s29, 0xa000
	s_cmp_gt_i32 s1, 0
	s_setprio 1
	s_waitcnt lgkmcnt(6)
	v_mfma_f32_16x16x32_bf16 v[126:129], v[158:161], v[136:139], v[126:129]
	s_cselect_b32 s29, s29, 0xc000
	v_add_u32_e32 v157, s29, v32
	v_lshl_add_u64 v[152:153], v[132:133], 0, s[22:23]
	s_waitcnt lgkmcnt(5)
	v_mfma_f32_16x16x32_bf16 v[110:113], v[158:161], v[140:143], v[110:113]
	v_lshl_add_u64 v[208:209], v[130:131], 0, s[22:23]
	v_lshl_add_u64 v[206:207], v[152:153], 0, s[34:35]
	v_add_u32_e32 v205, 0x2000, v157
	s_waitcnt lgkmcnt(4)
	v_mfma_f32_16x16x32_bf16 v[82:85], v[158:161], v[144:147], v[82:85]
	s_waitcnt lgkmcnt(3)
	v_mfma_f32_16x16x32_bf16 v[50:53], v[158:161], v[148:151], v[50:53]
	v_lshl_add_u64 v[158:159], v[208:209], 0, s[38:39]
	s_waitcnt lgkmcnt(2)
	v_mfma_f32_16x16x32_bf16 v[122:125], v[162:165], v[136:139], v[122:125]
	v_readfirstlane_b32 s29, v157
	s_mov_b32 m0, s29
	v_mfma_f32_16x16x32_bf16 v[102:105], v[162:165], v[140:143], v[102:105]
	global_load_lds_dwordx4 v[158:159], off
	ds_read_b128 v[158:161], v155 offset:12288
	ds_read_b128 v[174:177], v155 offset:13312
	ds_read_b128 v[178:181], v155 offset:14336
	ds_read_b128 v[182:185], v155 offset:15360
	v_mfma_f32_16x16x32_bf16 v[70:73], v[162:165], v[144:147], v[70:73]
	v_mfma_f32_16x16x32_bf16 v[38:41], v[162:165], v[148:151], v[38:41]
	s_waitcnt lgkmcnt(5)
	v_mfma_f32_16x16x32_bf16 v[118:121], v[166:169], v[136:139], v[118:121]
	v_mfma_f32_16x16x32_bf16 v[94:97], v[166:169], v[140:143], v[94:97]
	v_add_u32_e32 v155, 0x1000, v157
	v_lshl_add_u64 v[162:163], v[208:209], 0, s[40:41]
	v_readfirstlane_b32 s29, v155
	s_mov_b32 m0, s29
	v_mfma_f32_16x16x32_bf16 v[62:65], v[166:169], v[144:147], v[62:65]
	global_load_lds_dwordx4 v[162:163], off
	v_mfma_f32_16x16x32_bf16 v[28:31], v[166:169], v[148:151], v[28:31]
	s_waitcnt lgkmcnt(4)
	v_mfma_f32_16x16x32_bf16 v[114:117], v[170:173], v[136:139], v[114:117]
	v_mfma_f32_16x16x32_bf16 v[86:89], v[170:173], v[140:143], v[86:89]
	v_mfma_f32_16x16x32_bf16 v[54:57], v[170:173], v[144:147], v[54:57]
	v_readfirstlane_b32 s29, v205
	s_mov_b32 m0, s29
	v_mfma_f32_16x16x32_bf16 v[20:23], v[170:173], v[148:151], v[20:23]
	global_load_lds_dwordx4 v[206:207], off
	s_waitcnt lgkmcnt(0)
	v_mfma_f32_16x16x32_bf16 v[106:109], v[158:161], v[136:139], v[106:109]
	v_mfma_f32_16x16x32_bf16 v[74:77], v[158:161], v[140:143], v[74:77]
	v_mfma_f32_16x16x32_bf16 v[42:45], v[158:161], v[144:147], v[42:45]
	v_mfma_f32_16x16x32_bf16 v[12:15], v[158:161], v[148:151], v[12:15]
	v_add_u32_e32 v155, 0x3000, v157
	v_lshl_add_u64 v[158:159], v[152:153], 0, s[42:43]
	v_readfirstlane_b32 s29, v155
	s_mov_b32 m0, s29
	v_mfma_f32_16x16x32_bf16 v[98:101], v[174:177], v[136:139], v[98:101]
	global_load_lds_dwordx4 v[158:159], off
	v_mfma_f32_16x16x32_bf16 v[66:69], v[174:177], v[140:143], v[66:69]
	v_mfma_f32_16x16x32_bf16 v[34:37], v[174:177], v[144:147], v[34:37]
	v_mfma_f32_16x16x32_bf16 v[8:11], v[174:177], v[148:151], v[8:11]
	v_mfma_f32_16x16x32_bf16 v[90:93], v[178:181], v[136:139], v[90:93]
	v_add_u32_e32 v155, 0x4000, v157
	v_lshl_add_u64 v[158:159], v[152:153], 0, s[76:77]
	v_readfirstlane_b32 s29, v155
	s_mov_b32 m0, s29
	v_mfma_f32_16x16x32_bf16 v[58:61], v[178:181], v[140:143], v[58:61]
	global_load_lds_dwordx4 v[158:159], off
	v_mfma_f32_16x16x32_bf16 v[24:27], v[178:181], v[144:147], v[24:27]
	v_mfma_f32_16x16x32_bf16 v[4:7], v[178:181], v[148:151], v[4:7]
	v_mfma_f32_16x16x32_bf16 v[78:81], v[182:185], v[136:139], v[78:81]
	v_mfma_f32_16x16x32_bf16 v[46:49], v[182:185], v[140:143], v[46:49]
	v_add_u32_e32 v138, 0x5000, v157
	v_lshl_add_u64 v[136:137], v[152:153], 0, s[84:85]
	v_readfirstlane_b32 s29, v138
	s_mov_b32 m0, s29
	v_mfma_f32_16x16x32_bf16 v[16:19], v[182:185], v[144:147], v[16:19]
	global_load_lds_dwordx4 v[136:137], off
	v_mfma_f32_16x16x32_bf16 v[0:3], v[182:185], v[148:151], v[0:3]
	s_setprio 0
	s_add_i32 s29, s1, 1
	s_cmp_lg_u32 s1, 2
	s_cselect_b32 s1, s29, 0
	s_add_u32 s22, s22, 0x80
	s_addc_u32 s23, s23, 0
	s_cmpk_lg_i32 s22, 0xf00
	s_cbranch_scc1 .LBB0_1940
	s_waitcnt vmcnt(6)
	v_add_u32_e32 v32, 0, v134
	v_add_u32_e32 v152, 0, v135
	s_waitcnt lgkmcnt(0)
	s_barrier
; #define RAW_BARRIER() do { asm volatile("s_waitcnt lgkmcnt(0)" ::: "memory"); __builtin_amdgcn_s_barrier(); } while (0)
;     ...
;     for (int kt = 0; kt < nk - 1; ++kt) {
;         if (NI == 8) asm volatile("s_waitcnt vmcnt(6)" ::: "memory"); else if (NI == 4) asm volatile("s_waitcnt vmcnt(4)" ::: "memory"); else asm volatile("s_waitcnt vmcnt(3)" ::: "memory");
;         RAW_BARRIER();
;         const int s2 = st >= 1 ? st - 1 : 2;
;         const bool ld = kt + 2 < nk;
;         STEP_TILE(st, ld, kt + 2, s2);
;         st = st == 2 ? 0 : st + 1;
;     }
;     asm volatile("s_waitcnt vmcnt(0)" ::: "memory");
;     RAW_BARRIER();
;     STEP_TILE(st, false, 0, 0);
;     RAW_BARRIER();
	ds_read_b128 v[130:133], v32
	ds_read_b128 v[136:139], v32 offset:1024
	ds_read_b128 v[140:143], v32 offset:2048
	ds_read_b128 v[144:147], v32 offset:3072
	ds_read_b128 v[148:151], v152 offset:8192
	ds_read_b128 v[158:161], v152 offset:9216
	ds_read_b128 v[162:165], v152 offset:10240
	ds_read_b128 v[166:169], v152 offset:11264
	s_setprio 1
	s_waitcnt lgkmcnt(0)
	v_mfma_f32_16x16x32_bf16 v[126:129], v[148:151], v[130:133], v[126:129]
	v_mfma_f32_16x16x32_bf16 v[110:113], v[148:151], v[136:139], v[110:113]
	v_mfma_f32_16x16x32_bf16 v[82:85], v[148:151], v[140:143], v[82:85]
	v_mfma_f32_16x16x32_bf16 v[50:53], v[148:151], v[144:147], v[50:53]
	v_mfma_f32_16x16x32_bf16 v[122:125], v[158:161], v[130:133], v[122:125]
	ds_read_b128 v[148:151], v152 offset:12288
	ds_read_b128 v[170:173], v152 offset:13312
	ds_read_b128 v[174:177], v152 offset:14336
	ds_read_b128 v[178:181], v152 offset:15360
	v_mfma_f32_16x16x32_bf16 v[102:105], v[158:161], v[136:139], v[102:105]
	v_mfma_f32_16x16x32_bf16 v[70:73], v[158:161], v[140:143], v[70:73]
	v_mfma_f32_16x16x32_bf16 v[38:41], v[158:161], v[144:147], v[38:41]
	v_mfma_f32_16x16x32_bf16 v[118:121], v[162:165], v[130:133], v[118:121]
	v_mfma_f32_16x16x32_bf16 v[158:161], v[162:165], v[136:139], v[94:97]
	v_mfma_f32_16x16x32_bf16 v[62:65], v[162:165], v[140:143], v[62:65]
	v_mfma_f32_16x16x32_bf16 v[28:31], v[162:165], v[144:147], v[28:31]
	v_mfma_f32_16x16x32_bf16 v[114:117], v[166:169], v[130:133], v[114:117]
	v_mfma_f32_16x16x32_bf16 v[54:57], v[166:169], v[140:143], v[54:57]
	v_mfma_f32_16x16x32_bf16 v[162:165], v[166:169], v[136:139], v[86:89]
	v_mfma_f32_16x16x32_bf16 v[20:23], v[166:169], v[144:147], v[20:23]
	s_waitcnt lgkmcnt(0)
	v_mfma_f32_16x16x32_bf16 v[42:45], v[148:151], v[140:143], v[42:45]
	v_mfma_f32_16x16x32_bf16 v[12:15], v[148:151], v[144:147], v[12:15]
	v_mfma_f32_16x16x32_bf16 v[166:169], v[148:151], v[130:133], v[106:109]
	v_mfma_f32_16x16x32_bf16 v[182:185], v[148:151], v[136:139], v[74:77]
	v_mfma_f32_16x16x32_bf16 v[148:151], v[170:173], v[130:133], v[98:101]
	v_mfma_f32_16x16x32_bf16 v[206:209], v[170:173], v[136:139], v[66:69]
	v_mfma_f32_16x16x32_bf16 v[34:37], v[170:173], v[140:143], v[34:37]
	v_mfma_f32_16x16x32_bf16 v[8:11], v[170:173], v[144:147], v[8:11]
	v_mfma_f32_16x16x32_bf16 v[170:173], v[174:177], v[130:133], v[90:93]
	v_mfma_f32_16x16x32_bf16 v[4:7], v[174:177], v[144:147], v[4:7]
	v_mfma_f32_16x16x32_bf16 v[210:213], v[174:177], v[136:139], v[58:61]
	v_mfma_f32_16x16x32_bf16 v[214:217], v[174:177], v[140:143], v[24:27]
	v_mfma_f32_16x16x32_bf16 v[130:133], v[178:181], v[130:133], v[78:81]
	v_mfma_f32_16x16x32_bf16 v[134:137], v[178:181], v[136:139], v[46:49]
	v_mfma_f32_16x16x32_bf16 v[16:19], v[178:181], v[140:143], v[16:19]
	v_mfma_f32_16x16x32_bf16 v[0:3], v[178:181], v[144:147], v[0:3]
	s_setprio 0
	s_waitcnt vmcnt(0)
	s_waitcnt lgkmcnt(0)
	s_barrier
	ds_read_b128 v[138:141], v32 offset:24576
	ds_read_b128 v[142:145], v32 offset:25600
	ds_read_b128 v[174:177], v32 offset:26624
	ds_read_b128 v[178:181], v32 offset:27648
	ds_read_b128 v[24:27], v152 offset:32768
	ds_read_b128 v[46:49], v152 offset:33792
	ds_read_b128 v[58:61], v152 offset:34816
	ds_read_b128 v[66:69], v152 offset:35840
	s_setprio 1
	s_waitcnt lgkmcnt(0)
	v_mfma_f32_16x16x32_bf16 v[126:129], v[24:27], v[138:141], v[126:129]
	v_mfma_f32_16x16x32_bf16 v[110:113], v[24:27], v[142:145], v[110:113]
	v_mfma_f32_16x16x32_bf16 v[94:97], v[24:27], v[174:177], v[82:85]
	v_mfma_f32_16x16x32_bf16 v[78:81], v[24:27], v[178:181], v[50:53]
	v_mfma_f32_16x16x32_bf16 v[122:125], v[46:49], v[138:141], v[122:125]
	ds_read_b128 v[24:27], v152 offset:36864
	s_nop 0
	ds_read_b128 v[50:53], v152 offset:37888
	ds_read_b128 v[218:221], v152 offset:38912
	ds_read_b128 v[222:225], v152 offset:39936
	v_mfma_f32_16x16x32_bf16 v[106:109], v[46:49], v[142:145], v[102:105]
	v_mfma_f32_16x16x32_bf16 v[90:93], v[46:49], v[174:177], v[70:73]
	v_mfma_f32_16x16x32_bf16 v[74:77], v[46:49], v[178:181], v[38:41]
	v_mfma_f32_16x16x32_bf16 v[118:121], v[58:61], v[138:141], v[118:121]
	v_mfma_f32_16x16x32_bf16 v[102:105], v[58:61], v[142:145], v[158:161]
	v_mfma_f32_16x16x32_bf16 v[86:89], v[58:61], v[174:177], v[62:65]
	v_mfma_f32_16x16x32_bf16 v[70:73], v[58:61], v[178:181], v[28:31]
	v_mfma_f32_16x16x32_bf16 v[114:117], v[66:69], v[138:141], v[114:117]
	v_mfma_f32_16x16x32_bf16 v[98:101], v[66:69], v[142:145], v[162:165]
	v_mfma_f32_16x16x32_bf16 v[82:85], v[66:69], v[174:177], v[54:57]
	v_mfma_f32_16x16x32_bf16 v[66:69], v[66:69], v[178:181], v[20:23]
	s_waitcnt lgkmcnt(0)
	v_mfma_f32_16x16x32_bf16 v[62:65], v[24:27], v[138:141], v[166:169]
	v_mfma_f32_16x16x32_bf16 v[46:49], v[24:27], v[142:145], v[182:185]
	v_mfma_f32_16x16x32_bf16 v[28:31], v[24:27], v[174:177], v[42:45]
	v_mfma_f32_16x16x32_bf16 v[12:15], v[24:27], v[178:181], v[12:15]
	v_mfma_f32_16x16x32_bf16 v[58:61], v[50:53], v[138:141], v[148:151]
	v_mfma_f32_16x16x32_bf16 v[42:45], v[50:53], v[142:145], v[206:209]
	v_mfma_f32_16x16x32_bf16 v[24:27], v[50:53], v[174:177], v[34:37]
	v_mfma_f32_16x16x32_bf16 v[8:11], v[50:53], v[178:181], v[8:11]
	v_mfma_f32_16x16x32_bf16 v[54:57], v[218:221], v[138:141], v[170:173]
	v_mfma_f32_16x16x32_bf16 v[38:41], v[218:221], v[142:145], v[210:213]
	v_mfma_f32_16x16x32_bf16 v[20:23], v[218:221], v[174:177], v[214:217]
	v_mfma_f32_16x16x32_bf16 v[4:7], v[218:221], v[178:181], v[4:7]
	v_mfma_f32_16x16x32_bf16 v[50:53], v[222:225], v[138:141], v[130:133]
	v_mfma_f32_16x16x32_bf16 v[34:37], v[222:225], v[142:145], v[134:137]
	v_mfma_f32_16x16x32_bf16 v[16:19], v[222:225], v[174:177], v[16:19]
	v_mfma_f32_16x16x32_bf16 v[0:3], v[222:225], v[178:181], v[0:3]
	s_setprio 0
	v_mov_b32_e32 v32, v186
	s_waitcnt lgkmcnt(0)
	s_barrier
;     __device__ __forceinline__ bf16_t* W1t() const { return (bf16_t*)(ws + OFF_W1t); }
;     __device__ __forceinline__ bf16_t* H() const { return (bf16_t*)(ws + OFF_H); }
;     __device__ __forceinline__ bf16_t* U() const { return (bf16_t*)(ws + OFF_U); }
;     __device__ __forceinline__ bf16_t* Vs() const { return (bf16_t*)(ws + OFF_Vs); }
; DEV int tid_opaque() { int t = threadIdx.x; asm volatile("" : "+v"(t)); return t; }
; DEV void wst_put4(char* wsm, int row, int col, float a, float b, float c, float d) { uint2 w; w.x = pk_bf16(a, b); w.y = pk_bf16(c, d); *(uint2*)(wsm + row * WST_ROW + col * 2) = w; }
; template <int H>
; DEV void epi1_group(const Params& p, int l, bool samp, int rbase, int g64, int fq, int fr, char* wsm, const f32x4 (&acc)[4][8]) {
;     const int cl = fq * 4;
;     const int sc = H * 64 + cl;
;     if (g64 < 12) {
;         bf16_t* dst = g64 < 6 ? p.U() : p.Vs(); const int c0 = (g64 % 6) * 64 + cl;
;     ...
;     } else if (g64 < 90) {
;         const int c0 = (g64 - 42) * 64 + cl;
;         const float* bg = p.b_gate + l * 3072 + c0;
; #pragma unroll
;         for (int ni = 0; ni < 4; ++ni) {
;             const f32x4 b4 = *(const f32x4*)(bg + ni * 16);
; #pragma unroll
;             for (int mi = 0; mi < 4; ++mi) {
;                 f32x4 v = acc[mi][H * 4 + ni] + b4;
; #pragma unroll
;                 for (int j = 0; j < 4; ++j) v[j] = __builtin_amdgcn_rcpf(1.f + __expf(-v[j]));
;                 wst_put4(wsm, mi * 16 + fr, sc + ni * 16, v[0], v[1], v[2], v[3]);
;             }
; DEV void gemm1_big(const Params& p, int l, int mt, int nt, char* smem) {
;     f32x4 acc[4][8]; zero_accn<8>(acc);
;     gemm_glds<8>(p.H() + (size_t)mt * 128 * 1024, 1024, p.W1t() + (size_t)l * N1P * 1024 + (size_t)nt * 256 * 1024, 1024, 1024, acc, smem);
;     const int t = tid_opaque(), lane = t & 63, wid = t >> 6, wm = wid >> 1, wn = wid & 1, fr = lane & 15, fq = lane >> 4;
;     const int rbase = mt * 128 + wm * 64 + fr, g0 = nt * 4 + wn * 2;
;     char* wsm = smem + wid * WST_BYTES;
;     epi1_group<0>(p, l, mt == MT - 1, rbase, g0, fq, fr, wsm, acc);
	s_lshl_b32 s34, s0, 2
	v_ashrrev_i32_e32 v130, 6, v32
	v_and_b32_e32 v205, 15, v32
	v_bfe_u32 v155, v32, 4, 2
	v_ashrrev_i32_e32 v32, 1, v32
	v_and_b32_e32 v32, 0xffffffc0, v32
	v_lshl_add_u32 v146, s28, 7, v32
	v_lshlrev_b32_e32 v32, 1, v130
	s_movk_i32 s0, 0x4400
	v_and_or_b32 v206, v32, 2, s34
	v_mul_lo_u32 v32, v130, s0
	s_cmpk_lg_i32 s28, 0x80
	v_or_b32_e32 v148, v146, v205
	v_add_u32_e32 v157, 0, v32
	s_cselect_b64 s[42:43], -1, 0
	v_lshlrev_b32_e32 v147, 2, v155
	v_cmp_lt_i32_e64 s[38:39], 11, v206
	s_and_saveexec_b64 s[0:1], s[38:39]
	s_xor_b64 s[64:65], exec, s[0:1]
	s_cbranch_execz .LBB0_2265
	s_cmp_gt_u32 s34, 23
	s_mov_b64 s[0:1], -1
	s_cbranch_scc0 .LBB0_2151
	v_cmp_lt_u32_e32 vcc, 29, v206
	s_and_saveexec_b64 s[0:1], vcc
	s_xor_b64 s[66:67], exec, s[0:1]
	s_cbranch_execz .LBB0_2085
	v_cmp_lt_u32_e32 vcc, 33, v206
	s_and_saveexec_b64 s[0:1], vcc
	s_xor_b64 s[68:69], exec, s[0:1]
	s_cbranch_execz .LBB0_2082
	v_cmp_lt_u32_e32 vcc, 37, v206
	s_and_saveexec_b64 s[0:1], vcc
	s_xor_b64 s[0:1], exec, s[0:1]
	s_cbranch_execz .LBB0_2016
	v_cmp_lt_u32_e32 vcc, 41, v206
	s_and_saveexec_b64 s[22:23], vcc
	s_xor_b64 s[40:41], exec, s[22:23]
	s_cbranch_execz .LBB0_1950
	s_movk_i32 s22, 0x5a
	v_cmp_gt_u32_e32 vcc, s22, v206
	s_and_saveexec_b64 s[70:71], vcc
	s_cbranch_execz .LBB0_1949
	v_lshl_or_b32 v32, v206, 6, v147
	v_add_u32_e32 v32, 0xfffff580, v32
	v_lshl_add_u64 v[134:135], v[32:33], 2, s[6:7]
	flat_load_dwordx4 v[130:133], v[134:135]
	v_lshlrev_b32_e32 v32, 3, v155
	s_waitcnt vmcnt(0) lgkmcnt(0)
	v_pk_add_f32 v[136:137], v[128:129], v[132:133]
	s_nop 0
	v_mul_f32_e32 v136, 0xbfb8aa3b, v136
	v_exp_f32_e32 v136, v136
	v_pk_add_f32 v[138:139], v[126:127], v[130:131]
	v_add_f32_e32 v136, 1.0, v136
	v_mul_f32_e32 v138, 0xbfb8aa3b, v138
	v_mul_f32_e32 v139, 0xbfb8aa3b, v139
	v_exp_f32_e32 v138, v138
	v_exp_f32_e32 v139, v139
	v_rcp_f32_e32 v140, v136
	v_mul_f32_e32 v136, 0xbfb8aa3b, v137
	v_exp_f32_e32 v136, v136
	v_add_f32_e32 v138, 1.0, v138
	v_add_f32_e32 v139, 1.0, v139
	v_rcp_f32_e32 v138, v138
	v_rcp_f32_e32 v139, v139
	v_add_f32_e32 v136, 1.0, v136
	v_rcp_f32_e32 v137, v136
	v_cvt_pk_bf16_f32 v136, v138, v139
	v_mul_u32_u24_e32 v138, 0x110, v205
	v_cvt_pk_bf16_f32 v137, v140, v137
	v_add3_u32 v32, v157, v32, v138
	ds_write_b64 v32, v[136:137]
	v_pk_add_f32 v[136:137], v[112:113], v[132:133]
	v_pk_add_f32 v[138:139], v[110:111], v[130:131]
	v_mul_f32_e32 v136, 0xbfb8aa3b, v136
	v_exp_f32_e32 v136, v136
	v_mul_f32_e32 v138, 0xbfb8aa3b, v138
	v_mul_f32_e32 v139, 0xbfb8aa3b, v139
	v_exp_f32_e32 v138, v138
	v_add_f32_e32 v136, 1.0, v136
	v_rcp_f32_e32 v140, v136
	v_mul_f32_e32 v136, 0xbfb8aa3b, v137
	v_exp_f32_e32 v139, v139
	v_exp_f32_e32 v136, v136
	v_add_f32_e32 v138, 1.0, v138
	v_rcp_f32_e32 v138, v138
	v_add_f32_e32 v139, 1.0, v139
	v_add_f32_e32 v136, 1.0, v136
	v_rcp_f32_e32 v139, v139
	v_rcp_f32_e32 v137, v136
	v_cvt_pk_bf16_f32 v136, v138, v139
	v_cvt_pk_bf16_f32 v137, v140, v137
	ds_write_b64 v32, v[136:137] offset:4352
	v_pk_add_f32 v[136:137], v[96:97], v[132:133]
	v_pk_add_f32 v[138:139], v[94:95], v[130:131]
	v_mul_f32_e32 v136, 0xbfb8aa3b, v136
	v_exp_f32_e32 v136, v136
	v_pk_add_f32 v[132:133], v[80:81], v[132:133]
	v_pk_add_f32 v[130:131], v[78:79], v[130:131]
	v_mul_f32_e32 v138, 0xbfb8aa3b, v138
	v_add_f32_e32 v136, 1.0, v136
	v_mul_f32_e32 v139, 0xbfb8aa3b, v139
	v_rcp_f32_e32 v140, v136
	v_mul_f32_e32 v136, 0xbfb8aa3b, v137
	v_mul_f32_e32 v130, 0xbfb8aa3b, v130
	v_mul_f32_e32 v131, 0xbfb8aa3b, v131
	v_mul_f32_e32 v132, 0xbfb8aa3b, v132
	v_mul_f32_e32 v133, 0xbfb8aa3b, v133
	v_exp_f32_e32 v138, v138
	v_exp_f32_e32 v139, v139
	v_exp_f32_e32 v136, v136
	v_exp_f32_e32 v130, v130
	v_exp_f32_e32 v131, v131
	v_exp_f32_e32 v132, v132
	v_exp_f32_e32 v133, v133
	v_add_f32_e32 v138, 1.0, v138
	v_add_f32_e32 v139, 1.0, v139
	v_add_f32_e32 v136, 1.0, v136
	v_add_f32_e32 v130, 1.0, v130
	v_add_f32_e32 v131, 1.0, v131
	v_add_f32_e32 v132, 1.0, v132
	v_add_f32_e32 v133, 1.0, v133
	v_rcp_f32_e32 v138, v138
	v_rcp_f32_e32 v139, v139
	v_rcp_f32_e32 v137, v136
	v_rcp_f32_e32 v130, v130
	v_rcp_f32_e32 v131, v131
	v_rcp_f32_e32 v132, v132
	v_rcp_f32_e32 v133, v133
	v_cvt_pk_bf16_f32 v136, v138, v139
	v_cvt_pk_bf16_f32 v137, v140, v137
	v_cvt_pk_bf16_f32 v130, v130, v131
	v_cvt_pk_bf16_f32 v131, v132, v133
	ds_write_b64 v32, v[136:137] offset:8704
	ds_write_b64 v32, v[130:131] offset:13056
	flat_load_dwordx4 v[130:133], v[134:135] offset:64
	s_waitcnt vmcnt(0) lgkmcnt(0)
;     __device__ __forceinline__ bf16_t* H() const { return (bf16_t*)(ws + OFF_H); }
; DEV void wst_put4(char* wsm, int row, int col, float a, float b, float c, float d) { uint2 w; w.x = pk_bf16(a, b); w.y = pk_bf16(c, d); *(uint2*)(wsm + row * WST_ROW + col * 2) = w; }
; template <int H>
; DEV void epi1_group(const Params& p, int l, bool samp, int rbase, int g64, int fq, int fr, char* wsm, const f32x4 (&acc)[4][8]) {
;     ...
; #pragma unroll
;         for (int ni = 0; ni < 4; ++ni) {
;             const f32x4 b4 = *(const f32x4*)(bg + ni * 16);
; #pragma unroll
;             for (int mi = 0; mi < 4; ++mi) {
;                 f32x4 v = acc[mi][H * 4 + ni] + b4;
; #pragma unroll
;                 for (int j = 0; j < 4; ++j) v[j] = __builtin_amdgcn_rcpf(1.f + __expf(-v[j]));
;                 wst_put4(wsm, mi * 16 + fr, sc + ni * 16, v[0], v[1], v[2], v[3]);
;             }
	v_pk_add_f32 v[136:137], v[124:125], v[132:133]
	s_nop 0
	v_mul_f32_e32 v136, 0xbfb8aa3b, v136
	v_exp_f32_e32 v136, v136
	v_pk_add_f32 v[138:139], v[122:123], v[130:131]
	v_add_f32_e32 v136, 1.0, v136
	v_mul_f32_e32 v138, 0xbfb8aa3b, v138
	v_mul_f32_e32 v139, 0xbfb8aa3b, v139
	v_rcp_f32_e32 v140, v136
	v_mul_f32_e32 v136, 0xbfb8aa3b, v137
	v_exp_f32_e32 v138, v138
	v_exp_f32_e32 v139, v139
	v_exp_f32_e32 v136, v136
	v_add_f32_e32 v138, 1.0, v138
	v_add_f32_e32 v139, 1.0, v139
	v_add_f32_e32 v136, 1.0, v136
	v_rcp_f32_e32 v138, v138
	v_rcp_f32_e32 v139, v139
	v_rcp_f32_e32 v137, v136
	v_cvt_pk_bf16_f32 v136, v138, v139
	v_cvt_pk_bf16_f32 v137, v140, v137
	ds_write_b64 v32, v[136:137] offset:32
	v_pk_add_f32 v[136:137], v[108:109], v[132:133]
	v_pk_add_f32 v[138:139], v[106:107], v[130:131]
	v_mul_f32_e32 v136, 0xbfb8aa3b, v136
	v_exp_f32_e32 v136, v136
	v_mul_f32_e32 v138, 0xbfb8aa3b, v138
	v_mul_f32_e32 v139, 0xbfb8aa3b, v139
	v_exp_f32_e32 v138, v138
	v_add_f32_e32 v136, 1.0, v136
	v_rcp_f32_e32 v140, v136
	v_mul_f32_e32 v136, 0xbfb8aa3b, v137
	v_exp_f32_e32 v139, v139
	v_exp_f32_e32 v136, v136
	v_add_f32_e32 v138, 1.0, v138
	v_rcp_f32_e32 v138, v138
	v_add_f32_e32 v139, 1.0, v139
	v_add_f32_e32 v136, 1.0, v136
	v_rcp_f32_e32 v139, v139
	v_rcp_f32_e32 v137, v136
	v_cvt_pk_bf16_f32 v136, v138, v139
	v_cvt_pk_bf16_f32 v137, v140, v137
	ds_write_b64 v32, v[136:137] offset:4384
	v_pk_add_f32 v[136:137], v[92:93], v[132:133]
	v_pk_add_f32 v[138:139], v[90:91], v[130:131]
	v_mul_f32_e32 v136, 0xbfb8aa3b, v136
	v_exp_f32_e32 v136, v136
	v_pk_add_f32 v[132:133], v[76:77], v[132:133]
	v_pk_add_f32 v[130:131], v[74:75], v[130:131]
	v_mul_f32_e32 v138, 0xbfb8aa3b, v138
	v_add_f32_e32 v136, 1.0, v136
	v_mul_f32_e32 v139, 0xbfb8aa3b, v139
	v_rcp_f32_e32 v140, v136
	v_mul_f32_e32 v136, 0xbfb8aa3b, v137
	v_mul_f32_e32 v130, 0xbfb8aa3b, v130
	v_mul_f32_e32 v131, 0xbfb8aa3b, v131
	v_mul_f32_e32 v132, 0xbfb8aa3b, v132
	v_mul_f32_e32 v133, 0xbfb8aa3b, v133
	v_exp_f32_e32 v138, v138
	v_exp_f32_e32 v139, v139
	v_exp_f32_e32 v136, v136
	v_exp_f32_e32 v130, v130
	v_exp_f32_e32 v131, v131
	v_exp_f32_e32 v132, v132
	v_exp_f32_e32 v133, v133
	v_add_f32_e32 v138, 1.0, v138
	v_add_f32_e32 v139, 1.0, v139
	v_add_f32_e32 v136, 1.0, v136
	v_add_f32_e32 v130, 1.0, v130
	v_add_f32_e32 v131, 1.0, v131
	v_add_f32_e32 v132, 1.0, v132
	v_add_f32_e32 v133, 1.0, v133
	v_rcp_f32_e32 v138, v138
	v_rcp_f32_e32 v139, v139
	v_rcp_f32_e32 v137, v136
	v_rcp_f32_e32 v130, v130
	v_rcp_f32_e32 v131, v131
	v_rcp_f32_e32 v132, v132
	v_rcp_f32_e32 v133, v133
	v_cvt_pk_bf16_f32 v136, v138, v139
	v_cvt_pk_bf16_f32 v137, v140, v137
	v_cvt_pk_bf16_f32 v130, v130, v131
	v_cvt_pk_bf16_f32 v131, v132, v133
	ds_write_b64 v32, v[136:137] offset:8736
	ds_write_b64 v32, v[130:131] offset:13088
	flat_load_dwordx4 v[130:133], v[134:135] offset:128
	s_waitcnt vmcnt(0) lgkmcnt(0)
;     __device__ __forceinline__ bf16_t* H() const { return (bf16_t*)(ws + OFF_H); }
; DEV void wst_put4(char* wsm, int row, int col, float a, float b, float c, float d) { uint2 w; w.x = pk_bf16(a, b); w.y = pk_bf16(c, d); *(uint2*)(wsm + row * WST_ROW + col * 2) = w; }
; template <int H>
; DEV void epi1_group(const Params& p, int l, bool samp, int rbase, int g64, int fq, int fr, char* wsm, const f32x4 (&acc)[4][8]) {
;     ...
; #pragma unroll
;         for (int ni = 0; ni < 4; ++ni) {
;             const f32x4 b4 = *(const f32x4*)(bg + ni * 16);
; #pragma unroll
;             for (int mi = 0; mi < 4; ++mi) {
;                 f32x4 v = acc[mi][H * 4 + ni] + b4;
; #pragma unroll
;                 for (int j = 0; j < 4; ++j) v[j] = __builtin_amdgcn_rcpf(1.f + __expf(-v[j]));
;                 wst_put4(wsm, mi * 16 + fr, sc + ni * 16, v[0], v[1], v[2], v[3]);
;             }
	v_pk_add_f32 v[136:137], v[120:121], v[132:133]
	s_nop 0
	v_mul_f32_e32 v136, 0xbfb8aa3b, v136
	v_exp_f32_e32 v136, v136
	v_pk_add_f32 v[138:139], v[118:119], v[130:131]
	v_add_f32_e32 v136, 1.0, v136
	v_mul_f32_e32 v138, 0xbfb8aa3b, v138
	v_mul_f32_e32 v139, 0xbfb8aa3b, v139
	v_rcp_f32_e32 v140, v136
	v_mul_f32_e32 v136, 0xbfb8aa3b, v137
	v_exp_f32_e32 v138, v138
	v_exp_f32_e32 v139, v139
	v_exp_f32_e32 v136, v136
	v_add_f32_e32 v138, 1.0, v138
	v_add_f32_e32 v139, 1.0, v139
	v_add_f32_e32 v136, 1.0, v136
	v_rcp_f32_e32 v138, v138
	v_rcp_f32_e32 v139, v139
	v_rcp_f32_e32 v137, v136
	v_cvt_pk_bf16_f32 v136, v138, v139
	v_cvt_pk_bf16_f32 v137, v140, v137
	ds_write_b64 v32, v[136:137] offset:64
	v_pk_add_f32 v[136:137], v[104:105], v[132:133]
	v_pk_add_f32 v[138:139], v[102:103], v[130:131]
	v_mul_f32_e32 v136, 0xbfb8aa3b, v136
	v_exp_f32_e32 v136, v136
	v_mul_f32_e32 v138, 0xbfb8aa3b, v138
	v_mul_f32_e32 v139, 0xbfb8aa3b, v139
	v_exp_f32_e32 v138, v138
	v_add_f32_e32 v136, 1.0, v136
	v_rcp_f32_e32 v140, v136
	v_mul_f32_e32 v136, 0xbfb8aa3b, v137
	v_exp_f32_e32 v139, v139
	v_exp_f32_e32 v136, v136
	v_add_f32_e32 v138, 1.0, v138
	v_rcp_f32_e32 v138, v138
	v_add_f32_e32 v139, 1.0, v139
	v_add_f32_e32 v136, 1.0, v136
	v_rcp_f32_e32 v139, v139
	v_rcp_f32_e32 v137, v136
	v_cvt_pk_bf16_f32 v136, v138, v139
	v_cvt_pk_bf16_f32 v137, v140, v137
	ds_write_b64 v32, v[136:137] offset:4416
	v_pk_add_f32 v[136:137], v[88:89], v[132:133]
	v_pk_add_f32 v[138:139], v[86:87], v[130:131]
	v_mul_f32_e32 v136, 0xbfb8aa3b, v136
	v_exp_f32_e32 v136, v136
	v_pk_add_f32 v[132:133], v[72:73], v[132:133]
	v_pk_add_f32 v[130:131], v[70:71], v[130:131]
	v_mul_f32_e32 v138, 0xbfb8aa3b, v138
	v_add_f32_e32 v136, 1.0, v136
	v_mul_f32_e32 v139, 0xbfb8aa3b, v139
	v_rcp_f32_e32 v140, v136
	v_mul_f32_e32 v136, 0xbfb8aa3b, v137
	v_mul_f32_e32 v130, 0xbfb8aa3b, v130
	v_mul_f32_e32 v131, 0xbfb8aa3b, v131
	v_mul_f32_e32 v132, 0xbfb8aa3b, v132
	v_mul_f32_e32 v133, 0xbfb8aa3b, v133
	v_exp_f32_e32 v138, v138
	v_exp_f32_e32 v139, v139
	v_exp_f32_e32 v136, v136
	v_exp_f32_e32 v130, v130
	v_exp_f32_e32 v131, v131
	v_exp_f32_e32 v132, v132
	v_exp_f32_e32 v133, v133
	v_add_f32_e32 v138, 1.0, v138
	v_add_f32_e32 v139, 1.0, v139
	v_add_f32_e32 v136, 1.0, v136
	v_add_f32_e32 v130, 1.0, v130
	v_add_f32_e32 v131, 1.0, v131
	v_add_f32_e32 v132, 1.0, v132
	v_add_f32_e32 v133, 1.0, v133
	v_rcp_f32_e32 v138, v138
	v_rcp_f32_e32 v139, v139
	v_rcp_f32_e32 v137, v136
	v_rcp_f32_e32 v130, v130
	v_rcp_f32_e32 v131, v131
	v_rcp_f32_e32 v132, v132
	v_rcp_f32_e32 v133, v133
	v_cvt_pk_bf16_f32 v136, v138, v139
	v_cvt_pk_bf16_f32 v137, v140, v137
	v_cvt_pk_bf16_f32 v130, v130, v131
	v_cvt_pk_bf16_f32 v131, v132, v133
	ds_write_b64 v32, v[136:137] offset:8768
	ds_write_b64 v32, v[130:131] offset:13120
	flat_load_dwordx4 v[130:133], v[134:135] offset:192
	s_waitcnt vmcnt(0) lgkmcnt(0)
	v_pk_add_f32 v[134:135], v[116:117], v[132:133]
	s_nop 0
	v_mul_f32_e32 v134, 0xbfb8aa3b, v134
	v_exp_f32_e32 v134, v134
	v_pk_add_f32 v[136:137], v[114:115], v[130:131]
	v_add_f32_e32 v134, 1.0, v134
	v_mul_f32_e32 v136, 0xbfb8aa3b, v136
	v_mul_f32_e32 v137, 0xbfb8aa3b, v137
	v_rcp_f32_e32 v138, v134
	v_mul_f32_e32 v134, 0xbfb8aa3b, v135
	v_exp_f32_e32 v136, v136
	v_exp_f32_e32 v137, v137
	v_exp_f32_e32 v134, v134
	v_add_f32_e32 v136, 1.0, v136
	v_add_f32_e32 v137, 1.0, v137
	v_add_f32_e32 v134, 1.0, v134
	v_rcp_f32_e32 v136, v136
	v_rcp_f32_e32 v137, v137
	v_rcp_f32_e32 v135, v134
	v_cvt_pk_bf16_f32 v134, v136, v137
	v_cvt_pk_bf16_f32 v135, v138, v135
	ds_write_b64 v32, v[134:135] offset:96
	v_pk_add_f32 v[134:135], v[100:101], v[132:133]
	v_pk_add_f32 v[136:137], v[98:99], v[130:131]
	v_mul_f32_e32 v134, 0xbfb8aa3b, v134
	v_exp_f32_e32 v134, v134
	v_mul_f32_e32 v136, 0xbfb8aa3b, v136
	v_mul_f32_e32 v137, 0xbfb8aa3b, v137
	v_exp_f32_e32 v136, v136
	v_add_f32_e32 v134, 1.0, v134
	v_rcp_f32_e32 v138, v134
	v_mul_f32_e32 v134, 0xbfb8aa3b, v135
	v_exp_f32_e32 v137, v137
	v_exp_f32_e32 v134, v134
	v_add_f32_e32 v136, 1.0, v136
	v_rcp_f32_e32 v136, v136
	v_add_f32_e32 v137, 1.0, v137
	v_add_f32_e32 v134, 1.0, v134
	v_rcp_f32_e32 v137, v137
	v_rcp_f32_e32 v135, v134
	v_cvt_pk_bf16_f32 v134, v136, v137
	v_cvt_pk_bf16_f32 v135, v138, v135
	ds_write_b64 v32, v[134:135] offset:4448
	v_pk_add_f32 v[134:135], v[84:85], v[132:133]
	v_pk_add_f32 v[136:137], v[82:83], v[130:131]
	v_mul_f32_e32 v134, 0xbfb8aa3b, v134
	v_exp_f32_e32 v134, v134
	v_pk_add_f32 v[132:133], v[68:69], v[132:133]
	v_pk_add_f32 v[130:131], v[66:67], v[130:131]
	v_mul_f32_e32 v136, 0xbfb8aa3b, v136
	v_add_f32_e32 v134, 1.0, v134
	v_mul_f32_e32 v137, 0xbfb8aa3b, v137
	v_rcp_f32_e32 v138, v134
	v_mul_f32_e32 v134, 0xbfb8aa3b, v135
	v_mul_f32_e32 v130, 0xbfb8aa3b, v130
	v_mul_f32_e32 v131, 0xbfb8aa3b, v131
	v_mul_f32_e32 v132, 0xbfb8aa3b, v132
	v_mul_f32_e32 v133, 0xbfb8aa3b, v133
	v_exp_f32_e32 v136, v136
	v_exp_f32_e32 v137, v137
	v_exp_f32_e32 v134, v134
	v_exp_f32_e32 v130, v130
	v_exp_f32_e32 v131, v131
	v_exp_f32_e32 v132, v132
	v_exp_f32_e32 v133, v133
	v_add_f32_e32 v136, 1.0, v136
	v_add_f32_e32 v137, 1.0, v137
	v_add_f32_e32 v134, 1.0, v134
	v_add_f32_e32 v130, 1.0, v130
	v_add_f32_e32 v131, 1.0, v131
	v_add_f32_e32 v132, 1.0, v132
	v_add_f32_e32 v133, 1.0, v133
	v_rcp_f32_e32 v136, v136
	v_rcp_f32_e32 v137, v137
	v_rcp_f32_e32 v135, v134
	v_rcp_f32_e32 v130, v130
	v_rcp_f32_e32 v131, v131
	v_rcp_f32_e32 v132, v132
	v_rcp_f32_e32 v133, v133
	v_cvt_pk_bf16_f32 v134, v136, v137
	v_cvt_pk_bf16_f32 v135, v138, v135
	v_cvt_pk_bf16_f32 v130, v130, v131
	v_cvt_pk_bf16_f32 v131, v132, v133
	ds_write_b64 v32, v[134:135] offset:8800
	ds_write_b64 v32, v[130:131] offset:13152
